# B0 fragment LDS reads of load phases 1/5 moved into the wave's own MFMA phases 8/4 (LDS read burst balancing), pre-header read + exit drain
# baseline (speedup 1.0000x reference)
; #define G_STAGE(bufoff, gbase, o0, h64) do { \
;         __builtin_amdgcn_global_load_lds((const unsigned*)((const char*)(gbase) + (o0)), (LAS unsigned*)(lds + (bufoff) + ldsw), 16, 0, 0); \
;         __builtin_amdgcn_global_load_lds((const unsigned*)((const char*)(gbase) + (h64) + (o0)), (LAS unsigned*)(lds + (bufoff) + ldsw + 8192), 16, 0, 0); } while (0)
; #define G_LDA(dst, b, h) do { _Pragma("unroll") for (int m = 0; m < 4; ++m) _Pragma("unroll") for (int k = 0; k < 2; ++k) dst[m][k] = *(const LAS bf16x8*)(lds + G_SA(b, h) + aoff + m * 2048 + k * 1024); } while (0)
; #define G_LDB(dst, b, h) do { _Pragma("unroll") for (int n = 0; n < 2; ++n) _Pragma("unroll") for (int k = 0; k < 2; ++k) dst[n][k] = *(const LAS bf16x8*)(lds + G_SB(b, h) + boff + n * 2048 + k * 1024); } while (0)
; #define G_WAIT_L(n) asm volatile("s_waitcnt lgkmcnt(" #n ")" ::: "memory")
; #define G_BAR __builtin_amdgcn_s_barrier()
; #define G_SCHED __builtin_amdgcn_sched_barrier(0)
;     ...
;     for (;;) {
;         const bool has_next = sched_next<PH, SUB>(E.ws, E.layer, ui + 1, nxt, E.x);
;         if (!has_next) nxt = cur;
;         const char* nA = nxt.A; const char* nB = nxt.B;
; #pragma unroll 1
;         for (int t = 0; t < nt; t += 2) {
;             const bool last = (t == nt - 2);
;             const char* a1 = cA + (size_t)(t + 1) * ckA;
;             const char* a2 = last ? nA : cA + (size_t)(t + 2) * ckA; const char* b2 = last ? nB : cB + (size_t)(t + 2) * kB;
;             const char* a3 = a2 + ckA; const char* b3 = b2 + kB;
;             G_LDB(B0, 0, 0); G_SCHED; G_LDA(At, 0, 0); G_STAGE(G_SA(1, 1), a1 + chA, cA0, qA);
;             G_WAIT_L(8); G_BAR; G_WAIT_L(0); G_MMA(0, 0, At, B0); G_BAR; G_SCHED;
;             G_LDB(B1, 0, 1); G_STAGE(G_SB(0, 0), b2, cB0, qB);
;             G_BAR; G_WAIT_L(0); G_MMA(0, 1, At, B1); G_BAR;
;     ...
;         for (int a = 0; a < 2; ++a)
; #pragma unroll
;             for (int b = 0; b < 2; ++b)
; #pragma unroll
;                 for (int m = 0; m < 4; ++m)
; #pragma unroll
;                     for (int n = 0; n < 2; ++n) acc[a][b][m][n] = (f32x4){0.f, 0.f, 0.f, 0.f};
;         cur = nxt; cA = nA; cB = nB; ++ui;
.LBB0_211:
	s_add_u32 s2, s2, 0x40080
	s_addc_u32 s3, s3, 0
	s_add_u32 s7, s22, 0x100
	v_mov_b64_e32 v[8:9], 0
	s_addc_u32 s22, s23, 0
	s_mov_b32 s23, -2
	v_mov_b64_e32 v[10:11], 0
	v_mov_b64_e32 v[12:13], 0
	v_mov_b64_e32 v[14:15], 0
	v_mov_b64_e32 v[24:25], 0
	v_mov_b64_e32 v[26:27], 0
	v_mov_b64_e32 v[28:29], 0
	v_mov_b64_e32 v[30:31], 0
	v_mov_b64_e32 v[40:41], 0
	v_mov_b64_e32 v[42:43], 0
	v_mov_b64_e32 v[44:45], 0
	v_mov_b64_e32 v[46:47], 0
	v_mov_b64_e32 v[56:57], 0
	v_mov_b64_e32 v[58:59], 0
	v_mov_b64_e32 v[60:61], 0
	v_mov_b64_e32 v[62:63], 0
	v_mov_b64_e32 v[16:17], 0
	v_mov_b64_e32 v[18:19], 0
	v_mov_b64_e32 v[20:21], 0
	v_mov_b64_e32 v[22:23], 0
	v_mov_b64_e32 v[32:33], 0
	v_mov_b64_e32 v[34:35], 0
	v_mov_b64_e32 v[36:37], 0
	v_mov_b64_e32 v[38:39], 0
	v_mov_b64_e32 v[48:49], 0
	v_mov_b64_e32 v[50:51], 0
	v_mov_b64_e32 v[52:53], 0
	v_mov_b64_e32 v[54:55], 0
	v_mov_b64_e32 v[64:65], 0
	v_mov_b64_e32 v[66:67], 0
	v_mov_b64_e32 v[68:69], 0
	v_mov_b64_e32 v[70:71], 0
	v_mov_b64_e32 v[72:73], 0
	v_mov_b64_e32 v[74:75], 0
	v_mov_b64_e32 v[76:77], 0
	v_mov_b64_e32 v[78:79], 0
	v_mov_b64_e32 v[88:89], 0
	v_mov_b64_e32 v[90:91], 0
	v_mov_b64_e32 v[92:93], 0
	v_mov_b64_e32 v[94:95], 0
	v_mov_b64_e32 v[104:105], 0
	v_mov_b64_e32 v[106:107], 0
	v_mov_b64_e32 v[108:109], 0
	v_mov_b64_e32 v[110:111], 0
	v_mov_b64_e32 v[120:121], 0
	v_mov_b64_e32 v[122:123], 0
	v_mov_b64_e32 v[124:125], 0
	v_mov_b64_e32 v[126:127], 0
	v_mov_b64_e32 v[80:81], 0
	v_mov_b64_e32 v[82:83], 0
	v_mov_b64_e32 v[84:85], 0
	v_mov_b64_e32 v[86:87], 0
	v_mov_b64_e32 v[96:97], 0
	v_mov_b64_e32 v[98:99], 0
	v_mov_b64_e32 v[100:101], 0
	v_mov_b64_e32 v[102:103], 0
	v_mov_b64_e32 v[112:113], 0
	v_mov_b64_e32 v[114:115], 0
	v_mov_b64_e32 v[116:117], 0
	v_mov_b64_e32 v[118:119], 0
	v_mov_b64_e32 v[128:129], 0
	v_mov_b64_e32 v[130:131], 0
	v_mov_b64_e32 v[132:133], 0
	v_mov_b64_e32 v[134:135], 0
	s_mov_b64 s[52:53], 0x40000
	s_mov_b64 s[54:55], 0x60000
	s_mov_b64 s[58:59], 0x20080
	s_mov_b64 s[62:63], 0x40080
	s_mov_b64 s[64:65], 0x60080
	s_cmp_eq_u32 s101, 2
	s_cselect_b32 s101, 0, s101
	v_add_u32_e32 v255, 0x10000, v167
	ds_read_b128 v[136:139], v255 offset:0
	ds_read_b128 v[144:147], v255 offset:1024
	ds_read_b128 v[148:151], v255 offset:2048
	ds_read_b128 v[152:155], v255 offset:3072
.LBB0_212:
	s_add_u32 s4, s2, 0xfffc0080
	s_addc_u32 s5, s3, -1
	s_add_i32 s41, 0, 0x10000
	s_cmp_eq_u32 s23, 12
	s_cselect_b32 s43, s19, s5
	s_cselect_b32 s42, s18, s4
	s_cselect_b32 s51, s21, s22
	s_cselect_b32 s50, s20, s7
	s_add_i32 m0, s27, 0xc000
	ds_read_b128 v[156:159], v172
	ds_read_b128 v[160:163], v172 offset:1024
	ds_read_b128 v[174:177], v172 offset:2048
	ds_read_b128 v[178:181], v172 offset:3072
	ds_read_b128 v[182:185], v172 offset:4096
	ds_read_b128 v[196:199], v172 offset:5120
	ds_read_b128 v[200:203], v172 offset:6144
	ds_read_b128 v[204:207], v172 offset:7168
	global_load_lds_dwordx4 v142, s[2:3]
	s_add_i32 m0, s27, 0xe000
	s_nop 0
	s_add_u32 vcc_lo, s2, s0
	s_addc_u32 vcc_hi, s3, s1
	global_load_lds_dwordx4 v142, vcc
	s_waitcnt lgkmcnt(8)
	s_cmp_eq_u32 s101, 1
	s_cbranch_scc1 .Ldb_WIN_sk
	s_barrier
.Ldb_WIN_sk:
	s_mov_b32 s101, 0
	s_waitcnt lgkmcnt(0)
	v_mfma_f32_16x16x32_bf16 v[132:135], v[136:139], v[156:159], v[132:135]
	v_mfma_f32_16x16x32_bf16 v[128:131], v[148:151], v[156:159], v[128:131]
	v_mfma_f32_16x16x32_bf16 v[116:119], v[136:139], v[174:177], v[116:119]
	v_mfma_f32_16x16x32_bf16 v[112:115], v[148:151], v[174:177], v[112:115]
	v_mfma_f32_16x16x32_bf16 v[100:103], v[136:139], v[182:185], v[100:103]
	v_mfma_f32_16x16x32_bf16 v[96:99], v[148:151], v[182:185], v[96:99]
	v_mfma_f32_16x16x32_bf16 v[84:87], v[136:139], v[200:203], v[84:87]
	v_mfma_f32_16x16x32_bf16 v[80:83], v[148:151], v[200:203], v[80:83]
	v_mfma_f32_16x16x32_bf16 v[132:135], v[144:147], v[160:163], v[132:135]
	v_mfma_f32_16x16x32_bf16 v[128:131], v[152:155], v[160:163], v[128:131]
	v_mfma_f32_16x16x32_bf16 v[116:119], v[144:147], v[178:181], v[116:119]
	v_mfma_f32_16x16x32_bf16 v[112:115], v[152:155], v[178:181], v[112:115]
	v_mfma_f32_16x16x32_bf16 v[100:103], v[144:147], v[196:199], v[100:103]
	v_mfma_f32_16x16x32_bf16 v[96:99], v[152:155], v[196:199], v[96:99]
	v_mfma_f32_16x16x32_bf16 v[84:87], v[144:147], v[204:207], v[84:87]
	v_mfma_f32_16x16x32_bf16 v[80:83], v[152:155], v[204:207], v[80:83]
	s_barrier
	s_add_i32 s4, 0, 0x14000
	s_add_i32 s5, s41, s26
	s_mov_b32 m0, s5
	ds_read_b128 v[208:211], v255 offset:16384
	ds_read_b128 v[212:215], v255 offset:17408
	ds_read_b128 v[216:219], v255 offset:18432
	ds_read_b128 v[220:223], v255 offset:19456
	global_load_lds_dwordx4 v140, s[50:51]
	s_add_i32 m0, s5, 0x2000
	s_nop 0
	s_add_u32 vcc_lo, s50, s0
	s_addc_u32 vcc_hi, s51, s1
	global_load_lds_dwordx4 v140, vcc
	s_barrier
	s_waitcnt lgkmcnt(0)
	v_mfma_f32_16x16x32_bf16 v[124:127], v[208:211], v[156:159], v[124:127]
	v_mfma_f32_16x16x32_bf16 v[120:123], v[216:219], v[156:159], v[120:123]
	v_mfma_f32_16x16x32_bf16 v[108:111], v[208:211], v[174:177], v[108:111]
	v_mfma_f32_16x16x32_bf16 v[104:107], v[216:219], v[174:177], v[104:107]
	v_mfma_f32_16x16x32_bf16 v[92:95], v[208:211], v[182:185], v[92:95]
	v_mfma_f32_16x16x32_bf16 v[88:91], v[216:219], v[182:185], v[88:91]
	v_mfma_f32_16x16x32_bf16 v[76:79], v[208:211], v[200:203], v[76:79]
	v_mfma_f32_16x16x32_bf16 v[72:75], v[216:219], v[200:203], v[72:75]
	v_mfma_f32_16x16x32_bf16 v[124:127], v[212:215], v[160:163], v[124:127]
	v_mfma_f32_16x16x32_bf16 v[120:123], v[220:223], v[160:163], v[120:123]
	v_mfma_f32_16x16x32_bf16 v[108:111], v[212:215], v[178:181], v[108:111]
	v_mfma_f32_16x16x32_bf16 v[104:107], v[220:223], v[178:181], v[104:107]
	v_mfma_f32_16x16x32_bf16 v[92:95], v[212:215], v[196:199], v[92:95]
	v_mfma_f32_16x16x32_bf16 v[88:91], v[220:223], v[196:199], v[88:91]
	v_mfma_f32_16x16x32_bf16 v[76:79], v[212:215], v[204:207], v[76:79]
	v_mfma_f32_16x16x32_bf16 v[72:75], v[220:223], v[204:207], v[72:75]
	s_barrier
; #define G_STAGE(bufoff, gbase, o0, h64) do { \
;         __builtin_amdgcn_global_load_lds((const unsigned*)((const char*)(gbase) + (o0)), (LAS unsigned*)(lds + (bufoff) + ldsw), 16, 0, 0); \
;         __builtin_amdgcn_global_load_lds((const unsigned*)((const char*)(gbase) + (h64) + (o0)), (LAS unsigned*)(lds + (bufoff) + ldsw + 8192), 16, 0, 0); } while (0)
; #define G_LDA(dst, b, h) do { _Pragma("unroll") for (int m = 0; m < 4; ++m) _Pragma("unroll") for (int k = 0; k < 2; ++k) dst[m][k] = *(const LAS bf16x8*)(lds + G_SA(b, h) + aoff + m * 2048 + k * 1024); } while (0)
; #define G_LDB(dst, b, h) do { _Pragma("unroll") for (int n = 0; n < 2; ++n) _Pragma("unroll") for (int k = 0; k < 2; ++k) dst[n][k] = *(const LAS bf16x8*)(lds + G_SB(b, h) + boff + n * 2048 + k * 1024); } while (0)
; #define G_WAIT_V(n) asm volatile("s_waitcnt vmcnt(" #n ")" ::: "memory")
; #define G_WAIT_L(n) asm volatile("s_waitcnt lgkmcnt(" #n ")" ::: "memory")
; #define G_BAR __builtin_amdgcn_s_barrier()
; #define G_SCHED __builtin_amdgcn_sched_barrier(0)
;     ...
;             G_LDA(At, 0, 1); G_STAGE(G_SA(0, 0), a2, cA0, qA);
;             G_BAR; G_WAIT_L(0); G_MMA(1, 0, At, B0); G_BAR; G_SCHED;
;             G_STAGE(G_SB(0, 1), b2 + chB, cB0, qB);
;             G_WAIT_V(6); G_BAR; G_MMA(1, 1, At, B1); G_BAR;
;             G_LDB(B0, 1, 0); G_SCHED; G_LDA(At, 1, 0); G_STAGE(G_SA(0, 1), a2 + chA, cA0, qA);
;             G_WAIT_L(8); G_BAR; G_WAIT_L(0); G_MMA(0, 0, At, B0); G_BAR; G_SCHED;
;             G_LDB(B1, 1, 1); G_STAGE(G_SB(1, 0), b3, cB0, qB);
;             G_BAR; G_WAIT_L(0); G_MMA(0, 1, At, B1); G_BAR;
	s_mov_b32 m0, s27
	ds_read_b128 v[156:159], v172 offset:16384
	ds_read_b128 v[160:163], v172 offset:17408
	ds_read_b128 v[174:177], v172 offset:18432
	ds_read_b128 v[178:181], v172 offset:19456
	ds_read_b128 v[182:185], v172 offset:20480
	ds_read_b128 v[196:199], v172 offset:21504
	ds_read_b128 v[200:203], v172 offset:22528
	ds_read_b128 v[204:207], v172 offset:23552
	global_load_lds_dwordx4 v2, s[42:43]
	s_mov_b32 m0, s28
	s_nop 0
	s_add_u32 vcc_lo, s42, s0
	s_addc_u32 vcc_hi, s43, s1
	global_load_lds_dwordx4 v2, vcc
	s_barrier
	s_waitcnt lgkmcnt(0)
	v_mfma_f32_16x16x32_bf16 v[68:71], v[136:139], v[156:159], v[68:71]
	v_mfma_f32_16x16x32_bf16 v[64:67], v[148:151], v[156:159], v[64:67]
	v_mfma_f32_16x16x32_bf16 v[52:55], v[136:139], v[174:177], v[52:55]
	v_mfma_f32_16x16x32_bf16 v[48:51], v[148:151], v[174:177], v[48:51]
	v_mfma_f32_16x16x32_bf16 v[36:39], v[136:139], v[182:185], v[36:39]
	v_mfma_f32_16x16x32_bf16 v[32:35], v[148:151], v[182:185], v[32:35]
	v_mfma_f32_16x16x32_bf16 v[20:23], v[136:139], v[200:203], v[20:23]
	v_mfma_f32_16x16x32_bf16 v[16:19], v[148:151], v[200:203], v[16:19]
	v_mfma_f32_16x16x32_bf16 v[68:71], v[144:147], v[160:163], v[68:71]
	v_mfma_f32_16x16x32_bf16 v[64:67], v[152:155], v[160:163], v[64:67]
	v_mfma_f32_16x16x32_bf16 v[52:55], v[144:147], v[178:181], v[52:55]
	v_mfma_f32_16x16x32_bf16 v[48:51], v[152:155], v[178:181], v[48:51]
	v_mfma_f32_16x16x32_bf16 v[36:39], v[144:147], v[196:199], v[36:39]
	v_mfma_f32_16x16x32_bf16 v[32:35], v[152:155], v[196:199], v[32:35]
	v_mfma_f32_16x16x32_bf16 v[20:23], v[144:147], v[204:207], v[20:23]
	v_mfma_f32_16x16x32_bf16 v[16:19], v[152:155], v[204:207], v[16:19]
	s_barrier
	s_add_i32 s4, s4, s26
	s_mov_b32 m0, s4
	s_nop 0
	s_add_u32 vcc_lo, s50, s52
	s_addc_u32 vcc_hi, s51, s53
	global_load_lds_dwordx4 v140, vcc
	s_add_i32 m0, s4, 0x2000
	s_nop 0
	s_add_u32 vcc_lo, s50, s54
	s_addc_u32 vcc_hi, s51, s55
	global_load_lds_dwordx4 v140, vcc
	s_waitcnt vmcnt(6)
	s_barrier
	v_mfma_f32_16x16x32_bf16 v[60:63], v[208:211], v[156:159], v[60:63]
	v_mfma_f32_16x16x32_bf16 v[56:59], v[216:219], v[156:159], v[56:59]
	v_mfma_f32_16x16x32_bf16 v[44:47], v[208:211], v[174:177], v[44:47]
	v_mfma_f32_16x16x32_bf16 v[40:43], v[216:219], v[174:177], v[40:43]
	ds_read_b128 v[136:139], v255 offset:32768
	ds_read_b128 v[144:147], v255 offset:33792
	ds_read_b128 v[148:151], v255 offset:34816
	ds_read_b128 v[152:155], v255 offset:35840
	v_mfma_f32_16x16x32_bf16 v[28:31], v[208:211], v[182:185], v[28:31]
	v_mfma_f32_16x16x32_bf16 v[24:27], v[216:219], v[182:185], v[24:27]
	v_mfma_f32_16x16x32_bf16 v[12:15], v[208:211], v[200:203], v[12:15]
	v_mfma_f32_16x16x32_bf16 v[8:11], v[216:219], v[200:203], v[8:11]
	v_mfma_f32_16x16x32_bf16 v[60:63], v[212:215], v[160:163], v[60:63]
	v_mfma_f32_16x16x32_bf16 v[56:59], v[220:223], v[160:163], v[56:59]
	v_mfma_f32_16x16x32_bf16 v[44:47], v[212:215], v[178:181], v[44:47]
	v_mfma_f32_16x16x32_bf16 v[40:43], v[220:223], v[178:181], v[40:43]
	v_mfma_f32_16x16x32_bf16 v[28:31], v[212:215], v[196:199], v[28:31]
	v_mfma_f32_16x16x32_bf16 v[24:27], v[220:223], v[196:199], v[24:27]
	v_mfma_f32_16x16x32_bf16 v[12:15], v[212:215], v[204:207], v[12:15]
	v_mfma_f32_16x16x32_bf16 v[8:11], v[220:223], v[204:207], v[8:11]
	s_barrier
	s_add_i32 s4, 0, 0x18000
	s_mov_b32 m0, s29
	ds_read_b128 v[156:159], v172 offset:32768
	ds_read_b128 v[160:163], v172 offset:33792
	ds_read_b128 v[174:177], v172 offset:34816
	ds_read_b128 v[178:181], v172 offset:35840
	ds_read_b128 v[182:185], v172 offset:36864
	ds_read_b128 v[196:199], v172 offset:37888
	ds_read_b128 v[200:203], v172 offset:38912
	ds_read_b128 v[204:207], v172 offset:39936
	s_add_u32 vcc_lo, s42, s52
	s_addc_u32 vcc_hi, s43, s53
	global_load_lds_dwordx4 v2, vcc
	s_mov_b32 m0, s30
	s_nop 0
	s_add_u32 vcc_lo, s42, s54
	s_addc_u32 vcc_hi, s43, s55
	global_load_lds_dwordx4 v2, vcc
	s_waitcnt lgkmcnt(8)
	s_barrier
	s_waitcnt lgkmcnt(0)
	v_mfma_f32_16x16x32_bf16 v[132:135], v[136:139], v[156:159], v[132:135]
	v_mfma_f32_16x16x32_bf16 v[128:131], v[148:151], v[156:159], v[128:131]
	v_mfma_f32_16x16x32_bf16 v[116:119], v[136:139], v[174:177], v[116:119]
	v_mfma_f32_16x16x32_bf16 v[112:115], v[148:151], v[174:177], v[112:115]
	v_mfma_f32_16x16x32_bf16 v[100:103], v[136:139], v[182:185], v[100:103]
	v_mfma_f32_16x16x32_bf16 v[96:99], v[148:151], v[182:185], v[96:99]
	v_mfma_f32_16x16x32_bf16 v[84:87], v[136:139], v[200:203], v[84:87]
	v_mfma_f32_16x16x32_bf16 v[80:83], v[148:151], v[200:203], v[80:83]
	v_mfma_f32_16x16x32_bf16 v[132:135], v[144:147], v[160:163], v[132:135]
	v_mfma_f32_16x16x32_bf16 v[128:131], v[152:155], v[160:163], v[128:131]
	v_mfma_f32_16x16x32_bf16 v[116:119], v[144:147], v[178:181], v[116:119]
	v_mfma_f32_16x16x32_bf16 v[112:115], v[152:155], v[178:181], v[112:115]
	v_mfma_f32_16x16x32_bf16 v[100:103], v[144:147], v[196:199], v[100:103]
	v_mfma_f32_16x16x32_bf16 v[96:99], v[152:155], v[196:199], v[96:99]
	v_mfma_f32_16x16x32_bf16 v[84:87], v[144:147], v[204:207], v[84:87]
	v_mfma_f32_16x16x32_bf16 v[80:83], v[152:155], v[204:207], v[80:83]
	s_barrier
; #define G_STAGE(bufoff, gbase, o0, h64) do { \
;         __builtin_amdgcn_global_load_lds((const unsigned*)((const char*)(gbase) + (o0)), (LAS unsigned*)(lds + (bufoff) + ldsw), 16, 0, 0); \
;         __builtin_amdgcn_global_load_lds((const unsigned*)((const char*)(gbase) + (h64) + (o0)), (LAS unsigned*)(lds + (bufoff) + ldsw + 8192), 16, 0, 0); } while (0)
; #define G_LDA(dst, b, h) do { _Pragma("unroll") for (int m = 0; m < 4; ++m) _Pragma("unroll") for (int k = 0; k < 2; ++k) dst[m][k] = *(const LAS bf16x8*)(lds + G_SA(b, h) + aoff + m * 2048 + k * 1024); } while (0)
; #define G_LDB(dst, b, h) do { _Pragma("unroll") for (int n = 0; n < 2; ++n) _Pragma("unroll") for (int k = 0; k < 2; ++k) dst[n][k] = *(const LAS bf16x8*)(lds + G_SB(b, h) + boff + n * 2048 + k * 1024); } while (0)
; #define G_WAIT_V(n) asm volatile("s_waitcnt vmcnt(" #n ")" ::: "memory")
; #define G_WAIT_L(n) asm volatile("s_waitcnt lgkmcnt(" #n ")" ::: "memory")
; #define G_BAR __builtin_amdgcn_s_barrier()
; #define G_SCHED __builtin_amdgcn_sched_barrier(0)
;     ...
;             G_LDB(B1, 1, 1); G_STAGE(G_SB(1, 0), b3, cB0, qB);
;             G_BAR; G_WAIT_L(0); G_MMA(0, 1, At, B1); G_BAR;
;             G_LDA(At, 1, 1); G_STAGE(G_SA(1, 0), a3, cA0, qA);
;             G_BAR; G_WAIT_L(0); G_MMA(1, 0, At, B0); G_BAR; G_SCHED;
;             G_STAGE(G_SB(1, 1), b3 + chB, cB0, qB);
;             G_WAIT_V(6); G_BAR; G_MMA(1, 1, At, B1); G_BAR;
	s_add_i32 s5, 0, 0x1c000
	s_add_i32 s4, s4, s26
	s_mov_b32 m0, s4
	ds_read_b128 v[208:211], v255 offset:49152
	ds_read_b128 v[212:215], v255 offset:50176
	ds_read_b128 v[216:219], v255 offset:51200
	ds_read_b128 v[220:223], v255 offset:52224
	s_add_u32 vcc_lo, s50, s46
	s_addc_u32 vcc_hi, s51, s47
	global_load_lds_dwordx4 v140, vcc
	s_add_i32 m0, s4, 0x2000
	s_nop 0
	s_add_u32 vcc_lo, s50, s58
	s_addc_u32 vcc_hi, s51, s59
	global_load_lds_dwordx4 v140, vcc
	s_barrier
	s_waitcnt lgkmcnt(0)
	v_mfma_f32_16x16x32_bf16 v[124:127], v[208:211], v[156:159], v[124:127]
	v_mfma_f32_16x16x32_bf16 v[120:123], v[216:219], v[156:159], v[120:123]
	v_mfma_f32_16x16x32_bf16 v[108:111], v[208:211], v[174:177], v[108:111]
	v_mfma_f32_16x16x32_bf16 v[104:107], v[216:219], v[174:177], v[104:107]
	v_mfma_f32_16x16x32_bf16 v[92:95], v[208:211], v[182:185], v[92:95]
	v_mfma_f32_16x16x32_bf16 v[88:91], v[216:219], v[182:185], v[88:91]
	v_mfma_f32_16x16x32_bf16 v[76:79], v[208:211], v[200:203], v[76:79]
	v_mfma_f32_16x16x32_bf16 v[72:75], v[216:219], v[200:203], v[72:75]
	v_mfma_f32_16x16x32_bf16 v[124:127], v[212:215], v[160:163], v[124:127]
	v_mfma_f32_16x16x32_bf16 v[120:123], v[220:223], v[160:163], v[120:123]
	v_mfma_f32_16x16x32_bf16 v[108:111], v[212:215], v[178:181], v[108:111]
	v_mfma_f32_16x16x32_bf16 v[104:107], v[220:223], v[178:181], v[104:107]
	v_mfma_f32_16x16x32_bf16 v[92:95], v[212:215], v[196:199], v[92:95]
	v_mfma_f32_16x16x32_bf16 v[88:91], v[220:223], v[196:199], v[88:91]
	v_mfma_f32_16x16x32_bf16 v[76:79], v[212:215], v[204:207], v[76:79]
	v_mfma_f32_16x16x32_bf16 v[72:75], v[220:223], v[204:207], v[72:75]
	s_barrier
	s_mov_b32 m0, s31
	ds_read_b128 v[156:159], v172 offset:49152
	ds_read_b128 v[160:163], v172 offset:50176
	ds_read_b128 v[174:177], v172 offset:51200
	ds_read_b128 v[178:181], v172 offset:52224
	ds_read_b128 v[182:185], v172 offset:53248
	ds_read_b128 v[196:199], v172 offset:54272
	ds_read_b128 v[200:203], v172 offset:55296
	ds_read_b128 v[204:207], v172 offset:56320
	s_add_u32 vcc_lo, s42, s46
	s_addc_u32 vcc_hi, s43, s47
	global_load_lds_dwordx4 v2, vcc
	s_mov_b32 m0, s34
	s_nop 0
	s_add_u32 vcc_lo, s42, s58
	s_addc_u32 vcc_hi, s43, s59
	global_load_lds_dwordx4 v2, vcc
	s_barrier
	s_waitcnt lgkmcnt(0)
	v_mfma_f32_16x16x32_bf16 v[68:71], v[136:139], v[156:159], v[68:71]
	v_mfma_f32_16x16x32_bf16 v[64:67], v[148:151], v[156:159], v[64:67]
	v_mfma_f32_16x16x32_bf16 v[52:55], v[136:139], v[174:177], v[52:55]
	v_mfma_f32_16x16x32_bf16 v[48:51], v[148:151], v[174:177], v[48:51]
	v_mfma_f32_16x16x32_bf16 v[36:39], v[136:139], v[182:185], v[36:39]
	v_mfma_f32_16x16x32_bf16 v[32:35], v[148:151], v[182:185], v[32:35]
	v_mfma_f32_16x16x32_bf16 v[20:23], v[136:139], v[200:203], v[20:23]
	v_mfma_f32_16x16x32_bf16 v[16:19], v[148:151], v[200:203], v[16:19]
	v_mfma_f32_16x16x32_bf16 v[68:71], v[144:147], v[160:163], v[68:71]
	v_mfma_f32_16x16x32_bf16 v[64:67], v[152:155], v[160:163], v[64:67]
	v_mfma_f32_16x16x32_bf16 v[52:55], v[144:147], v[178:181], v[52:55]
	v_mfma_f32_16x16x32_bf16 v[48:51], v[152:155], v[178:181], v[48:51]
	v_mfma_f32_16x16x32_bf16 v[36:39], v[144:147], v[196:199], v[36:39]
	v_mfma_f32_16x16x32_bf16 v[32:35], v[152:155], v[196:199], v[32:35]
	v_mfma_f32_16x16x32_bf16 v[20:23], v[144:147], v[204:207], v[20:23]
	v_mfma_f32_16x16x32_bf16 v[16:19], v[152:155], v[204:207], v[16:19]
	s_barrier
	s_add_i32 s4, s5, s26
	s_mov_b32 m0, s4
	s_nop 0
	s_add_u32 vcc_lo, s50, s62
	s_addc_u32 vcc_hi, s51, s63
	global_load_lds_dwordx4 v140, vcc
	s_add_i32 m0, s4, 0x2000
	s_nop 0
	s_add_u32 vcc_lo, s50, s64
	s_addc_u32 vcc_hi, s51, s65
	global_load_lds_dwordx4 v140, vcc
	s_add_i32 s23, s23, 2
	s_add_u32 s2, s2, 0x100
	s_addc_u32 s3, s3, 0
	s_add_u32 s7, s7, 0x100
	s_addc_u32 s22, s22, 0
	s_cmp_gt_u32 s23, 13
	s_waitcnt vmcnt(6)
	s_barrier
	v_mfma_f32_16x16x32_bf16 v[60:63], v[208:211], v[156:159], v[60:63]
	v_mfma_f32_16x16x32_bf16 v[56:59], v[216:219], v[156:159], v[56:59]
	v_mfma_f32_16x16x32_bf16 v[44:47], v[208:211], v[174:177], v[44:47]
	v_mfma_f32_16x16x32_bf16 v[40:43], v[216:219], v[174:177], v[40:43]
	ds_read_b128 v[136:139], v255 offset:0
	ds_read_b128 v[144:147], v255 offset:1024
	ds_read_b128 v[148:151], v255 offset:2048
	ds_read_b128 v[152:155], v255 offset:3072
	v_mfma_f32_16x16x32_bf16 v[28:31], v[208:211], v[182:185], v[28:31]
	v_mfma_f32_16x16x32_bf16 v[24:27], v[216:219], v[182:185], v[24:27]
	v_mfma_f32_16x16x32_bf16 v[12:15], v[208:211], v[200:203], v[12:15]
	v_mfma_f32_16x16x32_bf16 v[8:11], v[216:219], v[200:203], v[8:11]
	v_mfma_f32_16x16x32_bf16 v[60:63], v[212:215], v[160:163], v[60:63]
	v_mfma_f32_16x16x32_bf16 v[56:59], v[220:223], v[160:163], v[56:59]
	v_mfma_f32_16x16x32_bf16 v[44:47], v[212:215], v[178:181], v[44:47]
	v_mfma_f32_16x16x32_bf16 v[40:43], v[220:223], v[178:181], v[40:43]
	v_mfma_f32_16x16x32_bf16 v[28:31], v[212:215], v[196:199], v[28:31]
	v_mfma_f32_16x16x32_bf16 v[24:27], v[220:223], v[196:199], v[24:27]
	v_mfma_f32_16x16x32_bf16 v[12:15], v[212:215], v[204:207], v[12:15]
	v_mfma_f32_16x16x32_bf16 v[8:11], v[220:223], v[204:207], v[8:11]
	s_cbranch_scc0 .Ldb_WIN_cont
	v_readfirstlane_b32 s101, v186
	s_cmpk_gt_u32 s101, 0xff
	s_cbranch_scc1 .Ldb_WIN_young
	s_barrier
	s_mov_b32 s101, 1
	s_branch .Ldb_WIN_exit

; __device__ __forceinline__ u32x4 pack8(const f32x4 a, const f32x4 b) { u32x4 w; w.x = cvt_pk_bf16(a[0], a[1]); w.y = cvt_pk_bf16(a[2], a[3]); w.z = cvt_pk_bf16(b[0], b[1]); w.w = cvt_pk_bf16(b[2], b[3]); return w; }
; #define MEMFENCE asm volatile("" ::: "memory")
;     __device__ __forceinline__ void get_rs(const Unit& u, int wr, int fr, float (&rs)[8]) const {
; #pragma unroll
;         for (int r8 = 0; r8 < 8; ++r8) rs[r8] = rstab[u.ord * 256 + (r8 >> 2) * 128 + wr * 64 + (r8 & 3) * 16 + fr];
;     }
;     template <int KIND> __device__ __forceinline__ void run(f32x4 (&acc)[2][2][4][2], const Unit& u, int tid_in) const {
;     ...
;         if constexpr (KIND == K_WIN) { float rs[8]; get_rs(u, wr, fr, rs);
; #pragma unroll
;             for (int ai = 0; ai < 2; ++ai)
; #pragma unroll
;                 for (int m = 0; m < 4; ++m) { int row = rbase + ai * 128 + m * 16; asm volatile("" : "+v"(row)); const float r = rs[ai * 4 + m];
;                     if (u.pn >= 4 && u.pn < 8) {
;                         const f32x4 v0 = (acc[ai][0][m][0] * r) * (acc[ai][1][m][0] * r), v1 = (acc[ai][0][m][1] * r) * (acc[ai][1][m][1] * r);
;                         *(u32x4*)(zb + (size_t)row * ZW + 1024 + (u.pn - 4) * 128 + cl) = pack8(v0, v1); }
;                     else
; #pragma unroll
;                     for (int bj = 0; bj < 2; ++bj) { const u32x4 w = pack8(acc[ai][bj][m][0] * r, acc[ai][bj][m][1] * r);
;                         if (u.pn < 2) { const int col = u.pn * 256 + bj * 128 + cl; *(u32x4*)((bf16_t*)x + ((size_t)(col >> 4) * T_TOK + row) * 16 + (col & 15)) = w; }
;                         else if (u.pn < 10 || bj == 0) *(u32x4*)(zb + (size_t)row * ZW + u.pn * 256 + bj * 128 + cl) = w;
;                         else { const int b = row >> 13, s = row & 8191; bf16_t* vp = (bf16_t*)(ws + OFF_VT) + ((size_t)(b * 128 + cl)) * SEQ + s;
;                             vp[0 * SEQ] = (bf16_t)(w.x & 0xffff); vp[1 * SEQ] = (bf16_t)(w.x >> 16); vp[2 * SEQ] = (bf16_t)(w.y & 0xffff); vp[3 * SEQ] = (bf16_t)(w.y >> 16);
;                             vp[4 * SEQ] = (bf16_t)(w.z & 0xffff); vp[5 * SEQ] = (bf16_t)(w.z >> 16); vp[6 * SEQ] = (bf16_t)(w.w & 0xffff); vp[7 * SEQ] = (bf16_t)(w.w >> 16); } } MEMFENCE; }
.Ldb_WIN_exit:
	s_waitcnt lgkmcnt(0)
	v_mov_b32_e32 v0, v166
	s_lshl_b32 s5, s6, 10
	v_readfirstlane_b32 s2, v0
	s_ashr_i32 s3, s2, 2
	s_lshr_b32 s4, s2, 1
	s_add_i32 s5, s5, 0
	s_and_b32 s2, s2, 0xffffff00
	v_and_b32_e32 v136, 15, v0
	s_add_i32 s5, s5, s2
	v_lshl_add_u32 v137, v136, 2, s5
	v_add_u32_e32 v137, 0x20010, v137
	ds_read2_b32 v[160:161], v137 offset1:16
	ds_read2_b32 v[154:155], v137 offset0:32 offset1:48
	ds_read2_b32 v[150:151], v137 offset0:128 offset1:144
	ds_read2_b32 v[146:147], v137 offset0:160 offset1:176
	s_andn2_b32 s3, s3, 63
	s_and_b32 s4, s4, 0x60
	v_lshrrev_b32_e32 v0, 1, v0
	v_and_or_b32 v173, v0, 24, s4
	v_or_b32_e32 v136, s3, v136
	s_and_b32 s4, s25, -4
	s_waitcnt lgkmcnt(0)
	v_mov_b32_e32 v156, v161
	v_lshl_add_u32 v145, s33, 8, v136
	s_cmp_lg_u32 s4, 4
	v_mov_b32_e32 v161, v160
	v_mov_b32_e32 v152, v155
	v_mov_b32_e32 v148, v151
	v_mov_b32_e32 v144, v147
	v_and_b32_e32 v174, 8, v0
	v_mov_b32_e32 v158, v145
	s_cselect_b64 s[2:3], -1, 0
	s_cmp_eq_u32 s4, 4
	s_mov_b64 s[6:7], -1
	v_pk_mul_f32 v[132:133], v[132:133], v[160:161]
	v_pk_mul_f32 v[128:129], v[128:129], v[160:161]
	s_cbranch_scc1 .LBB0_227
	v_mov_b64_e32 v[136:137], s[12:13]
	v_mad_i64_i32 v[162:163], s[6:7], v158, s76, v[136:137]
	s_cmp_gt_i32 s25, 1
	v_mov_b32_e32 v136, v160
	v_mov_b32_e32 v137, v160
	s_cselect_b64 s[6:7], -1, 0
	v_pk_mul_f32 v[138:139], v[134:135], v[136:137]
	s_lshl_b32 s74, s25, 8
	s_mov_b64 s[22:23], -1
	s_and_b64 vcc, exec, s[6:7]
	v_pk_mul_f32 v[164:165], v[130:131], v[136:137]
	v_cvt_pk_bf16_f32 v136, v132, v133
	v_cvt_pk_bf16_f32 v137, v138, v139
	v_cvt_pk_bf16_f32 v138, v128, v129
	s_nop 0
	v_cvt_pk_bf16_f32 v139, v164, v165
	s_cbranch_vccz .LBB0_216
	v_lshl_add_u64 v[164:165], s[74:75], 1, v[162:163]
	v_lshlrev_b32_e32 v0, 1, v173
	v_lshl_add_u64 v[164:165], v[164:165], 0, v[0:1]
	global_store_dwordx4 v[164:165], v[136:139], off
	s_mov_b64 s[22:23], 0

; #define G_STAGE(bufoff, gbase, o0, h64) do { \
;         __builtin_amdgcn_global_load_lds((const unsigned*)((const char*)(gbase) + (o0)), (LAS unsigned*)(lds + (bufoff) + ldsw), 16, 0, 0); \
;         __builtin_amdgcn_global_load_lds((const unsigned*)((const char*)(gbase) + (h64) + (o0)), (LAS unsigned*)(lds + (bufoff) + ldsw + 8192), 16, 0, 0); } while (0)
; #define G_LDA(dst, b, h) do { _Pragma("unroll") for (int m = 0; m < 4; ++m) _Pragma("unroll") for (int k = 0; k < 2; ++k) dst[m][k] = *(const LAS bf16x8*)(lds + G_SA(b, h) + aoff + m * 2048 + k * 1024); } while (0)
; #define G_LDB(dst, b, h) do { _Pragma("unroll") for (int n = 0; n < 2; ++n) _Pragma("unroll") for (int k = 0; k < 2; ++k) dst[n][k] = *(const LAS bf16x8*)(lds + G_SB(b, h) + boff + n * 2048 + k * 1024); } while (0)
; #define G_WAIT_L(n) asm volatile("s_waitcnt lgkmcnt(" #n ")" ::: "memory")
; #define G_BAR __builtin_amdgcn_s_barrier()
; #define G_SCHED __builtin_amdgcn_sched_barrier(0)
;     ...
;         for (int t = 0; t < nt; t += 2) {
;             const bool last = (t == nt - 2);
;             const char* a1 = cA + (size_t)(t + 1) * ckA;
;             const char* a2 = last ? nA : cA + (size_t)(t + 2) * ckA; const char* b2 = last ? nB : cB + (size_t)(t + 2) * kB;
;             const char* a3 = a2 + ckA; const char* b3 = b2 + kB;
;             G_LDB(B0, 0, 0); G_SCHED; G_LDA(At, 0, 0); G_STAGE(G_SA(1, 1), a1 + chA, cA0, qA);
;             G_WAIT_L(8); G_BAR; G_WAIT_L(0); G_MMA(0, 0, At, B0); G_BAR; G_SCHED;
;             G_LDB(B1, 0, 1); G_STAGE(G_SB(0, 0), b2, cB0, qB);
;             G_BAR; G_WAIT_L(0); G_MMA(0, 1, At, B1); G_BAR;
;     ...
;         if (!(cs.kind == K_MG_B && cur.aux < 2))
; #pragma unroll
;         for (int a = 0; a < 2; ++a)
; #pragma unroll
;             for (int b = 0; b < 2; ++b)
; #pragma unroll
;                 for (int m = 0; m < 4; ++m)
; #pragma unroll
;                     for (int n = 0; n < 2; ++n) acc[a][b][m][n] = (f32x4){0.f, 0.f, 0.f, 0.f};
;         cur = nxt; cA = nA; cB = nB; ++ui;
.LBB0_449:
	s_add_u32 s6, s22, 0x20080
	s_addc_u32 s7, s23, 0
	s_add_u32 s19, s20, 0x100
	v_mov_b64_e32 v[8:9], 0
	s_addc_u32 s20, s21, 0
	s_mov_b32 s21, -2
	v_mov_b64_e32 v[10:11], 0
	v_mov_b64_e32 v[12:13], 0
	v_mov_b64_e32 v[14:15], 0
	v_mov_b64_e32 v[24:25], 0
	v_mov_b64_e32 v[26:27], 0
	v_mov_b64_e32 v[28:29], 0
	v_mov_b64_e32 v[30:31], 0
	v_mov_b64_e32 v[40:41], 0
	v_mov_b64_e32 v[42:43], 0
	v_mov_b64_e32 v[44:45], 0
	v_mov_b64_e32 v[46:47], 0
	v_mov_b64_e32 v[56:57], 0
	v_mov_b64_e32 v[58:59], 0
	v_mov_b64_e32 v[60:61], 0
	v_mov_b64_e32 v[62:63], 0
	v_mov_b64_e32 v[16:17], 0
	v_mov_b64_e32 v[18:19], 0
	v_mov_b64_e32 v[20:21], 0
	v_mov_b64_e32 v[22:23], 0
	v_mov_b64_e32 v[32:33], 0
	v_mov_b64_e32 v[34:35], 0
	v_mov_b64_e32 v[36:37], 0
	v_mov_b64_e32 v[38:39], 0
	v_mov_b64_e32 v[48:49], 0
	v_mov_b64_e32 v[50:51], 0
	v_mov_b64_e32 v[52:53], 0
	v_mov_b64_e32 v[54:55], 0
	v_mov_b64_e32 v[64:65], 0
	v_mov_b64_e32 v[66:67], 0
	v_mov_b64_e32 v[68:69], 0
	v_mov_b64_e32 v[70:71], 0
	v_mov_b64_e32 v[72:73], 0
	v_mov_b64_e32 v[74:75], 0
	v_mov_b64_e32 v[76:77], 0
	v_mov_b64_e32 v[78:79], 0
	v_mov_b64_e32 v[88:89], 0
	v_mov_b64_e32 v[90:91], 0
	v_mov_b64_e32 v[92:93], 0
	v_mov_b64_e32 v[94:95], 0
	v_mov_b64_e32 v[104:105], 0
	v_mov_b64_e32 v[106:107], 0
	v_mov_b64_e32 v[108:109], 0
	v_mov_b64_e32 v[110:111], 0
	v_mov_b64_e32 v[120:121], 0
	v_mov_b64_e32 v[122:123], 0
	v_mov_b64_e32 v[124:125], 0
	v_mov_b64_e32 v[126:127], 0
	v_mov_b64_e32 v[80:81], 0
	v_mov_b64_e32 v[82:83], 0
	v_mov_b64_e32 v[84:85], 0
	v_mov_b64_e32 v[86:87], 0
	v_mov_b64_e32 v[96:97], 0
	v_mov_b64_e32 v[98:99], 0
	v_mov_b64_e32 v[100:101], 0
	v_mov_b64_e32 v[102:103], 0
	v_mov_b64_e32 v[112:113], 0
	v_mov_b64_e32 v[114:115], 0
	v_mov_b64_e32 v[116:117], 0
	v_mov_b64_e32 v[118:119], 0
	v_mov_b64_e32 v[128:129], 0
	v_mov_b64_e32 v[130:131], 0
	v_mov_b64_e32 v[132:133], 0
	v_mov_b64_e32 v[134:135], 0
	s_mov_b64 s[50:51], 0x20080
	s_mov_b64 s[52:53], 0x10000
	s_mov_b64 s[54:55], 0x30000
	s_mov_b64 s[58:59], 0x10080
	s_mov_b64 s[62:63], 0x30080
	s_cmp_eq_u32 s101, 2
	s_cselect_b32 s101, 0, s101
	v_add_u32_e32 v255, 0x10000, v145
	ds_read_b128 v[140:143], v255 offset:0
	ds_read_b128 v[148:151], v255 offset:1024
	ds_read_b128 v[152:155], v255 offset:2048
	ds_read_b128 v[156:159], v255 offset:3072
.LBB0_450:
	s_add_u32 s4, s6, 0xfffe0080
	s_addc_u32 s5, s7, -1
	s_add_i32 s41, 0, 0x10000
	s_cmp_eq_u32 s21, 4
	s_cselect_b32 s23, s11, s5
	s_cselect_b32 s22, s10, s4
	s_cselect_b32 s43, s17, s20
	s_cselect_b32 s42, s16, s19
	s_add_i32 m0, s27, 0xc000
	ds_read_b128 v[160:163], v146
	ds_read_b128 v[164:167], v146 offset:1024
	ds_read_b128 v[172:175], v146 offset:2048
	ds_read_b128 v[176:179], v146 offset:3072
	ds_read_b128 v[180:183], v146 offset:4096
	ds_read_b128 v[196:199], v146 offset:5120
	ds_read_b128 v[200:203], v146 offset:6144
	ds_read_b128 v[204:207], v146 offset:7168
	global_load_lds_dwordx4 v138, s[6:7]
	s_add_i32 m0, s27, 0xe000
	s_nop 0
	s_add_u32 vcc_lo, s6, s52
	s_addc_u32 vcc_hi, s7, s53
	global_load_lds_dwordx4 v138, vcc
	s_waitcnt lgkmcnt(8)
	s_cmp_eq_u32 s101, 1
	s_cbranch_scc1 .Ldb_SSM1_sk
	s_barrier
.Ldb_SSM1_sk:
	s_mov_b32 s101, 0
	s_waitcnt lgkmcnt(0)
	v_mfma_f32_16x16x32_bf16 v[132:135], v[140:143], v[160:163], v[132:135]
	v_mfma_f32_16x16x32_bf16 v[128:131], v[152:155], v[160:163], v[128:131]
	v_mfma_f32_16x16x32_bf16 v[116:119], v[140:143], v[172:175], v[116:119]
	v_mfma_f32_16x16x32_bf16 v[112:115], v[152:155], v[172:175], v[112:115]
	v_mfma_f32_16x16x32_bf16 v[100:103], v[140:143], v[180:183], v[100:103]
	v_mfma_f32_16x16x32_bf16 v[96:99], v[152:155], v[180:183], v[96:99]
	v_mfma_f32_16x16x32_bf16 v[84:87], v[140:143], v[200:203], v[84:87]
	v_mfma_f32_16x16x32_bf16 v[80:83], v[152:155], v[200:203], v[80:83]
	v_mfma_f32_16x16x32_bf16 v[132:135], v[148:151], v[164:167], v[132:135]
	v_mfma_f32_16x16x32_bf16 v[128:131], v[156:159], v[164:167], v[128:131]
	v_mfma_f32_16x16x32_bf16 v[116:119], v[148:151], v[176:179], v[116:119]
	v_mfma_f32_16x16x32_bf16 v[112:115], v[156:159], v[176:179], v[112:115]
	v_mfma_f32_16x16x32_bf16 v[100:103], v[148:151], v[196:199], v[100:103]
	v_mfma_f32_16x16x32_bf16 v[96:99], v[156:159], v[196:199], v[96:99]
	v_mfma_f32_16x16x32_bf16 v[84:87], v[148:151], v[204:207], v[84:87]
	v_mfma_f32_16x16x32_bf16 v[80:83], v[156:159], v[204:207], v[80:83]
	s_barrier
	s_add_i32 s4, 0, 0x14000
	s_add_i32 s5, s41, s26
	s_mov_b32 m0, s5
	ds_read_b128 v[208:211], v255 offset:16384
	ds_read_b128 v[212:215], v255 offset:17408
	ds_read_b128 v[216:219], v255 offset:18432
	ds_read_b128 v[220:223], v255 offset:19456
	global_load_lds_dwordx4 v136, s[42:43]
	s_add_i32 m0, s5, 0x2000
	s_nop 0
	s_add_u32 vcc_lo, s42, s52
	s_addc_u32 vcc_hi, s43, s53
	global_load_lds_dwordx4 v136, vcc
	s_barrier
	s_waitcnt lgkmcnt(0)
	v_mfma_f32_16x16x32_bf16 v[124:127], v[208:211], v[160:163], v[124:127]
	v_mfma_f32_16x16x32_bf16 v[120:123], v[216:219], v[160:163], v[120:123]
	v_mfma_f32_16x16x32_bf16 v[108:111], v[208:211], v[172:175], v[108:111]
	v_mfma_f32_16x16x32_bf16 v[104:107], v[216:219], v[172:175], v[104:107]
	v_mfma_f32_16x16x32_bf16 v[92:95], v[208:211], v[180:183], v[92:95]
	v_mfma_f32_16x16x32_bf16 v[88:91], v[216:219], v[180:183], v[88:91]
	v_mfma_f32_16x16x32_bf16 v[76:79], v[208:211], v[200:203], v[76:79]
	v_mfma_f32_16x16x32_bf16 v[72:75], v[216:219], v[200:203], v[72:75]
	v_mfma_f32_16x16x32_bf16 v[124:127], v[212:215], v[164:167], v[124:127]
	v_mfma_f32_16x16x32_bf16 v[120:123], v[220:223], v[164:167], v[120:123]
	v_mfma_f32_16x16x32_bf16 v[108:111], v[212:215], v[176:179], v[108:111]
	v_mfma_f32_16x16x32_bf16 v[104:107], v[220:223], v[176:179], v[104:107]
	v_mfma_f32_16x16x32_bf16 v[92:95], v[212:215], v[196:199], v[92:95]
	v_mfma_f32_16x16x32_bf16 v[88:91], v[220:223], v[196:199], v[88:91]
	v_mfma_f32_16x16x32_bf16 v[76:79], v[212:215], v[204:207], v[76:79]
	v_mfma_f32_16x16x32_bf16 v[72:75], v[220:223], v[204:207], v[72:75]
	s_barrier
; #define G_STAGE(bufoff, gbase, o0, h64) do { \
;         __builtin_amdgcn_global_load_lds((const unsigned*)((const char*)(gbase) + (o0)), (LAS unsigned*)(lds + (bufoff) + ldsw), 16, 0, 0); \
;         __builtin_amdgcn_global_load_lds((const unsigned*)((const char*)(gbase) + (h64) + (o0)), (LAS unsigned*)(lds + (bufoff) + ldsw + 8192), 16, 0, 0); } while (0)
; #define G_LDA(dst, b, h) do { _Pragma("unroll") for (int m = 0; m < 4; ++m) _Pragma("unroll") for (int k = 0; k < 2; ++k) dst[m][k] = *(const LAS bf16x8*)(lds + G_SA(b, h) + aoff + m * 2048 + k * 1024); } while (0)
; #define G_LDB(dst, b, h) do { _Pragma("unroll") for (int n = 0; n < 2; ++n) _Pragma("unroll") for (int k = 0; k < 2; ++k) dst[n][k] = *(const LAS bf16x8*)(lds + G_SB(b, h) + boff + n * 2048 + k * 1024); } while (0)
; #define G_WAIT_V(n) asm volatile("s_waitcnt vmcnt(" #n ")" ::: "memory")
; #define G_WAIT_L(n) asm volatile("s_waitcnt lgkmcnt(" #n ")" ::: "memory")
; #define G_BAR __builtin_amdgcn_s_barrier()
; #define G_SCHED __builtin_amdgcn_sched_barrier(0)
;     ...
;             G_LDA(At, 0, 1); G_STAGE(G_SA(0, 0), a2, cA0, qA);
;             G_BAR; G_WAIT_L(0); G_MMA(1, 0, At, B0); G_BAR; G_SCHED;
;             G_STAGE(G_SB(0, 1), b2 + chB, cB0, qB);
;             G_WAIT_V(6); G_BAR; G_MMA(1, 1, At, B1); G_BAR;
;             G_LDB(B0, 1, 0); G_SCHED; G_LDA(At, 1, 0); G_STAGE(G_SA(0, 1), a2 + chA, cA0, qA);
;             G_WAIT_L(8); G_BAR; G_WAIT_L(0); G_MMA(0, 0, At, B0); G_BAR; G_SCHED;
;             G_LDB(B1, 1, 1); G_STAGE(G_SB(1, 0), b3, cB0, qB);
;             G_BAR; G_WAIT_L(0); G_MMA(0, 1, At, B1); G_BAR;
	s_mov_b32 m0, s27
	ds_read_b128 v[160:163], v146 offset:16384
	ds_read_b128 v[164:167], v146 offset:17408
	ds_read_b128 v[172:175], v146 offset:18432
	ds_read_b128 v[176:179], v146 offset:19456
	ds_read_b128 v[180:183], v146 offset:20480
	ds_read_b128 v[196:199], v146 offset:21504
	ds_read_b128 v[200:203], v146 offset:22528
	ds_read_b128 v[204:207], v146 offset:23552
	global_load_lds_dwordx4 v2, s[22:23]
	s_mov_b32 m0, s28
	s_nop 0
	s_add_u32 vcc_lo, s22, s52
	s_addc_u32 vcc_hi, s23, s53
	global_load_lds_dwordx4 v2, vcc
	s_barrier
	s_waitcnt lgkmcnt(0)
	v_mfma_f32_16x16x32_bf16 v[68:71], v[140:143], v[160:163], v[68:71]
	v_mfma_f32_16x16x32_bf16 v[64:67], v[152:155], v[160:163], v[64:67]
	v_mfma_f32_16x16x32_bf16 v[52:55], v[140:143], v[172:175], v[52:55]
	v_mfma_f32_16x16x32_bf16 v[48:51], v[152:155], v[172:175], v[48:51]
	v_mfma_f32_16x16x32_bf16 v[36:39], v[140:143], v[180:183], v[36:39]
	v_mfma_f32_16x16x32_bf16 v[32:35], v[152:155], v[180:183], v[32:35]
	v_mfma_f32_16x16x32_bf16 v[20:23], v[140:143], v[200:203], v[20:23]
	v_mfma_f32_16x16x32_bf16 v[16:19], v[152:155], v[200:203], v[16:19]
	v_mfma_f32_16x16x32_bf16 v[68:71], v[148:151], v[164:167], v[68:71]
	v_mfma_f32_16x16x32_bf16 v[64:67], v[156:159], v[164:167], v[64:67]
	v_mfma_f32_16x16x32_bf16 v[52:55], v[148:151], v[176:179], v[52:55]
	v_mfma_f32_16x16x32_bf16 v[48:51], v[156:159], v[176:179], v[48:51]
	v_mfma_f32_16x16x32_bf16 v[36:39], v[148:151], v[196:199], v[36:39]
	v_mfma_f32_16x16x32_bf16 v[32:35], v[156:159], v[196:199], v[32:35]
	v_mfma_f32_16x16x32_bf16 v[20:23], v[148:151], v[204:207], v[20:23]
	v_mfma_f32_16x16x32_bf16 v[16:19], v[156:159], v[204:207], v[16:19]
	s_barrier
	s_add_i32 s4, s4, s26
	s_mov_b32 m0, s4
	s_nop 0
	s_add_u32 vcc_lo, s42, s0
	s_addc_u32 vcc_hi, s43, s1
	global_load_lds_dwordx4 v136, vcc
	s_add_i32 m0, s4, 0x2000
	s_nop 0
	s_add_u32 vcc_lo, s42, s54
	s_addc_u32 vcc_hi, s43, s55
	global_load_lds_dwordx4 v136, vcc
	s_waitcnt vmcnt(6)
	s_barrier
	v_mfma_f32_16x16x32_bf16 v[60:63], v[208:211], v[160:163], v[60:63]
	v_mfma_f32_16x16x32_bf16 v[56:59], v[216:219], v[160:163], v[56:59]
	v_mfma_f32_16x16x32_bf16 v[44:47], v[208:211], v[172:175], v[44:47]
	v_mfma_f32_16x16x32_bf16 v[40:43], v[216:219], v[172:175], v[40:43]
	ds_read_b128 v[140:143], v255 offset:32768
	ds_read_b128 v[148:151], v255 offset:33792
	ds_read_b128 v[152:155], v255 offset:34816
	ds_read_b128 v[156:159], v255 offset:35840
	v_mfma_f32_16x16x32_bf16 v[28:31], v[208:211], v[180:183], v[28:31]
	v_mfma_f32_16x16x32_bf16 v[24:27], v[216:219], v[180:183], v[24:27]
	v_mfma_f32_16x16x32_bf16 v[12:15], v[208:211], v[200:203], v[12:15]
	v_mfma_f32_16x16x32_bf16 v[8:11], v[216:219], v[200:203], v[8:11]
	v_mfma_f32_16x16x32_bf16 v[60:63], v[212:215], v[164:167], v[60:63]
	v_mfma_f32_16x16x32_bf16 v[56:59], v[220:223], v[164:167], v[56:59]
	v_mfma_f32_16x16x32_bf16 v[44:47], v[212:215], v[176:179], v[44:47]
	v_mfma_f32_16x16x32_bf16 v[40:43], v[220:223], v[176:179], v[40:43]
	v_mfma_f32_16x16x32_bf16 v[28:31], v[212:215], v[196:199], v[28:31]
	v_mfma_f32_16x16x32_bf16 v[24:27], v[220:223], v[196:199], v[24:27]
	v_mfma_f32_16x16x32_bf16 v[12:15], v[212:215], v[204:207], v[12:15]
	v_mfma_f32_16x16x32_bf16 v[8:11], v[220:223], v[204:207], v[8:11]
	s_barrier
	s_add_i32 s4, 0, 0x18000
	s_mov_b32 m0, s29
	ds_read_b128 v[160:163], v146 offset:32768
	ds_read_b128 v[164:167], v146 offset:33792
	ds_read_b128 v[172:175], v146 offset:34816
	ds_read_b128 v[176:179], v146 offset:35840
	ds_read_b128 v[180:183], v146 offset:36864
	ds_read_b128 v[196:199], v146 offset:37888
	ds_read_b128 v[200:203], v146 offset:38912
	ds_read_b128 v[204:207], v146 offset:39936
	s_add_u32 vcc_lo, s22, s0
	s_addc_u32 vcc_hi, s23, s1
	global_load_lds_dwordx4 v2, vcc
	s_mov_b32 m0, s30
	s_nop 0
	s_add_u32 vcc_lo, s22, s54
	s_addc_u32 vcc_hi, s23, s55
	global_load_lds_dwordx4 v2, vcc
	s_waitcnt lgkmcnt(8)
	s_barrier
	s_waitcnt lgkmcnt(0)
	v_mfma_f32_16x16x32_bf16 v[132:135], v[140:143], v[160:163], v[132:135]
	v_mfma_f32_16x16x32_bf16 v[128:131], v[152:155], v[160:163], v[128:131]
	v_mfma_f32_16x16x32_bf16 v[116:119], v[140:143], v[172:175], v[116:119]
	v_mfma_f32_16x16x32_bf16 v[112:115], v[152:155], v[172:175], v[112:115]
	v_mfma_f32_16x16x32_bf16 v[100:103], v[140:143], v[180:183], v[100:103]
	v_mfma_f32_16x16x32_bf16 v[96:99], v[152:155], v[180:183], v[96:99]
	v_mfma_f32_16x16x32_bf16 v[84:87], v[140:143], v[200:203], v[84:87]
	v_mfma_f32_16x16x32_bf16 v[80:83], v[152:155], v[200:203], v[80:83]
	v_mfma_f32_16x16x32_bf16 v[132:135], v[148:151], v[164:167], v[132:135]
	v_mfma_f32_16x16x32_bf16 v[128:131], v[156:159], v[164:167], v[128:131]
	v_mfma_f32_16x16x32_bf16 v[116:119], v[148:151], v[176:179], v[116:119]
	v_mfma_f32_16x16x32_bf16 v[112:115], v[156:159], v[176:179], v[112:115]
	v_mfma_f32_16x16x32_bf16 v[100:103], v[148:151], v[196:199], v[100:103]
	v_mfma_f32_16x16x32_bf16 v[96:99], v[156:159], v[196:199], v[96:99]
	v_mfma_f32_16x16x32_bf16 v[84:87], v[148:151], v[204:207], v[84:87]
	v_mfma_f32_16x16x32_bf16 v[80:83], v[156:159], v[204:207], v[80:83]
	s_barrier
; #define G_STAGE(bufoff, gbase, o0, h64) do { \
;         __builtin_amdgcn_global_load_lds((const unsigned*)((const char*)(gbase) + (o0)), (LAS unsigned*)(lds + (bufoff) + ldsw), 16, 0, 0); \
;         __builtin_amdgcn_global_load_lds((const unsigned*)((const char*)(gbase) + (h64) + (o0)), (LAS unsigned*)(lds + (bufoff) + ldsw + 8192), 16, 0, 0); } while (0)
; #define G_LDA(dst, b, h) do { _Pragma("unroll") for (int m = 0; m < 4; ++m) _Pragma("unroll") for (int k = 0; k < 2; ++k) dst[m][k] = *(const LAS bf16x8*)(lds + G_SA(b, h) + aoff + m * 2048 + k * 1024); } while (0)
; #define G_LDB(dst, b, h) do { _Pragma("unroll") for (int n = 0; n < 2; ++n) _Pragma("unroll") for (int k = 0; k < 2; ++k) dst[n][k] = *(const LAS bf16x8*)(lds + G_SB(b, h) + boff + n * 2048 + k * 1024); } while (0)
; #define G_WAIT_V(n) asm volatile("s_waitcnt vmcnt(" #n ")" ::: "memory")
; #define G_WAIT_L(n) asm volatile("s_waitcnt lgkmcnt(" #n ")" ::: "memory")
; #define G_BAR __builtin_amdgcn_s_barrier()
; #define G_SCHED __builtin_amdgcn_sched_barrier(0)
;     ...
;             G_LDB(B1, 1, 1); G_STAGE(G_SB(1, 0), b3, cB0, qB);
;             G_BAR; G_WAIT_L(0); G_MMA(0, 1, At, B1); G_BAR;
;             G_LDA(At, 1, 1); G_STAGE(G_SA(1, 0), a3, cA0, qA);
;             G_BAR; G_WAIT_L(0); G_MMA(1, 0, At, B0); G_BAR; G_SCHED;
;             G_STAGE(G_SB(1, 1), b3 + chB, cB0, qB);
;             G_WAIT_V(6); G_BAR; G_MMA(1, 1, At, B1); G_BAR;
	s_add_i32 s5, 0, 0x1c000
	s_add_i32 s4, s4, s26
	s_mov_b32 m0, s4
	ds_read_b128 v[208:211], v255 offset:49152
	ds_read_b128 v[212:215], v255 offset:50176
	ds_read_b128 v[216:219], v255 offset:51200
	ds_read_b128 v[220:223], v255 offset:52224
	s_add_u32 vcc_lo, s42, s46
	s_addc_u32 vcc_hi, s43, s47
	global_load_lds_dwordx4 v136, vcc
	s_add_i32 m0, s4, 0x2000
	s_nop 0
	s_add_u32 vcc_lo, s42, s58
	s_addc_u32 vcc_hi, s43, s59
	global_load_lds_dwordx4 v136, vcc
	s_barrier
	s_waitcnt lgkmcnt(0)
	v_mfma_f32_16x16x32_bf16 v[124:127], v[208:211], v[160:163], v[124:127]
	v_mfma_f32_16x16x32_bf16 v[120:123], v[216:219], v[160:163], v[120:123]
	v_mfma_f32_16x16x32_bf16 v[108:111], v[208:211], v[172:175], v[108:111]
	v_mfma_f32_16x16x32_bf16 v[104:107], v[216:219], v[172:175], v[104:107]
	v_mfma_f32_16x16x32_bf16 v[92:95], v[208:211], v[180:183], v[92:95]
	v_mfma_f32_16x16x32_bf16 v[88:91], v[216:219], v[180:183], v[88:91]
	v_mfma_f32_16x16x32_bf16 v[76:79], v[208:211], v[200:203], v[76:79]
	v_mfma_f32_16x16x32_bf16 v[72:75], v[216:219], v[200:203], v[72:75]
	v_mfma_f32_16x16x32_bf16 v[124:127], v[212:215], v[164:167], v[124:127]
	v_mfma_f32_16x16x32_bf16 v[120:123], v[220:223], v[164:167], v[120:123]
	v_mfma_f32_16x16x32_bf16 v[108:111], v[212:215], v[176:179], v[108:111]
	v_mfma_f32_16x16x32_bf16 v[104:107], v[220:223], v[176:179], v[104:107]
	v_mfma_f32_16x16x32_bf16 v[92:95], v[212:215], v[196:199], v[92:95]
	v_mfma_f32_16x16x32_bf16 v[88:91], v[220:223], v[196:199], v[88:91]
	v_mfma_f32_16x16x32_bf16 v[76:79], v[212:215], v[204:207], v[76:79]
	v_mfma_f32_16x16x32_bf16 v[72:75], v[220:223], v[204:207], v[72:75]
	s_barrier
	s_mov_b32 m0, s31
	ds_read_b128 v[160:163], v146 offset:49152
	ds_read_b128 v[164:167], v146 offset:50176
	ds_read_b128 v[172:175], v146 offset:51200
	ds_read_b128 v[176:179], v146 offset:52224
	ds_read_b128 v[180:183], v146 offset:53248
	ds_read_b128 v[196:199], v146 offset:54272
	ds_read_b128 v[200:203], v146 offset:55296
	ds_read_b128 v[204:207], v146 offset:56320
	s_add_u32 vcc_lo, s22, s46
	s_addc_u32 vcc_hi, s23, s47
	global_load_lds_dwordx4 v2, vcc
	s_mov_b32 m0, s33
	s_nop 0
	s_add_u32 vcc_lo, s22, s58
	s_addc_u32 vcc_hi, s23, s59
	global_load_lds_dwordx4 v2, vcc
	s_barrier
	s_waitcnt lgkmcnt(0)
	v_mfma_f32_16x16x32_bf16 v[68:71], v[140:143], v[160:163], v[68:71]
	v_mfma_f32_16x16x32_bf16 v[64:67], v[152:155], v[160:163], v[64:67]
	v_mfma_f32_16x16x32_bf16 v[52:55], v[140:143], v[172:175], v[52:55]
	v_mfma_f32_16x16x32_bf16 v[48:51], v[152:155], v[172:175], v[48:51]
	v_mfma_f32_16x16x32_bf16 v[36:39], v[140:143], v[180:183], v[36:39]
	v_mfma_f32_16x16x32_bf16 v[32:35], v[152:155], v[180:183], v[32:35]
	v_mfma_f32_16x16x32_bf16 v[20:23], v[140:143], v[200:203], v[20:23]
	v_mfma_f32_16x16x32_bf16 v[16:19], v[152:155], v[200:203], v[16:19]
	v_mfma_f32_16x16x32_bf16 v[68:71], v[148:151], v[164:167], v[68:71]
	v_mfma_f32_16x16x32_bf16 v[64:67], v[156:159], v[164:167], v[64:67]
	v_mfma_f32_16x16x32_bf16 v[52:55], v[148:151], v[176:179], v[52:55]
	v_mfma_f32_16x16x32_bf16 v[48:51], v[156:159], v[176:179], v[48:51]
	v_mfma_f32_16x16x32_bf16 v[36:39], v[148:151], v[196:199], v[36:39]
	v_mfma_f32_16x16x32_bf16 v[32:35], v[156:159], v[196:199], v[32:35]
	v_mfma_f32_16x16x32_bf16 v[20:23], v[148:151], v[204:207], v[20:23]
	v_mfma_f32_16x16x32_bf16 v[16:19], v[156:159], v[204:207], v[16:19]
	s_barrier
	s_add_i32 s4, s5, s26
	s_mov_b32 m0, s4
	s_nop 0
	s_add_u32 vcc_lo, s42, s50
	s_addc_u32 vcc_hi, s43, s51
	global_load_lds_dwordx4 v136, vcc
	s_add_i32 m0, s4, 0x2000
	s_nop 0
	s_add_u32 vcc_lo, s42, s62
	s_addc_u32 vcc_hi, s43, s63
	global_load_lds_dwordx4 v136, vcc
	s_add_i32 s21, s21, 2
	s_add_u32 s6, s6, 0x100
	s_addc_u32 s7, s7, 0
	s_add_u32 s19, s19, 0x100
	s_addc_u32 s20, s20, 0
	s_cmp_gt_u32 s21, 5
	s_waitcnt vmcnt(6)
	s_barrier
	v_mfma_f32_16x16x32_bf16 v[60:63], v[208:211], v[160:163], v[60:63]
	v_mfma_f32_16x16x32_bf16 v[56:59], v[216:219], v[160:163], v[56:59]
	v_mfma_f32_16x16x32_bf16 v[44:47], v[208:211], v[172:175], v[44:47]
	v_mfma_f32_16x16x32_bf16 v[40:43], v[216:219], v[172:175], v[40:43]
	ds_read_b128 v[140:143], v255 offset:0
	ds_read_b128 v[148:151], v255 offset:1024
	ds_read_b128 v[152:155], v255 offset:2048
	ds_read_b128 v[156:159], v255 offset:3072
	v_mfma_f32_16x16x32_bf16 v[28:31], v[208:211], v[180:183], v[28:31]
	v_mfma_f32_16x16x32_bf16 v[24:27], v[216:219], v[180:183], v[24:27]
	v_mfma_f32_16x16x32_bf16 v[12:15], v[208:211], v[200:203], v[12:15]
	v_mfma_f32_16x16x32_bf16 v[8:11], v[216:219], v[200:203], v[8:11]
	v_mfma_f32_16x16x32_bf16 v[60:63], v[212:215], v[164:167], v[60:63]
	v_mfma_f32_16x16x32_bf16 v[56:59], v[220:223], v[164:167], v[56:59]
	v_mfma_f32_16x16x32_bf16 v[44:47], v[212:215], v[176:179], v[44:47]
	v_mfma_f32_16x16x32_bf16 v[40:43], v[220:223], v[176:179], v[40:43]
	v_mfma_f32_16x16x32_bf16 v[28:31], v[212:215], v[196:199], v[28:31]
	v_mfma_f32_16x16x32_bf16 v[24:27], v[220:223], v[196:199], v[24:27]
	v_mfma_f32_16x16x32_bf16 v[12:15], v[212:215], v[204:207], v[12:15]
	v_mfma_f32_16x16x32_bf16 v[8:11], v[220:223], v[204:207], v[8:11]
	s_cbranch_scc0 .Ldb_SSM1_cont
	v_readfirstlane_b32 s101, v186
	s_cmpk_gt_u32 s101, 0xff
	s_cbranch_scc1 .Ldb_SSM1_young
	s_barrier
	s_mov_b32 s101, 1
	s_branch .Ldb_SSM1_exit

; __device__ __forceinline__ u32x4 pack8(const f32x4 a, const f32x4 b) { u32x4 w; w.x = cvt_pk_bf16(a[0], a[1]); w.y = cvt_pk_bf16(a[2], a[3]); w.z = cvt_pk_bf16(b[0], b[1]); w.w = cvt_pk_bf16(b[2], b[3]); return w; }
;     template <int KIND> __device__ __forceinline__ void run(f32x4 (&acc)[2][2][4][2], const Unit& u, int tid_in) const {
;     ...
;         if constexpr (KIND == K_SSM1) { const int g = u.aux;
; #pragma unroll
;             for (int ai = 0; ai < 2; ++ai)
; #pragma unroll
;                 for (int m = 0; m < 4; ++m) { int R = rbase + ai * 128 + m * 16; asm volatile("" : "+v"(R));
;                     if (u.pn < 2) {
; #pragma unroll
;                         for (int bj = 0; bj < 2; ++bj) { const int t = 16 * u.pn + 8 * bj + 2 * wc + (fq >> 1), p0 = 8 * (fq & 1);
;                             *(u32x4*)(yi + ((size_t)g * T_TOK + (size_t)(R * LCH + t)) * 16 + p0) = pack8(acc[ai][bj][m][0], acc[ai][bj][m][1]); }
;                     } else { float* sp = (float*)(ws + OFF_S) + ((size_t)(R * 32 + g)) * 128 + cl; *(f32x4*)sp = acc[ai][0][m][0]; *(f32x4*)(sp + 4) = acc[ai][0][m][1]; } }
.Ldb_SSM1_exit:
	s_waitcnt lgkmcnt(0)
	v_mov_b32_e32 v0, v144
	s_mov_b64 s[22:23], -1
	v_readfirstlane_b32 s4, v0
	s_bfe_u32 s19, s4, 0x20006
	s_ashr_i32 s4, s4, 2
	s_andn2_b32 s4, s4, 63
	v_and_or_b32 v141, v0, 15, s4
	v_lshl_add_u32 v147, s13, 8, v141
	s_ashr_i32 s13, s12, 31
	s_lshl_b64 s[6:7], s[12:13], 20
	s_add_u32 s6, s36, s6
	v_bfe_u32 v140, v0, 4, 2
	s_addc_u32 s7, s37, s7
	v_lshlrev_b32_e32 v140, 3, v140
	s_cmp_gt_i32 s25, 1
	v_lshl_or_b32 v140, s19, 5, v140
	v_mov_b32_e32 v141, v147
	s_cselect_b64 s[20:21], -1, 0
	s_and_b64 vcc, exec, s[20:21]
	v_lshlrev_b32_e32 v149, 5, v141
	v_lshlrev_b32_e32 v142, 2, v140
	s_cbranch_vccz .LBB0_453
	v_add_u32_e32 v140, s12, v149
	v_ashrrev_i32_e32 v141, 31, v140
	v_lshlrev_b64 v[140:141], 9, v[140:141]
	v_lshl_add_u64 v[140:141], s[2:3], 0, v[140:141]
	v_mov_b32_e32 v143, v1
	v_lshl_add_u64 v[140:141], v[140:141], 0, v[142:143]
	global_store_dwordx4 v[140:141], v[132:135], off
	global_store_dwordx4 v[140:141], v[128:131], off offset:16
	s_mov_b64 s[22:23], 0

; #define G_STAGE(bufoff, gbase, o0, h64) do { \
;         __builtin_amdgcn_global_load_lds((const unsigned*)((const char*)(gbase) + (o0)), (LAS unsigned*)(lds + (bufoff) + ldsw), 16, 0, 0); \
;         __builtin_amdgcn_global_load_lds((const unsigned*)((const char*)(gbase) + (h64) + (o0)), (LAS unsigned*)(lds + (bufoff) + ldsw + 8192), 16, 0, 0); } while (0)
; #define G_LDA(dst, b, h) do { _Pragma("unroll") for (int m = 0; m < 4; ++m) _Pragma("unroll") for (int k = 0; k < 2; ++k) dst[m][k] = *(const LAS bf16x8*)(lds + G_SA(b, h) + aoff + m * 2048 + k * 1024); } while (0)
; #define G_LDB(dst, b, h) do { _Pragma("unroll") for (int n = 0; n < 2; ++n) _Pragma("unroll") for (int k = 0; k < 2; ++k) dst[n][k] = *(const LAS bf16x8*)(lds + G_SB(b, h) + boff + n * 2048 + k * 1024); } while (0)
; #define G_WAIT_L(n) asm volatile("s_waitcnt lgkmcnt(" #n ")" ::: "memory")
; #define G_BAR __builtin_amdgcn_s_barrier()
; #define G_SCHED __builtin_amdgcn_sched_barrier(0)
;     ...
;         for (int t = 0; t < nt; t += 2) {
;             const bool last = (t == nt - 2);
;             const char* a1 = cA + (size_t)(t + 1) * ckA;
;             const char* a2 = last ? nA : cA + (size_t)(t + 2) * ckA; const char* b2 = last ? nB : cB + (size_t)(t + 2) * kB;
;             const char* a3 = a2 + ckA; const char* b3 = b2 + kB;
;             G_LDB(B0, 0, 0); G_SCHED; G_LDA(At, 0, 0); G_STAGE(G_SA(1, 1), a1 + chA, cA0, qA);
;             G_WAIT_L(8); G_BAR; G_WAIT_L(0); G_MMA(0, 0, At, B0); G_BAR; G_SCHED;
;             G_LDB(B1, 0, 1); G_STAGE(G_SB(0, 0), b2, cB0, qB);
;             G_BAR; G_WAIT_L(0); G_MMA(0, 1, At, B1); G_BAR;
;     ...
;         if (!(cs.kind == K_MG_B && cur.aux < 2))
; #pragma unroll
;         for (int a = 0; a < 2; ++a)
; #pragma unroll
;             for (int b = 0; b < 2; ++b)
; #pragma unroll
;                 for (int m = 0; m < 4; ++m)
; #pragma unroll
;                     for (int n = 0; n < 2; ++n) acc[a][b][m][n] = (f32x4){0.f, 0.f, 0.f, 0.f};
;         cur = nxt; cA = nA; cB = nB; ++ui;
.LBB0_803:
	s_add_u32 s13, s18, 0x100
	s_addc_u32 s18, s19, 0
	s_add_u32 s2, s2, 0x800000
	v_mov_b64_e32 v[8:9], 0
	s_addc_u32 s3, s3, 0
	s_mov_b32 s19, -2
	v_mov_b64_e32 v[10:11], 0
	v_mov_b64_e32 v[12:13], 0
	v_mov_b64_e32 v[14:15], 0
	v_mov_b64_e32 v[24:25], 0
	v_mov_b64_e32 v[26:27], 0
	v_mov_b64_e32 v[28:29], 0
	v_mov_b64_e32 v[30:31], 0
	v_mov_b64_e32 v[40:41], 0
	v_mov_b64_e32 v[42:43], 0
	v_mov_b64_e32 v[44:45], 0
	v_mov_b64_e32 v[46:47], 0
	v_mov_b64_e32 v[56:57], 0
	v_mov_b64_e32 v[58:59], 0
	v_mov_b64_e32 v[60:61], 0
	v_mov_b64_e32 v[62:63], 0
	v_mov_b64_e32 v[16:17], 0
	v_mov_b64_e32 v[18:19], 0
	v_mov_b64_e32 v[20:21], 0
	v_mov_b64_e32 v[22:23], 0
	v_mov_b64_e32 v[32:33], 0
	v_mov_b64_e32 v[34:35], 0
	v_mov_b64_e32 v[36:37], 0
	v_mov_b64_e32 v[38:39], 0
	v_mov_b64_e32 v[48:49], 0
	v_mov_b64_e32 v[50:51], 0
	v_mov_b64_e32 v[52:53], 0
	v_mov_b64_e32 v[54:55], 0
	v_mov_b64_e32 v[64:65], 0
	v_mov_b64_e32 v[66:67], 0
	v_mov_b64_e32 v[68:69], 0
	v_mov_b64_e32 v[70:71], 0
	v_mov_b64_e32 v[72:73], 0
	v_mov_b64_e32 v[74:75], 0
	v_mov_b64_e32 v[76:77], 0
	v_mov_b64_e32 v[78:79], 0
	v_mov_b64_e32 v[88:89], 0
	v_mov_b64_e32 v[90:91], 0
	v_mov_b64_e32 v[92:93], 0
	v_mov_b64_e32 v[94:95], 0
	v_mov_b64_e32 v[104:105], 0
	v_mov_b64_e32 v[106:107], 0
	v_mov_b64_e32 v[108:109], 0
	v_mov_b64_e32 v[110:111], 0
	v_mov_b64_e32 v[128:129], 0
	v_mov_b64_e32 v[130:131], 0
	v_mov_b64_e32 v[132:133], 0
	v_mov_b64_e32 v[134:135], 0
	v_mov_b64_e32 v[80:81], 0
	v_mov_b64_e32 v[82:83], 0
	v_mov_b64_e32 v[84:85], 0
	v_mov_b64_e32 v[86:87], 0
	v_mov_b64_e32 v[96:97], 0
	v_mov_b64_e32 v[98:99], 0
	v_mov_b64_e32 v[100:101], 0
	v_mov_b64_e32 v[102:103], 0
	v_mov_b64_e32 v[116:117], 0
	v_mov_b64_e32 v[118:119], 0
	v_mov_b64_e32 v[120:121], 0
	v_mov_b64_e32 v[122:123], 0
	v_mov_b64_e32 v[140:141], 0
	v_mov_b64_e32 v[142:143], 0
	v_mov_b64_e32 v[144:145], 0
	v_mov_b64_e32 v[146:147], 0
	s_mov_b64 s[42:43], 0x20080
	s_mov_b64 s[50:51], 0x10000
	s_mov_b64 s[52:53], 0x30000
	s_mov_b64 s[54:55], 0x10080
	s_mov_b64 s[58:59], 0x30080
	s_mov_b64 s[62:63], 0x400000
	s_cmp_eq_u32 s101, 2
	s_cselect_b32 s101, 0, s101
	v_add_u32_e32 v255, 0x10000, v196
	ds_read_b128 v[112:115], v255 offset:0
	ds_read_b128 v[124:127], v255 offset:1024
	ds_read_b128 v[136:139], v255 offset:2048
	ds_read_b128 v[148:151], v255 offset:3072
.LBB0_804:
	s_add_i32 s40, 0, 0x10000
	s_cmp_eq_u32 s19, 4
	s_cselect_b32 s5, s15, s3
	s_cselect_b32 s4, s14, s2
	s_cselect_b32 s37, s17, s18
	s_cselect_b32 s36, s16, s13
	s_mov_b32 s38, 0xffc01000
	s_mov_b32 s39, -1
	s_add_u32 vcc_lo, s2, s38
	s_addc_u32 vcc_hi, s3, s39
	s_mov_b32 s38, 0xffc01800
	s_add_i32 m0, s24, 0xc000
	s_mov_b32 s39, -1
	ds_read_b128 v[152:155], v197
	ds_read_b128 v[156:159], v197 offset:1024
	ds_read_b128 v[160:163], v197 offset:2048
	ds_read_b128 v[172:175], v197 offset:3072
	ds_read_b128 v[176:179], v197 offset:4096
	ds_read_b128 v[180:183], v197 offset:5120
	ds_read_b128 v[198:201], v197 offset:6144
	ds_read_b128 v[202:205], v197 offset:7168
	global_load_lds_dwordx4 v166, vcc
	s_add_i32 m0, s24, 0xe000
	s_nop 0
	s_add_u32 vcc_lo, s2, s38
	s_addc_u32 vcc_hi, s3, s39
	global_load_lds_dwordx4 v166, vcc
	s_waitcnt lgkmcnt(8)
	s_cmp_eq_u32 s101, 1
	s_cbranch_scc1 .Ldb_GLU_sk
	s_barrier
.Ldb_GLU_sk:
	s_mov_b32 s101, 0
	s_waitcnt lgkmcnt(0)
	v_mfma_f32_16x16x32_bf16 v[144:147], v[112:115], v[152:155], v[144:147]
	v_mfma_f32_16x16x32_bf16 v[140:143], v[136:139], v[152:155], v[140:143]
	v_mfma_f32_16x16x32_bf16 v[120:123], v[112:115], v[160:163], v[120:123]
	v_mfma_f32_16x16x32_bf16 v[116:119], v[136:139], v[160:163], v[116:119]
	v_mfma_f32_16x16x32_bf16 v[100:103], v[112:115], v[176:179], v[100:103]
	v_mfma_f32_16x16x32_bf16 v[96:99], v[136:139], v[176:179], v[96:99]
	v_mfma_f32_16x16x32_bf16 v[84:87], v[112:115], v[198:201], v[84:87]
	v_mfma_f32_16x16x32_bf16 v[80:83], v[136:139], v[198:201], v[80:83]
	v_mfma_f32_16x16x32_bf16 v[144:147], v[124:127], v[156:159], v[144:147]
	v_mfma_f32_16x16x32_bf16 v[140:143], v[148:151], v[156:159], v[140:143]
	v_mfma_f32_16x16x32_bf16 v[120:123], v[124:127], v[172:175], v[120:123]
	v_mfma_f32_16x16x32_bf16 v[116:119], v[148:151], v[172:175], v[116:119]
	v_mfma_f32_16x16x32_bf16 v[100:103], v[124:127], v[180:183], v[100:103]
	v_mfma_f32_16x16x32_bf16 v[96:99], v[148:151], v[180:183], v[96:99]
	v_mfma_f32_16x16x32_bf16 v[84:87], v[124:127], v[202:205], v[84:87]
	v_mfma_f32_16x16x32_bf16 v[80:83], v[148:151], v[202:205], v[80:83]
	s_barrier
	s_add_i32 s38, 0, 0x14000
	s_add_i32 s100, s40, s21
	s_mov_b32 m0, s100
	ds_read_b128 v[206:209], v255 offset:16384
	ds_read_b128 v[210:213], v255 offset:17408
	ds_read_b128 v[214:217], v255 offset:18432
	ds_read_b128 v[218:221], v255 offset:19456
	global_load_lds_dwordx4 v2, s[36:37]
	s_add_i32 m0, s100, 0x2000
	s_nop 0
	s_add_u32 vcc_lo, s36, s50
	s_addc_u32 vcc_hi, s37, s51
	global_load_lds_dwordx4 v2, vcc
	s_barrier
	s_waitcnt lgkmcnt(0)
	v_mfma_f32_16x16x32_bf16 v[132:135], v[206:209], v[152:155], v[132:135]
	v_mfma_f32_16x16x32_bf16 v[128:131], v[214:217], v[152:155], v[128:131]
	v_mfma_f32_16x16x32_bf16 v[108:111], v[206:209], v[160:163], v[108:111]
	v_mfma_f32_16x16x32_bf16 v[104:107], v[214:217], v[160:163], v[104:107]
	v_mfma_f32_16x16x32_bf16 v[92:95], v[206:209], v[176:179], v[92:95]
	v_mfma_f32_16x16x32_bf16 v[88:91], v[214:217], v[176:179], v[88:91]
	v_mfma_f32_16x16x32_bf16 v[76:79], v[206:209], v[198:201], v[76:79]
	v_mfma_f32_16x16x32_bf16 v[72:75], v[214:217], v[198:201], v[72:75]
	v_mfma_f32_16x16x32_bf16 v[132:135], v[210:213], v[156:159], v[132:135]
	v_mfma_f32_16x16x32_bf16 v[128:131], v[218:221], v[156:159], v[128:131]
	v_mfma_f32_16x16x32_bf16 v[108:111], v[210:213], v[172:175], v[108:111]
	v_mfma_f32_16x16x32_bf16 v[104:107], v[218:221], v[172:175], v[104:107]
	v_mfma_f32_16x16x32_bf16 v[92:95], v[210:213], v[180:183], v[92:95]
	v_mfma_f32_16x16x32_bf16 v[88:91], v[218:221], v[180:183], v[88:91]
	v_mfma_f32_16x16x32_bf16 v[76:79], v[210:213], v[202:205], v[76:79]
	v_mfma_f32_16x16x32_bf16 v[72:75], v[218:221], v[202:205], v[72:75]
	s_barrier
; #define G_STAGE(bufoff, gbase, o0, h64) do { \
;         __builtin_amdgcn_global_load_lds((const unsigned*)((const char*)(gbase) + (o0)), (LAS unsigned*)(lds + (bufoff) + ldsw), 16, 0, 0); \
;         __builtin_amdgcn_global_load_lds((const unsigned*)((const char*)(gbase) + (h64) + (o0)), (LAS unsigned*)(lds + (bufoff) + ldsw + 8192), 16, 0, 0); } while (0)
; #define G_LDA(dst, b, h) do { _Pragma("unroll") for (int m = 0; m < 4; ++m) _Pragma("unroll") for (int k = 0; k < 2; ++k) dst[m][k] = *(const LAS bf16x8*)(lds + G_SA(b, h) + aoff + m * 2048 + k * 1024); } while (0)
; #define G_LDB(dst, b, h) do { _Pragma("unroll") for (int n = 0; n < 2; ++n) _Pragma("unroll") for (int k = 0; k < 2; ++k) dst[n][k] = *(const LAS bf16x8*)(lds + G_SB(b, h) + boff + n * 2048 + k * 1024); } while (0)
; #define G_WAIT_V(n) asm volatile("s_waitcnt vmcnt(" #n ")" ::: "memory")
; #define G_WAIT_L(n) asm volatile("s_waitcnt lgkmcnt(" #n ")" ::: "memory")
; #define G_BAR __builtin_amdgcn_s_barrier()
; #define G_SCHED __builtin_amdgcn_sched_barrier(0)
;     ...
;             G_LDA(At, 0, 1); G_STAGE(G_SA(0, 0), a2, cA0, qA);
;             G_BAR; G_WAIT_L(0); G_MMA(1, 0, At, B0); G_BAR; G_SCHED;
;             G_STAGE(G_SB(0, 1), b2 + chB, cB0, qB);
;             G_WAIT_V(6); G_BAR; G_MMA(1, 1, At, B1); G_BAR;
;             G_LDB(B0, 1, 0); G_SCHED; G_LDA(At, 1, 0); G_STAGE(G_SA(0, 1), a2 + chA, cA0, qA);
;             G_WAIT_L(8); G_BAR; G_WAIT_L(0); G_MMA(0, 0, At, B0); G_BAR; G_SCHED;
;             G_LDB(B1, 1, 1); G_STAGE(G_SB(1, 0), b3, cB0, qB);
;             G_BAR; G_WAIT_L(0); G_MMA(0, 1, At, B1); G_BAR;
	s_mov_b32 m0, s24
	v_lshl_add_u64 v[222:223], s[4:5], 0, v[164:165]
	ds_read_b128 v[152:155], v197 offset:16384
	ds_read_b128 v[156:159], v197 offset:17408
	ds_read_b128 v[160:163], v197 offset:18432
	ds_read_b128 v[172:175], v197 offset:19456
	ds_read_b128 v[176:179], v197 offset:20480
	ds_read_b128 v[180:183], v197 offset:21504
	ds_read_b128 v[198:201], v197 offset:22528
	ds_read_b128 v[202:205], v197 offset:23552
	global_load_lds_dwordx4 v164, s[4:5]
	s_mov_b32 m0, s25
	s_nop 0
	s_add_u32 vcc_lo, s4, s70
	s_addc_u32 vcc_hi, s5, s71
	global_load_lds_dwordx4 v164, vcc
	s_barrier
	s_waitcnt lgkmcnt(0)
	v_mfma_f32_16x16x32_bf16 v[68:71], v[112:115], v[152:155], v[68:71]
	v_mfma_f32_16x16x32_bf16 v[64:67], v[136:139], v[152:155], v[64:67]
	v_mfma_f32_16x16x32_bf16 v[52:55], v[112:115], v[160:163], v[52:55]
	v_mfma_f32_16x16x32_bf16 v[48:51], v[136:139], v[160:163], v[48:51]
	v_mfma_f32_16x16x32_bf16 v[36:39], v[112:115], v[176:179], v[36:39]
	v_mfma_f32_16x16x32_bf16 v[32:35], v[136:139], v[176:179], v[32:35]
	v_mfma_f32_16x16x32_bf16 v[20:23], v[112:115], v[198:201], v[20:23]
	v_mfma_f32_16x16x32_bf16 v[16:19], v[136:139], v[198:201], v[16:19]
	v_mfma_f32_16x16x32_bf16 v[68:71], v[124:127], v[156:159], v[68:71]
	v_mfma_f32_16x16x32_bf16 v[64:67], v[148:151], v[156:159], v[64:67]
	v_mfma_f32_16x16x32_bf16 v[52:55], v[124:127], v[172:175], v[52:55]
	v_mfma_f32_16x16x32_bf16 v[48:51], v[148:151], v[172:175], v[48:51]
	v_mfma_f32_16x16x32_bf16 v[36:39], v[124:127], v[180:183], v[36:39]
	v_mfma_f32_16x16x32_bf16 v[32:35], v[148:151], v[180:183], v[32:35]
	v_mfma_f32_16x16x32_bf16 v[20:23], v[124:127], v[202:205], v[20:23]
	v_mfma_f32_16x16x32_bf16 v[16:19], v[148:151], v[202:205], v[16:19]
	s_barrier
	s_add_i32 s100, s38, s21
	s_mov_b32 m0, s100
	s_nop 0
	s_add_u32 vcc_lo, s36, s0
	s_addc_u32 vcc_hi, s37, s1
	global_load_lds_dwordx4 v2, vcc
	s_add_i32 m0, s100, 0x2000
	s_nop 0
	s_add_u32 vcc_lo, s36, s52
	s_addc_u32 vcc_hi, s37, s53
	global_load_lds_dwordx4 v2, vcc
	s_waitcnt vmcnt(6)
	s_barrier
	v_mfma_f32_16x16x32_bf16 v[60:63], v[206:209], v[152:155], v[60:63]
	v_mfma_f32_16x16x32_bf16 v[56:59], v[214:217], v[152:155], v[56:59]
	v_mfma_f32_16x16x32_bf16 v[44:47], v[206:209], v[160:163], v[44:47]
	v_mfma_f32_16x16x32_bf16 v[40:43], v[214:217], v[160:163], v[40:43]
	ds_read_b128 v[112:115], v255 offset:32768
	ds_read_b128 v[124:127], v255 offset:33792
	ds_read_b128 v[136:139], v255 offset:34816
	ds_read_b128 v[148:151], v255 offset:35840
	v_mfma_f32_16x16x32_bf16 v[28:31], v[206:209], v[176:179], v[28:31]
	v_mfma_f32_16x16x32_bf16 v[24:27], v[214:217], v[176:179], v[24:27]
	v_mfma_f32_16x16x32_bf16 v[12:15], v[206:209], v[198:201], v[12:15]
	v_mfma_f32_16x16x32_bf16 v[8:11], v[214:217], v[198:201], v[8:11]
	v_mfma_f32_16x16x32_bf16 v[60:63], v[210:213], v[156:159], v[60:63]
	v_mfma_f32_16x16x32_bf16 v[56:59], v[218:221], v[156:159], v[56:59]
	v_mfma_f32_16x16x32_bf16 v[44:47], v[210:213], v[172:175], v[44:47]
	v_mfma_f32_16x16x32_bf16 v[40:43], v[218:221], v[172:175], v[40:43]
	v_mfma_f32_16x16x32_bf16 v[28:31], v[210:213], v[180:183], v[28:31]
	v_mfma_f32_16x16x32_bf16 v[24:27], v[218:221], v[180:183], v[24:27]
	v_mfma_f32_16x16x32_bf16 v[12:15], v[210:213], v[202:205], v[12:15]
	v_mfma_f32_16x16x32_bf16 v[8:11], v[218:221], v[202:205], v[8:11]
	s_barrier
	s_add_i32 s100, 0, 0x18000
	s_mov_b32 m0, s26
	ds_read_b128 v[152:155], v197 offset:32768
	ds_read_b128 v[156:159], v197 offset:33792
	ds_read_b128 v[160:163], v197 offset:34816
	ds_read_b128 v[172:175], v197 offset:35840
	ds_read_b128 v[176:179], v197 offset:36864
	ds_read_b128 v[180:183], v197 offset:37888
	ds_read_b128 v[198:201], v197 offset:38912
	ds_read_b128 v[202:205], v197 offset:39936
	s_add_u32 vcc_lo, s4, s80
	s_addc_u32 vcc_hi, s5, s81
	global_load_lds_dwordx4 v164, vcc
	s_mov_b32 m0, s27
	s_nop 0
	s_add_u32 vcc_lo, s4, s82
	s_addc_u32 vcc_hi, s5, s83
	global_load_lds_dwordx4 v164, vcc
	s_waitcnt lgkmcnt(8)
	s_barrier
	s_waitcnt lgkmcnt(0)
	v_mfma_f32_16x16x32_bf16 v[144:147], v[112:115], v[152:155], v[144:147]
	v_mfma_f32_16x16x32_bf16 v[140:143], v[136:139], v[152:155], v[140:143]
	v_mfma_f32_16x16x32_bf16 v[120:123], v[112:115], v[160:163], v[120:123]
	v_mfma_f32_16x16x32_bf16 v[116:119], v[136:139], v[160:163], v[116:119]
	v_mfma_f32_16x16x32_bf16 v[100:103], v[112:115], v[176:179], v[100:103]
	v_mfma_f32_16x16x32_bf16 v[96:99], v[136:139], v[176:179], v[96:99]
	v_mfma_f32_16x16x32_bf16 v[84:87], v[112:115], v[198:201], v[84:87]
	v_mfma_f32_16x16x32_bf16 v[80:83], v[136:139], v[198:201], v[80:83]
	v_mfma_f32_16x16x32_bf16 v[144:147], v[124:127], v[156:159], v[144:147]
	v_mfma_f32_16x16x32_bf16 v[140:143], v[148:151], v[156:159], v[140:143]
	v_mfma_f32_16x16x32_bf16 v[120:123], v[124:127], v[172:175], v[120:123]
	v_mfma_f32_16x16x32_bf16 v[116:119], v[148:151], v[172:175], v[116:119]
	v_mfma_f32_16x16x32_bf16 v[100:103], v[124:127], v[180:183], v[100:103]
	v_mfma_f32_16x16x32_bf16 v[96:99], v[148:151], v[180:183], v[96:99]
	v_mfma_f32_16x16x32_bf16 v[84:87], v[124:127], v[202:205], v[84:87]
	v_mfma_f32_16x16x32_bf16 v[80:83], v[148:151], v[202:205], v[80:83]
	s_barrier
; #define G_STAGE(bufoff, gbase, o0, h64) do { \
;         __builtin_amdgcn_global_load_lds((const unsigned*)((const char*)(gbase) + (o0)), (LAS unsigned*)(lds + (bufoff) + ldsw), 16, 0, 0); \
;         __builtin_amdgcn_global_load_lds((const unsigned*)((const char*)(gbase) + (h64) + (o0)), (LAS unsigned*)(lds + (bufoff) + ldsw + 8192), 16, 0, 0); } while (0)
; #define G_LDA(dst, b, h) do { _Pragma("unroll") for (int m = 0; m < 4; ++m) _Pragma("unroll") for (int k = 0; k < 2; ++k) dst[m][k] = *(const LAS bf16x8*)(lds + G_SA(b, h) + aoff + m * 2048 + k * 1024); } while (0)
; #define G_LDB(dst, b, h) do { _Pragma("unroll") for (int n = 0; n < 2; ++n) _Pragma("unroll") for (int k = 0; k < 2; ++k) dst[n][k] = *(const LAS bf16x8*)(lds + G_SB(b, h) + boff + n * 2048 + k * 1024); } while (0)
; #define G_WAIT_V(n) asm volatile("s_waitcnt vmcnt(" #n ")" ::: "memory")
; #define G_WAIT_L(n) asm volatile("s_waitcnt lgkmcnt(" #n ")" ::: "memory")
; #define G_BAR __builtin_amdgcn_s_barrier()
; #define G_SCHED __builtin_amdgcn_sched_barrier(0)
;     ...
;             G_LDB(B1, 1, 1); G_STAGE(G_SB(1, 0), b3, cB0, qB);
;             G_BAR; G_WAIT_L(0); G_MMA(0, 1, At, B1); G_BAR;
;             G_LDA(At, 1, 1); G_STAGE(G_SA(1, 0), a3, cA0, qA);
;             G_BAR; G_WAIT_L(0); G_MMA(1, 0, At, B0); G_BAR; G_SCHED;
;             G_STAGE(G_SB(1, 1), b3 + chB, cB0, qB);
;             G_WAIT_V(6); G_BAR; G_MMA(1, 1, At, B1); G_BAR;
	s_add_i32 s5, 0, 0x1c000
	s_add_i32 s4, s100, s21
	s_mov_b32 m0, s4
	ds_read_b128 v[206:209], v255 offset:49152
	ds_read_b128 v[210:213], v255 offset:50176
	ds_read_b128 v[214:217], v255 offset:51200
	ds_read_b128 v[218:221], v255 offset:52224
	s_add_u32 vcc_lo, s36, s46
	s_addc_u32 vcc_hi, s37, s47
	global_load_lds_dwordx4 v2, vcc
	s_add_i32 m0, s4, 0x2000
	s_nop 0
	s_add_u32 vcc_lo, s36, s54
	s_addc_u32 vcc_hi, s37, s55
	global_load_lds_dwordx4 v2, vcc
	s_barrier
	s_waitcnt lgkmcnt(0)
	v_mfma_f32_16x16x32_bf16 v[132:135], v[206:209], v[152:155], v[132:135]
	v_mfma_f32_16x16x32_bf16 v[128:131], v[214:217], v[152:155], v[128:131]
	v_mfma_f32_16x16x32_bf16 v[108:111], v[206:209], v[160:163], v[108:111]
	v_mfma_f32_16x16x32_bf16 v[104:107], v[214:217], v[160:163], v[104:107]
	v_mfma_f32_16x16x32_bf16 v[92:95], v[206:209], v[176:179], v[92:95]
	v_mfma_f32_16x16x32_bf16 v[88:91], v[214:217], v[176:179], v[88:91]
	v_mfma_f32_16x16x32_bf16 v[76:79], v[206:209], v[198:201], v[76:79]
	v_mfma_f32_16x16x32_bf16 v[72:75], v[214:217], v[198:201], v[72:75]
	v_mfma_f32_16x16x32_bf16 v[132:135], v[210:213], v[156:159], v[132:135]
	v_mfma_f32_16x16x32_bf16 v[128:131], v[218:221], v[156:159], v[128:131]
	v_mfma_f32_16x16x32_bf16 v[108:111], v[210:213], v[172:175], v[108:111]
	v_mfma_f32_16x16x32_bf16 v[104:107], v[218:221], v[172:175], v[104:107]
	v_mfma_f32_16x16x32_bf16 v[92:95], v[210:213], v[180:183], v[92:95]
	v_mfma_f32_16x16x32_bf16 v[88:91], v[218:221], v[180:183], v[88:91]
	v_mfma_f32_16x16x32_bf16 v[76:79], v[210:213], v[202:205], v[76:79]
	v_mfma_f32_16x16x32_bf16 v[72:75], v[218:221], v[202:205], v[72:75]
	s_barrier
	s_mov_b32 m0, s29
	v_lshl_add_u64 v[224:225], v[222:223], 0, s[62:63]
	ds_read_b128 v[152:155], v197 offset:49152
	ds_read_b128 v[156:159], v197 offset:50176
	ds_read_b128 v[160:163], v197 offset:51200
	ds_read_b128 v[172:175], v197 offset:52224
	ds_read_b128 v[176:179], v197 offset:53248
	ds_read_b128 v[180:183], v197 offset:54272
	ds_read_b128 v[198:201], v197 offset:55296
	ds_read_b128 v[202:205], v197 offset:56320
	global_load_lds_dwordx4 v[224:225], off
	v_lshl_add_u64 v[222:223], v[222:223], 0, s[84:85]
	s_mov_b32 m0, s30
	s_nop 0
	global_load_lds_dwordx4 v[222:223], off
	s_barrier
	s_waitcnt lgkmcnt(0)
	v_mfma_f32_16x16x32_bf16 v[68:71], v[112:115], v[152:155], v[68:71]
	v_mfma_f32_16x16x32_bf16 v[64:67], v[136:139], v[152:155], v[64:67]
	v_mfma_f32_16x16x32_bf16 v[52:55], v[112:115], v[160:163], v[52:55]
	v_mfma_f32_16x16x32_bf16 v[48:51], v[136:139], v[160:163], v[48:51]
	v_mfma_f32_16x16x32_bf16 v[36:39], v[112:115], v[176:179], v[36:39]
	v_mfma_f32_16x16x32_bf16 v[32:35], v[136:139], v[176:179], v[32:35]
	v_mfma_f32_16x16x32_bf16 v[20:23], v[112:115], v[198:201], v[20:23]
	v_mfma_f32_16x16x32_bf16 v[16:19], v[136:139], v[198:201], v[16:19]
	v_mfma_f32_16x16x32_bf16 v[68:71], v[124:127], v[156:159], v[68:71]
	v_mfma_f32_16x16x32_bf16 v[64:67], v[148:151], v[156:159], v[64:67]
	v_mfma_f32_16x16x32_bf16 v[52:55], v[124:127], v[172:175], v[52:55]
	v_mfma_f32_16x16x32_bf16 v[48:51], v[148:151], v[172:175], v[48:51]
	v_mfma_f32_16x16x32_bf16 v[36:39], v[124:127], v[180:183], v[36:39]
	v_mfma_f32_16x16x32_bf16 v[32:35], v[148:151], v[180:183], v[32:35]
	v_mfma_f32_16x16x32_bf16 v[20:23], v[124:127], v[202:205], v[20:23]
	v_mfma_f32_16x16x32_bf16 v[16:19], v[148:151], v[202:205], v[16:19]
	s_barrier
	s_add_i32 s4, s5, s21
	s_mov_b32 m0, s4
	s_nop 0
	s_add_u32 vcc_lo, s36, s42
	s_addc_u32 vcc_hi, s37, s43
	global_load_lds_dwordx4 v2, vcc
	s_add_i32 m0, s4, 0x2000
	s_nop 0
	s_add_u32 vcc_lo, s36, s58
	s_addc_u32 vcc_hi, s37, s59
	global_load_lds_dwordx4 v2, vcc
	s_add_i32 s19, s19, 2
	s_add_u32 s13, s13, 0x100
	s_addc_u32 s18, s18, 0
	s_add_u32 s2, s2, 0x800000
	s_addc_u32 s3, s3, 0
	s_cmp_gt_u32 s19, 5
	s_waitcnt vmcnt(6)
	s_barrier
	v_mfma_f32_16x16x32_bf16 v[60:63], v[206:209], v[152:155], v[60:63]
	v_mfma_f32_16x16x32_bf16 v[56:59], v[214:217], v[152:155], v[56:59]
	v_mfma_f32_16x16x32_bf16 v[44:47], v[206:209], v[160:163], v[44:47]
	v_mfma_f32_16x16x32_bf16 v[40:43], v[214:217], v[160:163], v[40:43]
	ds_read_b128 v[112:115], v255 offset:0
	ds_read_b128 v[124:127], v255 offset:1024
	ds_read_b128 v[136:139], v255 offset:2048
	ds_read_b128 v[148:151], v255 offset:3072
	v_mfma_f32_16x16x32_bf16 v[28:31], v[206:209], v[176:179], v[28:31]
	v_mfma_f32_16x16x32_bf16 v[24:27], v[214:217], v[176:179], v[24:27]
	v_mfma_f32_16x16x32_bf16 v[12:15], v[206:209], v[198:201], v[12:15]
	v_mfma_f32_16x16x32_bf16 v[8:11], v[214:217], v[198:201], v[8:11]
	v_mfma_f32_16x16x32_bf16 v[60:63], v[210:213], v[156:159], v[60:63]
	v_mfma_f32_16x16x32_bf16 v[56:59], v[218:221], v[156:159], v[56:59]
	v_mfma_f32_16x16x32_bf16 v[44:47], v[210:213], v[172:175], v[44:47]
	v_mfma_f32_16x16x32_bf16 v[40:43], v[218:221], v[172:175], v[40:43]
	v_mfma_f32_16x16x32_bf16 v[28:31], v[210:213], v[180:183], v[28:31]
	v_mfma_f32_16x16x32_bf16 v[24:27], v[218:221], v[180:183], v[24:27]
	v_mfma_f32_16x16x32_bf16 v[12:15], v[210:213], v[202:205], v[12:15]
	v_mfma_f32_16x16x32_bf16 v[8:11], v[218:221], v[202:205], v[8:11]
	s_cbranch_scc0 .Ldb_GLU_cont
	v_readfirstlane_b32 s101, v186
	s_cmpk_gt_u32 s101, 0xff
	s_cbranch_scc1 .Ldb_GLU_young
	s_barrier
	s_mov_b32 s101, 1
	s_branch .Ldb_GLU_exit

; __device__ __forceinline__ float sigmoidf_(float v) { return __builtin_amdgcn_rcpf(1.0f + __expf(-v)); }
; __device__ __forceinline__ u32x4 pack8(const f32x4 a, const f32x4 b) { u32x4 w; w.x = cvt_pk_bf16(a[0], a[1]); w.y = cvt_pk_bf16(a[2], a[3]); w.z = cvt_pk_bf16(b[0], b[1]); w.w = cvt_pk_bf16(b[2], b[3]); return w; }
; __device__ __forceinline__ void unpack8(const u32x4 w, f32x4& a, f32x4& b) { a[0] = bf_lo(w.x); a[1] = bf_hi(w.x); a[2] = bf_lo(w.y); a[3] = bf_hi(w.y); b[0] = bf_lo(w.z); b[1] = bf_hi(w.z); b[2] = bf_lo(w.w); b[3] = bf_hi(w.w); }
; #define MEMFENCE asm volatile("" ::: "memory")
;     template <int KIND> __device__ __forceinline__ void run(f32x4 (&acc)[2][2][4][2], const Unit& u, int tid_in) const {
;     ...
;         if constexpr (KIND == K_GLU) {
; #pragma unroll
;             for (int ai = 0; ai < 2; ++ai) { u32x4 yv[4][2];
; #pragma unroll
;                 for (int m = 0; m < 4; ++m) { int row = rbase + ai * 128 + m * 16; asm volatile("" : "+v"(row));
; #pragma unroll
;                     for (int bj = 0; bj < 2; ++bj) { const int col = u.pn * 256 + bj * 128 + cl; yv[m][bj] = *(const u32x4*)(yi + ((size_t)(col >> 4) * T_TOK + row) * 16 + (col & 15)); } }
; #pragma unroll
;                 for (int m = 0; m < 4; ++m) { int row = rbase + ai * 128 + m * 16; asm volatile("" : "+v"(row));
; #pragma unroll
;                     for (int bj = 0; bj < 2; ++bj) { const int col = u.pn * 256 + bj * 128 + cl; f32x4 y0, y1; unpack8(yv[m][bj], y0, y1);
; #pragma unroll
;                         for (int j = 0; j < 4; ++j) { y0[j] *= sigmoidf_(acc[ai][bj][m][0][j]); y1[j] *= sigmoidf_(acc[ai][bj][m][1][j]); }
;                         *(u32x4*)(zb + (size_t)row * ZW + 1024 + col) = pack8(y0, y1); } }
;                 MEMFENCE; }
.Ldb_GLU_exit:
	s_waitcnt lgkmcnt(0)
	v_mov_b32_e32 v0, v195
	s_lshl_b32 s3, s35, 8
	v_readfirstlane_b32 s2, v0
	s_ashr_i32 s4, s2, 2
	s_lshr_b32 s2, s2, 1
	s_and_b32 s2, s2, 0x60
	v_lshrrev_b32_e32 v112, 1, v0
	v_and_or_b32 v112, v112, 24, s2
	s_andn2_b32 s4, s4, 63
	v_lshl_or_b32 v182, s33, 8, v112
	s_add_i32 s4, s4, s3
	v_ashrrev_i32_e32 v112, 4, v182
	v_and_or_b32 v198, v0, 15, s4
	v_ashrrev_i32_e32 v113, 31, v112
	v_lshlrev_b64 v[176:177], 20, v[112:113]
	v_mov_b32_e32 v112, v198
	v_and_b32_e32 v0, 16, v0
	v_lshl_add_u64 v[174:175], s[8:9], 0, v[0:1]
	v_ashrrev_i32_e32 v113, 31, v112
	v_lshlrev_b64 v[112:113], 5, v[112:113]
	v_lshl_add_u64 v[112:113], v[174:175], 0, v[112:113]
	v_lshl_add_u64 v[114:115], v[112:113], 0, v[176:177]
	global_load_dwordx4 v[202:205], v[114:115], off
	v_or_b32_e32 v180, 0x80, v182
	v_ashrrev_i32_e32 v114, 4, v180
	v_ashrrev_i32_e32 v115, 31, v114
	v_lshlrev_b64 v[178:179], 20, v[114:115]
	v_lshl_add_u64 v[112:113], v[112:113], 0, v[178:179]
	global_load_dwordx4 v[160:163], v[112:113], off
	v_or_b32_e32 v200, 16, v198
	v_mov_b32_e32 v112, v200
	v_or_b32_e32 v199, 32, v198
	v_ashrrev_i32_e32 v113, 31, v112
	v_lshlrev_b64 v[112:113], 5, v[112:113]
	v_lshl_add_u64 v[112:113], v[174:175], 0, v[112:113]
	v_lshl_add_u64 v[114:115], v[112:113], 0, v[176:177]
	global_load_dwordx4 v[156:159], v[114:115], off
	v_lshl_add_u64 v[112:113], v[112:113], 0, v[178:179]
	global_load_dwordx4 v[152:155], v[112:113], off
	v_mov_b32_e32 v112, v199
	v_mul_f32_e32 v144, 0xbfb8aa3b, v144
	v_ashrrev_i32_e32 v113, 31, v112
	v_lshlrev_b64 v[112:113], 5, v[112:113]
	v_mul_f32_e32 v142, 0xbfb8aa3b, v142
	v_lshl_add_u64 v[112:113], v[174:175], 0, v[112:113]
	v_exp_f32_e32 v144, v144
	v_exp_f32_e32 v142, v142
	v_lshl_add_u64 v[114:115], v[112:113], 0, v[176:177]
	v_lshl_add_u64 v[112:113], v[112:113], 0, v[178:179]
	v_or_b32_e32 v0, 48, v198
	global_load_dwordx4 v[148:151], v[114:115], off
	global_load_dwordx4 v[136:139], v[112:113], off
	v_mov_b32_e32 v112, v0
	v_add_f32_e32 v144, 1.0, v144
	v_ashrrev_i32_e32 v113, 31, v112
	v_lshlrev_b64 v[112:113], 5, v[112:113]
	v_add_f32_e32 v142, 1.0, v142
	v_lshl_add_u64 v[112:113], v[174:175], 0, v[112:113]
	v_rcp_f32_e32 v144, v144
	v_rcp_f32_e32 v142, v142
	v_lshl_add_u64 v[114:115], v[112:113], 0, v[176:177]
	v_lshl_add_u64 v[112:113], v[112:113], 0, v[178:179]
	v_mov_b32_e32 v181, v198
	global_load_dwordx4 v[124:127], v[114:115], off
	v_mov_b64_e32 v[172:173], s[6:7]
	global_load_dwordx4 v[112:115], v[112:113], off
	v_mul_f32_e32 v145, 0xbfb8aa3b, v145
	v_mad_i64_i32 v[184:185], s[2:3], v181, s76, v[172:173]
	v_mul_f32_e32 v140, 0xbfb8aa3b, v140
	v_exp_f32_e32 v145, v145
	v_mul_f32_e32 v141, 0xbfb8aa3b, v141
	v_mul_f32_e32 v146, 0xbfb8aa3b, v146
	v_exp_f32_e32 v140, v140
	v_exp_f32_e32 v141, v141
	v_exp_f32_e32 v146, v146
	v_add_f32_e32 v145, 1.0, v145
	v_mul_f32_e32 v132, 0xbfb8aa3b, v132
	v_mul_f32_e32 v130, 0xbfb8aa3b, v130
	v_add_f32_e32 v140, 1.0, v140
	v_rcp_f32_e32 v145, v145
	v_add_f32_e32 v141, 1.0, v141
	v_add_f32_e32 v146, 1.0, v146
	v_exp_f32_e32 v132, v132
	v_exp_f32_e32 v130, v130
	v_rcp_f32_e32 v140, v140
	v_rcp_f32_e32 v141, v141
	v_rcp_f32_e32 v146, v146
	v_add_f32_e32 v132, 1.0, v132
	v_add_f32_e32 v130, 1.0, v130
	s_mov_b64 s[4:5], 0xae00800
	v_rcp_f32_e32 v132, v132
	v_rcp_f32_e32 v130, v130
	v_lshl_add_u64 v[184:185], v[184:185], 0, s[4:5]
	v_mul_f32_e32 v128, 0xbfb8aa3b, v128
	v_mul_f32_e32 v129, 0xbfb8aa3b, v129
	v_exp_f32_e32 v128, v128
	v_mul_f32_e32 v133, 0xbfb8aa3b, v133
	s_waitcnt vmcnt(0)
	v_lshlrev_b32_e32 v181, 16, v202
	v_lshlrev_b32_e32 v206, 16, v205
	v_mul_f32_e32 v144, v144, v181
	v_mul_f32_e32 v181, v142, v206
	v_mul_f32_e32 v142, 0xbfb8aa3b, v147
	v_exp_f32_e32 v142, v142
	v_and_b32_e32 v183, 0xffff0000, v202
	v_and_b32_e32 v202, 0xffff0000, v203
	v_and_b32_e32 v205, 0xffff0000, v205
	v_add_f32_e32 v142, 1.0, v142
	v_rcp_f32_e32 v142, v142
	v_lshlrev_b32_e32 v201, 16, v203
	v_lshlrev_b32_e32 v203, 16, v204
	v_and_b32_e32 v204, 0xffff0000, v204
	v_mul_f32_e32 v147, v142, v202
	v_mul_f32_e32 v142, 0xbfb8aa3b, v143
	v_exp_f32_e32 v142, v142
	v_mul_f32_e32 v145, v145, v183
	v_mul_f32_e32 v140, v140, v203
	v_mul_f32_e32 v141, v141, v204
	v_add_f32_e32 v142, 1.0, v142
	v_rcp_f32_e32 v142, v142
	v_mul_f32_e32 v146, v146, v201
	v_exp_f32_e32 v129, v129
	v_mul_f32_e32 v134, 0xbfb8aa3b, v134
	v_mul_f32_e32 v183, v142, v205
	v_cvt_pk_bf16_f32 v142, v144, v145
	v_cvt_pk_bf16_f32 v143, v146, v147
	v_cvt_pk_bf16_f32 v144, v140, v141
	v_cvt_pk_bf16_f32 v145, v181, v183
	v_ashrrev_i32_e32 v183, 31, v182
	v_lshlrev_b64 v[140:141], 1, v[182:183]
	v_lshl_add_u64 v[146:147], v[184:185], 0, v[140:141]
	global_store_dwordx4 v[146:147], v[142:145], off
	v_exp_f32_e32 v133, v133
	v_exp_f32_e32 v134, v134
	v_lshlrev_b32_e32 v142, 16, v160
	v_and_b32_e32 v143, 0xffff0000, v160
	v_lshlrev_b32_e32 v160, 16, v163
	v_mul_f32_e32 v132, v132, v142
	v_mul_f32_e32 v142, v130, v160
	v_mul_f32_e32 v130, 0xbfb8aa3b, v135
	v_exp_f32_e32 v130, v130
	v_and_b32_e32 v145, 0xffff0000, v161
	v_mul_f32_e32 v120, 0xbfb8aa3b, v120
	v_mul_f32_e32 v116, 0xbfb8aa3b, v116
	v_add_f32_e32 v130, 1.0, v130
	v_rcp_f32_e32 v130, v130
	v_mul_f32_e32 v117, 0xbfb8aa3b, v117
	v_mul_f32_e32 v118, 0xbfb8aa3b, v118
	v_add_f32_e32 v128, 1.0, v128
	v_mul_f32_e32 v135, v130, v145
	v_mul_f32_e32 v130, 0xbfb8aa3b, v131
	v_exp_f32_e32 v130, v130
	v_add_f32_e32 v129, 1.0, v129
	v_exp_f32_e32 v120, v120
	v_exp_f32_e32 v116, v116
	v_exp_f32_e32 v117, v117
	v_exp_f32_e32 v118, v118
	v_rcp_f32_e32 v128, v128
	v_add_f32_e32 v133, 1.0, v133
	v_rcp_f32_e32 v129, v129
	v_add_f32_e32 v134, 1.0, v134
	v_add_f32_e32 v130, 1.0, v130
; __device__ __forceinline__ float sigmoidf_(float v) { return __builtin_amdgcn_rcpf(1.0f + __expf(-v)); }
; __device__ __forceinline__ u32x4 pack8(const f32x4 a, const f32x4 b) { u32x4 w; w.x = cvt_pk_bf16(a[0], a[1]); w.y = cvt_pk_bf16(a[2], a[3]); w.z = cvt_pk_bf16(b[0], b[1]); w.w = cvt_pk_bf16(b[2], b[3]); return w; }
; __device__ __forceinline__ void unpack8(const u32x4 w, f32x4& a, f32x4& b) { a[0] = bf_lo(w.x); a[1] = bf_hi(w.x); a[2] = bf_lo(w.y); a[3] = bf_hi(w.y); b[0] = bf_lo(w.z); b[1] = bf_hi(w.z); b[2] = bf_lo(w.w); b[3] = bf_hi(w.w); }
; #define MEMFENCE asm volatile("" ::: "memory")
;     template <int KIND> __device__ __forceinline__ void run(f32x4 (&acc)[2][2][4][2], const Unit& u, int tid_in) const {
;     ...
;         if constexpr (KIND == K_GLU) {
; #pragma unroll
;             for (int ai = 0; ai < 2; ++ai) { u32x4 yv[4][2];
; #pragma unroll
;                 for (int m = 0; m < 4; ++m) { int row = rbase + ai * 128 + m * 16; asm volatile("" : "+v"(row));
; #pragma unroll
;                     for (int bj = 0; bj < 2; ++bj) { const int col = u.pn * 256 + bj * 128 + cl; yv[m][bj] = *(const u32x4*)(yi + ((size_t)(col >> 4) * T_TOK + row) * 16 + (col & 15)); } }
; #pragma unroll
;                 for (int m = 0; m < 4; ++m) { int row = rbase + ai * 128 + m * 16; asm volatile("" : "+v"(row));
; #pragma unroll
;                     for (int bj = 0; bj < 2; ++bj) { const int col = u.pn * 256 + bj * 128 + cl; f32x4 y0, y1; unpack8(yv[m][bj], y0, y1);
; #pragma unroll
;                         for (int j = 0; j < 4; ++j) { y0[j] *= sigmoidf_(acc[ai][bj][m][0][j]); y1[j] *= sigmoidf_(acc[ai][bj][m][1][j]); }
;                         *(u32x4*)(zb + (size_t)row * ZW + 1024 + col) = pack8(y0, y1); } }
;                 MEMFENCE; }
	v_rcp_f32_e32 v133, v133
	v_rcp_f32_e32 v134, v134
	v_rcp_f32_e32 v130, v130
	v_lshlrev_b32_e32 v146, 16, v162
	v_and_b32_e32 v147, 0xffff0000, v162
	v_add_f32_e32 v120, 1.0, v120
	v_add_f32_e32 v116, 1.0, v116
	v_add_f32_e32 v117, 1.0, v117
	v_add_f32_e32 v118, 1.0, v118
	v_lshlrev_b32_e32 v144, 16, v161
	v_and_b32_e32 v161, 0xffff0000, v163
	v_mul_f32_e32 v128, v128, v146
	v_mul_f32_e32 v129, v129, v147
	v_ashrrev_i32_e32 v181, 31, v180
	v_rcp_f32_e32 v120, v120
	v_rcp_f32_e32 v116, v116
	v_rcp_f32_e32 v117, v117
	v_rcp_f32_e32 v118, v118
	v_mul_f32_e32 v133, v133, v143
	v_mul_f32_e32 v134, v134, v144
	v_mul_f32_e32 v143, v130, v161
	v_cvt_pk_bf16_f32 v130, v132, v133
	v_cvt_pk_bf16_f32 v131, v134, v135
	v_cvt_pk_bf16_f32 v132, v128, v129
	v_lshlrev_b64 v[128:129], 1, v[180:181]
	v_lshl_add_u64 v[134:135], v[184:185], 0, v[128:129]
	v_cvt_pk_bf16_f32 v133, v142, v143
	global_store_dwordx4 v[134:135], v[130:133], off
	v_lshlrev_b32_e32 v142, 16, v158
	v_and_b32_e32 v143, 0xffff0000, v158
	v_lshlrev_b32_e32 v132, 16, v156
	v_lshlrev_b32_e32 v144, 16, v159
	v_mul_f32_e32 v120, v120, v132
	v_mul_f32_e32 v132, v116, v142
	v_mul_f32_e32 v116, 0xbfb8aa3b, v121
	v_mul_f32_e32 v121, v117, v143
	v_mul_f32_e32 v117, 0xbfb8aa3b, v122
	v_mul_f32_e32 v122, v118, v144
	v_mul_f32_e32 v118, 0xbfb8aa3b, v123
	v_exp_f32_e32 v116, v116
	v_exp_f32_e32 v117, v117
	v_exp_f32_e32 v118, v118
	v_mul_f32_e32 v119, 0xbfb8aa3b, v119
	v_exp_f32_e32 v119, v119
	v_mul_f32_e32 v108, 0xbfb8aa3b, v108
	v_mul_f32_e32 v104, 0xbfb8aa3b, v104
	v_mul_f32_e32 v105, 0xbfb8aa3b, v105
	v_mul_f32_e32 v106, 0xbfb8aa3b, v106
	v_exp_f32_e32 v108, v108
	v_exp_f32_e32 v104, v104
	v_exp_f32_e32 v105, v105
	v_exp_f32_e32 v106, v106
	v_add_f32_e32 v116, 1.0, v116
	v_add_f32_e32 v117, 1.0, v117
	v_add_f32_e32 v118, 1.0, v118
	v_rcp_f32_e32 v116, v116
	v_rcp_f32_e32 v117, v117
	v_rcp_f32_e32 v118, v118
	v_add_f32_e32 v119, 1.0, v119
	v_rcp_f32_e32 v119, v119
	v_add_f32_e32 v108, 1.0, v108
	v_add_f32_e32 v104, 1.0, v104
	v_add_f32_e32 v105, 1.0, v105
	v_add_f32_e32 v106, 1.0, v106
	v_and_b32_e32 v133, 0xffff0000, v156
	v_mad_i64_i32 v[130:131], s[2:3], v200, s76, v[172:173]
	v_lshlrev_b32_e32 v134, 16, v157
	v_and_b32_e32 v135, 0xffff0000, v157
	v_rcp_f32_e32 v108, v108
	v_rcp_f32_e32 v104, v104
	v_rcp_f32_e32 v105, v105
	v_rcp_f32_e32 v106, v106
	v_lshl_add_u64 v[130:131], v[130:131], 0, s[4:5]
	v_and_b32_e32 v145, 0xffff0000, v159
	v_mul_f32_e32 v116, v116, v133
	v_mul_f32_e32 v117, v117, v134
	v_mul_f32_e32 v118, v118, v135
	v_mul_f32_e32 v119, v119, v145
	v_cvt_pk_bf16_f32 v116, v120, v116
	v_cvt_pk_bf16_f32 v117, v117, v118
	v_cvt_pk_bf16_f32 v118, v132, v121
	v_lshl_add_u64 v[120:121], v[130:131], 0, v[140:141]
	v_cvt_pk_bf16_f32 v119, v122, v119
	global_store_dwordx4 v[120:121], v[116:119], off
	v_lshlrev_b32_e32 v120, 16, v154
	v_and_b32_e32 v121, 0xffff0000, v154
	v_lshlrev_b32_e32 v116, 16, v152
	v_lshlrev_b32_e32 v122, 16, v155
	v_mul_f32_e32 v108, v108, v116
	v_mul_f32_e32 v116, v104, v120
	v_mul_f32_e32 v104, 0xbfb8aa3b, v109
	v_mul_f32_e32 v109, v105, v121
	v_mul_f32_e32 v105, 0xbfb8aa3b, v110
	v_mul_f32_e32 v110, v106, v122
	v_mul_f32_e32 v106, 0xbfb8aa3b, v111
	v_exp_f32_e32 v104, v104
	v_exp_f32_e32 v105, v105
	v_exp_f32_e32 v106, v106
	v_mul_f32_e32 v107, 0xbfb8aa3b, v107
	v_exp_f32_e32 v107, v107
	v_mul_f32_e32 v100, 0xbfb8aa3b, v100
	v_mul_f32_e32 v96, 0xbfb8aa3b, v96
	v_mul_f32_e32 v97, 0xbfb8aa3b, v97
	v_mul_f32_e32 v98, 0xbfb8aa3b, v98
	v_exp_f32_e32 v100, v100
	v_exp_f32_e32 v96, v96
	v_exp_f32_e32 v97, v97
	v_exp_f32_e32 v98, v98
	v_add_f32_e32 v104, 1.0, v104
	v_add_f32_e32 v105, 1.0, v105
	v_add_f32_e32 v106, 1.0, v106
	v_rcp_f32_e32 v104, v104
	v_rcp_f32_e32 v105, v105
	v_rcp_f32_e32 v106, v106
	v_add_f32_e32 v107, 1.0, v107
	v_rcp_f32_e32 v107, v107
	v_add_f32_e32 v100, 1.0, v100
	v_add_f32_e32 v96, 1.0, v96
	v_add_f32_e32 v97, 1.0, v97
	v_add_f32_e32 v98, 1.0, v98
	v_and_b32_e32 v117, 0xffff0000, v152
	v_lshlrev_b32_e32 v118, 16, v153
	v_and_b32_e32 v119, 0xffff0000, v153
	v_rcp_f32_e32 v100, v100
	v_rcp_f32_e32 v96, v96
	v_rcp_f32_e32 v97, v97
	v_rcp_f32_e32 v98, v98
	v_and_b32_e32 v123, 0xffff0000, v155
	v_mul_f32_e32 v104, v104, v117
	v_mul_f32_e32 v105, v105, v118
	v_mul_f32_e32 v106, v106, v119
	v_mul_f32_e32 v107, v107, v123
	v_cvt_pk_bf16_f32 v104, v108, v104
	v_cvt_pk_bf16_f32 v105, v105, v106
	v_cvt_pk_bf16_f32 v106, v116, v109
	v_lshl_add_u64 v[108:109], v[130:131], 0, v[128:129]
	v_cvt_pk_bf16_f32 v107, v110, v107
	global_store_dwordx4 v[108:109], v[104:107], off
	v_lshlrev_b32_e32 v110, 16, v150
	v_and_b32_e32 v111, 0xffff0000, v150
	v_lshlrev_b32_e32 v106, 16, v148
	v_lshlrev_b32_e32 v116, 16, v151
	v_mul_f32_e32 v100, v100, v106
	v_mul_f32_e32 v106, v96, v110
	v_mul_f32_e32 v96, 0xbfb8aa3b, v101
	v_mul_f32_e32 v101, v97, v111
	v_mul_f32_e32 v97, 0xbfb8aa3b, v102
	v_mul_f32_e32 v102, v98, v116
	v_mul_f32_e32 v98, 0xbfb8aa3b, v103
	v_exp_f32_e32 v96, v96
	v_exp_f32_e32 v97, v97
	v_exp_f32_e32 v98, v98
	v_mul_f32_e32 v99, 0xbfb8aa3b, v99
	v_exp_f32_e32 v99, v99
	v_mul_f32_e32 v92, 0xbfb8aa3b, v92
	v_mul_f32_e32 v88, 0xbfb8aa3b, v88
	v_mul_f32_e32 v89, 0xbfb8aa3b, v89
	v_mul_f32_e32 v90, 0xbfb8aa3b, v90
	v_exp_f32_e32 v92, v92
	v_exp_f32_e32 v88, v88
	v_exp_f32_e32 v89, v89
	v_exp_f32_e32 v90, v90
	v_add_f32_e32 v96, 1.0, v96
	v_add_f32_e32 v97, 1.0, v97
	v_add_f32_e32 v98, 1.0, v98
	v_rcp_f32_e32 v96, v96
	v_rcp_f32_e32 v97, v97
	v_rcp_f32_e32 v98, v98
	v_add_f32_e32 v99, 1.0, v99
	v_rcp_f32_e32 v99, v99
	v_add_f32_e32 v92, 1.0, v92
	v_add_f32_e32 v88, 1.0, v88
	v_add_f32_e32 v89, 1.0, v89
	v_add_f32_e32 v90, 1.0, v90
	v_and_b32_e32 v107, 0xffff0000, v148
; __device__ __forceinline__ float sigmoidf_(float v) { return __builtin_amdgcn_rcpf(1.0f + __expf(-v)); }
; __device__ __forceinline__ u32x4 pack8(const f32x4 a, const f32x4 b) { u32x4 w; w.x = cvt_pk_bf16(a[0], a[1]); w.y = cvt_pk_bf16(a[2], a[3]); w.z = cvt_pk_bf16(b[0], b[1]); w.w = cvt_pk_bf16(b[2], b[3]); return w; }
; __device__ __forceinline__ void unpack8(const u32x4 w, f32x4& a, f32x4& b) { a[0] = bf_lo(w.x); a[1] = bf_hi(w.x); a[2] = bf_lo(w.y); a[3] = bf_hi(w.y); b[0] = bf_lo(w.z); b[1] = bf_hi(w.z); b[2] = bf_lo(w.w); b[3] = bf_hi(w.w); }
; #define MEMFENCE asm volatile("" ::: "memory")
;     template <int KIND> __device__ __forceinline__ void run(f32x4 (&acc)[2][2][4][2], const Unit& u, int tid_in) const {
;     ...
;         if constexpr (KIND == K_GLU) {
; #pragma unroll
;             for (int ai = 0; ai < 2; ++ai) { u32x4 yv[4][2];
; #pragma unroll
;                 for (int m = 0; m < 4; ++m) { int row = rbase + ai * 128 + m * 16; asm volatile("" : "+v"(row));
; #pragma unroll
;                     for (int bj = 0; bj < 2; ++bj) { const int col = u.pn * 256 + bj * 128 + cl; yv[m][bj] = *(const u32x4*)(yi + ((size_t)(col >> 4) * T_TOK + row) * 16 + (col & 15)); } }
; #pragma unroll
;                 for (int m = 0; m < 4; ++m) { int row = rbase + ai * 128 + m * 16; asm volatile("" : "+v"(row));
; #pragma unroll
;                     for (int bj = 0; bj < 2; ++bj) { const int col = u.pn * 256 + bj * 128 + cl; f32x4 y0, y1; unpack8(yv[m][bj], y0, y1);
; #pragma unroll
;                         for (int j = 0; j < 4; ++j) { y0[j] *= sigmoidf_(acc[ai][bj][m][0][j]); y1[j] *= sigmoidf_(acc[ai][bj][m][1][j]); }
;                         *(u32x4*)(zb + (size_t)row * ZW + 1024 + col) = pack8(y0, y1); } }
;                 MEMFENCE; }
	v_mad_i64_i32 v[104:105], s[2:3], v199, s76, v[172:173]
	v_lshlrev_b32_e32 v108, 16, v149
	v_and_b32_e32 v109, 0xffff0000, v149
	v_rcp_f32_e32 v92, v92
	v_rcp_f32_e32 v88, v88
	v_rcp_f32_e32 v89, v89
	v_rcp_f32_e32 v90, v90
	v_lshl_add_u64 v[104:105], v[104:105], 0, s[4:5]
	v_and_b32_e32 v117, 0xffff0000, v151
	v_mul_f32_e32 v96, v96, v107
	v_mul_f32_e32 v97, v97, v108
	v_mul_f32_e32 v98, v98, v109
	v_mul_f32_e32 v99, v99, v117
	v_cvt_pk_bf16_f32 v96, v100, v96
	v_cvt_pk_bf16_f32 v97, v97, v98
	v_cvt_pk_bf16_f32 v98, v106, v101
	v_lshl_add_u64 v[100:101], v[104:105], 0, v[140:141]
	v_cvt_pk_bf16_f32 v99, v102, v99
	global_store_dwordx4 v[100:101], v[96:99], off
	v_lshlrev_b32_e32 v100, 16, v138
	v_and_b32_e32 v101, 0xffff0000, v138
	v_lshlrev_b32_e32 v96, 16, v136
	v_lshlrev_b32_e32 v102, 16, v139
	v_mul_f32_e32 v92, v92, v96
	v_mul_f32_e32 v96, v88, v100
	v_mul_f32_e32 v88, 0xbfb8aa3b, v93
	v_mul_f32_e32 v93, v89, v101
	v_mul_f32_e32 v89, 0xbfb8aa3b, v94
	v_mul_f32_e32 v94, v90, v102
	v_mul_f32_e32 v90, 0xbfb8aa3b, v95
	v_exp_f32_e32 v88, v88
	v_exp_f32_e32 v89, v89
	v_exp_f32_e32 v90, v90
	v_mul_f32_e32 v91, 0xbfb8aa3b, v91
	v_exp_f32_e32 v91, v91
	v_mul_f32_e32 v84, 0xbfb8aa3b, v84
	v_mul_f32_e32 v80, 0xbfb8aa3b, v80
	v_mul_f32_e32 v81, 0xbfb8aa3b, v81
	v_mul_f32_e32 v82, 0xbfb8aa3b, v82
	v_add_f32_e32 v88, 1.0, v88
	v_add_f32_e32 v89, 1.0, v89
	v_add_f32_e32 v90, 1.0, v90
	v_exp_f32_e32 v84, v84
	v_exp_f32_e32 v80, v80
	v_exp_f32_e32 v81, v81
	v_exp_f32_e32 v82, v82
	v_rcp_f32_e32 v88, v88
	v_rcp_f32_e32 v89, v89
	v_rcp_f32_e32 v90, v90
	v_add_f32_e32 v91, 1.0, v91
	v_rcp_f32_e32 v91, v91
	v_and_b32_e32 v97, 0xffff0000, v136
	v_lshlrev_b32_e32 v98, 16, v137
	v_and_b32_e32 v99, 0xffff0000, v137
	v_add_f32_e32 v84, 1.0, v84
	v_add_f32_e32 v80, 1.0, v80
	v_add_f32_e32 v81, 1.0, v81
	v_add_f32_e32 v82, 1.0, v82
	v_and_b32_e32 v103, 0xffff0000, v139
	v_mul_f32_e32 v88, v88, v97
	v_mul_f32_e32 v89, v89, v98
	v_mul_f32_e32 v90, v90, v99
	v_rcp_f32_e32 v84, v84
	v_rcp_f32_e32 v80, v80
	v_rcp_f32_e32 v81, v81
	v_rcp_f32_e32 v82, v82
	v_mul_f32_e32 v91, v91, v103
	v_cvt_pk_bf16_f32 v88, v92, v88
	v_cvt_pk_bf16_f32 v89, v89, v90
	v_cvt_pk_bf16_f32 v90, v96, v93
	v_lshl_add_u64 v[92:93], v[104:105], 0, v[128:129]
	v_cvt_pk_bf16_f32 v91, v94, v91
	global_store_dwordx4 v[92:93], v[88:91], off
	v_lshlrev_b32_e32 v93, 16, v126
	v_and_b32_e32 v94, 0xffff0000, v126
	v_mad_i64_i32 v[88:89], s[2:3], v0, s76, v[172:173]
	v_lshlrev_b32_e32 v0, 16, v124
	v_lshlrev_b32_e32 v95, 16, v127
	v_mul_f32_e32 v0, v84, v0
	v_mul_f32_e32 v84, v80, v93
	v_mul_f32_e32 v80, 0xbfb8aa3b, v85
	v_mul_f32_e32 v85, v81, v94
	v_mul_f32_e32 v81, 0xbfb8aa3b, v86
	v_mul_f32_e32 v86, v82, v95
	v_mul_f32_e32 v82, 0xbfb8aa3b, v87
	v_mul_f32_e32 v83, 0xbfb8aa3b, v83
	v_exp_f32_e32 v80, v80
	v_exp_f32_e32 v81, v81
	v_exp_f32_e32 v82, v82
	v_exp_f32_e32 v83, v83
	v_mul_f32_e32 v76, 0xbfb8aa3b, v76
	v_mul_f32_e32 v72, 0xbfb8aa3b, v72
	v_mul_f32_e32 v73, 0xbfb8aa3b, v73
	v_mul_f32_e32 v74, 0xbfb8aa3b, v74
	v_exp_f32_e32 v76, v76
	v_exp_f32_e32 v72, v72
	v_exp_f32_e32 v73, v73
	v_exp_f32_e32 v74, v74
	v_add_f32_e32 v80, 1.0, v80
	v_add_f32_e32 v81, 1.0, v81
	v_add_f32_e32 v82, 1.0, v82
	v_add_f32_e32 v83, 1.0, v83
	v_rcp_f32_e32 v80, v80
	v_rcp_f32_e32 v81, v81
	v_rcp_f32_e32 v82, v82
	v_rcp_f32_e32 v83, v83
	v_add_f32_e32 v76, 1.0, v76
	v_add_f32_e32 v72, 1.0, v72
	v_add_f32_e32 v73, 1.0, v73
	v_add_f32_e32 v74, 1.0, v74
	v_and_b32_e32 v90, 0xffff0000, v124
	v_lshlrev_b32_e32 v91, 16, v125
	v_and_b32_e32 v92, 0xffff0000, v125
	v_and_b32_e32 v96, 0xffff0000, v127
	v_rcp_f32_e32 v76, v76
	v_rcp_f32_e32 v72, v72
	v_rcp_f32_e32 v73, v73
	v_rcp_f32_e32 v74, v74
	v_lshl_add_u64 v[88:89], v[88:89], 0, s[4:5]
	v_mul_f32_e32 v80, v80, v90
	v_mul_f32_e32 v81, v81, v91
	v_mul_f32_e32 v82, v82, v92
	v_mul_f32_e32 v83, v83, v96
	v_cvt_pk_bf16_f32 v80, v0, v80
	v_cvt_pk_bf16_f32 v81, v81, v82
	v_cvt_pk_bf16_f32 v82, v84, v85
	v_cvt_pk_bf16_f32 v83, v86, v83
	v_lshl_add_u64 v[84:85], v[88:89], 0, v[140:141]
	global_store_dwordx4 v[84:85], v[80:83], off
	v_lshlrev_b32_e32 v0, 16, v112
	v_and_b32_e32 v84, 0xffff0000, v114
	v_lshlrev_b32_e32 v83, 16, v114
	v_lshlrev_b32_e32 v85, 16, v115
	v_mul_f32_e32 v0, v76, v0
	v_mul_f32_e32 v76, v72, v83
	v_mul_f32_e32 v72, 0xbfb8aa3b, v77
	v_mul_f32_e32 v77, v73, v84
	v_mul_f32_e32 v73, 0xbfb8aa3b, v78
	v_mul_f32_e32 v78, v74, v85
	v_mul_f32_e32 v74, 0xbfb8aa3b, v79
	v_exp_f32_e32 v72, v72
	v_exp_f32_e32 v73, v73
	v_exp_f32_e32 v74, v74
	v_mul_f32_e32 v75, 0xbfb8aa3b, v75
	v_exp_f32_e32 v75, v75
	v_add_f32_e32 v72, 1.0, v72
	v_add_f32_e32 v73, 1.0, v73
	v_add_f32_e32 v74, 1.0, v74
	v_rcp_f32_e32 v72, v72
	v_rcp_f32_e32 v73, v73
	v_rcp_f32_e32 v74, v74
	v_add_f32_e32 v75, 1.0, v75
	v_rcp_f32_e32 v75, v75
	v_and_b32_e32 v80, 0xffff0000, v112
	v_lshlrev_b32_e32 v81, 16, v113
	v_and_b32_e32 v82, 0xffff0000, v113
	v_and_b32_e32 v86, 0xffff0000, v115
	v_mul_f32_e32 v72, v72, v80
	v_mul_f32_e32 v73, v73, v81
	v_mul_f32_e32 v74, v74, v82
	v_mul_f32_e32 v75, v75, v86
	v_cvt_pk_bf16_f32 v72, v0, v72
	v_cvt_pk_bf16_f32 v73, v73, v74
	v_cvt_pk_bf16_f32 v74, v76, v77
	v_lshl_add_u64 v[76:77], v[88:89], 0, v[128:129]
	v_add_u32_e32 v100, 0x80, v198
	v_cvt_pk_bf16_f32 v75, v78, v75
	global_store_dwordx4 v[76:77], v[72:75], off
	v_add_u32_e32 v103, 0x90, v198
	v_add_u32_e32 v102, 0xa0, v198
	v_mov_b32_e32 v72, v100
	v_mul_f32_e32 v68, 0xbfb8aa3b, v68
	v_ashrrev_i32_e32 v73, 31, v72
	v_lshlrev_b64 v[72:73], 5, v[72:73]
	v_lshl_add_u64 v[72:73], v[174:175], 0, v[72:73]
	v_lshl_add_u64 v[74:75], v[72:73], 0, v[176:177]
	global_load_dwordx4 v[104:107], v[74:75], off
; __device__ __forceinline__ float sigmoidf_(float v) { return __builtin_amdgcn_rcpf(1.0f + __expf(-v)); }
; __device__ __forceinline__ u32x4 pack8(const f32x4 a, const f32x4 b) { u32x4 w; w.x = cvt_pk_bf16(a[0], a[1]); w.y = cvt_pk_bf16(a[2], a[3]); w.z = cvt_pk_bf16(b[0], b[1]); w.w = cvt_pk_bf16(b[2], b[3]); return w; }
; __device__ __forceinline__ void unpack8(const u32x4 w, f32x4& a, f32x4& b) { a[0] = bf_lo(w.x); a[1] = bf_hi(w.x); a[2] = bf_lo(w.y); a[3] = bf_hi(w.y); b[0] = bf_lo(w.z); b[1] = bf_hi(w.z); b[2] = bf_lo(w.w); b[3] = bf_hi(w.w); }
; #define MEMFENCE asm volatile("" ::: "memory")
;     template <int KIND> __device__ __forceinline__ void run(f32x4 (&acc)[2][2][4][2], const Unit& u, int tid_in) const {
;     ...
;         if constexpr (KIND == K_GLU) {
; #pragma unroll
;             for (int ai = 0; ai < 2; ++ai) { u32x4 yv[4][2];
; #pragma unroll
;                 for (int m = 0; m < 4; ++m) { int row = rbase + ai * 128 + m * 16; asm volatile("" : "+v"(row));
; #pragma unroll
;                     for (int bj = 0; bj < 2; ++bj) { const int col = u.pn * 256 + bj * 128 + cl; yv[m][bj] = *(const u32x4*)(yi + ((size_t)(col >> 4) * T_TOK + row) * 16 + (col & 15)); } }
; #pragma unroll
;                 for (int m = 0; m < 4; ++m) { int row = rbase + ai * 128 + m * 16; asm volatile("" : "+v"(row));
; #pragma unroll
;                     for (int bj = 0; bj < 2; ++bj) { const int col = u.pn * 256 + bj * 128 + cl; f32x4 y0, y1; unpack8(yv[m][bj], y0, y1);
; #pragma unroll
;                         for (int j = 0; j < 4; ++j) { y0[j] *= sigmoidf_(acc[ai][bj][m][0][j]); y1[j] *= sigmoidf_(acc[ai][bj][m][1][j]); }
;                         *(u32x4*)(zb + (size_t)row * ZW + 1024 + col) = pack8(y0, y1); } }
;                 MEMFENCE; }
	v_lshl_add_u64 v[72:73], v[72:73], 0, v[178:179]
	global_load_dwordx4 v[96:99], v[72:73], off
	v_mov_b32_e32 v72, v103
	v_mul_f32_e32 v64, 0xbfb8aa3b, v64
	v_ashrrev_i32_e32 v73, 31, v72
	v_lshlrev_b64 v[72:73], 5, v[72:73]
	v_lshl_add_u64 v[72:73], v[174:175], 0, v[72:73]
	v_lshl_add_u64 v[74:75], v[72:73], 0, v[176:177]
	global_load_dwordx4 v[92:95], v[74:75], off
	v_lshl_add_u64 v[72:73], v[72:73], 0, v[178:179]
	global_load_dwordx4 v[88:91], v[72:73], off
	v_mov_b32_e32 v72, v102
	v_mul_f32_e32 v65, 0xbfb8aa3b, v65
	v_ashrrev_i32_e32 v73, 31, v72
	v_lshlrev_b64 v[72:73], 5, v[72:73]
	v_lshl_add_u64 v[72:73], v[174:175], 0, v[72:73]
	v_lshl_add_u64 v[74:75], v[72:73], 0, v[176:177]
	global_load_dwordx4 v[84:87], v[74:75], off
	v_lshl_add_u64 v[72:73], v[72:73], 0, v[178:179]
	global_load_dwordx4 v[80:83], v[72:73], off
	v_mul_f32_e32 v66, 0xbfb8aa3b, v66
	v_exp_f32_e32 v68, v68
	v_exp_f32_e32 v64, v64
	v_exp_f32_e32 v65, v65
	v_exp_f32_e32 v66, v66
	v_add_u32_e32 v0, 0xb0, v198
	v_mov_b32_e32 v72, v0
	v_add_f32_e32 v68, 1.0, v68
	v_ashrrev_i32_e32 v73, 31, v72
	v_lshlrev_b64 v[72:73], 5, v[72:73]
	v_add_f32_e32 v64, 1.0, v64
	v_add_f32_e32 v65, 1.0, v65
	v_add_f32_e32 v66, 1.0, v66
	v_lshl_add_u64 v[72:73], v[174:175], 0, v[72:73]
	v_rcp_f32_e32 v68, v68
	v_rcp_f32_e32 v64, v64
	v_rcp_f32_e32 v65, v65
	v_rcp_f32_e32 v66, v66
	v_lshl_add_u64 v[74:75], v[72:73], 0, v[176:177]
	global_load_dwordx4 v[76:79], v[74:75], off
	v_mul_f32_e32 v67, 0xbfb8aa3b, v67
	v_exp_f32_e32 v67, v67
	v_mul_f32_e32 v60, 0xbfb8aa3b, v60
	v_mul_f32_e32 v56, 0xbfb8aa3b, v56
	v_mul_f32_e32 v57, 0xbfb8aa3b, v57
	v_mul_f32_e32 v58, 0xbfb8aa3b, v58
	v_exp_f32_e32 v60, v60
	v_exp_f32_e32 v56, v56
	v_exp_f32_e32 v57, v57
	v_exp_f32_e32 v58, v58
	v_add_f32_e32 v67, 1.0, v67
	v_lshl_add_u64 v[72:73], v[72:73], 0, v[178:179]
	v_rcp_f32_e32 v67, v67
	global_load_dwordx4 v[72:75], v[72:73], off
	v_add_f32_e32 v60, 1.0, v60
	v_add_f32_e32 v56, 1.0, v56
	v_add_f32_e32 v57, 1.0, v57
	v_add_f32_e32 v58, 1.0, v58
	v_mad_i64_i32 v[100:101], s[2:3], v100, s76, v[172:173]
	v_rcp_f32_e32 v60, v60
	v_rcp_f32_e32 v56, v56
	v_rcp_f32_e32 v57, v57
	v_rcp_f32_e32 v58, v58
	v_lshl_add_u64 v[100:101], v[100:101], 0, s[4:5]
	v_mul_f32_e32 v59, 0xbfb8aa3b, v59
	v_exp_f32_e32 v59, v59
	v_mul_f32_e32 v52, 0xbfb8aa3b, v52
	v_mul_f32_e32 v48, 0xbfb8aa3b, v48
	v_mul_f32_e32 v49, 0xbfb8aa3b, v49
	v_mul_f32_e32 v50, 0xbfb8aa3b, v50
	v_exp_f32_e32 v52, v52
	v_exp_f32_e32 v48, v48
	v_exp_f32_e32 v49, v49
	v_exp_f32_e32 v50, v50
	s_waitcnt vmcnt(0)
	v_lshlrev_b32_e32 v108, 16, v104
	v_lshlrev_b32_e32 v110, 16, v106
	v_and_b32_e32 v106, 0xffff0000, v106
	v_lshlrev_b32_e32 v111, 16, v107
	v_mul_f32_e32 v68, v68, v108
	v_mul_f32_e32 v108, v64, v110
	v_mul_f32_e32 v64, 0xbfb8aa3b, v69
	v_mul_f32_e32 v69, v65, v106
	v_mul_f32_e32 v65, 0xbfb8aa3b, v70
	v_mul_f32_e32 v70, v66, v111
	v_mul_f32_e32 v66, 0xbfb8aa3b, v71
	v_exp_f32_e32 v64, v64
	v_exp_f32_e32 v65, v65
	v_exp_f32_e32 v66, v66
	v_and_b32_e32 v104, 0xffff0000, v104
	v_add_f32_e32 v64, 1.0, v64
	v_add_f32_e32 v65, 1.0, v65
	v_add_f32_e32 v66, 1.0, v66
	v_rcp_f32_e32 v64, v64
	v_rcp_f32_e32 v65, v65
	v_rcp_f32_e32 v66, v66
	v_lshlrev_b32_e32 v109, 16, v105
	v_and_b32_e32 v105, 0xffff0000, v105
	v_and_b32_e32 v107, 0xffff0000, v107
	v_mul_f32_e32 v64, v64, v104
	v_mul_f32_e32 v65, v65, v109
	v_mul_f32_e32 v66, v66, v105
	v_mul_f32_e32 v67, v67, v107
	v_cvt_pk_bf16_f32 v64, v68, v64
	v_cvt_pk_bf16_f32 v65, v65, v66
	v_cvt_pk_bf16_f32 v66, v108, v69
	v_lshl_add_u64 v[68:69], v[100:101], 0, v[140:141]
	v_cvt_pk_bf16_f32 v67, v70, v67
	global_store_dwordx4 v[68:69], v[64:67], off
	v_lshlrev_b32_e32 v68, 16, v98
	v_and_b32_e32 v69, 0xffff0000, v98
	v_lshlrev_b32_e32 v64, 16, v96
	v_lshlrev_b32_e32 v70, 16, v99
	v_mul_f32_e32 v60, v60, v64
	v_mul_f32_e32 v64, v56, v68
	v_mul_f32_e32 v56, 0xbfb8aa3b, v61
	v_mul_f32_e32 v61, v57, v69
	v_mul_f32_e32 v57, 0xbfb8aa3b, v62
	v_mul_f32_e32 v62, v58, v70
	v_mul_f32_e32 v58, 0xbfb8aa3b, v63
	v_exp_f32_e32 v56, v56
	v_exp_f32_e32 v57, v57
	v_exp_f32_e32 v58, v58
	v_add_f32_e32 v59, 1.0, v59
	v_add_f32_e32 v56, 1.0, v56
	v_add_f32_e32 v57, 1.0, v57
	v_add_f32_e32 v58, 1.0, v58
	v_rcp_f32_e32 v56, v56
	v_rcp_f32_e32 v57, v57
	v_rcp_f32_e32 v58, v58
	v_rcp_f32_e32 v59, v59
	v_add_f32_e32 v52, 1.0, v52
	v_add_f32_e32 v48, 1.0, v48
	v_add_f32_e32 v49, 1.0, v49
	v_add_f32_e32 v50, 1.0, v50
	v_and_b32_e32 v65, 0xffff0000, v96
	v_lshlrev_b32_e32 v66, 16, v97
	v_and_b32_e32 v67, 0xffff0000, v97
	v_rcp_f32_e32 v52, v52
	v_rcp_f32_e32 v48, v48
	v_rcp_f32_e32 v49, v49
	v_rcp_f32_e32 v50, v50
	v_and_b32_e32 v71, 0xffff0000, v99
	v_mul_f32_e32 v56, v56, v65
	v_mul_f32_e32 v57, v57, v66
	v_mul_f32_e32 v58, v58, v67
	v_mul_f32_e32 v59, v59, v71
	v_cvt_pk_bf16_f32 v56, v60, v56
	v_cvt_pk_bf16_f32 v57, v57, v58
	v_cvt_pk_bf16_f32 v58, v64, v61
	v_lshl_add_u64 v[60:61], v[100:101], 0, v[128:129]
	v_cvt_pk_bf16_f32 v59, v62, v59
	global_store_dwordx4 v[60:61], v[56:59], off
	v_lshlrev_b32_e32 v62, 16, v94
	v_and_b32_e32 v63, 0xffff0000, v94
	v_lshlrev_b32_e32 v58, 16, v92
	v_lshlrev_b32_e32 v64, 16, v95
	v_mul_f32_e32 v52, v52, v58
	v_mul_f32_e32 v58, v48, v62
	v_mul_f32_e32 v48, 0xbfb8aa3b, v53
	v_mul_f32_e32 v53, v49, v63
	v_mul_f32_e32 v49, 0xbfb8aa3b, v54
	v_mul_f32_e32 v54, v50, v64
	v_mul_f32_e32 v50, 0xbfb8aa3b, v55
	v_exp_f32_e32 v48, v48
	v_exp_f32_e32 v49, v49
	v_exp_f32_e32 v50, v50
	v_mul_f32_e32 v51, 0xbfb8aa3b, v51
	v_exp_f32_e32 v51, v51
	v_mul_f32_e32 v44, 0xbfb8aa3b, v44
	v_mul_f32_e32 v40, 0xbfb8aa3b, v40
	v_mul_f32_e32 v41, 0xbfb8aa3b, v41
	v_mul_f32_e32 v42, 0xbfb8aa3b, v42
	v_exp_f32_e32 v44, v44
	v_exp_f32_e32 v40, v40
; __device__ __forceinline__ float sigmoidf_(float v) { return __builtin_amdgcn_rcpf(1.0f + __expf(-v)); }
; __device__ __forceinline__ u32x4 pack8(const f32x4 a, const f32x4 b) { u32x4 w; w.x = cvt_pk_bf16(a[0], a[1]); w.y = cvt_pk_bf16(a[2], a[3]); w.z = cvt_pk_bf16(b[0], b[1]); w.w = cvt_pk_bf16(b[2], b[3]); return w; }
; __device__ __forceinline__ void unpack8(const u32x4 w, f32x4& a, f32x4& b) { a[0] = bf_lo(w.x); a[1] = bf_hi(w.x); a[2] = bf_lo(w.y); a[3] = bf_hi(w.y); b[0] = bf_lo(w.z); b[1] = bf_hi(w.z); b[2] = bf_lo(w.w); b[3] = bf_hi(w.w); }
; #define MEMFENCE asm volatile("" ::: "memory")
;     template <int KIND> __device__ __forceinline__ void run(f32x4 (&acc)[2][2][4][2], const Unit& u, int tid_in) const {
;     ...
;         if constexpr (KIND == K_GLU) {
; #pragma unroll
;             for (int ai = 0; ai < 2; ++ai) { u32x4 yv[4][2];
; #pragma unroll
;                 for (int m = 0; m < 4; ++m) { int row = rbase + ai * 128 + m * 16; asm volatile("" : "+v"(row));
; #pragma unroll
;                     for (int bj = 0; bj < 2; ++bj) { const int col = u.pn * 256 + bj * 128 + cl; yv[m][bj] = *(const u32x4*)(yi + ((size_t)(col >> 4) * T_TOK + row) * 16 + (col & 15)); } }
; #pragma unroll
;                 for (int m = 0; m < 4; ++m) { int row = rbase + ai * 128 + m * 16; asm volatile("" : "+v"(row));
; #pragma unroll
;                     for (int bj = 0; bj < 2; ++bj) { const int col = u.pn * 256 + bj * 128 + cl; f32x4 y0, y1; unpack8(yv[m][bj], y0, y1);
; #pragma unroll
;                         for (int j = 0; j < 4; ++j) { y0[j] *= sigmoidf_(acc[ai][bj][m][0][j]); y1[j] *= sigmoidf_(acc[ai][bj][m][1][j]); }
;                         *(u32x4*)(zb + (size_t)row * ZW + 1024 + col) = pack8(y0, y1); } }
;                 MEMFENCE; }
	v_exp_f32_e32 v41, v41
	v_exp_f32_e32 v42, v42
	v_add_f32_e32 v48, 1.0, v48
	v_add_f32_e32 v49, 1.0, v49
	v_add_f32_e32 v50, 1.0, v50
	v_rcp_f32_e32 v48, v48
	v_rcp_f32_e32 v49, v49
	v_rcp_f32_e32 v50, v50
	v_add_f32_e32 v51, 1.0, v51
	v_rcp_f32_e32 v51, v51
	v_add_f32_e32 v44, 1.0, v44
	v_add_f32_e32 v40, 1.0, v40
	v_add_f32_e32 v41, 1.0, v41
	v_add_f32_e32 v42, 1.0, v42
	v_and_b32_e32 v59, 0xffff0000, v92
	v_mad_i64_i32 v[56:57], s[2:3], v103, s76, v[172:173]
	v_lshlrev_b32_e32 v60, 16, v93
	v_and_b32_e32 v61, 0xffff0000, v93
	v_rcp_f32_e32 v44, v44
	v_rcp_f32_e32 v40, v40
	v_rcp_f32_e32 v41, v41
	v_rcp_f32_e32 v42, v42
	v_lshl_add_u64 v[56:57], v[56:57], 0, s[4:5]
	v_and_b32_e32 v65, 0xffff0000, v95
	v_mul_f32_e32 v48, v48, v59
	v_mul_f32_e32 v49, v49, v60
	v_mul_f32_e32 v50, v50, v61
	v_mul_f32_e32 v51, v51, v65
	v_cvt_pk_bf16_f32 v48, v52, v48
	v_cvt_pk_bf16_f32 v49, v49, v50
	v_cvt_pk_bf16_f32 v50, v58, v53
	v_lshl_add_u64 v[52:53], v[56:57], 0, v[140:141]
	v_cvt_pk_bf16_f32 v51, v54, v51
	global_store_dwordx4 v[52:53], v[48:51], off
	v_lshlrev_b32_e32 v52, 16, v90
	v_and_b32_e32 v53, 0xffff0000, v90
	v_lshlrev_b32_e32 v48, 16, v88
	v_lshlrev_b32_e32 v54, 16, v91
	v_mul_f32_e32 v44, v44, v48
	v_mul_f32_e32 v48, v40, v52
	v_mul_f32_e32 v40, 0xbfb8aa3b, v45
	v_mul_f32_e32 v45, v41, v53
	v_mul_f32_e32 v41, 0xbfb8aa3b, v46
	v_mul_f32_e32 v46, v42, v54
	v_mul_f32_e32 v42, 0xbfb8aa3b, v47
	v_exp_f32_e32 v40, v40
	v_exp_f32_e32 v41, v41
	v_exp_f32_e32 v42, v42
	v_mul_f32_e32 v43, 0xbfb8aa3b, v43
	v_exp_f32_e32 v43, v43
	v_mul_f32_e32 v36, 0xbfb8aa3b, v36
	v_mul_f32_e32 v32, 0xbfb8aa3b, v32
	v_mul_f32_e32 v33, 0xbfb8aa3b, v33
	v_mul_f32_e32 v34, 0xbfb8aa3b, v34
	v_exp_f32_e32 v36, v36
	v_exp_f32_e32 v32, v32
	v_exp_f32_e32 v33, v33
	v_exp_f32_e32 v34, v34
	v_add_f32_e32 v40, 1.0, v40
	v_add_f32_e32 v41, 1.0, v41
	v_add_f32_e32 v42, 1.0, v42
	v_rcp_f32_e32 v40, v40
	v_rcp_f32_e32 v41, v41
	v_rcp_f32_e32 v42, v42
	v_add_f32_e32 v43, 1.0, v43
	v_rcp_f32_e32 v43, v43
	v_add_f32_e32 v36, 1.0, v36
	v_add_f32_e32 v32, 1.0, v32
	v_add_f32_e32 v33, 1.0, v33
	v_add_f32_e32 v34, 1.0, v34
	v_and_b32_e32 v49, 0xffff0000, v88
	v_lshlrev_b32_e32 v50, 16, v89
	v_and_b32_e32 v51, 0xffff0000, v89
	v_rcp_f32_e32 v36, v36
	v_rcp_f32_e32 v32, v32
	v_rcp_f32_e32 v33, v33
	v_rcp_f32_e32 v34, v34
	v_and_b32_e32 v55, 0xffff0000, v91
	v_mul_f32_e32 v40, v40, v49
	v_mul_f32_e32 v41, v41, v50
	v_mul_f32_e32 v42, v42, v51
	v_mul_f32_e32 v43, v43, v55
	v_cvt_pk_bf16_f32 v40, v44, v40
	v_cvt_pk_bf16_f32 v41, v41, v42
	v_cvt_pk_bf16_f32 v42, v48, v45
	v_lshl_add_u64 v[44:45], v[56:57], 0, v[128:129]
	v_cvt_pk_bf16_f32 v43, v46, v43
	global_store_dwordx4 v[44:45], v[40:43], off
	v_lshlrev_b32_e32 v46, 16, v86
	v_and_b32_e32 v47, 0xffff0000, v86
	v_lshlrev_b32_e32 v42, 16, v84
	v_lshlrev_b32_e32 v48, 16, v87
	v_mul_f32_e32 v36, v36, v42
	v_mul_f32_e32 v42, v32, v46
	v_mul_f32_e32 v32, 0xbfb8aa3b, v37
	v_mul_f32_e32 v37, v33, v47
	v_mul_f32_e32 v33, 0xbfb8aa3b, v38
	v_mul_f32_e32 v38, v34, v48
	v_mul_f32_e32 v34, 0xbfb8aa3b, v39
	v_exp_f32_e32 v32, v32
	v_exp_f32_e32 v33, v33
	v_exp_f32_e32 v34, v34
	v_mul_f32_e32 v35, 0xbfb8aa3b, v35
	v_exp_f32_e32 v35, v35
	v_mul_f32_e32 v28, 0xbfb8aa3b, v28
	v_mul_f32_e32 v24, 0xbfb8aa3b, v24
	v_mul_f32_e32 v25, 0xbfb8aa3b, v25
	v_mul_f32_e32 v26, 0xbfb8aa3b, v26
	v_exp_f32_e32 v28, v28
	v_exp_f32_e32 v24, v24
	v_exp_f32_e32 v25, v25
	v_exp_f32_e32 v26, v26
	v_add_f32_e32 v32, 1.0, v32
	v_add_f32_e32 v33, 1.0, v33
	v_add_f32_e32 v34, 1.0, v34
	v_rcp_f32_e32 v32, v32
	v_rcp_f32_e32 v33, v33
	v_rcp_f32_e32 v34, v34
	v_add_f32_e32 v35, 1.0, v35
	v_rcp_f32_e32 v35, v35
	v_add_f32_e32 v28, 1.0, v28
	v_add_f32_e32 v24, 1.0, v24
	v_add_f32_e32 v25, 1.0, v25
	v_add_f32_e32 v26, 1.0, v26
	v_and_b32_e32 v43, 0xffff0000, v84
	v_mad_i64_i32 v[40:41], s[2:3], v102, s76, v[172:173]
	v_lshlrev_b32_e32 v44, 16, v85
	v_and_b32_e32 v45, 0xffff0000, v85
	v_rcp_f32_e32 v28, v28
	v_rcp_f32_e32 v24, v24
	v_rcp_f32_e32 v25, v25
	v_rcp_f32_e32 v26, v26
	v_lshl_add_u64 v[40:41], v[40:41], 0, s[4:5]
	v_and_b32_e32 v49, 0xffff0000, v87
	v_mul_f32_e32 v32, v32, v43
	v_mul_f32_e32 v33, v33, v44
	v_mul_f32_e32 v34, v34, v45
	v_mul_f32_e32 v35, v35, v49
	v_cvt_pk_bf16_f32 v32, v36, v32
	v_cvt_pk_bf16_f32 v33, v33, v34
	v_cvt_pk_bf16_f32 v34, v42, v37
	v_lshl_add_u64 v[36:37], v[40:41], 0, v[140:141]
	v_cvt_pk_bf16_f32 v35, v38, v35
	global_store_dwordx4 v[36:37], v[32:35], off
	v_lshlrev_b32_e32 v36, 16, v82
	v_and_b32_e32 v37, 0xffff0000, v82
	v_lshlrev_b32_e32 v32, 16, v80
	v_lshlrev_b32_e32 v38, 16, v83
; __device__ __forceinline__ float sigmoidf_(float v) { return __builtin_amdgcn_rcpf(1.0f + __expf(-v)); }
; __device__ __forceinline__ u32x4 pack8(const f32x4 a, const f32x4 b) { u32x4 w; w.x = cvt_pk_bf16(a[0], a[1]); w.y = cvt_pk_bf16(a[2], a[3]); w.z = cvt_pk_bf16(b[0], b[1]); w.w = cvt_pk_bf16(b[2], b[3]); return w; }
; __device__ __forceinline__ void unpack8(const u32x4 w, f32x4& a, f32x4& b) { a[0] = bf_lo(w.x); a[1] = bf_hi(w.x); a[2] = bf_lo(w.y); a[3] = bf_hi(w.y); b[0] = bf_lo(w.z); b[1] = bf_hi(w.z); b[2] = bf_lo(w.w); b[3] = bf_hi(w.w); }
; #define MEMFENCE asm volatile("" ::: "memory")
;     template <int KIND> __device__ __forceinline__ void run(f32x4 (&acc)[2][2][4][2], const Unit& u, int tid_in) const {
;     ...
;         if constexpr (KIND == K_GLU) {
; #pragma unroll
;             for (int ai = 0; ai < 2; ++ai) { u32x4 yv[4][2];
; #pragma unroll
;                 for (int m = 0; m < 4; ++m) { int row = rbase + ai * 128 + m * 16; asm volatile("" : "+v"(row));
; #pragma unroll
;                     for (int bj = 0; bj < 2; ++bj) { const int col = u.pn * 256 + bj * 128 + cl; yv[m][bj] = *(const u32x4*)(yi + ((size_t)(col >> 4) * T_TOK + row) * 16 + (col & 15)); } }
; #pragma unroll
;                 for (int m = 0; m < 4; ++m) { int row = rbase + ai * 128 + m * 16; asm volatile("" : "+v"(row));
; #pragma unroll
;                     for (int bj = 0; bj < 2; ++bj) { const int col = u.pn * 256 + bj * 128 + cl; f32x4 y0, y1; unpack8(yv[m][bj], y0, y1);
; #pragma unroll
;                         for (int j = 0; j < 4; ++j) { y0[j] *= sigmoidf_(acc[ai][bj][m][0][j]); y1[j] *= sigmoidf_(acc[ai][bj][m][1][j]); }
;                         *(u32x4*)(zb + (size_t)row * ZW + 1024 + col) = pack8(y0, y1); } }
;                 MEMFENCE; }
;     ...
;         if (!has_next) break;
;         if (!(cs.kind == K_MG_B && cur.aux < 2))
	v_mul_f32_e32 v28, v28, v32
	v_mul_f32_e32 v32, v24, v36
	v_mul_f32_e32 v24, 0xbfb8aa3b, v29
	v_mul_f32_e32 v29, v25, v37
	v_mul_f32_e32 v25, 0xbfb8aa3b, v30
	v_mul_f32_e32 v30, v26, v38
	v_mul_f32_e32 v26, 0xbfb8aa3b, v31
	v_exp_f32_e32 v24, v24
	v_exp_f32_e32 v25, v25
	v_exp_f32_e32 v26, v26
	v_mul_f32_e32 v27, 0xbfb8aa3b, v27
	v_exp_f32_e32 v27, v27
	v_mul_f32_e32 v20, 0xbfb8aa3b, v20
	v_mul_f32_e32 v16, 0xbfb8aa3b, v16
	v_mul_f32_e32 v17, 0xbfb8aa3b, v17
	v_mul_f32_e32 v18, 0xbfb8aa3b, v18
	v_add_f32_e32 v24, 1.0, v24
	v_add_f32_e32 v25, 1.0, v25
	v_add_f32_e32 v26, 1.0, v26
	v_exp_f32_e32 v20, v20
	v_exp_f32_e32 v16, v16
	v_exp_f32_e32 v17, v17
	v_exp_f32_e32 v18, v18
	v_rcp_f32_e32 v24, v24
	v_rcp_f32_e32 v25, v25
	v_rcp_f32_e32 v26, v26
	v_add_f32_e32 v27, 1.0, v27
	v_rcp_f32_e32 v27, v27
	v_and_b32_e32 v33, 0xffff0000, v80
	v_lshlrev_b32_e32 v34, 16, v81
	v_and_b32_e32 v35, 0xffff0000, v81
	v_add_f32_e32 v20, 1.0, v20
	v_add_f32_e32 v16, 1.0, v16
	v_add_f32_e32 v17, 1.0, v17
	v_add_f32_e32 v18, 1.0, v18
	v_and_b32_e32 v39, 0xffff0000, v83
	v_mul_f32_e32 v24, v24, v33
	v_mul_f32_e32 v25, v25, v34
	v_mul_f32_e32 v26, v26, v35
	v_rcp_f32_e32 v20, v20
	v_rcp_f32_e32 v16, v16
	v_rcp_f32_e32 v17, v17
	v_rcp_f32_e32 v18, v18
	v_mul_f32_e32 v27, v27, v39
	v_cvt_pk_bf16_f32 v24, v28, v24
	v_cvt_pk_bf16_f32 v25, v25, v26
	v_cvt_pk_bf16_f32 v26, v32, v29
	v_lshl_add_u64 v[28:29], v[40:41], 0, v[128:129]
	v_cvt_pk_bf16_f32 v27, v30, v27
	global_store_dwordx4 v[28:29], v[24:27], off
	v_lshlrev_b32_e32 v29, 16, v78
	v_and_b32_e32 v30, 0xffff0000, v78
	v_mad_i64_i32 v[24:25], s[2:3], v0, s76, v[172:173]
	v_lshlrev_b32_e32 v0, 16, v76
	v_lshlrev_b32_e32 v31, 16, v79
	v_mul_f32_e32 v0, v20, v0
	v_mul_f32_e32 v20, v16, v29
	v_mul_f32_e32 v16, 0xbfb8aa3b, v21
	v_mul_f32_e32 v21, v17, v30
	v_mul_f32_e32 v17, 0xbfb8aa3b, v22
	v_mul_f32_e32 v22, v18, v31
	v_mul_f32_e32 v18, 0xbfb8aa3b, v23
	v_mul_f32_e32 v19, 0xbfb8aa3b, v19
	v_exp_f32_e32 v16, v16
	v_exp_f32_e32 v17, v17
	v_exp_f32_e32 v18, v18
	v_exp_f32_e32 v19, v19
	v_mul_f32_e32 v12, 0xbfb8aa3b, v12
	v_mul_f32_e32 v8, 0xbfb8aa3b, v8
	v_mul_f32_e32 v9, 0xbfb8aa3b, v9
	v_mul_f32_e32 v10, 0xbfb8aa3b, v10
	v_exp_f32_e32 v12, v12
	v_exp_f32_e32 v8, v8
	v_exp_f32_e32 v9, v9
	v_exp_f32_e32 v10, v10
	v_add_f32_e32 v16, 1.0, v16
	v_add_f32_e32 v17, 1.0, v17
	v_add_f32_e32 v18, 1.0, v18
	v_add_f32_e32 v19, 1.0, v19
	v_rcp_f32_e32 v16, v16
	v_rcp_f32_e32 v17, v17
	v_rcp_f32_e32 v18, v18
	v_rcp_f32_e32 v19, v19
	v_add_f32_e32 v12, 1.0, v12
	v_add_f32_e32 v8, 1.0, v8
	v_add_f32_e32 v9, 1.0, v9
	v_add_f32_e32 v10, 1.0, v10
	v_and_b32_e32 v26, 0xffff0000, v76
	v_lshlrev_b32_e32 v27, 16, v77
	v_and_b32_e32 v28, 0xffff0000, v77
	v_and_b32_e32 v32, 0xffff0000, v79
	v_rcp_f32_e32 v12, v12
	v_rcp_f32_e32 v8, v8
	v_rcp_f32_e32 v9, v9
	v_rcp_f32_e32 v10, v10
	v_lshl_add_u64 v[24:25], v[24:25], 0, s[4:5]
	v_mul_f32_e32 v16, v16, v26
	v_mul_f32_e32 v17, v17, v27
	v_mul_f32_e32 v18, v18, v28
	v_mul_f32_e32 v19, v19, v32
	v_cvt_pk_bf16_f32 v16, v0, v16
	v_cvt_pk_bf16_f32 v17, v17, v18
	v_cvt_pk_bf16_f32 v18, v20, v21
	v_cvt_pk_bf16_f32 v19, v22, v19
	v_lshl_add_u64 v[20:21], v[24:25], 0, v[140:141]
	global_store_dwordx4 v[20:21], v[16:19], off
	v_lshlrev_b32_e32 v0, 16, v72
	v_and_b32_e32 v20, 0xffff0000, v74
	v_lshlrev_b32_e32 v19, 16, v74
	v_lshlrev_b32_e32 v21, 16, v75
	v_mul_f32_e32 v0, v12, v0
	v_mul_f32_e32 v12, v8, v19
	v_mul_f32_e32 v8, 0xbfb8aa3b, v13
	v_mul_f32_e32 v13, v9, v20
	v_mul_f32_e32 v9, 0xbfb8aa3b, v14
	v_mul_f32_e32 v14, v10, v21
	v_mul_f32_e32 v10, 0xbfb8aa3b, v15
	v_exp_f32_e32 v8, v8
	v_exp_f32_e32 v9, v9
	v_exp_f32_e32 v10, v10
	v_mul_f32_e32 v11, 0xbfb8aa3b, v11
	v_exp_f32_e32 v11, v11
	v_add_f32_e32 v8, 1.0, v8
	v_add_f32_e32 v9, 1.0, v9
	v_add_f32_e32 v10, 1.0, v10
	v_rcp_f32_e32 v8, v8
	v_rcp_f32_e32 v9, v9
	v_rcp_f32_e32 v10, v10
	v_add_f32_e32 v11, 1.0, v11
	v_rcp_f32_e32 v11, v11
	v_and_b32_e32 v16, 0xffff0000, v72
	v_lshlrev_b32_e32 v17, 16, v73
	v_and_b32_e32 v18, 0xffff0000, v73
	v_and_b32_e32 v22, 0xffff0000, v75
	v_mul_f32_e32 v8, v8, v16
	v_mul_f32_e32 v9, v9, v17
	v_mul_f32_e32 v10, v10, v18
	v_mul_f32_e32 v11, v11, v22
	v_cvt_pk_bf16_f32 v8, v0, v8
	v_cvt_pk_bf16_f32 v9, v9, v10
	v_cvt_pk_bf16_f32 v10, v12, v13
	v_lshl_add_u64 v[12:13], v[24:25], 0, v[128:129]
	v_cvt_pk_bf16_f32 v11, v14, v11
	global_store_dwordx4 v[12:13], v[8:11], off
	s_and_b64 vcc, exec, s[10:11]
	s_mov_b32 s33, s34
	s_mov_b32 s35, s12
	s_mov_b64 s[18:19], s[16:17]
	s_mov_b64 s[2:3], s[14:15]
	s_cbranch_vccz .LBB0_799
	s_cmp_eq_u32 s101, 2
	s_cbranch_scc0 .Ldbj_GLU_pe
	s_barrier

; #define G_STAGE(bufoff, gbase, o0, h64) do { \
;         __builtin_amdgcn_global_load_lds((const unsigned*)((const char*)(gbase) + (o0)), (LAS unsigned*)(lds + (bufoff) + ldsw), 16, 0, 0); \
;         __builtin_amdgcn_global_load_lds((const unsigned*)((const char*)(gbase) + (h64) + (o0)), (LAS unsigned*)(lds + (bufoff) + ldsw + 8192), 16, 0, 0); } while (0)
; #define G_LDA(dst, b, h) do { _Pragma("unroll") for (int m = 0; m < 4; ++m) _Pragma("unroll") for (int k = 0; k < 2; ++k) dst[m][k] = *(const LAS bf16x8*)(lds + G_SA(b, h) + aoff + m * 2048 + k * 1024); } while (0)
; #define G_LDB(dst, b, h) do { _Pragma("unroll") for (int n = 0; n < 2; ++n) _Pragma("unroll") for (int k = 0; k < 2; ++k) dst[n][k] = *(const LAS bf16x8*)(lds + G_SB(b, h) + boff + n * 2048 + k * 1024); } while (0)
; #define G_WAIT_L(n) asm volatile("s_waitcnt lgkmcnt(" #n ")" ::: "memory")
; #define G_BAR __builtin_amdgcn_s_barrier()
; #define G_SCHED __builtin_amdgcn_sched_barrier(0)
;     ...
;         for (int t = 0; t < nt; t += 2) {
;             const bool last = (t == nt - 2);
;             const char* a1 = cA + (size_t)(t + 1) * ckA;
;             const char* a2 = last ? nA : cA + (size_t)(t + 2) * ckA; const char* b2 = last ? nB : cB + (size_t)(t + 2) * kB;
;             const char* a3 = a2 + ckA; const char* b3 = b2 + kB;
;             G_LDB(B0, 0, 0); G_SCHED; G_LDA(At, 0, 0); G_STAGE(G_SA(1, 1), a1 + chA, cA0, qA);
;             G_WAIT_L(8); G_BAR; G_WAIT_L(0); G_MMA(0, 0, At, B0); G_BAR; G_SCHED;
;             G_LDB(B1, 0, 1); G_STAGE(G_SB(0, 0), b2, cB0, qB);
;             G_BAR; G_WAIT_L(0); G_MMA(0, 1, At, B1); G_BAR;
;     ...
;         if (!(cs.kind == K_MG_B && cur.aux < 2))
; #pragma unroll
;         for (int a = 0; a < 2; ++a)
; #pragma unroll
;             for (int b = 0; b < 2; ++b)
; #pragma unroll
;                 for (int m = 0; m < 4; ++m)
; #pragma unroll
;                     for (int n = 0; n < 2; ++n) acc[a][b][m][n] = (f32x4){0.f, 0.f, 0.f, 0.f};
;         cur = nxt; cA = nA; cB = nB; ++ui;
.LBB0_871:
	s_add_u32 s2, s2, 0xb0080
	s_addc_u32 s3, s3, 0
	s_add_u32 s37, s12, 0x100
	v_mov_b64_e32 v[8:9], 0
	s_addc_u32 s38, s13, 0
	s_mov_b32 s39, -2
	v_mov_b64_e32 v[10:11], 0
	v_mov_b64_e32 v[12:13], 0
	v_mov_b64_e32 v[14:15], 0
	v_mov_b64_e32 v[24:25], 0
	v_mov_b64_e32 v[26:27], 0
	v_mov_b64_e32 v[28:29], 0
	v_mov_b64_e32 v[30:31], 0
	v_mov_b64_e32 v[40:41], 0
	v_mov_b64_e32 v[42:43], 0
	v_mov_b64_e32 v[44:45], 0
	v_mov_b64_e32 v[46:47], 0
	v_mov_b64_e32 v[56:57], 0
	v_mov_b64_e32 v[58:59], 0
	v_mov_b64_e32 v[60:61], 0
	v_mov_b64_e32 v[62:63], 0
	v_mov_b64_e32 v[16:17], 0
	v_mov_b64_e32 v[18:19], 0
	v_mov_b64_e32 v[20:21], 0
	v_mov_b64_e32 v[22:23], 0
	v_mov_b64_e32 v[36:37], 0
	v_mov_b64_e32 v[38:39], 0
	v_mov_b64_e32 v[32:33], 0
	v_mov_b64_e32 v[34:35], 0
	v_mov_b64_e32 v[52:53], 0
	v_mov_b64_e32 v[54:55], 0
	v_mov_b64_e32 v[48:49], 0
	v_mov_b64_e32 v[50:51], 0
	v_mov_b64_e32 v[68:69], 0
	v_mov_b64_e32 v[70:71], 0
	v_mov_b64_e32 v[64:65], 0
	v_mov_b64_e32 v[66:67], 0
	v_mov_b64_e32 v[72:73], 0
	v_mov_b64_e32 v[74:75], 0
	v_mov_b64_e32 v[76:77], 0
	v_mov_b64_e32 v[78:79], 0
	v_mov_b64_e32 v[88:89], 0
	v_mov_b64_e32 v[90:91], 0
	v_mov_b64_e32 v[92:93], 0
	v_mov_b64_e32 v[94:95], 0
	v_mov_b64_e32 v[104:105], 0
	v_mov_b64_e32 v[106:107], 0
	v_mov_b64_e32 v[108:109], 0
	v_mov_b64_e32 v[110:111], 0
	v_mov_b64_e32 v[120:121], 0
	v_mov_b64_e32 v[122:123], 0
	v_mov_b64_e32 v[124:125], 0
	v_mov_b64_e32 v[126:127], 0
	v_mov_b64_e32 v[84:85], 0
	v_mov_b64_e32 v[86:87], 0
	v_mov_b64_e32 v[80:81], 0
	v_mov_b64_e32 v[82:83], 0
	v_mov_b64_e32 v[100:101], 0
	v_mov_b64_e32 v[102:103], 0
	v_mov_b64_e32 v[96:97], 0
	v_mov_b64_e32 v[98:99], 0
	v_mov_b64_e32 v[116:117], 0
	v_mov_b64_e32 v[118:119], 0
	v_mov_b64_e32 v[112:113], 0
	v_mov_b64_e32 v[114:115], 0
	v_mov_b64_e32 v[132:133], 0
	v_mov_b64_e32 v[134:135], 0
	v_mov_b64_e32 v[128:129], 0
	v_mov_b64_e32 v[130:131], 0
	s_mov_b64 s[42:43], 0x20080
	s_mov_b64 s[50:51], 0x10000
	s_mov_b64 s[52:53], 0x30000
	s_mov_b64 s[54:55], 0x10080
	s_mov_b64 s[58:59], 0x30080
	s_cmp_eq_u32 s101, 2
	s_cselect_b32 s101, 0, s101
	v_add_u32_e32 v239, 0x10000, v159
	ds_read_b128 v[144:147], v239 offset:0
	ds_read_b128 v[148:151], v239 offset:1024
	ds_read_b128 v[136:139], v239 offset:2048
	ds_read_b128 v[140:143], v239 offset:3072
.LBB0_872:
	s_add_u32 s4, s2, 0xfff50080
	s_addc_u32 s5, s3, -1
	s_add_i32 s40, 0, 0x10000
	s_cmp_eq_u32 s39, 4
	s_cselect_b32 s13, s9, s5
	s_cselect_b32 s12, s8, s4
	s_cselect_b32 s15, s11, s38
	s_cselect_b32 s14, s10, s37
	s_add_i32 m0, s22, 0xc000
	ds_read_b128 v[160:163], v236
	ds_read_b128 v[164:167], v236 offset:1024
	ds_read_b128 v[176:179], v236 offset:2048
	ds_read_b128 v[180:183], v236 offset:3072
	ds_read_b128 v[196:199], v236 offset:4096
	ds_read_b128 v[200:203], v236 offset:5120
	ds_read_b128 v[204:207], v236 offset:6144
	ds_read_b128 v[208:211], v236 offset:7168
	global_load_lds_dwordx4 v152, s[2:3]
	s_add_i32 m0, s22, 0xe000
	s_nop 0
	s_add_u32 vcc_lo, s2, s86
	s_addc_u32 vcc_hi, s3, s87
	global_load_lds_dwordx4 v152, vcc
	s_waitcnt lgkmcnt(8)
	s_cmp_eq_u32 s101, 1
	s_cbranch_scc1 .Ldb_MG0_sk
	s_barrier
.Ldb_MG0_sk:
	s_mov_b32 s101, 0
	s_waitcnt lgkmcnt(0)
	v_mfma_f32_16x16x128_f8f6f4 v[128:131], v[144:151], v[160:167], v[128:131]
	v_mfma_f32_16x16x128_f8f6f4 v[132:135], v[136:143], v[160:167], v[132:135]
	v_mfma_f32_16x16x128_f8f6f4 v[112:115], v[144:151], v[176:183], v[112:115]
	v_mfma_f32_16x16x128_f8f6f4 v[116:119], v[136:143], v[176:183], v[116:119]
	v_mfma_f32_16x16x128_f8f6f4 v[96:99], v[144:151], v[196:203], v[96:99]
	v_mfma_f32_16x16x128_f8f6f4 v[100:103], v[136:143], v[196:203], v[100:103]
	v_mfma_f32_16x16x128_f8f6f4 v[80:83], v[144:151], v[204:211], v[80:83]
	v_mfma_f32_16x16x128_f8f6f4 v[84:87], v[136:143], v[204:211], v[84:87]
	s_barrier
	s_add_i32 s4, 0, 0x14000
	s_add_i32 s5, s40, s17
	ds_read_b128 v[212:215], v239 offset:16384
	ds_read_b128 v[216:219], v239 offset:17408
	ds_read_b128 v[220:223], v239 offset:18432
	ds_read_b128 v[224:227], v239 offset:19456
	s_mov_b32 m0, s5
	global_load_lds_dwordx4 v0, s[14:15]
	s_add_i32 m0, s5, 0x2000
	s_nop 0
	s_add_u32 vcc_lo, s14, s50
	s_addc_u32 vcc_hi, s15, s51
	global_load_lds_dwordx4 v0, vcc
	s_barrier
	s_waitcnt lgkmcnt(0)
	v_mfma_f32_16x16x128_f8f6f4 v[124:127], v[212:219], v[160:167], v[124:127]
	v_mfma_f32_16x16x128_f8f6f4 v[120:123], v[220:227], v[160:167], v[120:123]
	v_mfma_f32_16x16x128_f8f6f4 v[108:111], v[212:219], v[176:183], v[108:111]
	v_mfma_f32_16x16x128_f8f6f4 v[104:107], v[220:227], v[176:183], v[104:107]
	v_mfma_f32_16x16x128_f8f6f4 v[92:95], v[212:219], v[196:203], v[92:95]
	v_mfma_f32_16x16x128_f8f6f4 v[88:91], v[220:227], v[196:203], v[88:91]
	v_mfma_f32_16x16x128_f8f6f4 v[76:79], v[212:219], v[204:211], v[76:79]
	v_mfma_f32_16x16x128_f8f6f4 v[72:75], v[220:227], v[204:211], v[72:75]
	s_barrier
	s_mov_b32 m0, s22
	ds_read_b128 v[160:163], v236 offset:16384
	ds_read_b128 v[164:167], v236 offset:17408
	ds_read_b128 v[176:179], v236 offset:18432
	ds_read_b128 v[180:183], v236 offset:19456
	ds_read_b128 v[196:199], v236 offset:20480
	ds_read_b128 v[200:203], v236 offset:21504
	ds_read_b128 v[204:207], v236 offset:22528
	ds_read_b128 v[208:211], v236 offset:23552
	global_load_lds_dwordx4 v2, s[12:13]
	s_mov_b32 m0, s23
	s_nop 0
	s_add_u32 vcc_lo, s12, s86
	s_addc_u32 vcc_hi, s13, s87
	global_load_lds_dwordx4 v2, vcc
	s_barrier
; #define G_STAGE(bufoff, gbase, o0, h64) do { \
;         __builtin_amdgcn_global_load_lds((const unsigned*)((const char*)(gbase) + (o0)), (LAS unsigned*)(lds + (bufoff) + ldsw), 16, 0, 0); \
;         __builtin_amdgcn_global_load_lds((const unsigned*)((const char*)(gbase) + (h64) + (o0)), (LAS unsigned*)(lds + (bufoff) + ldsw + 8192), 16, 0, 0); } while (0)
; #define G_LDA(dst, b, h) do { _Pragma("unroll") for (int m = 0; m < 4; ++m) _Pragma("unroll") for (int k = 0; k < 2; ++k) dst[m][k] = *(const LAS bf16x8*)(lds + G_SA(b, h) + aoff + m * 2048 + k * 1024); } while (0)
; #define G_LDB(dst, b, h) do { _Pragma("unroll") for (int n = 0; n < 2; ++n) _Pragma("unroll") for (int k = 0; k < 2; ++k) dst[n][k] = *(const LAS bf16x8*)(lds + G_SB(b, h) + boff + n * 2048 + k * 1024); } while (0)
; #define G_WAIT_V(n) asm volatile("s_waitcnt vmcnt(" #n ")" ::: "memory")
; #define G_WAIT_L(n) asm volatile("s_waitcnt lgkmcnt(" #n ")" ::: "memory")
; #define G_BAR __builtin_amdgcn_s_barrier()
; #define G_SCHED __builtin_amdgcn_sched_barrier(0)
;     ...
;             G_LDB(B1, 0, 1); G_STAGE(G_SB(0, 0), b2, cB0, qB);
;             G_BAR; G_WAIT_L(0); G_MMA(0, 1, At, B1); G_BAR;
;             G_LDA(At, 0, 1); G_STAGE(G_SA(0, 0), a2, cA0, qA);
;             G_BAR; G_WAIT_L(0); G_MMA(1, 0, At, B0); G_BAR; G_SCHED;
;             G_STAGE(G_SB(0, 1), b2 + chB, cB0, qB);
;             G_WAIT_V(6); G_BAR; G_MMA(1, 1, At, B1); G_BAR;
;             G_LDB(B0, 1, 0); G_SCHED; G_LDA(At, 1, 0); G_STAGE(G_SA(0, 1), a2 + chA, cA0, qA);
;             G_WAIT_L(8); G_BAR; G_WAIT_L(0); G_MMA(0, 0, At, B0); G_BAR; G_SCHED;
;             G_LDB(B1, 1, 1); G_STAGE(G_SB(1, 0), b3, cB0, qB);
;             G_BAR; G_WAIT_L(0); G_MMA(0, 1, At, B1); G_BAR;
;             G_LDA(At, 1, 1); G_STAGE(G_SA(1, 0), a3, cA0, qA);
;             G_BAR; G_WAIT_L(0); G_MMA(1, 0, At, B0); G_BAR; G_SCHED;
;             G_STAGE(G_SB(1, 1), b3 + chB, cB0, qB);
;             G_WAIT_V(6); G_BAR; G_MMA(1, 1, At, B1); G_BAR;
	s_waitcnt lgkmcnt(0)
	v_mfma_f32_16x16x128_f8f6f4 v[64:67], v[144:151], v[160:167], v[64:67]
	v_mfma_f32_16x16x128_f8f6f4 v[68:71], v[136:143], v[160:167], v[68:71]
	v_mfma_f32_16x16x128_f8f6f4 v[48:51], v[144:151], v[176:183], v[48:51]
	v_mfma_f32_16x16x128_f8f6f4 v[52:55], v[136:143], v[176:183], v[52:55]
	v_mfma_f32_16x16x128_f8f6f4 v[32:35], v[144:151], v[196:203], v[32:35]
	v_mfma_f32_16x16x128_f8f6f4 v[36:39], v[136:143], v[196:203], v[36:39]
	v_mfma_f32_16x16x128_f8f6f4 v[20:23], v[144:151], v[204:211], v[20:23]
	v_mfma_f32_16x16x128_f8f6f4 v[16:19], v[136:143], v[204:211], v[16:19]
	s_barrier
	s_add_i32 s4, s4, s17
	s_mov_b32 m0, s4
	s_nop 0
	s_add_u32 vcc_lo, s14, s0
	s_addc_u32 vcc_hi, s15, s1
	global_load_lds_dwordx4 v0, vcc
	s_add_i32 m0, s4, 0x2000
	s_nop 0
	s_add_u32 vcc_lo, s14, s52
	s_addc_u32 vcc_hi, s15, s53
	global_load_lds_dwordx4 v0, vcc
	s_waitcnt vmcnt(6)
	s_barrier
	v_mfma_f32_16x16x128_f8f6f4 v[60:63], v[212:219], v[160:167], v[60:63]
	v_mfma_f32_16x16x128_f8f6f4 v[56:59], v[220:227], v[160:167], v[56:59]
	v_mfma_f32_16x16x128_f8f6f4 v[44:47], v[212:219], v[176:183], v[44:47]
	v_mfma_f32_16x16x128_f8f6f4 v[40:43], v[220:227], v[176:183], v[40:43]
	ds_read_b128 v[144:147], v239 offset:32768
	ds_read_b128 v[148:151], v239 offset:33792
	ds_read_b128 v[136:139], v239 offset:34816
	ds_read_b128 v[140:143], v239 offset:35840
	v_mfma_f32_16x16x128_f8f6f4 v[28:31], v[212:219], v[196:203], v[28:31]
	v_mfma_f32_16x16x128_f8f6f4 v[24:27], v[220:227], v[196:203], v[24:27]
	v_mfma_f32_16x16x128_f8f6f4 v[12:15], v[212:219], v[204:211], v[12:15]
	v_mfma_f32_16x16x128_f8f6f4 v[8:11], v[220:227], v[204:211], v[8:11]
	s_barrier
	s_add_i32 s4, 0, 0x18000
	s_mov_b32 m0, s24
	ds_read_b128 v[160:163], v236 offset:32768
	ds_read_b128 v[164:167], v236 offset:33792
	ds_read_b128 v[176:179], v236 offset:34816
	ds_read_b128 v[180:183], v236 offset:35840
	ds_read_b128 v[196:199], v236 offset:36864
	ds_read_b128 v[200:203], v236 offset:37888
	ds_read_b128 v[204:207], v236 offset:38912
	ds_read_b128 v[208:211], v236 offset:39936
	s_add_u32 vcc_lo, s12, s88
	s_addc_u32 vcc_hi, s13, s89
	global_load_lds_dwordx4 v2, vcc
	s_mov_b32 m0, s25
	s_nop 0
	s_add_u32 vcc_lo, s12, s64
	s_addc_u32 vcc_hi, s13, s65
	global_load_lds_dwordx4 v2, vcc
	s_waitcnt lgkmcnt(8)
	s_barrier
	s_waitcnt lgkmcnt(0)
	v_mfma_f32_16x16x128_f8f6f4 v[128:131], v[144:151], v[160:167], v[128:131]
	v_mfma_f32_16x16x128_f8f6f4 v[132:135], v[136:143], v[160:167], v[132:135]
	v_mfma_f32_16x16x128_f8f6f4 v[112:115], v[144:151], v[176:183], v[112:115]
	v_mfma_f32_16x16x128_f8f6f4 v[116:119], v[136:143], v[176:183], v[116:119]
	v_mfma_f32_16x16x128_f8f6f4 v[96:99], v[144:151], v[196:203], v[96:99]
	v_mfma_f32_16x16x128_f8f6f4 v[100:103], v[136:143], v[196:203], v[100:103]
	v_mfma_f32_16x16x128_f8f6f4 v[80:83], v[144:151], v[204:211], v[80:83]
	v_mfma_f32_16x16x128_f8f6f4 v[84:87], v[136:143], v[204:211], v[84:87]
	s_barrier
	s_add_i32 s5, 0, 0x1c000
	s_add_i32 s4, s4, s17
	s_mov_b32 m0, s4
	ds_read_b128 v[212:215], v239 offset:49152
	ds_read_b128 v[216:219], v239 offset:50176
	ds_read_b128 v[220:223], v239 offset:51200
	ds_read_b128 v[224:227], v239 offset:52224
	s_add_u32 vcc_lo, s14, s46
	s_addc_u32 vcc_hi, s15, s47
	global_load_lds_dwordx4 v0, vcc
	s_add_i32 m0, s4, 0x2000
	s_nop 0
	s_add_u32 vcc_lo, s14, s54
	s_addc_u32 vcc_hi, s15, s55
	global_load_lds_dwordx4 v0, vcc
	s_barrier
	s_waitcnt lgkmcnt(0)
	v_mfma_f32_16x16x128_f8f6f4 v[124:127], v[212:219], v[160:167], v[124:127]
	v_mfma_f32_16x16x128_f8f6f4 v[120:123], v[220:227], v[160:167], v[120:123]
	v_mfma_f32_16x16x128_f8f6f4 v[108:111], v[212:219], v[176:183], v[108:111]
	v_mfma_f32_16x16x128_f8f6f4 v[104:107], v[220:227], v[176:183], v[104:107]
	v_mfma_f32_16x16x128_f8f6f4 v[92:95], v[212:219], v[196:203], v[92:95]
	v_mfma_f32_16x16x128_f8f6f4 v[88:91], v[220:227], v[196:203], v[88:91]
	v_mfma_f32_16x16x128_f8f6f4 v[76:79], v[212:219], v[204:211], v[76:79]
	v_mfma_f32_16x16x128_f8f6f4 v[72:75], v[220:227], v[204:211], v[72:75]
	s_barrier
	s_mov_b32 m0, s26
	ds_read_b128 v[160:163], v236 offset:49152
	ds_read_b128 v[164:167], v236 offset:50176
	ds_read_b128 v[176:179], v236 offset:51200
	ds_read_b128 v[180:183], v236 offset:52224
	ds_read_b128 v[196:199], v236 offset:53248
	ds_read_b128 v[200:203], v236 offset:54272
	ds_read_b128 v[204:207], v236 offset:55296
	ds_read_b128 v[208:211], v236 offset:56320
	s_add_u32 vcc_lo, s12, s46
	s_addc_u32 vcc_hi, s13, s47
	global_load_lds_dwordx4 v2, vcc
	s_mov_b32 m0, s27
	s_nop 0
	s_add_u32 vcc_lo, s12, s66
	s_addc_u32 vcc_hi, s13, s67
	global_load_lds_dwordx4 v2, vcc
	s_barrier
	s_waitcnt lgkmcnt(0)
	v_mfma_f32_16x16x128_f8f6f4 v[64:67], v[144:151], v[160:167], v[64:67]
	v_mfma_f32_16x16x128_f8f6f4 v[68:71], v[136:143], v[160:167], v[68:71]
	v_mfma_f32_16x16x128_f8f6f4 v[48:51], v[144:151], v[176:183], v[48:51]
	v_mfma_f32_16x16x128_f8f6f4 v[52:55], v[136:143], v[176:183], v[52:55]
	v_mfma_f32_16x16x128_f8f6f4 v[32:35], v[144:151], v[196:203], v[32:35]
	v_mfma_f32_16x16x128_f8f6f4 v[36:39], v[136:143], v[196:203], v[36:39]
	v_mfma_f32_16x16x128_f8f6f4 v[20:23], v[144:151], v[204:211], v[20:23]
	v_mfma_f32_16x16x128_f8f6f4 v[16:19], v[136:143], v[204:211], v[16:19]
	s_barrier
	s_add_i32 s4, s5, s17
	s_mov_b32 m0, s4
	s_nop 0
	s_add_u32 vcc_lo, s14, s42
	s_addc_u32 vcc_hi, s15, s43
	global_load_lds_dwordx4 v0, vcc
	s_add_i32 m0, s4, 0x2000
	s_nop 0
	s_add_u32 vcc_lo, s14, s58
	s_addc_u32 vcc_hi, s15, s59
	global_load_lds_dwordx4 v0, vcc
	s_add_i32 s39, s39, 2
	s_add_u32 s2, s2, 0x100
	s_addc_u32 s3, s3, 0
	s_add_u32 s37, s37, 0x100
	s_addc_u32 s38, s38, 0
	s_cmp_gt_u32 s39, 5
	s_waitcnt vmcnt(6)
	s_barrier
	v_mfma_f32_16x16x128_f8f6f4 v[60:63], v[212:219], v[160:167], v[60:63]
	v_mfma_f32_16x16x128_f8f6f4 v[56:59], v[220:227], v[160:167], v[56:59]
	v_mfma_f32_16x16x128_f8f6f4 v[44:47], v[212:219], v[176:183], v[44:47]
	v_mfma_f32_16x16x128_f8f6f4 v[40:43], v[220:227], v[176:183], v[40:43]
	ds_read_b128 v[144:147], v239 offset:0
	ds_read_b128 v[148:151], v239 offset:1024
	ds_read_b128 v[136:139], v239 offset:2048
	ds_read_b128 v[140:143], v239 offset:3072
	v_mfma_f32_16x16x128_f8f6f4 v[28:31], v[212:219], v[196:203], v[28:31]
	v_mfma_f32_16x16x128_f8f6f4 v[24:27], v[220:227], v[196:203], v[24:27]
	v_mfma_f32_16x16x128_f8f6f4 v[12:15], v[212:219], v[204:211], v[12:15]
	v_mfma_f32_16x16x128_f8f6f4 v[8:11], v[220:227], v[204:211], v[8:11]
	s_cbranch_scc0 .Ldb_MG0_cont
	v_readfirstlane_b32 s101, v186
	s_cmpk_gt_u32 s101, 0xff
	s_cbranch_scc1 .Ldb_MG0_young
	s_barrier
	s_mov_b32 s101, 1
	s_branch .Ldb_MG0_exit

; __device__ __forceinline__ float sigmoidf_(float v) { return __builtin_amdgcn_rcpf(1.0f + __expf(-v)); }
; #define MEMFENCE asm volatile("" ::: "memory")
;     __device__ __forceinline__ void get_rs(const Unit& u, int wr, int fr, float (&rs)[8]) const {
; #pragma unroll
;         for (int r8 = 0; r8 < 8; ++r8) rs[r8] = rstab[u.ord * 256 + (r8 >> 2) * 128 + wr * 64 + (r8 & 3) * 16 + fr];
;     }
;     template <int KIND> __device__ __forceinline__ void run(f32x4 (&acc)[2][2][4][2], const Unit& u, int tid_in) const {
;     ...
;         if constexpr (KIND == K_MG_G) { float rs[8]; get_rs(u, wr, fr, rs);
;             u32x4* gst = (u32x4*)((unsigned char*)x + 32 * MiB) + ((size_t)(blockIdx.x * 2 + (u.ord & 1)) * 3 + u.aux) * 4096;
; #pragma unroll
;             for (int ai = 0; ai < 2; ++ai)
; #pragma unroll
;                 for (int m = 0; m < 4; ++m) { const float r = rs[ai * 4 + m] * (1.0f / GATE_WSCALE); u32x4 w;
; #pragma unroll
;                     for (int bj = 0; bj < 2; ++bj) { f32x4 a = acc[ai][bj][m][0] * r, b = acc[ai][bj][m][1] * r;
; #pragma unroll
;                         for (int j = 0; j < 4; ++j) { a[j] = sigmoidf_(a[j]); b[j] = sigmoidf_(b[j]); }
;                         if (bj == 0) { w.x = pack4_u8c(a); w.y = pack4_u8c(b); } else { w.z = pack4_u8c(a); w.w = pack4_u8c(b); } }
;                     gst[(ai * 4 + m) * 512 + tid] = w; MEMFENCE; }
.Ldb_MG0_exit:
	s_waitcnt lgkmcnt(0)
	v_mov_b32_e32 v142, v158
	s_lshl_b32 s3, s33, 10
	v_readfirstlane_b32 s2, v142
	s_add_i32 s3, s3, 0
	s_and_b32 s2, s2, 0xffffff00
	v_and_b32_e32 v136, 15, v142
	s_add_i32 s3, s3, s2
	v_lshl_add_u32 v136, v136, 2, s3
	v_add_u32_e32 v136, 0x20010, v136
	ds_read2_b32 v[144:145], v136 offset1:16
	ds_read2_b32 v[140:141], v136 offset0:32 offset1:48
	ds_read2_b32 v[138:139], v136 offset0:128 offset1:144
	ds_read2_b32 v[136:137], v136 offset0:160 offset1:176
	s_and_b32 s2, s33, 1
	s_waitcnt lgkmcnt(0)
	v_mul_f32_e32 v144, 0x3c800000, v144
	v_pk_mul_f32 v[128:129], v[128:129], v[144:145] op_sel_hi:[1,0]
	v_pk_mul_f32 v[130:131], v[130:131], v[144:145] op_sel_hi:[1,0]
	v_mul_f32_e32 v128, 0xbfb8aa3b, v128
	v_mul_f32_e32 v129, 0xbfb8aa3b, v129
	v_mul_f32_e32 v131, 0xbfb8aa3b, v131
	v_exp_f32_e32 v128, v128
	v_exp_f32_e32 v129, v129
	v_mul_f32_e32 v130, 0xbfb8aa3b, v130
	v_exp_f32_e32 v131, v131
	v_exp_f32_e32 v130, v130
	v_add_f32_e32 v128, 1.0, v128
	v_add_f32_e32 v129, 1.0, v129
	s_or_b32 s2, s2, s60
	v_pk_mul_f32 v[132:133], v[132:133], v[144:145] op_sel_hi:[1,0]
	v_add_f32_e32 v131, 1.0, v131
	v_rcp_f32_e32 v128, v128
	v_rcp_f32_e32 v129, v129
	v_add_f32_e32 v130, 1.0, v130
	s_mul_hi_u32 s3, s2, 3
	s_mul_i32 s2, s2, 3
	s_ashr_i32 s4, s36, 31
	v_pk_mul_f32 v[134:135], v[134:135], v[144:145] op_sel_hi:[1,0]
	v_mul_f32_e32 v132, 0xbfb8aa3b, v132
	v_mul_f32_e32 v133, 0xbfb8aa3b, v133
	v_rcp_f32_e32 v131, v131
	v_rcp_f32_e32 v130, v130
	s_add_u32 s2, s2, s36
	v_mul_f32_e32 v135, 0xbfb8aa3b, v135
	v_exp_f32_e32 v132, v132
	v_exp_f32_e32 v133, v133
	v_mul_f32_e32 v134, 0xbfb8aa3b, v134
	s_addc_u32 s3, s3, s4
	v_exp_f32_e32 v135, v135
	v_exp_f32_e32 v134, v134
	s_mov_b32 s4, 0x437f0000
	v_fma_f32 v128, v128, s4, 0.5
	v_fma_f32 v129, v129, s4, 0.5
	v_max_f32_e32 v128, 1.0, v128
	v_max_f32_e32 v129, 1.0, v129
	v_fma_f32 v130, v130, s4, 0.5
	v_fma_f32 v131, v131, s4, 0.5
	v_add_f32_e32 v132, 1.0, v132
	v_add_f32_e32 v133, 1.0, v133
	v_cvt_u32_f32_e32 v128, v128
	v_cvt_u32_f32_e32 v129, v129
	v_max_f32_e32 v130, 1.0, v130
	v_max_f32_e32 v131, 1.0, v131
	v_add_f32_e32 v135, 1.0, v135
	v_rcp_f32_e32 v132, v132
	v_rcp_f32_e32 v133, v133
	v_cvt_u32_f32_sdwa v130, v130 dst_sel:WORD_1 dst_unused:UNUSED_PAD src0_sel:DWORD
	v_cvt_u32_f32_sdwa v131, v131 dst_sel:BYTE_3 dst_unused:UNUSED_PAD src0_sel:DWORD
	v_add_f32_e32 v134, 1.0, v134
	v_rcp_f32_e32 v135, v135
	v_rcp_f32_e32 v134, v134
	v_lshl_or_b32 v128, v129, 8, v128
	v_or3_b32 v128, v128, v130, v131
	v_fma_f32 v129, v132, s4, 0.5
	v_fma_f32 v130, v133, s4, 0.5
	v_pk_mul_f32 v[124:125], v[124:125], v[144:145] op_sel_hi:[1,0]
	v_max_f32_e32 v129, 1.0, v129
	v_max_f32_e32 v130, 1.0, v130
	v_fma_f32 v131, v134, s4, 0.5
	v_fma_f32 v132, v135, s4, 0.5
	v_mul_f32_e32 v125, 0xbfb8aa3b, v125
	v_cvt_u32_f32_e32 v129, v129
	v_cvt_u32_f32_e32 v130, v130
	v_max_f32_e32 v131, 1.0, v131
	v_max_f32_e32 v132, 1.0, v132
	v_exp_f32_e32 v125, v125
	v_cvt_u32_f32_sdwa v131, v131 dst_sel:WORD_1 dst_unused:UNUSED_PAD src0_sel:DWORD
	v_cvt_u32_f32_sdwa v132, v132 dst_sel:BYTE_3 dst_unused:UNUSED_PAD src0_sel:DWORD
	v_pk_mul_f32 v[120:121], v[120:121], v[144:145] op_sel_hi:[1,0]
	v_mul_f32_e32 v124, 0xbfb8aa3b, v124
	v_mul_f32_e32 v121, 0xbfb8aa3b, v121
	v_lshl_or_b32 v129, v130, 8, v129
	v_exp_f32_e32 v130, v124
	v_add_f32_e32 v124, 1.0, v125
	v_exp_f32_e32 v121, v121
	v_or3_b32 v129, v129, v131, v132
	v_rcp_f32_e32 v131, v124
	v_mul_f32_e32 v120, 0xbfb8aa3b, v120
	v_pk_mul_f32 v[124:125], v[126:127], v[144:145] op_sel_hi:[1,0]
	v_add_f32_e32 v126, 1.0, v130
	v_exp_f32_e32 v130, v120
	v_add_f32_e32 v120, 1.0, v121
	v_fma_f32 v127, v131, s4, 0.5
	v_rcp_f32_e32 v131, v120
	v_pk_mul_f32 v[120:121], v[122:123], v[144:145] op_sel_hi:[1,0]
	v_add_f32_e32 v122, 1.0, v130
	v_mul_f32_e32 v120, 0xbfb8aa3b, v120
	v_mul_f32_e32 v121, 0xbfb8aa3b, v121
	v_exp_f32_e32 v120, v120
	v_exp_f32_e32 v121, v121
	v_rcp_f32_e32 v122, v122
	v_fma_f32 v123, v131, s4, 0.5
	v_add_f32_e32 v120, 1.0, v120
	v_add_f32_e32 v121, 1.0, v121
	v_rcp_f32_e32 v120, v120
	v_rcp_f32_e32 v121, v121
	v_fma_f32 v122, v122, s4, 0.5
	v_max_f32_e32 v123, 1.0, v123
	v_max_f32_e32 v122, 1.0, v122
	v_fma_f32 v120, v120, s4, 0.5
	v_fma_f32 v121, v121, s4, 0.5
	v_cvt_u32_f32_e32 v123, v123
	v_cvt_u32_f32_e32 v122, v122
	v_max_f32_e32 v120, 1.0, v120
	v_max_f32_e32 v121, 1.0, v121
	v_cvt_u32_f32_sdwa v120, v120 dst_sel:WORD_1 dst_unused:UNUSED_PAD src0_sel:DWORD
	v_cvt_u32_f32_sdwa v121, v121 dst_sel:BYTE_3 dst_unused:UNUSED_PAD src0_sel:DWORD
	v_lshl_or_b32 v122, v123, 8, v122
	v_mul_f32_e32 v124, 0xbfb8aa3b, v124
	v_mul_f32_e32 v125, 0xbfb8aa3b, v125
	v_or3_b32 v131, v122, v120, v121
	v_mul_f32_e32 v122, 0x3c800000, v145
	v_pk_mul_f32 v[112:113], v[112:113], v[122:123] op_sel_hi:[1,0]
	v_pk_mul_f32 v[114:115], v[114:115], v[122:123] op_sel_hi:[1,0]
	v_mul_f32_e32 v112, 0xbfb8aa3b, v112
	v_mul_f32_e32 v113, 0xbfb8aa3b, v113
	v_mul_f32_e32 v115, 0xbfb8aa3b, v115
	v_exp_f32_e32 v112, v112
	v_exp_f32_e32 v113, v113
	v_mul_f32_e32 v114, 0xbfb8aa3b, v114
	v_exp_f32_e32 v115, v115
	v_exp_f32_e32 v114, v114
	v_add_f32_e32 v112, 1.0, v112
	v_add_f32_e32 v113, 1.0, v113
	v_pk_mul_f32 v[116:117], v[116:117], v[122:123] op_sel_hi:[1,0]
	v_add_f32_e32 v115, 1.0, v115
	v_rcp_f32_e32 v112, v112
	v_rcp_f32_e32 v113, v113
	v_add_f32_e32 v114, 1.0, v114
	v_pk_mul_f32 v[118:119], v[118:119], v[122:123] op_sel_hi:[1,0]
	v_mul_f32_e32 v116, 0xbfb8aa3b, v116
	v_mul_f32_e32 v117, 0xbfb8aa3b, v117
	v_rcp_f32_e32 v115, v115
	v_rcp_f32_e32 v114, v114
	v_mul_f32_e32 v119, 0xbfb8aa3b, v119
	v_exp_f32_e32 v116, v116
	v_exp_f32_e32 v117, v117
	v_mul_f32_e32 v118, 0xbfb8aa3b, v118
; __device__ __forceinline__ float sigmoidf_(float v) { return __builtin_amdgcn_rcpf(1.0f + __expf(-v)); }
; #define MEMFENCE asm volatile("" ::: "memory")
;     template <int KIND> __device__ __forceinline__ void run(f32x4 (&acc)[2][2][4][2], const Unit& u, int tid_in) const {
;     ...
;         if constexpr (KIND == K_MG_G) { float rs[8]; get_rs(u, wr, fr, rs);
;             u32x4* gst = (u32x4*)((unsigned char*)x + 32 * MiB) + ((size_t)(blockIdx.x * 2 + (u.ord & 1)) * 3 + u.aux) * 4096;
; #pragma unroll
;             for (int ai = 0; ai < 2; ++ai)
; #pragma unroll
;                 for (int m = 0; m < 4; ++m) { const float r = rs[ai * 4 + m] * (1.0f / GATE_WSCALE); u32x4 w;
; #pragma unroll
;                     for (int bj = 0; bj < 2; ++bj) { f32x4 a = acc[ai][bj][m][0] * r, b = acc[ai][bj][m][1] * r;
; #pragma unroll
;                         for (int j = 0; j < 4; ++j) { a[j] = sigmoidf_(a[j]); b[j] = sigmoidf_(b[j]); }
;                         if (bj == 0) { w.x = pack4_u8c(a); w.y = pack4_u8c(b); } else { w.z = pack4_u8c(a); w.w = pack4_u8c(b); } }
;                     gst[(ai * 4 + m) * 512 + tid] = w; MEMFENCE; }
	v_exp_f32_e32 v119, v119
	v_exp_f32_e32 v118, v118
	v_fma_f32 v112, v112, s4, 0.5
	v_fma_f32 v113, v113, s4, 0.5
	v_max_f32_e32 v112, 1.0, v112
	v_max_f32_e32 v113, 1.0, v113
	v_fma_f32 v114, v114, s4, 0.5
	v_fma_f32 v115, v115, s4, 0.5
	v_add_f32_e32 v116, 1.0, v116
	v_add_f32_e32 v117, 1.0, v117
	v_cvt_u32_f32_e32 v112, v112
	v_cvt_u32_f32_e32 v113, v113
	v_max_f32_e32 v114, 1.0, v114
	v_max_f32_e32 v115, 1.0, v115
	v_add_f32_e32 v119, 1.0, v119
	v_rcp_f32_e32 v116, v116
	v_rcp_f32_e32 v117, v117
	v_cvt_u32_f32_sdwa v114, v114 dst_sel:WORD_1 dst_unused:UNUSED_PAD src0_sel:DWORD
	v_cvt_u32_f32_sdwa v115, v115 dst_sel:BYTE_3 dst_unused:UNUSED_PAD src0_sel:DWORD
	v_add_f32_e32 v118, 1.0, v118
	v_rcp_f32_e32 v119, v119
	v_rcp_f32_e32 v118, v118
	v_lshl_or_b32 v112, v113, 8, v112
	v_or3_b32 v112, v112, v114, v115
	v_fma_f32 v113, v116, s4, 0.5
	v_fma_f32 v114, v117, s4, 0.5
	v_pk_mul_f32 v[108:109], v[108:109], v[122:123] op_sel_hi:[1,0]
	v_max_f32_e32 v113, 1.0, v113
	v_max_f32_e32 v114, 1.0, v114
	v_fma_f32 v115, v118, s4, 0.5
	v_fma_f32 v116, v119, s4, 0.5
	v_mul_f32_e32 v109, 0xbfb8aa3b, v109
	v_cvt_u32_f32_e32 v113, v113
	v_cvt_u32_f32_e32 v114, v114
	v_max_f32_e32 v115, 1.0, v115
	v_max_f32_e32 v116, 1.0, v116
	v_exp_f32_e32 v109, v109
	v_cvt_u32_f32_sdwa v115, v115 dst_sel:WORD_1 dst_unused:UNUSED_PAD src0_sel:DWORD
	v_cvt_u32_f32_sdwa v116, v116 dst_sel:BYTE_3 dst_unused:UNUSED_PAD src0_sel:DWORD
	v_pk_mul_f32 v[104:105], v[104:105], v[122:123] op_sel_hi:[1,0]
	v_mul_f32_e32 v108, 0xbfb8aa3b, v108
	v_mul_f32_e32 v105, 0xbfb8aa3b, v105
	v_lshl_or_b32 v113, v114, 8, v113
	v_exp_f32_e32 v114, v108
	v_add_f32_e32 v108, 1.0, v109
	v_exp_f32_e32 v105, v105
	v_or3_b32 v113, v113, v115, v116
	v_rcp_f32_e32 v115, v108
	v_mul_f32_e32 v104, 0xbfb8aa3b, v104
	v_pk_mul_f32 v[108:109], v[110:111], v[122:123] op_sel_hi:[1,0]
	v_add_f32_e32 v110, 1.0, v114
	v_exp_f32_e32 v114, v104
	v_add_f32_e32 v104, 1.0, v105
	v_fma_f32 v111, v115, s4, 0.5
	v_rcp_f32_e32 v115, v104
	v_pk_mul_f32 v[104:105], v[106:107], v[122:123] op_sel_hi:[1,0]
	v_add_f32_e32 v106, 1.0, v114
	v_mul_f32_e32 v104, 0xbfb8aa3b, v104
	v_mul_f32_e32 v105, 0xbfb8aa3b, v105
	v_exp_f32_e32 v104, v104
	v_exp_f32_e32 v105, v105
	v_rcp_f32_e32 v106, v106
	v_fma_f32 v107, v115, s4, 0.5
	v_add_f32_e32 v104, 1.0, v104
	v_add_f32_e32 v105, 1.0, v105
	v_rcp_f32_e32 v104, v104
	v_rcp_f32_e32 v105, v105
	v_fma_f32 v106, v106, s4, 0.5
	v_max_f32_e32 v107, 1.0, v107
	v_max_f32_e32 v106, 1.0, v106
	v_fma_f32 v104, v104, s4, 0.5
	v_fma_f32 v105, v105, s4, 0.5
	v_cvt_u32_f32_e32 v107, v107
	v_cvt_u32_f32_e32 v106, v106
	v_max_f32_e32 v104, 1.0, v104
	v_max_f32_e32 v105, 1.0, v105
	v_cvt_u32_f32_sdwa v104, v104 dst_sel:WORD_1 dst_unused:UNUSED_PAD src0_sel:DWORD
	v_cvt_u32_f32_sdwa v105, v105 dst_sel:BYTE_3 dst_unused:UNUSED_PAD src0_sel:DWORD
	v_lshl_or_b32 v106, v107, 8, v106
	v_exp_f32_e32 v124, v124
	v_exp_f32_e32 v125, v125
	v_or3_b32 v115, v106, v104, v105
	v_mul_f32_e32 v106, 0x3c800000, v140
	v_pk_mul_f32 v[96:97], v[96:97], v[106:107] op_sel_hi:[1,0]
	v_pk_mul_f32 v[98:99], v[98:99], v[106:107] op_sel_hi:[1,0]
	v_mul_f32_e32 v96, 0xbfb8aa3b, v96
	v_mul_f32_e32 v97, 0xbfb8aa3b, v97
	v_mul_f32_e32 v99, 0xbfb8aa3b, v99
	v_exp_f32_e32 v96, v96
	v_exp_f32_e32 v97, v97
	v_mul_f32_e32 v98, 0xbfb8aa3b, v98
	v_exp_f32_e32 v99, v99
	v_exp_f32_e32 v98, v98
	v_add_f32_e32 v96, 1.0, v96
	v_add_f32_e32 v97, 1.0, v97
	v_pk_mul_f32 v[100:101], v[100:101], v[106:107] op_sel_hi:[1,0]
	v_add_f32_e32 v99, 1.0, v99
	v_rcp_f32_e32 v96, v96
	v_rcp_f32_e32 v97, v97
	v_add_f32_e32 v98, 1.0, v98
	v_pk_mul_f32 v[102:103], v[102:103], v[106:107] op_sel_hi:[1,0]
	v_mul_f32_e32 v100, 0xbfb8aa3b, v100
	v_mul_f32_e32 v101, 0xbfb8aa3b, v101
	v_rcp_f32_e32 v99, v99
	v_rcp_f32_e32 v98, v98
	v_mul_f32_e32 v103, 0xbfb8aa3b, v103
	v_exp_f32_e32 v100, v100
	v_exp_f32_e32 v101, v101
	v_mul_f32_e32 v102, 0xbfb8aa3b, v102
	v_exp_f32_e32 v103, v103
	v_exp_f32_e32 v102, v102
	v_fma_f32 v96, v96, s4, 0.5
	v_fma_f32 v97, v97, s4, 0.5
	v_max_f32_e32 v96, 1.0, v96
	v_max_f32_e32 v97, 1.0, v97
	v_fma_f32 v98, v98, s4, 0.5
	v_fma_f32 v99, v99, s4, 0.5
	v_add_f32_e32 v100, 1.0, v100
	v_add_f32_e32 v101, 1.0, v101
	v_cvt_u32_f32_e32 v96, v96
	v_cvt_u32_f32_e32 v97, v97
	v_max_f32_e32 v98, 1.0, v98
	v_max_f32_e32 v99, 1.0, v99
	v_add_f32_e32 v103, 1.0, v103
	v_rcp_f32_e32 v100, v100
	v_rcp_f32_e32 v101, v101
	v_cvt_u32_f32_sdwa v98, v98 dst_sel:WORD_1 dst_unused:UNUSED_PAD src0_sel:DWORD
	v_cvt_u32_f32_sdwa v99, v99 dst_sel:BYTE_3 dst_unused:UNUSED_PAD src0_sel:DWORD
	v_add_f32_e32 v102, 1.0, v102
	v_rcp_f32_e32 v103, v103
	v_rcp_f32_e32 v102, v102
	v_lshl_or_b32 v96, v97, 8, v96
	v_or3_b32 v96, v96, v98, v99
	v_fma_f32 v97, v100, s4, 0.5
	v_fma_f32 v98, v101, s4, 0.5
	v_pk_mul_f32 v[92:93], v[92:93], v[106:107] op_sel_hi:[1,0]
	v_max_f32_e32 v97, 1.0, v97
	v_max_f32_e32 v98, 1.0, v98
	v_fma_f32 v99, v102, s4, 0.5
	v_fma_f32 v100, v103, s4, 0.5
	v_mul_f32_e32 v93, 0xbfb8aa3b, v93
	v_cvt_u32_f32_e32 v97, v97
	v_cvt_u32_f32_e32 v98, v98
	v_max_f32_e32 v99, 1.0, v99
	v_max_f32_e32 v100, 1.0, v100
	v_exp_f32_e32 v93, v93
	v_cvt_u32_f32_sdwa v99, v99 dst_sel:WORD_1 dst_unused:UNUSED_PAD src0_sel:DWORD
	v_cvt_u32_f32_sdwa v100, v100 dst_sel:BYTE_3 dst_unused:UNUSED_PAD src0_sel:DWORD
	v_pk_mul_f32 v[88:89], v[88:89], v[106:107] op_sel_hi:[1,0]
	v_mul_f32_e32 v92, 0xbfb8aa3b, v92
	v_mul_f32_e32 v89, 0xbfb8aa3b, v89
	v_lshl_or_b32 v97, v98, 8, v97
	v_exp_f32_e32 v98, v92
	v_add_f32_e32 v92, 1.0, v93
	v_exp_f32_e32 v89, v89
	v_or3_b32 v97, v97, v99, v100
	v_rcp_f32_e32 v99, v92
	v_mul_f32_e32 v88, 0xbfb8aa3b, v88
	v_pk_mul_f32 v[92:93], v[94:95], v[106:107] op_sel_hi:[1,0]
; __device__ __forceinline__ float sigmoidf_(float v) { return __builtin_amdgcn_rcpf(1.0f + __expf(-v)); }
; #define MEMFENCE asm volatile("" ::: "memory")
;     template <int KIND> __device__ __forceinline__ void run(f32x4 (&acc)[2][2][4][2], const Unit& u, int tid_in) const {
;     ...
;         if constexpr (KIND == K_MG_G) { float rs[8]; get_rs(u, wr, fr, rs);
;             u32x4* gst = (u32x4*)((unsigned char*)x + 32 * MiB) + ((size_t)(blockIdx.x * 2 + (u.ord & 1)) * 3 + u.aux) * 4096;
; #pragma unroll
;             for (int ai = 0; ai < 2; ++ai)
; #pragma unroll
;                 for (int m = 0; m < 4; ++m) { const float r = rs[ai * 4 + m] * (1.0f / GATE_WSCALE); u32x4 w;
; #pragma unroll
;                     for (int bj = 0; bj < 2; ++bj) { f32x4 a = acc[ai][bj][m][0] * r, b = acc[ai][bj][m][1] * r;
; #pragma unroll
;                         for (int j = 0; j < 4; ++j) { a[j] = sigmoidf_(a[j]); b[j] = sigmoidf_(b[j]); }
;                         if (bj == 0) { w.x = pack4_u8c(a); w.y = pack4_u8c(b); } else { w.z = pack4_u8c(a); w.w = pack4_u8c(b); } }
;                     gst[(ai * 4 + m) * 512 + tid] = w; MEMFENCE; }
	v_add_f32_e32 v94, 1.0, v98
	v_exp_f32_e32 v98, v88
	v_add_f32_e32 v88, 1.0, v89
	v_fma_f32 v95, v99, s4, 0.5
	v_rcp_f32_e32 v99, v88
	v_pk_mul_f32 v[88:89], v[90:91], v[106:107] op_sel_hi:[1,0]
	v_add_f32_e32 v90, 1.0, v98
	v_mul_f32_e32 v88, 0xbfb8aa3b, v88
	v_mul_f32_e32 v89, 0xbfb8aa3b, v89
	v_exp_f32_e32 v88, v88
	v_exp_f32_e32 v89, v89
	v_rcp_f32_e32 v90, v90
	v_fma_f32 v91, v99, s4, 0.5
	v_add_f32_e32 v88, 1.0, v88
	v_add_f32_e32 v89, 1.0, v89
	v_rcp_f32_e32 v88, v88
	v_rcp_f32_e32 v89, v89
	v_fma_f32 v90, v90, s4, 0.5
	v_max_f32_e32 v91, 1.0, v91
	v_max_f32_e32 v90, 1.0, v90
	v_fma_f32 v88, v88, s4, 0.5
	v_fma_f32 v89, v89, s4, 0.5
	v_cvt_u32_f32_e32 v91, v91
	v_cvt_u32_f32_e32 v90, v90
	v_max_f32_e32 v88, 1.0, v88
	v_max_f32_e32 v89, 1.0, v89
	v_cvt_u32_f32_sdwa v88, v88 dst_sel:WORD_1 dst_unused:UNUSED_PAD src0_sel:DWORD
	v_cvt_u32_f32_sdwa v89, v89 dst_sel:BYTE_3 dst_unused:UNUSED_PAD src0_sel:DWORD
	v_lshl_or_b32 v90, v91, 8, v90
	v_mul_f32_e32 v108, 0xbfb8aa3b, v108
	v_mul_f32_e32 v109, 0xbfb8aa3b, v109
	v_or3_b32 v99, v90, v88, v89
	v_mul_f32_e32 v90, 0x3c800000, v141
	v_pk_mul_f32 v[80:81], v[80:81], v[90:91] op_sel_hi:[1,0]
	v_pk_mul_f32 v[82:83], v[82:83], v[90:91] op_sel_hi:[1,0]
	v_mul_f32_e32 v80, 0xbfb8aa3b, v80
	v_mul_f32_e32 v81, 0xbfb8aa3b, v81
	v_mul_f32_e32 v83, 0xbfb8aa3b, v83
	v_exp_f32_e32 v80, v80
	v_exp_f32_e32 v81, v81
	v_mul_f32_e32 v82, 0xbfb8aa3b, v82
	v_exp_f32_e32 v83, v83
	v_exp_f32_e32 v82, v82
	v_add_f32_e32 v80, 1.0, v80
	v_add_f32_e32 v81, 1.0, v81
	v_pk_mul_f32 v[84:85], v[84:85], v[90:91] op_sel_hi:[1,0]
	v_add_f32_e32 v83, 1.0, v83
	v_rcp_f32_e32 v80, v80
	v_rcp_f32_e32 v81, v81
	v_add_f32_e32 v82, 1.0, v82
	v_pk_mul_f32 v[86:87], v[86:87], v[90:91] op_sel_hi:[1,0]
	v_mul_f32_e32 v84, 0xbfb8aa3b, v84
	v_mul_f32_e32 v85, 0xbfb8aa3b, v85
	v_rcp_f32_e32 v83, v83
	v_rcp_f32_e32 v82, v82
	v_mul_f32_e32 v87, 0xbfb8aa3b, v87
	v_exp_f32_e32 v84, v84
	v_exp_f32_e32 v85, v85
	v_mul_f32_e32 v86, 0xbfb8aa3b, v86
	v_exp_f32_e32 v87, v87
	v_exp_f32_e32 v86, v86
	v_fma_f32 v80, v80, s4, 0.5
	v_fma_f32 v81, v81, s4, 0.5
	v_max_f32_e32 v80, 1.0, v80
	v_max_f32_e32 v81, 1.0, v81
	v_fma_f32 v82, v82, s4, 0.5
	v_fma_f32 v83, v83, s4, 0.5
	v_add_f32_e32 v84, 1.0, v84
	v_add_f32_e32 v85, 1.0, v85
	v_cvt_u32_f32_e32 v80, v80
	v_cvt_u32_f32_e32 v81, v81
	v_max_f32_e32 v82, 1.0, v82
	v_max_f32_e32 v83, 1.0, v83
	v_add_f32_e32 v87, 1.0, v87
	v_rcp_f32_e32 v84, v84
	v_rcp_f32_e32 v85, v85
	v_cvt_u32_f32_sdwa v82, v82 dst_sel:WORD_1 dst_unused:UNUSED_PAD src0_sel:DWORD
	v_cvt_u32_f32_sdwa v83, v83 dst_sel:BYTE_3 dst_unused:UNUSED_PAD src0_sel:DWORD
	v_add_f32_e32 v86, 1.0, v86
	v_rcp_f32_e32 v87, v87
	v_rcp_f32_e32 v86, v86
	v_lshl_or_b32 v80, v81, 8, v80
	v_or3_b32 v80, v80, v82, v83
	v_fma_f32 v81, v84, s4, 0.5
	v_fma_f32 v82, v85, s4, 0.5
	v_pk_mul_f32 v[76:77], v[76:77], v[90:91] op_sel_hi:[1,0]
	v_max_f32_e32 v81, 1.0, v81
	v_max_f32_e32 v82, 1.0, v82
	v_fma_f32 v83, v86, s4, 0.5
	v_fma_f32 v84, v87, s4, 0.5
	v_mul_f32_e32 v77, 0xbfb8aa3b, v77
	v_cvt_u32_f32_e32 v81, v81
	v_cvt_u32_f32_e32 v82, v82
	v_max_f32_e32 v83, 1.0, v83
	v_max_f32_e32 v84, 1.0, v84
	v_exp_f32_e32 v77, v77
	v_cvt_u32_f32_sdwa v83, v83 dst_sel:WORD_1 dst_unused:UNUSED_PAD src0_sel:DWORD
	v_cvt_u32_f32_sdwa v84, v84 dst_sel:BYTE_3 dst_unused:UNUSED_PAD src0_sel:DWORD
	v_pk_mul_f32 v[72:73], v[72:73], v[90:91] op_sel_hi:[1,0]
	v_mul_f32_e32 v76, 0xbfb8aa3b, v76
	v_mul_f32_e32 v73, 0xbfb8aa3b, v73
	v_lshl_or_b32 v81, v82, 8, v81
	v_exp_f32_e32 v82, v76
	v_add_f32_e32 v76, 1.0, v77
	v_exp_f32_e32 v73, v73
	v_or3_b32 v81, v81, v83, v84
	v_rcp_f32_e32 v83, v76
	v_mul_f32_e32 v72, 0xbfb8aa3b, v72
	v_pk_mul_f32 v[76:77], v[78:79], v[90:91] op_sel_hi:[1,0]
	v_add_f32_e32 v78, 1.0, v82
	v_exp_f32_e32 v82, v72
	v_add_f32_e32 v72, 1.0, v73
	v_fma_f32 v79, v83, s4, 0.5
	v_rcp_f32_e32 v83, v72
	v_pk_mul_f32 v[72:73], v[74:75], v[90:91] op_sel_hi:[1,0]
	v_add_f32_e32 v74, 1.0, v82
	v_mul_f32_e32 v72, 0xbfb8aa3b, v72
	v_mul_f32_e32 v73, 0xbfb8aa3b, v73
	v_exp_f32_e32 v72, v72
	v_exp_f32_e32 v73, v73
	v_rcp_f32_e32 v74, v74
	v_fma_f32 v75, v83, s4, 0.5
	v_add_f32_e32 v72, 1.0, v72
	v_add_f32_e32 v73, 1.0, v73
	v_rcp_f32_e32 v72, v72
	v_rcp_f32_e32 v73, v73
	v_fma_f32 v74, v74, s4, 0.5
	v_max_f32_e32 v75, 1.0, v75
	v_max_f32_e32 v74, 1.0, v74
	v_fma_f32 v72, v72, s4, 0.5
	v_fma_f32 v73, v73, s4, 0.5
	v_cvt_u32_f32_e32 v75, v75
	v_cvt_u32_f32_e32 v74, v74
	v_max_f32_e32 v72, 1.0, v72
	v_max_f32_e32 v73, 1.0, v73
	v_cvt_u32_f32_sdwa v72, v72 dst_sel:WORD_1 dst_unused:UNUSED_PAD src0_sel:DWORD
	v_cvt_u32_f32_sdwa v73, v73 dst_sel:BYTE_3 dst_unused:UNUSED_PAD src0_sel:DWORD
	v_lshl_or_b32 v74, v75, 8, v74
	v_exp_f32_e32 v108, v108
	v_exp_f32_e32 v109, v109
	v_or3_b32 v83, v74, v72, v73
	v_mul_f32_e32 v74, 0x3c800000, v138
	v_pk_mul_f32 v[64:65], v[64:65], v[74:75] op_sel_hi:[1,0]
	v_pk_mul_f32 v[66:67], v[66:67], v[74:75] op_sel_hi:[1,0]
	v_mul_f32_e32 v64, 0xbfb8aa3b, v64
	v_mul_f32_e32 v65, 0xbfb8aa3b, v65
	v_mul_f32_e32 v67, 0xbfb8aa3b, v67
	v_exp_f32_e32 v64, v64
	v_exp_f32_e32 v65, v65
	v_mul_f32_e32 v66, 0xbfb8aa3b, v66
	v_exp_f32_e32 v67, v67
	v_exp_f32_e32 v66, v66
	v_add_f32_e32 v64, 1.0, v64
	v_add_f32_e32 v65, 1.0, v65
	v_pk_mul_f32 v[68:69], v[68:69], v[74:75] op_sel_hi:[1,0]
	v_add_f32_e32 v67, 1.0, v67
	v_rcp_f32_e32 v64, v64
	v_rcp_f32_e32 v65, v65
	v_add_f32_e32 v66, 1.0, v66
	v_pk_mul_f32 v[70:71], v[70:71], v[74:75] op_sel_hi:[1,0]
	v_mul_f32_e32 v68, 0xbfb8aa3b, v68
	v_mul_f32_e32 v69, 0xbfb8aa3b, v69
	v_rcp_f32_e32 v67, v67
	v_rcp_f32_e32 v66, v66
	v_mul_f32_e32 v71, 0xbfb8aa3b, v71
	v_exp_f32_e32 v68, v68
	v_exp_f32_e32 v69, v69
; __device__ __forceinline__ float sigmoidf_(float v) { return __builtin_amdgcn_rcpf(1.0f + __expf(-v)); }
; #define MEMFENCE asm volatile("" ::: "memory")
;     template <int KIND> __device__ __forceinline__ void run(f32x4 (&acc)[2][2][4][2], const Unit& u, int tid_in) const {
;     ...
;         if constexpr (KIND == K_MG_G) { float rs[8]; get_rs(u, wr, fr, rs);
;             u32x4* gst = (u32x4*)((unsigned char*)x + 32 * MiB) + ((size_t)(blockIdx.x * 2 + (u.ord & 1)) * 3 + u.aux) * 4096;
; #pragma unroll
;             for (int ai = 0; ai < 2; ++ai)
; #pragma unroll
;                 for (int m = 0; m < 4; ++m) { const float r = rs[ai * 4 + m] * (1.0f / GATE_WSCALE); u32x4 w;
; #pragma unroll
;                     for (int bj = 0; bj < 2; ++bj) { f32x4 a = acc[ai][bj][m][0] * r, b = acc[ai][bj][m][1] * r;
; #pragma unroll
;                         for (int j = 0; j < 4; ++j) { a[j] = sigmoidf_(a[j]); b[j] = sigmoidf_(b[j]); }
;                         if (bj == 0) { w.x = pack4_u8c(a); w.y = pack4_u8c(b); } else { w.z = pack4_u8c(a); w.w = pack4_u8c(b); } }
;                     gst[(ai * 4 + m) * 512 + tid] = w; MEMFENCE; }
	v_mul_f32_e32 v70, 0xbfb8aa3b, v70
	v_exp_f32_e32 v71, v71
	v_exp_f32_e32 v70, v70
	v_fma_f32 v64, v64, s4, 0.5
	v_fma_f32 v65, v65, s4, 0.5
	v_max_f32_e32 v64, 1.0, v64
	v_max_f32_e32 v65, 1.0, v65
	v_fma_f32 v66, v66, s4, 0.5
	v_fma_f32 v67, v67, s4, 0.5
	v_add_f32_e32 v68, 1.0, v68
	v_add_f32_e32 v69, 1.0, v69
	v_cvt_u32_f32_e32 v64, v64
	v_cvt_u32_f32_e32 v65, v65
	v_max_f32_e32 v66, 1.0, v66
	v_max_f32_e32 v67, 1.0, v67
	v_add_f32_e32 v71, 1.0, v71
	v_rcp_f32_e32 v68, v68
	v_rcp_f32_e32 v69, v69
	v_cvt_u32_f32_sdwa v66, v66 dst_sel:WORD_1 dst_unused:UNUSED_PAD src0_sel:DWORD
	v_cvt_u32_f32_sdwa v67, v67 dst_sel:BYTE_3 dst_unused:UNUSED_PAD src0_sel:DWORD
	v_add_f32_e32 v70, 1.0, v70
	v_rcp_f32_e32 v71, v71
	v_rcp_f32_e32 v70, v70
	v_lshl_or_b32 v64, v65, 8, v64
	v_or3_b32 v64, v64, v66, v67
	v_fma_f32 v65, v68, s4, 0.5
	v_fma_f32 v66, v69, s4, 0.5
	v_pk_mul_f32 v[60:61], v[60:61], v[74:75] op_sel_hi:[1,0]
	v_max_f32_e32 v65, 1.0, v65
	v_max_f32_e32 v66, 1.0, v66
	v_fma_f32 v67, v70, s4, 0.5
	v_fma_f32 v68, v71, s4, 0.5
	v_mul_f32_e32 v61, 0xbfb8aa3b, v61
	v_cvt_u32_f32_e32 v65, v65
	v_cvt_u32_f32_e32 v66, v66
	v_max_f32_e32 v67, 1.0, v67
	v_max_f32_e32 v68, 1.0, v68
	v_exp_f32_e32 v61, v61
	v_cvt_u32_f32_sdwa v67, v67 dst_sel:WORD_1 dst_unused:UNUSED_PAD src0_sel:DWORD
	v_cvt_u32_f32_sdwa v68, v68 dst_sel:BYTE_3 dst_unused:UNUSED_PAD src0_sel:DWORD
	v_pk_mul_f32 v[56:57], v[56:57], v[74:75] op_sel_hi:[1,0]
	v_mul_f32_e32 v60, 0xbfb8aa3b, v60
	v_mul_f32_e32 v57, 0xbfb8aa3b, v57
	v_lshl_or_b32 v65, v66, 8, v65
	v_exp_f32_e32 v66, v60
	v_add_f32_e32 v60, 1.0, v61
	v_exp_f32_e32 v57, v57
	v_or3_b32 v65, v65, v67, v68
	v_rcp_f32_e32 v67, v60
	v_mul_f32_e32 v56, 0xbfb8aa3b, v56
	v_pk_mul_f32 v[60:61], v[62:63], v[74:75] op_sel_hi:[1,0]
	v_add_f32_e32 v62, 1.0, v66
	v_exp_f32_e32 v66, v56
	v_add_f32_e32 v56, 1.0, v57
	v_fma_f32 v63, v67, s4, 0.5
	v_rcp_f32_e32 v67, v56
	v_pk_mul_f32 v[56:57], v[58:59], v[74:75] op_sel_hi:[1,0]
	v_add_f32_e32 v58, 1.0, v66
	v_mul_f32_e32 v56, 0xbfb8aa3b, v56
	v_mul_f32_e32 v57, 0xbfb8aa3b, v57
	v_exp_f32_e32 v56, v56
	v_exp_f32_e32 v57, v57
	v_rcp_f32_e32 v58, v58
	v_fma_f32 v59, v67, s4, 0.5
	v_add_f32_e32 v56, 1.0, v56
	v_add_f32_e32 v57, 1.0, v57
	v_rcp_f32_e32 v56, v56
	v_rcp_f32_e32 v57, v57
	v_fma_f32 v58, v58, s4, 0.5
	v_max_f32_e32 v59, 1.0, v59
	v_max_f32_e32 v58, 1.0, v58
	v_fma_f32 v56, v56, s4, 0.5
	v_fma_f32 v57, v57, s4, 0.5
	v_cvt_u32_f32_e32 v59, v59
	v_cvt_u32_f32_e32 v58, v58
	v_max_f32_e32 v56, 1.0, v56
	v_max_f32_e32 v57, 1.0, v57
	v_cvt_u32_f32_sdwa v56, v56 dst_sel:WORD_1 dst_unused:UNUSED_PAD src0_sel:DWORD
	v_cvt_u32_f32_sdwa v57, v57 dst_sel:BYTE_3 dst_unused:UNUSED_PAD src0_sel:DWORD
	v_lshl_or_b32 v58, v59, 8, v58
	v_mul_f32_e32 v92, 0xbfb8aa3b, v92
	v_mul_f32_e32 v93, 0xbfb8aa3b, v93
	v_or3_b32 v67, v58, v56, v57
	v_mul_f32_e32 v58, 0x3c800000, v139
	v_pk_mul_f32 v[48:49], v[48:49], v[58:59] op_sel_hi:[1,0]
	v_pk_mul_f32 v[50:51], v[50:51], v[58:59] op_sel_hi:[1,0]
	v_mul_f32_e32 v48, 0xbfb8aa3b, v48
	v_mul_f32_e32 v49, 0xbfb8aa3b, v49
	v_mul_f32_e32 v51, 0xbfb8aa3b, v51
	v_exp_f32_e32 v48, v48
	v_exp_f32_e32 v49, v49
	v_mul_f32_e32 v50, 0xbfb8aa3b, v50
	v_exp_f32_e32 v51, v51
	v_exp_f32_e32 v50, v50
	v_add_f32_e32 v48, 1.0, v48
	v_add_f32_e32 v49, 1.0, v49
	v_pk_mul_f32 v[52:53], v[52:53], v[58:59] op_sel_hi:[1,0]
	v_add_f32_e32 v51, 1.0, v51
	v_rcp_f32_e32 v48, v48
	v_rcp_f32_e32 v49, v49
	v_add_f32_e32 v50, 1.0, v50
	v_pk_mul_f32 v[54:55], v[54:55], v[58:59] op_sel_hi:[1,0]
	v_mul_f32_e32 v52, 0xbfb8aa3b, v52
	v_mul_f32_e32 v53, 0xbfb8aa3b, v53
	v_rcp_f32_e32 v51, v51
	v_rcp_f32_e32 v50, v50
	v_mul_f32_e32 v55, 0xbfb8aa3b, v55
	v_exp_f32_e32 v52, v52
	v_exp_f32_e32 v53, v53
	v_mul_f32_e32 v54, 0xbfb8aa3b, v54
	v_exp_f32_e32 v55, v55
	v_exp_f32_e32 v54, v54
	v_fma_f32 v48, v48, s4, 0.5
	v_fma_f32 v49, v49, s4, 0.5
	v_max_f32_e32 v48, 1.0, v48
	v_max_f32_e32 v49, 1.0, v49
	v_fma_f32 v50, v50, s4, 0.5
	v_fma_f32 v51, v51, s4, 0.5
	v_add_f32_e32 v52, 1.0, v52
	v_add_f32_e32 v53, 1.0, v53
	v_cvt_u32_f32_e32 v48, v48
	v_cvt_u32_f32_e32 v49, v49
	v_max_f32_e32 v50, 1.0, v50
	v_max_f32_e32 v51, 1.0, v51
	v_add_f32_e32 v55, 1.0, v55
	v_rcp_f32_e32 v52, v52
	v_rcp_f32_e32 v53, v53
	v_cvt_u32_f32_sdwa v50, v50 dst_sel:WORD_1 dst_unused:UNUSED_PAD src0_sel:DWORD
	v_cvt_u32_f32_sdwa v51, v51 dst_sel:BYTE_3 dst_unused:UNUSED_PAD src0_sel:DWORD
	v_add_f32_e32 v54, 1.0, v54
	v_rcp_f32_e32 v55, v55
	v_rcp_f32_e32 v54, v54
	v_lshl_or_b32 v48, v49, 8, v48
	v_or3_b32 v48, v48, v50, v51
	v_fma_f32 v49, v52, s4, 0.5
	v_fma_f32 v50, v53, s4, 0.5
	v_pk_mul_f32 v[44:45], v[44:45], v[58:59] op_sel_hi:[1,0]
	v_max_f32_e32 v49, 1.0, v49
	v_max_f32_e32 v50, 1.0, v50
	v_fma_f32 v51, v54, s4, 0.5
	v_fma_f32 v52, v55, s4, 0.5
	v_mul_f32_e32 v45, 0xbfb8aa3b, v45
	v_cvt_u32_f32_e32 v49, v49
	v_cvt_u32_f32_e32 v50, v50
	v_max_f32_e32 v51, 1.0, v51
	v_max_f32_e32 v52, 1.0, v52
	v_exp_f32_e32 v45, v45
	v_cvt_u32_f32_sdwa v51, v51 dst_sel:WORD_1 dst_unused:UNUSED_PAD src0_sel:DWORD
	v_cvt_u32_f32_sdwa v52, v52 dst_sel:BYTE_3 dst_unused:UNUSED_PAD src0_sel:DWORD
	v_pk_mul_f32 v[40:41], v[40:41], v[58:59] op_sel_hi:[1,0]
	v_mul_f32_e32 v44, 0xbfb8aa3b, v44
	v_mul_f32_e32 v41, 0xbfb8aa3b, v41
	v_lshl_or_b32 v49, v50, 8, v49
	v_exp_f32_e32 v50, v44
	v_add_f32_e32 v44, 1.0, v45
	v_exp_f32_e32 v41, v41
	v_or3_b32 v49, v49, v51, v52
	v_rcp_f32_e32 v51, v44
	v_mul_f32_e32 v40, 0xbfb8aa3b, v40
	v_pk_mul_f32 v[44:45], v[46:47], v[58:59] op_sel_hi:[1,0]
	v_add_f32_e32 v46, 1.0, v50
	v_exp_f32_e32 v50, v40
	v_add_f32_e32 v40, 1.0, v41
	v_fma_f32 v47, v51, s4, 0.5
	v_rcp_f32_e32 v51, v40
	v_pk_mul_f32 v[40:41], v[42:43], v[58:59] op_sel_hi:[1,0]
; __device__ __forceinline__ float sigmoidf_(float v) { return __builtin_amdgcn_rcpf(1.0f + __expf(-v)); }
; #define MEMFENCE asm volatile("" ::: "memory")
;     template <int KIND> __device__ __forceinline__ void run(f32x4 (&acc)[2][2][4][2], const Unit& u, int tid_in) const {
;     ...
;         if constexpr (KIND == K_MG_G) { float rs[8]; get_rs(u, wr, fr, rs);
;             u32x4* gst = (u32x4*)((unsigned char*)x + 32 * MiB) + ((size_t)(blockIdx.x * 2 + (u.ord & 1)) * 3 + u.aux) * 4096;
; #pragma unroll
;             for (int ai = 0; ai < 2; ++ai)
; #pragma unroll
;                 for (int m = 0; m < 4; ++m) { const float r = rs[ai * 4 + m] * (1.0f / GATE_WSCALE); u32x4 w;
; #pragma unroll
;                     for (int bj = 0; bj < 2; ++bj) { f32x4 a = acc[ai][bj][m][0] * r, b = acc[ai][bj][m][1] * r;
; #pragma unroll
;                         for (int j = 0; j < 4; ++j) { a[j] = sigmoidf_(a[j]); b[j] = sigmoidf_(b[j]); }
;                         if (bj == 0) { w.x = pack4_u8c(a); w.y = pack4_u8c(b); } else { w.z = pack4_u8c(a); w.w = pack4_u8c(b); } }
;                     gst[(ai * 4 + m) * 512 + tid] = w; MEMFENCE; }
	v_add_f32_e32 v42, 1.0, v50
	v_mul_f32_e32 v40, 0xbfb8aa3b, v40
	v_mul_f32_e32 v41, 0xbfb8aa3b, v41
	v_exp_f32_e32 v40, v40
	v_exp_f32_e32 v41, v41
	v_rcp_f32_e32 v42, v42
	v_fma_f32 v43, v51, s4, 0.5
	v_add_f32_e32 v40, 1.0, v40
	v_add_f32_e32 v41, 1.0, v41
	v_rcp_f32_e32 v40, v40
	v_rcp_f32_e32 v41, v41
	v_fma_f32 v42, v42, s4, 0.5
	v_max_f32_e32 v43, 1.0, v43
	v_max_f32_e32 v42, 1.0, v42
	v_fma_f32 v40, v40, s4, 0.5
	v_fma_f32 v41, v41, s4, 0.5
	v_cvt_u32_f32_e32 v43, v43
	v_cvt_u32_f32_e32 v42, v42
	v_max_f32_e32 v40, 1.0, v40
	v_max_f32_e32 v41, 1.0, v41
	v_cvt_u32_f32_sdwa v40, v40 dst_sel:WORD_1 dst_unused:UNUSED_PAD src0_sel:DWORD
	v_cvt_u32_f32_sdwa v41, v41 dst_sel:BYTE_3 dst_unused:UNUSED_PAD src0_sel:DWORD
	v_lshl_or_b32 v42, v43, 8, v42
	v_exp_f32_e32 v92, v92
	v_exp_f32_e32 v93, v93
	v_or3_b32 v51, v42, v40, v41
	v_mul_f32_e32 v42, 0x3c800000, v136
	v_pk_mul_f32 v[32:33], v[32:33], v[42:43] op_sel_hi:[1,0]
	v_pk_mul_f32 v[34:35], v[34:35], v[42:43] op_sel_hi:[1,0]
	v_mul_f32_e32 v32, 0xbfb8aa3b, v32
	v_mul_f32_e32 v33, 0xbfb8aa3b, v33
	v_mul_f32_e32 v35, 0xbfb8aa3b, v35
	v_exp_f32_e32 v32, v32
	v_exp_f32_e32 v33, v33
	v_mul_f32_e32 v34, 0xbfb8aa3b, v34
	v_exp_f32_e32 v35, v35
	v_exp_f32_e32 v34, v34
	v_add_f32_e32 v32, 1.0, v32
	v_add_f32_e32 v33, 1.0, v33
	v_pk_mul_f32 v[36:37], v[36:37], v[42:43] op_sel_hi:[1,0]
	v_add_f32_e32 v35, 1.0, v35
	v_rcp_f32_e32 v32, v32
	v_rcp_f32_e32 v33, v33
	v_add_f32_e32 v34, 1.0, v34
	v_pk_mul_f32 v[38:39], v[38:39], v[42:43] op_sel_hi:[1,0]
	v_mul_f32_e32 v36, 0xbfb8aa3b, v36
	v_mul_f32_e32 v37, 0xbfb8aa3b, v37
	v_rcp_f32_e32 v35, v35
	v_rcp_f32_e32 v34, v34
	v_mul_f32_e32 v39, 0xbfb8aa3b, v39
	v_exp_f32_e32 v36, v36
	v_exp_f32_e32 v37, v37
	v_mul_f32_e32 v38, 0xbfb8aa3b, v38
	v_exp_f32_e32 v39, v39
	v_exp_f32_e32 v38, v38
	v_fma_f32 v32, v32, s4, 0.5
	v_fma_f32 v33, v33, s4, 0.5
	v_max_f32_e32 v32, 1.0, v32
	v_max_f32_e32 v33, 1.0, v33
	v_fma_f32 v34, v34, s4, 0.5
	v_fma_f32 v35, v35, s4, 0.5
	v_add_f32_e32 v36, 1.0, v36
	v_add_f32_e32 v37, 1.0, v37
	v_cvt_u32_f32_e32 v32, v32
	v_cvt_u32_f32_e32 v33, v33
	v_max_f32_e32 v34, 1.0, v34
	v_max_f32_e32 v35, 1.0, v35
	v_add_f32_e32 v39, 1.0, v39
	v_rcp_f32_e32 v36, v36
	v_rcp_f32_e32 v37, v37
	v_cvt_u32_f32_sdwa v34, v34 dst_sel:WORD_1 dst_unused:UNUSED_PAD src0_sel:DWORD
	v_cvt_u32_f32_sdwa v35, v35 dst_sel:BYTE_3 dst_unused:UNUSED_PAD src0_sel:DWORD
	v_add_f32_e32 v38, 1.0, v38
	v_rcp_f32_e32 v39, v39
	v_rcp_f32_e32 v38, v38
	v_lshl_or_b32 v32, v33, 8, v32
	v_or3_b32 v32, v32, v34, v35
	v_fma_f32 v33, v36, s4, 0.5
	v_fma_f32 v34, v37, s4, 0.5
	v_pk_mul_f32 v[28:29], v[28:29], v[42:43] op_sel_hi:[1,0]
	v_max_f32_e32 v33, 1.0, v33
	v_max_f32_e32 v34, 1.0, v34
	v_fma_f32 v35, v38, s4, 0.5
	v_fma_f32 v36, v39, s4, 0.5
	v_mul_f32_e32 v29, 0xbfb8aa3b, v29
	v_cvt_u32_f32_e32 v33, v33
	v_cvt_u32_f32_e32 v34, v34
	v_max_f32_e32 v35, 1.0, v35
	v_max_f32_e32 v36, 1.0, v36
	v_exp_f32_e32 v29, v29
	v_cvt_u32_f32_sdwa v35, v35 dst_sel:WORD_1 dst_unused:UNUSED_PAD src0_sel:DWORD
	v_cvt_u32_f32_sdwa v36, v36 dst_sel:BYTE_3 dst_unused:UNUSED_PAD src0_sel:DWORD
	v_pk_mul_f32 v[24:25], v[24:25], v[42:43] op_sel_hi:[1,0]
	v_mul_f32_e32 v28, 0xbfb8aa3b, v28
	v_mul_f32_e32 v25, 0xbfb8aa3b, v25
	v_lshl_or_b32 v33, v34, 8, v33
	v_exp_f32_e32 v34, v28
	v_add_f32_e32 v28, 1.0, v29
	v_exp_f32_e32 v25, v25
	v_or3_b32 v33, v33, v35, v36
	v_rcp_f32_e32 v35, v28
	v_mul_f32_e32 v24, 0xbfb8aa3b, v24
	v_mul_f32_e32 v76, 0xbfb8aa3b, v76
	v_mul_f32_e32 v77, 0xbfb8aa3b, v77
	v_pk_mul_f32 v[28:29], v[30:31], v[42:43] op_sel_hi:[1,0]
	v_add_f32_e32 v30, 1.0, v34
	v_exp_f32_e32 v34, v24
	v_add_f32_e32 v24, 1.0, v25
	v_exp_f32_e32 v76, v76
	v_exp_f32_e32 v77, v77
	v_mul_f32_e32 v60, 0xbfb8aa3b, v60
	v_mul_f32_e32 v61, 0xbfb8aa3b, v61
	v_fma_f32 v31, v35, s4, 0.5
	v_rcp_f32_e32 v35, v24
	v_pk_mul_f32 v[24:25], v[26:27], v[42:43] op_sel_hi:[1,0]
	v_rcp_f32_e32 v126, v126
	v_add_f32_e32 v124, 1.0, v124
	v_add_f32_e32 v125, 1.0, v125
	v_exp_f32_e32 v60, v60
	v_exp_f32_e32 v61, v61
	v_mul_f32_e32 v44, 0xbfb8aa3b, v44
	v_mul_f32_e32 v45, 0xbfb8aa3b, v45
	v_mul_f32_e32 v24, 0xbfb8aa3b, v24
	v_mul_f32_e32 v25, 0xbfb8aa3b, v25
	v_rcp_f32_e32 v124, v124
	v_rcp_f32_e32 v125, v125
	v_rcp_f32_e32 v110, v110
	v_add_f32_e32 v108, 1.0, v108
	v_add_f32_e32 v109, 1.0, v109
	v_exp_f32_e32 v44, v44
	v_exp_f32_e32 v45, v45
	v_mul_f32_e32 v28, 0xbfb8aa3b, v28
	v_mul_f32_e32 v29, 0xbfb8aa3b, v29
	v_exp_f32_e32 v24, v24
	v_exp_f32_e32 v25, v25
	s_lshl_b64 s[2:3], s[2:3], 16
	v_rcp_f32_e32 v108, v108
	v_rcp_f32_e32 v109, v109
	v_rcp_f32_e32 v94, v94
	v_add_f32_e32 v92, 1.0, v92
	v_add_f32_e32 v93, 1.0, v93
	v_exp_f32_e32 v28, v28
	v_exp_f32_e32 v29, v29
	s_add_u32 s2, s29, s2
	v_rcp_f32_e32 v92, v92
	v_rcp_f32_e32 v93, v93
	v_rcp_f32_e32 v78, v78
	v_add_f32_e32 v76, 1.0, v76
	v_add_f32_e32 v77, 1.0, v77
	s_addc_u32 s3, s30, s3
	v_fma_f32 v126, v126, s4, 0.5
	v_ashrrev_i32_e32 v143, 31, v142
	v_rcp_f32_e32 v76, v76
	v_rcp_f32_e32 v77, v77
	v_rcp_f32_e32 v62, v62
	v_add_f32_e32 v60, 1.0, v60
	v_add_f32_e32 v61, 1.0, v61
	v_add_f32_e32 v26, 1.0, v34
	v_max_f32_e32 v127, 1.0, v127
	v_max_f32_e32 v126, 1.0, v126
	v_fma_f32 v124, v124, s4, 0.5
	v_fma_f32 v125, v125, s4, 0.5
	v_lshl_add_u64 v[120:121], v[142:143], 4, s[2:3]
	v_fma_f32 v110, v110, s4, 0.5
	s_movk_i32 s2, 0x2000
	v_rcp_f32_e32 v60, v60
	v_rcp_f32_e32 v61, v61
	v_rcp_f32_e32 v46, v46
	v_add_f32_e32 v44, 1.0, v44
	v_add_f32_e32 v45, 1.0, v45
	v_rcp_f32_e32 v26, v26
	v_add_f32_e32 v24, 1.0, v24
	v_add_f32_e32 v25, 1.0, v25
	v_cvt_u32_f32_e32 v127, v127
	v_cvt_u32_f32_e32 v126, v126
	v_max_f32_e32 v124, 1.0, v124
	v_max_f32_e32 v125, 1.0, v125
; __device__ __forceinline__ float sigmoidf_(float v) { return __builtin_amdgcn_rcpf(1.0f + __expf(-v)); }
; #define MEMFENCE asm volatile("" ::: "memory")
; __device__ __forceinline__ unsigned pack4_u8c(const f32x4 v) { const unsigned q0 = (unsigned)fmaxf(v[0] * 255.0f + 0.5f, 1.0f), q1 = (unsigned)fmaxf(v[1] * 255.0f + 0.5f, 1.0f), q2 = (unsigned)fmaxf(v[2] * 255.0f + 0.5f, 1.0f), q3 = (unsigned)fmaxf(v[3] * 255.0f + 0.5f, 1.0f);
;     return q0 | (q1 << 8) | (q2 << 16) | (q3 << 24); }
;     template <int KIND> __device__ __forceinline__ void run(f32x4 (&acc)[2][2][4][2], const Unit& u, int tid_in) const {
;     ...
;                 for (int m = 0; m < 4; ++m) { const float r = rs[ai * 4 + m] * (1.0f / GATE_WSCALE); u32x4 w;
; #pragma unroll
;                     for (int bj = 0; bj < 2; ++bj) { f32x4 a = acc[ai][bj][m][0] * r, b = acc[ai][bj][m][1] * r;
; #pragma unroll
;                         for (int j = 0; j < 4; ++j) { a[j] = sigmoidf_(a[j]); b[j] = sigmoidf_(b[j]); }
;                         if (bj == 0) { w.x = pack4_u8c(a); w.y = pack4_u8c(b); } else { w.z = pack4_u8c(a); w.w = pack4_u8c(b); } }
;                     gst[(ai * 4 + m) * 512 + tid] = w; MEMFENCE; }
	v_max_f32_e32 v111, 1.0, v111
	v_max_f32_e32 v110, 1.0, v110
	v_fma_f32 v108, v108, s4, 0.5
	v_fma_f32 v109, v109, s4, 0.5
	v_add_co_u32_e32 v104, vcc, s2, v120
	v_fma_f32 v94, v94, s4, 0.5
	v_rcp_f32_e32 v44, v44
	v_rcp_f32_e32 v45, v45
	v_rcp_f32_e32 v30, v30
	v_add_f32_e32 v28, 1.0, v28
	v_add_f32_e32 v29, 1.0, v29
	v_rcp_f32_e32 v24, v24
	v_rcp_f32_e32 v25, v25
	v_cvt_u32_f32_sdwa v124, v124 dst_sel:WORD_1 dst_unused:UNUSED_PAD src0_sel:DWORD
	v_cvt_u32_f32_sdwa v125, v125 dst_sel:BYTE_3 dst_unused:UNUSED_PAD src0_sel:DWORD
	v_cvt_u32_f32_e32 v111, v111
	v_cvt_u32_f32_e32 v110, v110
	v_max_f32_e32 v108, 1.0, v108
	v_max_f32_e32 v109, 1.0, v109
	v_addc_co_u32_e32 v105, vcc, 0, v121, vcc
	v_max_f32_e32 v95, 1.0, v95
	v_max_f32_e32 v94, 1.0, v94
	v_fma_f32 v92, v92, s4, 0.5
	v_fma_f32 v93, v93, s4, 0.5
	v_fma_f32 v78, v78, s4, 0.5
	v_rcp_f32_e32 v28, v28
	v_rcp_f32_e32 v29, v29
	v_cvt_u32_f32_sdwa v108, v108 dst_sel:WORD_1 dst_unused:UNUSED_PAD src0_sel:DWORD
	v_cvt_u32_f32_sdwa v109, v109 dst_sel:BYTE_3 dst_unused:UNUSED_PAD src0_sel:DWORD
	v_cvt_u32_f32_e32 v95, v95
	v_cvt_u32_f32_e32 v94, v94
	v_max_f32_e32 v92, 1.0, v92
	v_max_f32_e32 v93, 1.0, v93
	v_add_co_u32_e32 v88, vcc, s49, v120
	v_max_f32_e32 v79, 1.0, v79
	v_max_f32_e32 v78, 1.0, v78
	v_fma_f32 v76, v76, s4, 0.5
	v_fma_f32 v77, v77, s4, 0.5
	v_fma_f32 v62, v62, s4, 0.5
	v_cvt_u32_f32_sdwa v92, v92 dst_sel:WORD_1 dst_unused:UNUSED_PAD src0_sel:DWORD
	v_cvt_u32_f32_sdwa v93, v93 dst_sel:BYTE_3 dst_unused:UNUSED_PAD src0_sel:DWORD
	v_addc_co_u32_e32 v89, vcc, 0, v121, vcc
	v_cvt_u32_f32_e32 v79, v79
	v_cvt_u32_f32_e32 v78, v78
	v_max_f32_e32 v76, 1.0, v76
	v_max_f32_e32 v77, 1.0, v77
	s_movk_i32 s2, 0x6000
	v_max_f32_e32 v63, 1.0, v63
	v_max_f32_e32 v62, 1.0, v62
	v_fma_f32 v60, v60, s4, 0.5
	v_fma_f32 v61, v61, s4, 0.5
	v_fma_f32 v46, v46, s4, 0.5
	v_fma_f32 v27, v35, s4, 0.5
	v_fma_f32 v26, v26, s4, 0.5
	v_lshl_or_b32 v126, v127, 8, v126
	v_cvt_u32_f32_sdwa v76, v76 dst_sel:WORD_1 dst_unused:UNUSED_PAD src0_sel:DWORD
	v_cvt_u32_f32_sdwa v77, v77 dst_sel:BYTE_3 dst_unused:UNUSED_PAD src0_sel:DWORD
	v_add_co_u32_e32 v72, vcc, s2, v120
	v_cvt_u32_f32_e32 v63, v63
	v_cvt_u32_f32_e32 v62, v62
	v_max_f32_e32 v60, 1.0, v60
	v_max_f32_e32 v61, 1.0, v61
	v_max_f32_e32 v47, 1.0, v47
	v_max_f32_e32 v46, 1.0, v46
	v_fma_f32 v44, v44, s4, 0.5
	v_fma_f32 v45, v45, s4, 0.5
	v_fma_f32 v30, v30, s4, 0.5
	v_max_f32_e32 v27, 1.0, v27
	v_max_f32_e32 v26, 1.0, v26
	v_fma_f32 v24, v24, s4, 0.5
	v_fma_f32 v25, v25, s4, 0.5
	v_or3_b32 v130, v126, v124, v125
	v_lshl_or_b32 v110, v111, 8, v110
	v_addc_co_u32_e32 v73, vcc, 0, v121, vcc
	v_cvt_u32_f32_sdwa v60, v60 dst_sel:WORD_1 dst_unused:UNUSED_PAD src0_sel:DWORD
	v_cvt_u32_f32_sdwa v61, v61 dst_sel:BYTE_3 dst_unused:UNUSED_PAD src0_sel:DWORD
	v_cvt_u32_f32_e32 v47, v47
	v_cvt_u32_f32_e32 v46, v46
	v_max_f32_e32 v44, 1.0, v44
	v_max_f32_e32 v45, 1.0, v45
	v_max_f32_e32 v31, 1.0, v31
	v_max_f32_e32 v30, 1.0, v30
	v_fma_f32 v28, v28, s4, 0.5
	v_fma_f32 v29, v29, s4, 0.5
	v_cvt_u32_f32_e32 v27, v27
	v_cvt_u32_f32_e32 v26, v26
	v_max_f32_e32 v24, 1.0, v24
	v_max_f32_e32 v25, 1.0, v25
	global_store_dwordx4 v[120:121], v[128:131], off
	v_or3_b32 v114, v110, v108, v109
	v_lshl_or_b32 v94, v95, 8, v94
	v_add_co_u32_e32 v56, vcc, s77, v120
	v_cvt_u32_f32_sdwa v44, v44 dst_sel:WORD_1 dst_unused:UNUSED_PAD src0_sel:DWORD
	v_cvt_u32_f32_sdwa v45, v45 dst_sel:BYTE_3 dst_unused:UNUSED_PAD src0_sel:DWORD
	v_cvt_u32_f32_e32 v31, v31
	v_cvt_u32_f32_e32 v30, v30
	v_max_f32_e32 v28, 1.0, v28
	v_max_f32_e32 v29, 1.0, v29
	v_cvt_u32_f32_sdwa v24, v24 dst_sel:WORD_1 dst_unused:UNUSED_PAD src0_sel:DWORD
	v_cvt_u32_f32_sdwa v25, v25 dst_sel:BYTE_3 dst_unused:UNUSED_PAD src0_sel:DWORD
	global_store_dwordx4 v[104:105], v[112:115], off
	v_or3_b32 v98, v94, v92, v93
	v_lshl_or_b32 v78, v79, 8, v78
	v_addc_co_u32_e32 v57, vcc, 0, v121, vcc
	s_mov_b32 s2, 0xa000
	v_cvt_u32_f32_sdwa v28, v28 dst_sel:WORD_1 dst_unused:UNUSED_PAD src0_sel:DWORD
	v_cvt_u32_f32_sdwa v29, v29 dst_sel:BYTE_3 dst_unused:UNUSED_PAD src0_sel:DWORD
	global_store_dwordx4 v[88:89], v[96:99], off
	v_or3_b32 v82, v78, v76, v77
	v_lshl_or_b32 v62, v63, 8, v62
	v_add_co_u32_e32 v40, vcc, s2, v120
	global_store_dwordx4 v[72:73], v[80:83], off
	v_or3_b32 v66, v62, v60, v61
	v_lshl_or_b32 v46, v47, 8, v46
	v_addc_co_u32_e32 v41, vcc, 0, v121, vcc
	v_lshl_or_b32 v26, v27, 8, v26
	s_mov_b32 s2, 0xc000
	global_store_dwordx4 v[56:57], v[64:67], off
	v_or3_b32 v50, v46, v44, v45
	v_lshl_or_b32 v30, v31, 8, v30
	v_or3_b32 v35, v26, v24, v25
	v_add_co_u32_e32 v24, vcc, s2, v120
	global_store_dwordx4 v[40:41], v[48:51], off
	v_or3_b32 v34, v30, v28, v29
	v_addc_co_u32_e32 v25, vcc, 0, v121, vcc
; #define MEMFENCE asm volatile("" ::: "memory")
; __device__ __forceinline__ float sigmoidf_(float v) { return __builtin_amdgcn_rcpf(1.0f + __expf(-v)); }
; __device__ __forceinline__ unsigned pack4_u8c(const f32x4 v) { const unsigned q0 = (unsigned)fmaxf(v[0] * 255.0f + 0.5f, 1.0f), q1 = (unsigned)fmaxf(v[1] * 255.0f + 0.5f, 1.0f), q2 = (unsigned)fmaxf(v[2] * 255.0f + 0.5f, 1.0f), q3 = (unsigned)fmaxf(v[3] * 255.0f + 0.5f, 1.0f);
;     return q0 | (q1 << 8) | (q2 << 16) | (q3 << 24); }
;     template <int KIND> __device__ __forceinline__ void run(f32x4 (&acc)[2][2][4][2], const Unit& u, int tid_in) const {
;     ...
;                 for (int m = 0; m < 4; ++m) { const float r = rs[ai * 4 + m] * (1.0f / GATE_WSCALE); u32x4 w;
; #pragma unroll
;                     for (int bj = 0; bj < 2; ++bj) { f32x4 a = acc[ai][bj][m][0] * r, b = acc[ai][bj][m][1] * r;
; #pragma unroll
;                         for (int j = 0; j < 4; ++j) { a[j] = sigmoidf_(a[j]); b[j] = sigmoidf_(b[j]); }
;                         if (bj == 0) { w.x = pack4_u8c(a); w.y = pack4_u8c(b); } else { w.z = pack4_u8c(a); w.w = pack4_u8c(b); } }
;                     gst[(ai * 4 + m) * 512 + tid] = w; MEMFENCE; }
	global_store_dwordx4 v[24:25], v[32:35], off
	v_mul_f32_e32 v24, 0x3c800000, v137
	v_pk_mul_f32 v[20:21], v[20:21], v[24:25] op_sel_hi:[1,0]
	s_mov_b32 s33, s35
	v_mul_f32_e32 v21, 0xbfb8aa3b, v21
	v_exp_f32_e32 v21, v21
	v_mul_f32_e32 v20, 0xbfb8aa3b, v20
	v_exp_f32_e32 v25, v20
	s_mov_b32 s36, s34
	v_add_f32_e32 v20, 1.0, v21
	v_rcp_f32_e32 v26, v20
	v_pk_mul_f32 v[20:21], v[22:23], v[24:25] op_sel_hi:[1,0]
	v_add_f32_e32 v22, 1.0, v25
	v_mul_f32_e32 v20, 0xbfb8aa3b, v20
	v_exp_f32_e32 v20, v20
	v_rcp_f32_e32 v22, v22
	v_mul_f32_e32 v21, 0xbfb8aa3b, v21
	v_exp_f32_e32 v21, v21
	v_add_f32_e32 v20, 1.0, v20
	v_fma_f32 v23, v26, s4, 0.5
	v_fma_f32 v22, v22, s4, 0.5
	v_rcp_f32_e32 v20, v20
	v_max_f32_e32 v23, 1.0, v23
	v_max_f32_e32 v22, 1.0, v22
	v_add_f32_e32 v21, 1.0, v21
	v_cvt_u32_f32_e32 v23, v23
	v_cvt_u32_f32_e32 v22, v22
	v_rcp_f32_e32 v21, v21
	v_fma_f32 v20, v20, s4, 0.5
	v_max_f32_e32 v20, 1.0, v20
	v_lshl_or_b32 v22, v23, 8, v22
	v_cvt_u32_f32_sdwa v23, v20 dst_sel:WORD_1 dst_unused:UNUSED_PAD src0_sel:DWORD
	v_fma_f32 v20, v21, s4, 0.5
	v_max_f32_e32 v20, 1.0, v20
	v_cvt_u32_f32_sdwa v25, v20 dst_sel:BYTE_3 dst_unused:UNUSED_PAD src0_sel:DWORD
	s_mov_b64 s[12:13], s[10:11]
	s_mov_b64 s[2:3], s[8:9]
	v_pk_mul_f32 v[20:21], v[16:17], v[24:25] op_sel_hi:[1,0]
	s_nop 0
	v_mul_f32_e32 v16, 0xbfb8aa3b, v21
	v_mul_f32_e32 v20, 0xbfb8aa3b, v20
	v_pk_mul_f32 v[18:19], v[18:19], v[24:25] op_sel_hi:[1,0]
	v_exp_f32_e32 v17, v16
	v_exp_f32_e32 v20, v20
	v_mul_f32_e32 v18, 0xbfb8aa3b, v18
	v_mul_f32_e32 v19, 0xbfb8aa3b, v19
	v_exp_f32_e32 v18, v18
	v_exp_f32_e32 v19, v19
	v_add_f32_e32 v17, 1.0, v17
	v_add_f32_e32 v20, 1.0, v20
	v_rcp_f32_e32 v17, v17
	v_rcp_f32_e32 v20, v20
	v_add_f32_e32 v18, 1.0, v18
	v_add_f32_e32 v19, 1.0, v19
	v_rcp_f32_e32 v18, v18
	v_rcp_f32_e32 v19, v19
	v_fma_f32 v17, v17, s4, 0.5
	v_fma_f32 v20, v20, s4, 0.5
	v_max_f32_e32 v17, 1.0, v17
	v_max_f32_e32 v20, 1.0, v20
	v_fma_f32 v18, v18, s4, 0.5
	v_fma_f32 v19, v19, s4, 0.5
	v_pk_mul_f32 v[12:13], v[12:13], v[24:25] op_sel_hi:[1,0]
	v_cvt_u32_f32_e32 v17, v17
	v_cvt_u32_f32_e32 v20, v20
	v_max_f32_e32 v18, 1.0, v18
	v_max_f32_e32 v19, 1.0, v19
	v_mul_f32_e32 v13, 0xbfb8aa3b, v13
	v_cvt_u32_f32_sdwa v18, v18 dst_sel:WORD_1 dst_unused:UNUSED_PAD src0_sel:DWORD
	v_cvt_u32_f32_sdwa v19, v19 dst_sel:BYTE_3 dst_unused:UNUSED_PAD src0_sel:DWORD
	v_exp_f32_e32 v13, v13
	v_pk_mul_f32 v[8:9], v[8:9], v[24:25] op_sel_hi:[1,0]
	v_lshl_or_b32 v17, v17, 8, v20
	v_mul_f32_e32 v12, 0xbfb8aa3b, v12
	v_mul_f32_e32 v9, 0xbfb8aa3b, v9
	v_or3_b32 v17, v17, v18, v19
	v_exp_f32_e32 v18, v12
	v_add_f32_e32 v12, 1.0, v13
	v_exp_f32_e32 v9, v9
	v_rcp_f32_e32 v19, v12
	v_mul_f32_e32 v8, 0xbfb8aa3b, v8
	v_pk_mul_f32 v[12:13], v[14:15], v[24:25] op_sel_hi:[1,0]
	v_add_f32_e32 v14, 1.0, v18
	v_exp_f32_e32 v18, v8
	v_add_f32_e32 v8, 1.0, v9
	v_fma_f32 v15, v19, s4, 0.5
	v_rcp_f32_e32 v19, v8
	v_pk_mul_f32 v[8:9], v[10:11], v[24:25] op_sel_hi:[1,0]
	v_mul_f32_e32 v12, 0xbfb8aa3b, v12
	v_mul_f32_e32 v8, 0xbfb8aa3b, v8
	v_mul_f32_e32 v9, 0xbfb8aa3b, v9
	v_mul_f32_e32 v13, 0xbfb8aa3b, v13
	v_exp_f32_e32 v8, v8
	v_exp_f32_e32 v9, v9
	v_exp_f32_e32 v12, v12
	v_exp_f32_e32 v13, v13
	v_add_f32_e32 v10, 1.0, v18
	v_rcp_f32_e32 v10, v10
	v_add_f32_e32 v8, 1.0, v8
	v_add_f32_e32 v9, 1.0, v9
	v_rcp_f32_e32 v14, v14
	v_add_f32_e32 v12, 1.0, v12
	v_add_f32_e32 v13, 1.0, v13
	v_rcp_f32_e32 v8, v8
	v_rcp_f32_e32 v9, v9
	v_rcp_f32_e32 v12, v12
	v_rcp_f32_e32 v13, v13
	v_fma_f32 v11, v19, s4, 0.5
	v_fma_f32 v10, v10, s4, 0.5
	v_fma_f32 v14, v14, s4, 0.5
	v_max_f32_e32 v11, 1.0, v11
	v_max_f32_e32 v10, 1.0, v10
	v_fma_f32 v8, v8, s4, 0.5
	v_fma_f32 v9, v9, s4, 0.5
	v_max_f32_e32 v15, 1.0, v15
	v_max_f32_e32 v14, 1.0, v14
	v_fma_f32 v12, v12, s4, 0.5
	v_fma_f32 v13, v13, s4, 0.5
	v_cvt_u32_f32_e32 v11, v11
	v_cvt_u32_f32_e32 v10, v10
	v_max_f32_e32 v8, 1.0, v8
	v_max_f32_e32 v9, 1.0, v9
	v_cvt_u32_f32_e32 v15, v15
	v_cvt_u32_f32_e32 v14, v14
	v_max_f32_e32 v12, 1.0, v12
	v_max_f32_e32 v13, 1.0, v13
	v_cvt_u32_f32_sdwa v8, v8 dst_sel:WORD_1 dst_unused:UNUSED_PAD src0_sel:DWORD
	v_cvt_u32_f32_sdwa v9, v9 dst_sel:BYTE_3 dst_unused:UNUSED_PAD src0_sel:DWORD
	v_cvt_u32_f32_sdwa v12, v12 dst_sel:WORD_1 dst_unused:UNUSED_PAD src0_sel:DWORD
	v_cvt_u32_f32_sdwa v13, v13 dst_sel:BYTE_3 dst_unused:UNUSED_PAD src0_sel:DWORD
	v_lshl_or_b32 v10, v11, 8, v10
	v_lshl_or_b32 v14, v15, 8, v14
	v_or3_b32 v19, v10, v8, v9
	v_add_co_u32_e32 v8, vcc, 0xe000, v120
	v_or3_b32 v16, v22, v23, v25
	v_or3_b32 v18, v14, v12, v13
	v_addc_co_u32_e32 v9, vcc, 0, v121, vcc
	global_store_dwordx4 v[8:9], v[16:19], off
	s_and_b64 vcc, exec, s[6:7]
	s_cbranch_vccz .LBB0_867
	s_cmp_eq_u32 s101, 2
	s_cbranch_scc0 .Ldbj_MG0_pe
	s_barrier

; #define G_STAGE(bufoff, gbase, o0, h64) do { \
;         __builtin_amdgcn_global_load_lds((const unsigned*)((const char*)(gbase) + (o0)), (LAS unsigned*)(lds + (bufoff) + ldsw), 16, 0, 0); \
;         __builtin_amdgcn_global_load_lds((const unsigned*)((const char*)(gbase) + (h64) + (o0)), (LAS unsigned*)(lds + (bufoff) + ldsw + 8192), 16, 0, 0); } while (0)
; #define G_LDA(dst, b, h) do { _Pragma("unroll") for (int m = 0; m < 4; ++m) _Pragma("unroll") for (int k = 0; k < 2; ++k) dst[m][k] = *(const LAS bf16x8*)(lds + G_SA(b, h) + aoff + m * 2048 + k * 1024); } while (0)
; #define G_LDB(dst, b, h) do { _Pragma("unroll") for (int n = 0; n < 2; ++n) _Pragma("unroll") for (int k = 0; k < 2; ++k) dst[n][k] = *(const LAS bf16x8*)(lds + G_SB(b, h) + boff + n * 2048 + k * 1024); } while (0)
; #define G_WAIT_L(n) asm volatile("s_waitcnt lgkmcnt(" #n ")" ::: "memory")
; #define G_BAR __builtin_amdgcn_s_barrier()
; #define G_SCHED __builtin_amdgcn_sched_barrier(0)
;     ...
;     for (;;) {
;         const bool has_next = sched_next<PH, SUB>(E.ws, E.layer, ui + 1, nxt, E.x);
;         if (!has_next) nxt = cur;
;         const char* nA = nxt.A; const char* nB = nxt.B;
; #pragma unroll 1
;         for (int t = 0; t < nt; t += 2) {
;             const bool last = (t == nt - 2);
;             const char* a1 = cA + (size_t)(t + 1) * ckA;
;             const char* a2 = last ? nA : cA + (size_t)(t + 2) * ckA; const char* b2 = last ? nB : cB + (size_t)(t + 2) * kB;
;             const char* a3 = a2 + ckA; const char* b3 = b2 + kB;
;             G_LDB(B0, 0, 0); G_SCHED; G_LDA(At, 0, 0); G_STAGE(G_SA(1, 1), a1 + chA, cA0, qA);
;             G_WAIT_L(8); G_BAR; G_WAIT_L(0); G_MMA(0, 0, At, B0); G_BAR; G_SCHED;
;             G_LDB(B1, 0, 1); G_STAGE(G_SB(0, 0), b2, cB0, qB);
;             G_BAR; G_WAIT_L(0); G_MMA(0, 1, At, B1); G_BAR;
;             G_LDA(At, 0, 1); G_STAGE(G_SA(0, 0), a2, cA0, qA);
;             G_BAR; G_WAIT_L(0); G_MMA(1, 0, At, B0); G_BAR; G_SCHED;
.LBB0_889:
	s_add_u32 s6, s6, 0xb0080
	s_addc_u32 s7, s7, 0
	s_add_u32 s8, s18, 0x100
	s_addc_u32 s9, s19, 0
	s_mov_b32 s18, -2
	s_mov_b64 s[50:51], 0x20080
	s_mov_b64 s[52:53], 0x30000
	s_mov_b64 s[54:55], 0x10080
	s_mov_b64 s[58:59], 0x30080
	s_cmp_eq_u32 s101, 2
	s_cselect_b32 s101, 0, s101
	v_add_u32_e32 v239, 0x10000, v175
	ds_read_b128 v[136:139], v239 offset:0
	ds_read_b128 v[140:143], v239 offset:1024
	ds_read_b128 v[144:147], v239 offset:2048
	ds_read_b128 v[148:151], v239 offset:3072
.LBB0_890:
	s_add_u32 s4, s6, 0xfff50080
	s_addc_u32 s5, s7, -1
	s_add_i32 s19, 0, 0x10000
	s_cmp_eq_u32 s18, 4
	s_cselect_b32 s45, s15, s9
	s_cselect_b32 s44, s14, s8
	s_cselect_b32 s5, s13, s5
	s_cselect_b32 s4, s12, s4
	s_add_i32 m0, s22, 0xc000
	ds_read_b128 v[158:161], v176
	ds_read_b128 v[162:165], v176 offset:1024
	ds_read_b128 v[178:181], v176 offset:2048
	ds_read_b128 v[182:185], v176 offset:3072
	ds_read_b128 v[196:199], v176 offset:4096
	ds_read_b128 v[200:203], v176 offset:5120
	ds_read_b128 v[204:207], v176 offset:6144
	ds_read_b128 v[208:211], v176 offset:7168
	global_load_lds_dwordx4 v156, s[6:7]
	s_add_i32 m0, s22, 0xe000
	s_nop 0
	s_add_u32 vcc_lo, s6, s86
	s_addc_u32 vcc_hi, s7, s87
	global_load_lds_dwordx4 v156, vcc
	s_waitcnt lgkmcnt(8)
	s_cmp_eq_u32 s101, 1
	s_cbranch_scc1 .Ldb_MG1_sk
	s_barrier
.Ldb_MG1_sk:
	s_mov_b32 s101, 0
	s_waitcnt lgkmcnt(0)
	v_mfma_f32_16x16x32_bf16 v[104:107], v[136:139], v[158:161], v[104:107]
	v_mfma_f32_16x16x32_bf16 v[108:111], v[144:147], v[158:161], v[108:111]
	v_mfma_f32_16x16x32_bf16 v[132:135], v[136:139], v[178:181], v[132:135]
	v_mfma_f32_16x16x32_bf16 v[128:131], v[144:147], v[178:181], v[128:131]
	v_mfma_f32_16x16x32_bf16 v[124:127], v[136:139], v[196:199], v[124:127]
	v_mfma_f32_16x16x32_bf16 v[120:123], v[144:147], v[196:199], v[120:123]
	v_mfma_f32_16x16x32_bf16 v[116:119], v[136:139], v[204:207], v[116:119]
	v_mfma_f32_16x16x32_bf16 v[112:115], v[144:147], v[204:207], v[112:115]
	v_mfma_f32_16x16x32_bf16 v[104:107], v[140:143], v[162:165], v[104:107]
	v_mfma_f32_16x16x32_bf16 v[108:111], v[148:151], v[162:165], v[108:111]
	v_mfma_f32_16x16x32_bf16 v[132:135], v[140:143], v[182:185], v[132:135]
	v_mfma_f32_16x16x32_bf16 v[128:131], v[148:151], v[182:185], v[128:131]
	v_mfma_f32_16x16x32_bf16 v[124:127], v[140:143], v[200:203], v[124:127]
	v_mfma_f32_16x16x32_bf16 v[120:123], v[148:151], v[200:203], v[120:123]
	v_mfma_f32_16x16x32_bf16 v[116:119], v[140:143], v[208:211], v[116:119]
	v_mfma_f32_16x16x32_bf16 v[112:115], v[148:151], v[208:211], v[112:115]
	s_barrier
	s_add_i32 s43, 0, 0x14000
	s_add_i32 s19, s19, s21
	v_lshl_add_u64 v[2:3], s[44:45], 0, v[154:155]
	s_mov_b64 vcc, s[44:45]
	s_mov_b64 s[44:45], 0x10000
	s_mov_b32 m0, s19
	ds_read_b128 v[212:215], v239 offset:16384
	ds_read_b128 v[216:219], v239 offset:17408
	ds_read_b128 v[220:223], v239 offset:18432
	ds_read_b128 v[224:227], v239 offset:19456
	global_load_lds_dwordx4 v154, vcc
	v_lshl_add_u64 v[166:167], v[2:3], 0, s[44:45]
	s_add_i32 m0, s19, 0x2000
	s_nop 0
	global_load_lds_dwordx4 v[166:167], off
	s_barrier
	s_waitcnt lgkmcnt(0)
	v_mfma_f32_16x16x32_bf16 v[100:103], v[212:215], v[158:161], v[100:103]
	v_mfma_f32_16x16x32_bf16 v[96:99], v[220:223], v[158:161], v[96:99]
	v_mfma_f32_16x16x32_bf16 v[92:95], v[212:215], v[178:181], v[92:95]
	v_mfma_f32_16x16x32_bf16 v[88:91], v[220:223], v[178:181], v[88:91]
	v_mfma_f32_16x16x32_bf16 v[84:87], v[212:215], v[196:199], v[84:87]
	v_mfma_f32_16x16x32_bf16 v[80:83], v[220:223], v[196:199], v[80:83]
	v_mfma_f32_16x16x32_bf16 v[76:79], v[212:215], v[204:207], v[76:79]
	v_mfma_f32_16x16x32_bf16 v[72:75], v[220:223], v[204:207], v[72:75]
	v_mfma_f32_16x16x32_bf16 v[100:103], v[216:219], v[162:165], v[100:103]
	v_mfma_f32_16x16x32_bf16 v[96:99], v[224:227], v[162:165], v[96:99]
	v_mfma_f32_16x16x32_bf16 v[92:95], v[216:219], v[182:185], v[92:95]
	v_mfma_f32_16x16x32_bf16 v[88:91], v[224:227], v[182:185], v[88:91]
	v_mfma_f32_16x16x32_bf16 v[84:87], v[216:219], v[200:203], v[84:87]
	v_mfma_f32_16x16x32_bf16 v[80:83], v[224:227], v[200:203], v[80:83]
	v_mfma_f32_16x16x32_bf16 v[76:79], v[216:219], v[208:211], v[76:79]
	v_mfma_f32_16x16x32_bf16 v[72:75], v[224:227], v[208:211], v[72:75]
	s_barrier
	s_mov_b32 m0, s22
	v_lshl_add_u64 v[166:167], s[4:5], 0, v[152:153]
	ds_read_b128 v[158:161], v176 offset:16384
	ds_read_b128 v[162:165], v176 offset:17408
	ds_read_b128 v[178:181], v176 offset:18432
	ds_read_b128 v[182:185], v176 offset:19456
	ds_read_b128 v[196:199], v176 offset:20480
	ds_read_b128 v[200:203], v176 offset:21504
	ds_read_b128 v[204:207], v176 offset:22528
	ds_read_b128 v[208:211], v176 offset:23552
	global_load_lds_dwordx4 v152, s[4:5]
	s_mov_b32 m0, s23
	s_nop 0
	s_add_u32 vcc_lo, s4, s86
	s_addc_u32 vcc_hi, s5, s87
	global_load_lds_dwordx4 v152, vcc
	s_barrier
	s_waitcnt lgkmcnt(0)
	v_mfma_f32_16x16x32_bf16 v[68:71], v[136:139], v[158:161], v[68:71]
	v_mfma_f32_16x16x32_bf16 v[64:67], v[144:147], v[158:161], v[64:67]
	v_mfma_f32_16x16x32_bf16 v[60:63], v[136:139], v[178:181], v[60:63]
	v_mfma_f32_16x16x32_bf16 v[56:59], v[144:147], v[178:181], v[56:59]
	v_mfma_f32_16x16x32_bf16 v[52:55], v[136:139], v[196:199], v[52:55]
	v_mfma_f32_16x16x32_bf16 v[48:51], v[144:147], v[196:199], v[48:51]
	v_mfma_f32_16x16x32_bf16 v[44:47], v[136:139], v[204:207], v[44:47]
	v_mfma_f32_16x16x32_bf16 v[40:43], v[144:147], v[204:207], v[40:43]
	v_mfma_f32_16x16x32_bf16 v[68:71], v[140:143], v[162:165], v[68:71]
	v_mfma_f32_16x16x32_bf16 v[64:67], v[148:151], v[162:165], v[64:67]
	v_mfma_f32_16x16x32_bf16 v[60:63], v[140:143], v[182:185], v[60:63]
	v_mfma_f32_16x16x32_bf16 v[56:59], v[148:151], v[182:185], v[56:59]
	v_mfma_f32_16x16x32_bf16 v[52:55], v[140:143], v[200:203], v[52:55]
	v_mfma_f32_16x16x32_bf16 v[48:51], v[148:151], v[200:203], v[48:51]
	v_mfma_f32_16x16x32_bf16 v[44:47], v[140:143], v[208:211], v[44:47]
	v_mfma_f32_16x16x32_bf16 v[40:43], v[148:151], v[208:211], v[40:43]
	s_barrier
; #define G_STAGE(bufoff, gbase, o0, h64) do { \
;         __builtin_amdgcn_global_load_lds((const unsigned*)((const char*)(gbase) + (o0)), (LAS unsigned*)(lds + (bufoff) + ldsw), 16, 0, 0); \
;         __builtin_amdgcn_global_load_lds((const unsigned*)((const char*)(gbase) + (h64) + (o0)), (LAS unsigned*)(lds + (bufoff) + ldsw + 8192), 16, 0, 0); } while (0)
; #define G_LDA(dst, b, h) do { _Pragma("unroll") for (int m = 0; m < 4; ++m) _Pragma("unroll") for (int k = 0; k < 2; ++k) dst[m][k] = *(const LAS bf16x8*)(lds + G_SA(b, h) + aoff + m * 2048 + k * 1024); } while (0)
; #define G_LDB(dst, b, h) do { _Pragma("unroll") for (int n = 0; n < 2; ++n) _Pragma("unroll") for (int k = 0; k < 2; ++k) dst[n][k] = *(const LAS bf16x8*)(lds + G_SB(b, h) + boff + n * 2048 + k * 1024); } while (0)
; #define G_WAIT_V(n) asm volatile("s_waitcnt vmcnt(" #n ")" ::: "memory")
; #define G_WAIT_L(n) asm volatile("s_waitcnt lgkmcnt(" #n ")" ::: "memory")
; #define G_BAR __builtin_amdgcn_s_barrier()
; #define G_SCHED __builtin_amdgcn_sched_barrier(0)
;     ...
;             G_STAGE(G_SB(0, 1), b2 + chB, cB0, qB);
;             G_WAIT_V(6); G_BAR; G_MMA(1, 1, At, B1); G_BAR;
;             G_LDB(B0, 1, 0); G_SCHED; G_LDA(At, 1, 0); G_STAGE(G_SA(0, 1), a2 + chA, cA0, qA);
;             G_WAIT_L(8); G_BAR; G_WAIT_L(0); G_MMA(0, 0, At, B0); G_BAR; G_SCHED;
;             G_LDB(B1, 1, 1); G_STAGE(G_SB(1, 0), b3, cB0, qB);
	s_add_i32 s4, s43, s21
	v_lshl_add_u64 v[136:137], v[2:3], 0, s[0:1]
	s_mov_b32 m0, s4
	s_nop 0
	global_load_lds_dwordx4 v[136:137], off
	v_lshl_add_u64 v[136:137], v[2:3], 0, s[52:53]
	s_add_i32 m0, s4, 0x2000
	s_nop 0
	global_load_lds_dwordx4 v[136:137], off
	s_waitcnt vmcnt(6)
	s_barrier
	v_mfma_f32_16x16x32_bf16 v[36:39], v[212:215], v[158:161], v[36:39]
	v_mfma_f32_16x16x32_bf16 v[32:35], v[220:223], v[158:161], v[32:35]
	v_mfma_f32_16x16x32_bf16 v[28:31], v[212:215], v[178:181], v[28:31]
	v_mfma_f32_16x16x32_bf16 v[24:27], v[220:223], v[178:181], v[24:27]
	ds_read_b128 v[136:139], v239 offset:32768
	ds_read_b128 v[140:143], v239 offset:33792
	ds_read_b128 v[144:147], v239 offset:34816
	ds_read_b128 v[148:151], v239 offset:35840
	v_mfma_f32_16x16x32_bf16 v[20:23], v[212:215], v[196:199], v[20:23]
	v_mfma_f32_16x16x32_bf16 v[16:19], v[220:223], v[196:199], v[16:19]
	v_mfma_f32_16x16x32_bf16 v[12:15], v[212:215], v[204:207], v[12:15]
	v_mfma_f32_16x16x32_bf16 v[8:11], v[220:223], v[204:207], v[8:11]
	v_mfma_f32_16x16x32_bf16 v[36:39], v[216:219], v[162:165], v[36:39]
	v_mfma_f32_16x16x32_bf16 v[32:35], v[224:227], v[162:165], v[32:35]
	v_mfma_f32_16x16x32_bf16 v[28:31], v[216:219], v[182:185], v[28:31]
	v_mfma_f32_16x16x32_bf16 v[24:27], v[224:227], v[182:185], v[24:27]
	v_mfma_f32_16x16x32_bf16 v[20:23], v[216:219], v[200:203], v[20:23]
	v_mfma_f32_16x16x32_bf16 v[16:19], v[224:227], v[200:203], v[16:19]
	v_mfma_f32_16x16x32_bf16 v[12:15], v[216:219], v[208:211], v[12:15]
	v_mfma_f32_16x16x32_bf16 v[8:11], v[224:227], v[208:211], v[8:11]
	s_barrier
	s_add_i32 s4, 0, 0x18000
	s_mov_b32 m0, s24
	v_lshl_add_u64 v[172:173], v[166:167], 0, s[88:89]
	ds_read_b128 v[158:161], v176 offset:32768
	ds_read_b128 v[162:165], v176 offset:33792
	ds_read_b128 v[178:181], v176 offset:34816
	ds_read_b128 v[182:185], v176 offset:35840
	ds_read_b128 v[196:199], v176 offset:36864
	ds_read_b128 v[200:203], v176 offset:37888
	ds_read_b128 v[204:207], v176 offset:38912
	ds_read_b128 v[208:211], v176 offset:39936
	global_load_lds_dwordx4 v[172:173], off
	v_lshl_add_u64 v[172:173], v[166:167], 0, s[64:65]
	s_mov_b32 m0, s25
	s_nop 0
	global_load_lds_dwordx4 v[172:173], off
	s_waitcnt lgkmcnt(8)
	s_barrier
	s_waitcnt lgkmcnt(0)
	v_mfma_f32_16x16x32_bf16 v[104:107], v[136:139], v[158:161], v[104:107]
	v_mfma_f32_16x16x32_bf16 v[108:111], v[144:147], v[158:161], v[108:111]
	v_mfma_f32_16x16x32_bf16 v[132:135], v[136:139], v[178:181], v[132:135]
	v_mfma_f32_16x16x32_bf16 v[128:131], v[144:147], v[178:181], v[128:131]
	v_mfma_f32_16x16x32_bf16 v[124:127], v[136:139], v[196:199], v[124:127]
	v_mfma_f32_16x16x32_bf16 v[120:123], v[144:147], v[196:199], v[120:123]
	v_mfma_f32_16x16x32_bf16 v[116:119], v[136:139], v[204:207], v[116:119]
	v_mfma_f32_16x16x32_bf16 v[112:115], v[144:147], v[204:207], v[112:115]
	v_mfma_f32_16x16x32_bf16 v[104:107], v[140:143], v[162:165], v[104:107]
	v_mfma_f32_16x16x32_bf16 v[108:111], v[148:151], v[162:165], v[108:111]
	v_mfma_f32_16x16x32_bf16 v[132:135], v[140:143], v[182:185], v[132:135]
	v_mfma_f32_16x16x32_bf16 v[128:131], v[148:151], v[182:185], v[128:131]
	v_mfma_f32_16x16x32_bf16 v[124:127], v[140:143], v[200:203], v[124:127]
	v_mfma_f32_16x16x32_bf16 v[120:123], v[148:151], v[200:203], v[120:123]
	v_mfma_f32_16x16x32_bf16 v[116:119], v[140:143], v[208:211], v[116:119]
	v_mfma_f32_16x16x32_bf16 v[112:115], v[148:151], v[208:211], v[112:115]
	s_barrier
	s_add_i32 s5, 0, 0x1c000
	s_add_i32 s4, s4, s21
	v_lshl_add_u64 v[172:173], v[2:3], 0, s[46:47]
	s_mov_b32 m0, s4
	ds_read_b128 v[212:215], v239 offset:49152
	ds_read_b128 v[216:219], v239 offset:50176
	ds_read_b128 v[220:223], v239 offset:51200
	ds_read_b128 v[224:227], v239 offset:52224
	global_load_lds_dwordx4 v[172:173], off
	v_lshl_add_u64 v[172:173], v[2:3], 0, s[54:55]
	s_add_i32 m0, s4, 0x2000
	s_nop 0
	global_load_lds_dwordx4 v[172:173], off
	s_barrier
; #define G_STAGE(bufoff, gbase, o0, h64) do { \
;         __builtin_amdgcn_global_load_lds((const unsigned*)((const char*)(gbase) + (o0)), (LAS unsigned*)(lds + (bufoff) + ldsw), 16, 0, 0); \
;         __builtin_amdgcn_global_load_lds((const unsigned*)((const char*)(gbase) + (h64) + (o0)), (LAS unsigned*)(lds + (bufoff) + ldsw + 8192), 16, 0, 0); } while (0)
; #define G_LDA(dst, b, h) do { _Pragma("unroll") for (int m = 0; m < 4; ++m) _Pragma("unroll") for (int k = 0; k < 2; ++k) dst[m][k] = *(const LAS bf16x8*)(lds + G_SA(b, h) + aoff + m * 2048 + k * 1024); } while (0)
; #define G_LDB(dst, b, h) do { _Pragma("unroll") for (int n = 0; n < 2; ++n) _Pragma("unroll") for (int k = 0; k < 2; ++k) dst[n][k] = *(const LAS bf16x8*)(lds + G_SB(b, h) + boff + n * 2048 + k * 1024); } while (0)
; #define G_WAIT_V(n) asm volatile("s_waitcnt vmcnt(" #n ")" ::: "memory")
; #define G_WAIT_L(n) asm volatile("s_waitcnt lgkmcnt(" #n ")" ::: "memory")
; #define G_BAR __builtin_amdgcn_s_barrier()
; #define G_SCHED __builtin_amdgcn_sched_barrier(0)
;     ...
;             G_WAIT_L(8); G_BAR; G_WAIT_L(0); G_MMA(0, 0, At, B0); G_BAR; G_SCHED;
;             G_LDB(B1, 1, 1); G_STAGE(G_SB(1, 0), b3, cB0, qB);
;             G_BAR; G_WAIT_L(0); G_MMA(0, 1, At, B1); G_BAR;
;             G_LDA(At, 1, 1); G_STAGE(G_SA(1, 0), a3, cA0, qA);
;             G_BAR; G_WAIT_L(0); G_MMA(1, 0, At, B0); G_BAR; G_SCHED;
;             G_STAGE(G_SB(1, 1), b3 + chB, cB0, qB);
;             G_WAIT_V(6); G_BAR; G_MMA(1, 1, At, B1); G_BAR;
;         }
	s_waitcnt lgkmcnt(0)
	v_mfma_f32_16x16x32_bf16 v[100:103], v[212:215], v[158:161], v[100:103]
	v_mfma_f32_16x16x32_bf16 v[96:99], v[220:223], v[158:161], v[96:99]
	v_mfma_f32_16x16x32_bf16 v[92:95], v[212:215], v[178:181], v[92:95]
	v_mfma_f32_16x16x32_bf16 v[88:91], v[220:223], v[178:181], v[88:91]
	v_mfma_f32_16x16x32_bf16 v[84:87], v[212:215], v[196:199], v[84:87]
	v_mfma_f32_16x16x32_bf16 v[80:83], v[220:223], v[196:199], v[80:83]
	v_mfma_f32_16x16x32_bf16 v[76:79], v[212:215], v[204:207], v[76:79]
	v_mfma_f32_16x16x32_bf16 v[72:75], v[220:223], v[204:207], v[72:75]
	v_mfma_f32_16x16x32_bf16 v[100:103], v[216:219], v[162:165], v[100:103]
	v_mfma_f32_16x16x32_bf16 v[96:99], v[224:227], v[162:165], v[96:99]
	v_mfma_f32_16x16x32_bf16 v[92:95], v[216:219], v[182:185], v[92:95]
	v_mfma_f32_16x16x32_bf16 v[88:91], v[224:227], v[182:185], v[88:91]
	v_mfma_f32_16x16x32_bf16 v[84:87], v[216:219], v[200:203], v[84:87]
	v_mfma_f32_16x16x32_bf16 v[80:83], v[224:227], v[200:203], v[80:83]
	v_mfma_f32_16x16x32_bf16 v[76:79], v[216:219], v[208:211], v[76:79]
	v_mfma_f32_16x16x32_bf16 v[72:75], v[224:227], v[208:211], v[72:75]
	s_barrier
	s_mov_b32 m0, s26
	v_lshl_add_u64 v[172:173], v[166:167], 0, s[46:47]
	ds_read_b128 v[158:161], v176 offset:49152
	ds_read_b128 v[162:165], v176 offset:50176
	ds_read_b128 v[178:181], v176 offset:51200
	ds_read_b128 v[182:185], v176 offset:52224
	ds_read_b128 v[196:199], v176 offset:53248
	ds_read_b128 v[200:203], v176 offset:54272
	ds_read_b128 v[204:207], v176 offset:55296
	ds_read_b128 v[208:211], v176 offset:56320
	global_load_lds_dwordx4 v[172:173], off
	v_lshl_add_u64 v[166:167], v[166:167], 0, s[66:67]
	s_mov_b32 m0, s27
	s_nop 0
	global_load_lds_dwordx4 v[166:167], off
	s_barrier
	s_waitcnt lgkmcnt(0)
	v_mfma_f32_16x16x32_bf16 v[68:71], v[136:139], v[158:161], v[68:71]
	v_mfma_f32_16x16x32_bf16 v[64:67], v[144:147], v[158:161], v[64:67]
	v_mfma_f32_16x16x32_bf16 v[60:63], v[136:139], v[178:181], v[60:63]
	v_mfma_f32_16x16x32_bf16 v[56:59], v[144:147], v[178:181], v[56:59]
	v_mfma_f32_16x16x32_bf16 v[52:55], v[136:139], v[196:199], v[52:55]
	v_mfma_f32_16x16x32_bf16 v[48:51], v[144:147], v[196:199], v[48:51]
	v_mfma_f32_16x16x32_bf16 v[44:47], v[136:139], v[204:207], v[44:47]
	v_mfma_f32_16x16x32_bf16 v[40:43], v[144:147], v[204:207], v[40:43]
	v_mfma_f32_16x16x32_bf16 v[68:71], v[140:143], v[162:165], v[68:71]
	v_mfma_f32_16x16x32_bf16 v[64:67], v[148:151], v[162:165], v[64:67]
	v_mfma_f32_16x16x32_bf16 v[60:63], v[140:143], v[182:185], v[60:63]
	v_mfma_f32_16x16x32_bf16 v[56:59], v[148:151], v[182:185], v[56:59]
	v_mfma_f32_16x16x32_bf16 v[52:55], v[140:143], v[200:203], v[52:55]
	v_mfma_f32_16x16x32_bf16 v[48:51], v[148:151], v[200:203], v[48:51]
	v_mfma_f32_16x16x32_bf16 v[44:47], v[140:143], v[208:211], v[44:47]
	v_mfma_f32_16x16x32_bf16 v[40:43], v[148:151], v[208:211], v[40:43]
	s_barrier
	s_add_i32 s4, s5, s21
	v_lshl_add_u64 v[136:137], v[2:3], 0, s[50:51]
	s_mov_b32 m0, s4
	v_lshl_add_u64 v[2:3], v[2:3], 0, s[58:59]
	global_load_lds_dwordx4 v[136:137], off
	s_add_i32 m0, s4, 0x2000
	s_nop 0
	global_load_lds_dwordx4 v[2:3], off
	s_add_i32 s18, s18, 2
	s_add_u32 s6, s6, 0x100
	s_addc_u32 s7, s7, 0
	s_add_u32 s8, s8, 0x100
	s_addc_u32 s9, s9, 0
	s_cmp_gt_u32 s18, 5
	s_waitcnt vmcnt(6)
	s_barrier
	v_mfma_f32_16x16x32_bf16 v[36:39], v[212:215], v[158:161], v[36:39]
	v_mfma_f32_16x16x32_bf16 v[32:35], v[220:223], v[158:161], v[32:35]
	v_mfma_f32_16x16x32_bf16 v[28:31], v[212:215], v[178:181], v[28:31]
	v_mfma_f32_16x16x32_bf16 v[24:27], v[220:223], v[178:181], v[24:27]
	ds_read_b128 v[136:139], v239 offset:0
	ds_read_b128 v[140:143], v239 offset:1024
	ds_read_b128 v[144:147], v239 offset:2048
	ds_read_b128 v[148:151], v239 offset:3072
	v_mfma_f32_16x16x32_bf16 v[20:23], v[212:215], v[196:199], v[20:23]
	v_mfma_f32_16x16x32_bf16 v[16:19], v[220:223], v[196:199], v[16:19]
	v_mfma_f32_16x16x32_bf16 v[12:15], v[212:215], v[204:207], v[12:15]
	v_mfma_f32_16x16x32_bf16 v[8:11], v[220:223], v[204:207], v[8:11]
	v_mfma_f32_16x16x32_bf16 v[36:39], v[216:219], v[162:165], v[36:39]
	v_mfma_f32_16x16x32_bf16 v[32:35], v[224:227], v[162:165], v[32:35]
	v_mfma_f32_16x16x32_bf16 v[28:31], v[216:219], v[182:185], v[28:31]
	v_mfma_f32_16x16x32_bf16 v[24:27], v[224:227], v[182:185], v[24:27]
	v_mfma_f32_16x16x32_bf16 v[20:23], v[216:219], v[200:203], v[20:23]
	v_mfma_f32_16x16x32_bf16 v[16:19], v[224:227], v[200:203], v[16:19]
	v_mfma_f32_16x16x32_bf16 v[12:15], v[216:219], v[208:211], v[12:15]
	v_mfma_f32_16x16x32_bf16 v[8:11], v[224:227], v[208:211], v[8:11]
	s_cbranch_scc0 .Ldb_MG1_cont
	v_readfirstlane_b32 s101, v186
	s_cmpk_gt_u32 s101, 0xff
	s_cbranch_scc1 .Ldb_MG1_young
	s_barrier
	s_mov_b32 s101, 1
	s_branch .Ldb_MG1_exit

;     template <int KIND> __device__ __forceinline__ void run(f32x4 (&acc)[2][2][4][2], const Unit& u, int tid_in) const {
;     ...
;         if constexpr (KIND == K_MG_B) { const int r = u.aux;
;             const u32x4* gst = (const u32x4*)((unsigned char*)x + 32 * MiB) + ((size_t)(blockIdx.x * 2 + (u.ord & 1)) * 3) * 4096;
; #pragma unroll
;             for (int ai = 0; ai < 2; ++ai)
; #pragma unroll
;                 for (int mh = 0; mh < 2; ++mh) { u32x4 qa[2], qb[2];
; #pragma unroll
;                     for (int ml = 0; ml < 2; ++ml) { const int m = mh * 2 + ml; qa[ml] = gst[(size_t)r * 4096 + (ai * 4 + m) * 512 + tid]; qb[ml] = (r < 2) ? gst[(size_t)(r + 1) * 4096 + (ai * 4 + m) * 512 + tid] : qa[ml]; }
; #pragma unroll
;                     for (int ml = 0; ml < 2; ++ml) { const int m = mh * 2 + ml; int row = rbase + ai * 128 + m * 16; asm volatile("" : "+v"(row));
; #pragma unroll
;                         for (int bj = 0; bj < 2; ++bj) {
;                             const f32x4 n0 = unpack4_raw(bj == 0 ? qa[ml].x : qa[ml].z), n1 = unpack4_raw(bj == 0 ? qa[ml].y : qa[ml].w);
;                             if (r < 2) { const f32x4 d0 = unpack4_raw(bj == 0 ? qb[ml].x : qb[ml].z), d1 = unpack4_raw(bj == 0 ? qb[ml].y : qb[ml].w);
; #pragma unroll
;                                 for (int j = 0; j < 4; ++j) { acc[ai][bj][m][0][j] *= n0[j] * __builtin_amdgcn_rcpf(d0[j]); acc[ai][bj][m][1][j] *= n1[j] * __builtin_amdgcn_rcpf(d1[j]); } }
.Ldb_MG1_exit:
	s_waitcnt lgkmcnt(0)
	s_and_b32 s3, s3, 1
	s_or_b32 s3, s3, s60
	s_mul_hi_u32 s4, s3, 0x30000
	s_mul_i32 s3, s3, 0x30000
	s_add_u32 s6, s35, s3
	s_addc_u32 s7, s36, s4
	s_ashr_i32 s3, s2, 31
	s_lshl_b64 s[4:5], s[2:3], 16
	s_add_u32 s4, s6, s4
	s_addc_u32 s5, s7, s5
	v_lshlrev_b32_e32 v166, 4, v174
	s_cmp_gt_i32 s2, 1
	s_cbranch_scc1 .Lmg1_r2
	s_add_u32 s8, s4, 0x10000
	s_addc_u32 s9, s5, 0
	global_load_dwordx4 v[136:139], v166, s[4:5]
	global_load_dwordx4 v[212:215], v166, s[8:9]
	s_add_u32 s4, s4, 0x2000
	s_addc_u32 s5, s5, 0
	s_add_u32 s8, s8, 0x2000
	s_addc_u32 s9, s9, 0
	global_load_dwordx4 v[140:143], v166, s[4:5]
	global_load_dwordx4 v[216:219], v166, s[8:9]
	s_add_u32 s4, s4, 0x2000
	s_addc_u32 s5, s5, 0
	s_add_u32 s8, s8, 0x2000
	s_addc_u32 s9, s9, 0
	global_load_dwordx4 v[144:147], v166, s[4:5]
	global_load_dwordx4 v[220:223], v166, s[8:9]
	s_add_u32 s4, s4, 0x2000
	s_addc_u32 s5, s5, 0
	s_add_u32 s8, s8, 0x2000
	s_addc_u32 s9, s9, 0
	global_load_dwordx4 v[148:151], v166, s[4:5]
	global_load_dwordx4 v[224:227], v166, s[8:9]
	s_add_u32 s4, s4, 0x2000
	s_addc_u32 s5, s5, 0
	s_add_u32 s8, s8, 0x2000
	s_addc_u32 s9, s9, 0
	global_load_dwordx4 v[196:199], v166, s[4:5]
	global_load_dwordx4 v[178:181], v166, s[8:9]
	s_add_u32 s4, s4, 0x2000
	s_addc_u32 s5, s5, 0
	s_add_u32 s8, s8, 0x2000
	s_addc_u32 s9, s9, 0
	global_load_dwordx4 v[200:203], v166, s[4:5]
	global_load_dwordx4 v[182:185], v166, s[8:9]
	s_add_u32 s4, s4, 0x2000
	s_addc_u32 s5, s5, 0
	s_add_u32 s8, s8, 0x2000
	s_addc_u32 s9, s9, 0
	global_load_dwordx4 v[204:207], v166, s[4:5]
	global_load_dwordx4 v[158:161], v166, s[8:9]
	s_add_u32 s4, s4, 0x2000
	s_addc_u32 s5, s5, 0
	s_add_u32 s8, s8, 0x2000
	s_addc_u32 s9, s9, 0
	global_load_dwordx4 v[208:211], v166, s[4:5]
	global_load_dwordx4 v[162:165], v166, s[8:9]
	s_waitcnt vmcnt(14)
	v_cvt_f32_ubyte0_e32 v240, v136
	v_cvt_f32_ubyte1_e32 v241, v136
	v_cvt_f32_ubyte2_e32 v242, v136
	v_cvt_f32_ubyte3_e32 v243, v136
	v_cvt_f32_ubyte0_e32 v244, v137
	v_cvt_f32_ubyte1_e32 v245, v137
	v_cvt_f32_ubyte2_e32 v246, v137
	v_cvt_f32_ubyte3_e32 v247, v137
	v_cvt_f32_ubyte0_e32 v248, v212
	v_cvt_f32_ubyte1_e32 v249, v212
	v_cvt_f32_ubyte2_e32 v250, v212
	v_cvt_f32_ubyte3_e32 v251, v212
	v_cvt_f32_ubyte0_e32 v252, v213
	v_cvt_f32_ubyte1_e32 v253, v213
	v_cvt_f32_ubyte2_e32 v254, v213
	v_cvt_f32_ubyte3_e32 v255, v213
	v_rcp_iflag_f32_e32 v248, v248
	v_rcp_iflag_f32_e32 v249, v249
	v_rcp_iflag_f32_e32 v250, v250
	v_rcp_iflag_f32_e32 v251, v251
	v_rcp_iflag_f32_e32 v252, v252
	v_rcp_iflag_f32_e32 v253, v253
	v_rcp_iflag_f32_e32 v254, v254
	v_rcp_iflag_f32_e32 v255, v255
	v_pk_mul_f32 v[240:241], v[248:249], v[240:241]
	v_pk_mul_f32 v[242:243], v[250:251], v[242:243]
	v_pk_mul_f32 v[244:245], v[252:253], v[244:245]
	v_pk_mul_f32 v[246:247], v[254:255], v[246:247]
	v_pk_mul_f32 v[104:105], v[104:105], v[240:241]
	v_pk_mul_f32 v[106:107], v[106:107], v[242:243]
	v_pk_mul_f32 v[108:109], v[108:109], v[244:245]
	v_pk_mul_f32 v[110:111], v[110:111], v[246:247]
	v_cvt_f32_ubyte0_e32 v240, v138
	v_cvt_f32_ubyte1_e32 v241, v138
	v_cvt_f32_ubyte2_e32 v242, v138
	v_cvt_f32_ubyte3_e32 v243, v138
	v_cvt_f32_ubyte0_e32 v244, v139
	v_cvt_f32_ubyte1_e32 v245, v139
	v_cvt_f32_ubyte2_e32 v246, v139
	v_cvt_f32_ubyte3_e32 v247, v139
	v_cvt_f32_ubyte0_e32 v248, v214
	v_cvt_f32_ubyte1_e32 v249, v214
	v_cvt_f32_ubyte2_e32 v250, v214
	v_cvt_f32_ubyte3_e32 v251, v214
	v_cvt_f32_ubyte0_e32 v252, v215
	v_cvt_f32_ubyte1_e32 v253, v215
	v_cvt_f32_ubyte2_e32 v254, v215
	v_cvt_f32_ubyte3_e32 v255, v215
	v_rcp_iflag_f32_e32 v248, v248
	v_rcp_iflag_f32_e32 v249, v249
	v_rcp_iflag_f32_e32 v250, v250
	v_rcp_iflag_f32_e32 v251, v251
	v_rcp_iflag_f32_e32 v252, v252
	v_rcp_iflag_f32_e32 v253, v253
	v_rcp_iflag_f32_e32 v254, v254
	v_rcp_iflag_f32_e32 v255, v255
	v_pk_mul_f32 v[240:241], v[248:249], v[240:241]
	v_pk_mul_f32 v[242:243], v[250:251], v[242:243]
	v_pk_mul_f32 v[244:245], v[252:253], v[244:245]
	v_pk_mul_f32 v[246:247], v[254:255], v[246:247]
	v_pk_mul_f32 v[100:101], v[100:101], v[240:241]
	v_pk_mul_f32 v[102:103], v[102:103], v[242:243]
	v_pk_mul_f32 v[96:97], v[96:97], v[244:245]
	v_pk_mul_f32 v[98:99], v[98:99], v[246:247]
	s_waitcnt vmcnt(12)
	v_cvt_f32_ubyte0_e32 v240, v140
	v_cvt_f32_ubyte1_e32 v241, v140
	v_cvt_f32_ubyte2_e32 v242, v140
	v_cvt_f32_ubyte3_e32 v243, v140
	v_cvt_f32_ubyte0_e32 v244, v141
	v_cvt_f32_ubyte1_e32 v245, v141
	v_cvt_f32_ubyte2_e32 v246, v141
	v_cvt_f32_ubyte3_e32 v247, v141
	v_cvt_f32_ubyte0_e32 v248, v216
	v_cvt_f32_ubyte1_e32 v249, v216
	v_cvt_f32_ubyte2_e32 v250, v216
	v_cvt_f32_ubyte3_e32 v251, v216
	v_cvt_f32_ubyte0_e32 v252, v217
	v_cvt_f32_ubyte1_e32 v253, v217
	v_cvt_f32_ubyte2_e32 v254, v217
	v_cvt_f32_ubyte3_e32 v255, v217
	v_rcp_iflag_f32_e32 v248, v248
	v_rcp_iflag_f32_e32 v249, v249
	v_rcp_iflag_f32_e32 v250, v250
	v_rcp_iflag_f32_e32 v251, v251
	v_rcp_iflag_f32_e32 v252, v252
	v_rcp_iflag_f32_e32 v253, v253
	v_rcp_iflag_f32_e32 v254, v254
	v_rcp_iflag_f32_e32 v255, v255
	v_pk_mul_f32 v[240:241], v[248:249], v[240:241]
	v_pk_mul_f32 v[242:243], v[250:251], v[242:243]
	v_pk_mul_f32 v[244:245], v[252:253], v[244:245]
	v_pk_mul_f32 v[246:247], v[254:255], v[246:247]
	v_pk_mul_f32 v[132:133], v[132:133], v[240:241]
	v_pk_mul_f32 v[134:135], v[134:135], v[242:243]
	v_pk_mul_f32 v[128:129], v[128:129], v[244:245]
	v_pk_mul_f32 v[130:131], v[130:131], v[246:247]
	v_cvt_f32_ubyte0_e32 v240, v142
	v_cvt_f32_ubyte1_e32 v241, v142
	v_cvt_f32_ubyte2_e32 v242, v142
	v_cvt_f32_ubyte3_e32 v243, v142
	v_cvt_f32_ubyte0_e32 v244, v143
	v_cvt_f32_ubyte1_e32 v245, v143
	v_cvt_f32_ubyte2_e32 v246, v143
	v_cvt_f32_ubyte3_e32 v247, v143
	v_cvt_f32_ubyte0_e32 v248, v218
	v_cvt_f32_ubyte1_e32 v249, v218
	v_cvt_f32_ubyte2_e32 v250, v218
	v_cvt_f32_ubyte3_e32 v251, v218
	v_cvt_f32_ubyte0_e32 v252, v219
	v_cvt_f32_ubyte1_e32 v253, v219
	v_cvt_f32_ubyte2_e32 v254, v219
	v_cvt_f32_ubyte3_e32 v255, v219
	v_rcp_iflag_f32_e32 v248, v248
	v_rcp_iflag_f32_e32 v249, v249
	v_rcp_iflag_f32_e32 v250, v250
	v_rcp_iflag_f32_e32 v251, v251
	v_rcp_iflag_f32_e32 v252, v252
	v_rcp_iflag_f32_e32 v253, v253
	v_rcp_iflag_f32_e32 v254, v254
	v_rcp_iflag_f32_e32 v255, v255
	v_pk_mul_f32 v[240:241], v[248:249], v[240:241]
	v_pk_mul_f32 v[242:243], v[250:251], v[242:243]
	v_pk_mul_f32 v[244:245], v[252:253], v[244:245]
	v_pk_mul_f32 v[246:247], v[254:255], v[246:247]
	v_pk_mul_f32 v[92:93], v[92:93], v[240:241]
	v_pk_mul_f32 v[94:95], v[94:95], v[242:243]
	v_pk_mul_f32 v[88:89], v[88:89], v[244:245]
	v_pk_mul_f32 v[90:91], v[90:91], v[246:247]
	s_waitcnt vmcnt(10)
;     template <int KIND> __device__ __forceinline__ void run(f32x4 (&acc)[2][2][4][2], const Unit& u, int tid_in) const {
;     ...
;                     for (int ml = 0; ml < 2; ++ml) { const int m = mh * 2 + ml; qa[ml] = gst[(size_t)r * 4096 + (ai * 4 + m) * 512 + tid]; qb[ml] = (r < 2) ? gst[(size_t)(r + 1) * 4096 + (ai * 4 + m) * 512 + tid] : qa[ml]; }
; #pragma unroll
;                     for (int ml = 0; ml < 2; ++ml) { const int m = mh * 2 + ml; int row = rbase + ai * 128 + m * 16; asm volatile("" : "+v"(row));
; #pragma unroll
;                         for (int bj = 0; bj < 2; ++bj) {
;                             const f32x4 n0 = unpack4_raw(bj == 0 ? qa[ml].x : qa[ml].z), n1 = unpack4_raw(bj == 0 ? qa[ml].y : qa[ml].w);
;                             if (r < 2) { const f32x4 d0 = unpack4_raw(bj == 0 ? qb[ml].x : qb[ml].z), d1 = unpack4_raw(bj == 0 ? qb[ml].y : qb[ml].w);
; #pragma unroll
;                                 for (int j = 0; j < 4; ++j) { acc[ai][bj][m][0][j] *= n0[j] * __builtin_amdgcn_rcpf(d0[j]); acc[ai][bj][m][1][j] *= n1[j] * __builtin_amdgcn_rcpf(d1[j]); } }
	v_cvt_f32_ubyte0_e32 v240, v144
	v_cvt_f32_ubyte1_e32 v241, v144
	v_cvt_f32_ubyte2_e32 v242, v144
	v_cvt_f32_ubyte3_e32 v243, v144
	v_cvt_f32_ubyte0_e32 v244, v145
	v_cvt_f32_ubyte1_e32 v245, v145
	v_cvt_f32_ubyte2_e32 v246, v145
	v_cvt_f32_ubyte3_e32 v247, v145
	v_cvt_f32_ubyte0_e32 v248, v220
	v_cvt_f32_ubyte1_e32 v249, v220
	v_cvt_f32_ubyte2_e32 v250, v220
	v_cvt_f32_ubyte3_e32 v251, v220
	v_cvt_f32_ubyte0_e32 v252, v221
	v_cvt_f32_ubyte1_e32 v253, v221
	v_cvt_f32_ubyte2_e32 v254, v221
	v_cvt_f32_ubyte3_e32 v255, v221
	v_rcp_iflag_f32_e32 v248, v248
	v_rcp_iflag_f32_e32 v249, v249
	v_rcp_iflag_f32_e32 v250, v250
	v_rcp_iflag_f32_e32 v251, v251
	v_rcp_iflag_f32_e32 v252, v252
	v_rcp_iflag_f32_e32 v253, v253
	v_rcp_iflag_f32_e32 v254, v254
	v_rcp_iflag_f32_e32 v255, v255
	v_pk_mul_f32 v[240:241], v[248:249], v[240:241]
	v_pk_mul_f32 v[242:243], v[250:251], v[242:243]
	v_pk_mul_f32 v[244:245], v[252:253], v[244:245]
	v_pk_mul_f32 v[246:247], v[254:255], v[246:247]
	v_pk_mul_f32 v[124:125], v[124:125], v[240:241]
	v_pk_mul_f32 v[126:127], v[126:127], v[242:243]
	v_pk_mul_f32 v[120:121], v[120:121], v[244:245]
	v_pk_mul_f32 v[122:123], v[122:123], v[246:247]
	v_cvt_f32_ubyte0_e32 v240, v146
	v_cvt_f32_ubyte1_e32 v241, v146
	v_cvt_f32_ubyte2_e32 v242, v146
	v_cvt_f32_ubyte3_e32 v243, v146
	v_cvt_f32_ubyte0_e32 v244, v147
	v_cvt_f32_ubyte1_e32 v245, v147
	v_cvt_f32_ubyte2_e32 v246, v147
	v_cvt_f32_ubyte3_e32 v247, v147
	v_cvt_f32_ubyte0_e32 v248, v222
	v_cvt_f32_ubyte1_e32 v249, v222
	v_cvt_f32_ubyte2_e32 v250, v222
	v_cvt_f32_ubyte3_e32 v251, v222
	v_cvt_f32_ubyte0_e32 v252, v223
	v_cvt_f32_ubyte1_e32 v253, v223
	v_cvt_f32_ubyte2_e32 v254, v223
	v_cvt_f32_ubyte3_e32 v255, v223
	v_rcp_iflag_f32_e32 v248, v248
	v_rcp_iflag_f32_e32 v249, v249
	v_rcp_iflag_f32_e32 v250, v250
	v_rcp_iflag_f32_e32 v251, v251
	v_rcp_iflag_f32_e32 v252, v252
	v_rcp_iflag_f32_e32 v253, v253
	v_rcp_iflag_f32_e32 v254, v254
	v_rcp_iflag_f32_e32 v255, v255
	v_pk_mul_f32 v[240:241], v[248:249], v[240:241]
	v_pk_mul_f32 v[242:243], v[250:251], v[242:243]
	v_pk_mul_f32 v[244:245], v[252:253], v[244:245]
	v_pk_mul_f32 v[246:247], v[254:255], v[246:247]
	v_pk_mul_f32 v[84:85], v[84:85], v[240:241]
	v_pk_mul_f32 v[86:87], v[86:87], v[242:243]
	v_pk_mul_f32 v[80:81], v[80:81], v[244:245]
	v_pk_mul_f32 v[82:83], v[82:83], v[246:247]
	s_waitcnt vmcnt(8)
	v_cvt_f32_ubyte0_e32 v240, v148
	v_cvt_f32_ubyte1_e32 v241, v148
	v_cvt_f32_ubyte2_e32 v242, v148
	v_cvt_f32_ubyte3_e32 v243, v148
	v_cvt_f32_ubyte0_e32 v244, v149
	v_cvt_f32_ubyte1_e32 v245, v149
	v_cvt_f32_ubyte2_e32 v246, v149
	v_cvt_f32_ubyte3_e32 v247, v149
	v_cvt_f32_ubyte0_e32 v248, v224
	v_cvt_f32_ubyte1_e32 v249, v224
	v_cvt_f32_ubyte2_e32 v250, v224
	v_cvt_f32_ubyte3_e32 v251, v224
	v_cvt_f32_ubyte0_e32 v252, v225
	v_cvt_f32_ubyte1_e32 v253, v225
	v_cvt_f32_ubyte2_e32 v254, v225
	v_cvt_f32_ubyte3_e32 v255, v225
	v_rcp_iflag_f32_e32 v248, v248
	v_rcp_iflag_f32_e32 v249, v249
	v_rcp_iflag_f32_e32 v250, v250
	v_rcp_iflag_f32_e32 v251, v251
	v_rcp_iflag_f32_e32 v252, v252
	v_rcp_iflag_f32_e32 v253, v253
	v_rcp_iflag_f32_e32 v254, v254
	v_rcp_iflag_f32_e32 v255, v255
	v_pk_mul_f32 v[240:241], v[248:249], v[240:241]
	v_pk_mul_f32 v[242:243], v[250:251], v[242:243]
	v_pk_mul_f32 v[244:245], v[252:253], v[244:245]
	v_pk_mul_f32 v[246:247], v[254:255], v[246:247]
	v_pk_mul_f32 v[116:117], v[116:117], v[240:241]
	v_pk_mul_f32 v[118:119], v[118:119], v[242:243]
	v_pk_mul_f32 v[112:113], v[112:113], v[244:245]
	v_pk_mul_f32 v[114:115], v[114:115], v[246:247]
	v_cvt_f32_ubyte0_e32 v240, v150
	v_cvt_f32_ubyte1_e32 v241, v150
	v_cvt_f32_ubyte2_e32 v242, v150
	v_cvt_f32_ubyte3_e32 v243, v150
	v_cvt_f32_ubyte0_e32 v244, v151
	v_cvt_f32_ubyte1_e32 v245, v151
	v_cvt_f32_ubyte2_e32 v246, v151
	v_cvt_f32_ubyte3_e32 v247, v151
	v_cvt_f32_ubyte0_e32 v248, v226
	v_cvt_f32_ubyte1_e32 v249, v226
	v_cvt_f32_ubyte2_e32 v250, v226
	v_cvt_f32_ubyte3_e32 v251, v226
	v_cvt_f32_ubyte0_e32 v252, v227
	v_cvt_f32_ubyte1_e32 v253, v227
	v_cvt_f32_ubyte2_e32 v254, v227
	v_cvt_f32_ubyte3_e32 v255, v227
	v_rcp_iflag_f32_e32 v248, v248
	v_rcp_iflag_f32_e32 v249, v249
	v_rcp_iflag_f32_e32 v250, v250
	v_rcp_iflag_f32_e32 v251, v251
	v_rcp_iflag_f32_e32 v252, v252
	v_rcp_iflag_f32_e32 v253, v253
	v_rcp_iflag_f32_e32 v254, v254
	v_rcp_iflag_f32_e32 v255, v255
	v_pk_mul_f32 v[240:241], v[248:249], v[240:241]
	v_pk_mul_f32 v[242:243], v[250:251], v[242:243]
	v_pk_mul_f32 v[244:245], v[252:253], v[244:245]
	v_pk_mul_f32 v[246:247], v[254:255], v[246:247]
	v_pk_mul_f32 v[76:77], v[76:77], v[240:241]
	v_pk_mul_f32 v[78:79], v[78:79], v[242:243]
	v_pk_mul_f32 v[72:73], v[72:73], v[244:245]
	v_pk_mul_f32 v[74:75], v[74:75], v[246:247]
	s_waitcnt vmcnt(6)
;     template <int KIND> __device__ __forceinline__ void run(f32x4 (&acc)[2][2][4][2], const Unit& u, int tid_in) const {
;     ...
;                     for (int ml = 0; ml < 2; ++ml) { const int m = mh * 2 + ml; qa[ml] = gst[(size_t)r * 4096 + (ai * 4 + m) * 512 + tid]; qb[ml] = (r < 2) ? gst[(size_t)(r + 1) * 4096 + (ai * 4 + m) * 512 + tid] : qa[ml]; }
; #pragma unroll
;                     for (int ml = 0; ml < 2; ++ml) { const int m = mh * 2 + ml; int row = rbase + ai * 128 + m * 16; asm volatile("" : "+v"(row));
; #pragma unroll
;                         for (int bj = 0; bj < 2; ++bj) {
;                             const f32x4 n0 = unpack4_raw(bj == 0 ? qa[ml].x : qa[ml].z), n1 = unpack4_raw(bj == 0 ? qa[ml].y : qa[ml].w);
;                             if (r < 2) { const f32x4 d0 = unpack4_raw(bj == 0 ? qb[ml].x : qb[ml].z), d1 = unpack4_raw(bj == 0 ? qb[ml].y : qb[ml].w);
; #pragma unroll
;                                 for (int j = 0; j < 4; ++j) { acc[ai][bj][m][0][j] *= n0[j] * __builtin_amdgcn_rcpf(d0[j]); acc[ai][bj][m][1][j] *= n1[j] * __builtin_amdgcn_rcpf(d1[j]); } }
	v_cvt_f32_ubyte0_e32 v240, v196
	v_cvt_f32_ubyte1_e32 v241, v196
	v_cvt_f32_ubyte2_e32 v242, v196
	v_cvt_f32_ubyte3_e32 v243, v196
	v_cvt_f32_ubyte0_e32 v244, v197
	v_cvt_f32_ubyte1_e32 v245, v197
	v_cvt_f32_ubyte2_e32 v246, v197
	v_cvt_f32_ubyte3_e32 v247, v197
	v_cvt_f32_ubyte0_e32 v248, v178
	v_cvt_f32_ubyte1_e32 v249, v178
	v_cvt_f32_ubyte2_e32 v250, v178
	v_cvt_f32_ubyte3_e32 v251, v178
	v_cvt_f32_ubyte0_e32 v252, v179
	v_cvt_f32_ubyte1_e32 v253, v179
	v_cvt_f32_ubyte2_e32 v254, v179
	v_cvt_f32_ubyte3_e32 v255, v179
	v_rcp_iflag_f32_e32 v248, v248
	v_rcp_iflag_f32_e32 v249, v249
	v_rcp_iflag_f32_e32 v250, v250
	v_rcp_iflag_f32_e32 v251, v251
	v_rcp_iflag_f32_e32 v252, v252
	v_rcp_iflag_f32_e32 v253, v253
	v_rcp_iflag_f32_e32 v254, v254
	v_rcp_iflag_f32_e32 v255, v255
	v_pk_mul_f32 v[240:241], v[248:249], v[240:241]
	v_pk_mul_f32 v[242:243], v[250:251], v[242:243]
	v_pk_mul_f32 v[244:245], v[252:253], v[244:245]
	v_pk_mul_f32 v[246:247], v[254:255], v[246:247]
	v_pk_mul_f32 v[68:69], v[68:69], v[240:241]
	v_pk_mul_f32 v[70:71], v[70:71], v[242:243]
	v_pk_mul_f32 v[64:65], v[64:65], v[244:245]
	v_pk_mul_f32 v[66:67], v[66:67], v[246:247]
	v_cvt_f32_ubyte0_e32 v240, v198
	v_cvt_f32_ubyte1_e32 v241, v198
	v_cvt_f32_ubyte2_e32 v242, v198
	v_cvt_f32_ubyte3_e32 v243, v198
	v_cvt_f32_ubyte0_e32 v244, v199
	v_cvt_f32_ubyte1_e32 v245, v199
	v_cvt_f32_ubyte2_e32 v246, v199
	v_cvt_f32_ubyte3_e32 v247, v199
	v_cvt_f32_ubyte0_e32 v248, v180
	v_cvt_f32_ubyte1_e32 v249, v180
	v_cvt_f32_ubyte2_e32 v250, v180
	v_cvt_f32_ubyte3_e32 v251, v180
	v_cvt_f32_ubyte0_e32 v252, v181
	v_cvt_f32_ubyte1_e32 v253, v181
	v_cvt_f32_ubyte2_e32 v254, v181
	v_cvt_f32_ubyte3_e32 v255, v181
	v_rcp_iflag_f32_e32 v248, v248
	v_rcp_iflag_f32_e32 v249, v249
	v_rcp_iflag_f32_e32 v250, v250
	v_rcp_iflag_f32_e32 v251, v251
	v_rcp_iflag_f32_e32 v252, v252
	v_rcp_iflag_f32_e32 v253, v253
	v_rcp_iflag_f32_e32 v254, v254
	v_rcp_iflag_f32_e32 v255, v255
	v_pk_mul_f32 v[240:241], v[248:249], v[240:241]
	v_pk_mul_f32 v[242:243], v[250:251], v[242:243]
	v_pk_mul_f32 v[244:245], v[252:253], v[244:245]
	v_pk_mul_f32 v[246:247], v[254:255], v[246:247]
	v_pk_mul_f32 v[36:37], v[36:37], v[240:241]
	v_pk_mul_f32 v[38:39], v[38:39], v[242:243]
	v_pk_mul_f32 v[32:33], v[32:33], v[244:245]
	v_pk_mul_f32 v[34:35], v[34:35], v[246:247]
	s_waitcnt vmcnt(4)
	v_cvt_f32_ubyte0_e32 v240, v200
	v_cvt_f32_ubyte1_e32 v241, v200
	v_cvt_f32_ubyte2_e32 v242, v200
	v_cvt_f32_ubyte3_e32 v243, v200
	v_cvt_f32_ubyte0_e32 v244, v201
	v_cvt_f32_ubyte1_e32 v245, v201
	v_cvt_f32_ubyte2_e32 v246, v201
	v_cvt_f32_ubyte3_e32 v247, v201
	v_cvt_f32_ubyte0_e32 v248, v182
	v_cvt_f32_ubyte1_e32 v249, v182
	v_cvt_f32_ubyte2_e32 v250, v182
	v_cvt_f32_ubyte3_e32 v251, v182
	v_cvt_f32_ubyte0_e32 v252, v183
	v_cvt_f32_ubyte1_e32 v253, v183
	v_cvt_f32_ubyte2_e32 v254, v183
	v_cvt_f32_ubyte3_e32 v255, v183
	v_rcp_iflag_f32_e32 v248, v248
	v_rcp_iflag_f32_e32 v249, v249
	v_rcp_iflag_f32_e32 v250, v250
	v_rcp_iflag_f32_e32 v251, v251
	v_rcp_iflag_f32_e32 v252, v252
	v_rcp_iflag_f32_e32 v253, v253
	v_rcp_iflag_f32_e32 v254, v254
	v_rcp_iflag_f32_e32 v255, v255
	v_pk_mul_f32 v[240:241], v[248:249], v[240:241]
	v_pk_mul_f32 v[242:243], v[250:251], v[242:243]
	v_pk_mul_f32 v[244:245], v[252:253], v[244:245]
	v_pk_mul_f32 v[246:247], v[254:255], v[246:247]
	v_pk_mul_f32 v[60:61], v[60:61], v[240:241]
	v_pk_mul_f32 v[62:63], v[62:63], v[242:243]
	v_pk_mul_f32 v[56:57], v[56:57], v[244:245]
	v_pk_mul_f32 v[58:59], v[58:59], v[246:247]
	v_cvt_f32_ubyte0_e32 v240, v202
	v_cvt_f32_ubyte1_e32 v241, v202
	v_cvt_f32_ubyte2_e32 v242, v202
	v_cvt_f32_ubyte3_e32 v243, v202
	v_cvt_f32_ubyte0_e32 v244, v203
	v_cvt_f32_ubyte1_e32 v245, v203
	v_cvt_f32_ubyte2_e32 v246, v203
	v_cvt_f32_ubyte3_e32 v247, v203
	v_cvt_f32_ubyte0_e32 v248, v184
	v_cvt_f32_ubyte1_e32 v249, v184
	v_cvt_f32_ubyte2_e32 v250, v184
	v_cvt_f32_ubyte3_e32 v251, v184
	v_cvt_f32_ubyte0_e32 v252, v185
	v_cvt_f32_ubyte1_e32 v253, v185
	v_cvt_f32_ubyte2_e32 v254, v185
	v_cvt_f32_ubyte3_e32 v255, v185
	v_rcp_iflag_f32_e32 v248, v248
	v_rcp_iflag_f32_e32 v249, v249
	v_rcp_iflag_f32_e32 v250, v250
	v_rcp_iflag_f32_e32 v251, v251
	v_rcp_iflag_f32_e32 v252, v252
	v_rcp_iflag_f32_e32 v253, v253
	v_rcp_iflag_f32_e32 v254, v254
	v_rcp_iflag_f32_e32 v255, v255
	v_pk_mul_f32 v[240:241], v[248:249], v[240:241]
	v_pk_mul_f32 v[242:243], v[250:251], v[242:243]
	v_pk_mul_f32 v[244:245], v[252:253], v[244:245]
	v_pk_mul_f32 v[246:247], v[254:255], v[246:247]
	v_pk_mul_f32 v[28:29], v[28:29], v[240:241]
	v_pk_mul_f32 v[30:31], v[30:31], v[242:243]
	v_pk_mul_f32 v[24:25], v[24:25], v[244:245]
	v_pk_mul_f32 v[26:27], v[26:27], v[246:247]
	s_waitcnt vmcnt(2)
;     template <int KIND> __device__ __forceinline__ void run(f32x4 (&acc)[2][2][4][2], const Unit& u, int tid_in) const {
;     ...
;                     for (int ml = 0; ml < 2; ++ml) { const int m = mh * 2 + ml; qa[ml] = gst[(size_t)r * 4096 + (ai * 4 + m) * 512 + tid]; qb[ml] = (r < 2) ? gst[(size_t)(r + 1) * 4096 + (ai * 4 + m) * 512 + tid] : qa[ml]; }
; #pragma unroll
;                     for (int ml = 0; ml < 2; ++ml) { const int m = mh * 2 + ml; int row = rbase + ai * 128 + m * 16; asm volatile("" : "+v"(row));
; #pragma unroll
;                         for (int bj = 0; bj < 2; ++bj) {
;                             const f32x4 n0 = unpack4_raw(bj == 0 ? qa[ml].x : qa[ml].z), n1 = unpack4_raw(bj == 0 ? qa[ml].y : qa[ml].w);
;                             if (r < 2) { const f32x4 d0 = unpack4_raw(bj == 0 ? qb[ml].x : qb[ml].z), d1 = unpack4_raw(bj == 0 ? qb[ml].y : qb[ml].w);
; #pragma unroll
;                                 for (int j = 0; j < 4; ++j) { acc[ai][bj][m][0][j] *= n0[j] * __builtin_amdgcn_rcpf(d0[j]); acc[ai][bj][m][1][j] *= n1[j] * __builtin_amdgcn_rcpf(d1[j]); } }
	v_cvt_f32_ubyte0_e32 v240, v204
	v_cvt_f32_ubyte1_e32 v241, v204
	v_cvt_f32_ubyte2_e32 v242, v204
	v_cvt_f32_ubyte3_e32 v243, v204
	v_cvt_f32_ubyte0_e32 v244, v205
	v_cvt_f32_ubyte1_e32 v245, v205
	v_cvt_f32_ubyte2_e32 v246, v205
	v_cvt_f32_ubyte3_e32 v247, v205
	v_cvt_f32_ubyte0_e32 v248, v158
	v_cvt_f32_ubyte1_e32 v249, v158
	v_cvt_f32_ubyte2_e32 v250, v158
	v_cvt_f32_ubyte3_e32 v251, v158
	v_cvt_f32_ubyte0_e32 v252, v159
	v_cvt_f32_ubyte1_e32 v253, v159
	v_cvt_f32_ubyte2_e32 v254, v159
	v_cvt_f32_ubyte3_e32 v255, v159
	v_rcp_iflag_f32_e32 v248, v248
	v_rcp_iflag_f32_e32 v249, v249
	v_rcp_iflag_f32_e32 v250, v250
	v_rcp_iflag_f32_e32 v251, v251
	v_rcp_iflag_f32_e32 v252, v252
	v_rcp_iflag_f32_e32 v253, v253
	v_rcp_iflag_f32_e32 v254, v254
	v_rcp_iflag_f32_e32 v255, v255
	v_pk_mul_f32 v[240:241], v[248:249], v[240:241]
	v_pk_mul_f32 v[242:243], v[250:251], v[242:243]
	v_pk_mul_f32 v[244:245], v[252:253], v[244:245]
	v_pk_mul_f32 v[246:247], v[254:255], v[246:247]
	v_pk_mul_f32 v[52:53], v[52:53], v[240:241]
	v_pk_mul_f32 v[54:55], v[54:55], v[242:243]
	v_pk_mul_f32 v[48:49], v[48:49], v[244:245]
	v_pk_mul_f32 v[50:51], v[50:51], v[246:247]
	v_cvt_f32_ubyte0_e32 v240, v206
	v_cvt_f32_ubyte1_e32 v241, v206
	v_cvt_f32_ubyte2_e32 v242, v206
	v_cvt_f32_ubyte3_e32 v243, v206
	v_cvt_f32_ubyte0_e32 v244, v207
	v_cvt_f32_ubyte1_e32 v245, v207
	v_cvt_f32_ubyte2_e32 v246, v207
	v_cvt_f32_ubyte3_e32 v247, v207
	v_cvt_f32_ubyte0_e32 v248, v160
	v_cvt_f32_ubyte1_e32 v249, v160
	v_cvt_f32_ubyte2_e32 v250, v160
	v_cvt_f32_ubyte3_e32 v251, v160
	v_cvt_f32_ubyte0_e32 v252, v161
	v_cvt_f32_ubyte1_e32 v253, v161
	v_cvt_f32_ubyte2_e32 v254, v161
	v_cvt_f32_ubyte3_e32 v255, v161
	v_rcp_iflag_f32_e32 v248, v248
	v_rcp_iflag_f32_e32 v249, v249
	v_rcp_iflag_f32_e32 v250, v250
	v_rcp_iflag_f32_e32 v251, v251
	v_rcp_iflag_f32_e32 v252, v252
	v_rcp_iflag_f32_e32 v253, v253
	v_rcp_iflag_f32_e32 v254, v254
	v_rcp_iflag_f32_e32 v255, v255
	v_pk_mul_f32 v[240:241], v[248:249], v[240:241]
	v_pk_mul_f32 v[242:243], v[250:251], v[242:243]
	v_pk_mul_f32 v[244:245], v[252:253], v[244:245]
	v_pk_mul_f32 v[246:247], v[254:255], v[246:247]
	v_pk_mul_f32 v[20:21], v[20:21], v[240:241]
	v_pk_mul_f32 v[22:23], v[22:23], v[242:243]
	v_pk_mul_f32 v[16:17], v[16:17], v[244:245]
	v_pk_mul_f32 v[18:19], v[18:19], v[246:247]
	s_waitcnt vmcnt(0)
	v_cvt_f32_ubyte0_e32 v240, v208
	v_cvt_f32_ubyte1_e32 v241, v208
	v_cvt_f32_ubyte2_e32 v242, v208
	v_cvt_f32_ubyte3_e32 v243, v208
	v_cvt_f32_ubyte0_e32 v244, v209
	v_cvt_f32_ubyte1_e32 v245, v209
	v_cvt_f32_ubyte2_e32 v246, v209
	v_cvt_f32_ubyte3_e32 v247, v209
	v_cvt_f32_ubyte0_e32 v248, v162
	v_cvt_f32_ubyte1_e32 v249, v162
	v_cvt_f32_ubyte2_e32 v250, v162
	v_cvt_f32_ubyte3_e32 v251, v162
	v_cvt_f32_ubyte0_e32 v252, v163
	v_cvt_f32_ubyte1_e32 v253, v163
	v_cvt_f32_ubyte2_e32 v254, v163
	v_cvt_f32_ubyte3_e32 v255, v163
	v_rcp_iflag_f32_e32 v248, v248
	v_rcp_iflag_f32_e32 v249, v249
	v_rcp_iflag_f32_e32 v250, v250
	v_rcp_iflag_f32_e32 v251, v251
	v_rcp_iflag_f32_e32 v252, v252
	v_rcp_iflag_f32_e32 v253, v253
	v_rcp_iflag_f32_e32 v254, v254
	v_rcp_iflag_f32_e32 v255, v255
	v_pk_mul_f32 v[240:241], v[248:249], v[240:241]
	v_pk_mul_f32 v[242:243], v[250:251], v[242:243]
	v_pk_mul_f32 v[244:245], v[252:253], v[244:245]
	v_pk_mul_f32 v[246:247], v[254:255], v[246:247]
	v_pk_mul_f32 v[44:45], v[44:45], v[240:241]
	v_pk_mul_f32 v[46:47], v[46:47], v[242:243]
	v_pk_mul_f32 v[40:41], v[40:41], v[244:245]
	v_pk_mul_f32 v[42:43], v[42:43], v[246:247]
	v_cvt_f32_ubyte0_e32 v240, v210
	v_cvt_f32_ubyte1_e32 v241, v210
	v_cvt_f32_ubyte2_e32 v242, v210
	v_cvt_f32_ubyte3_e32 v243, v210
	v_cvt_f32_ubyte0_e32 v244, v211
	v_cvt_f32_ubyte1_e32 v245, v211
	v_cvt_f32_ubyte2_e32 v246, v211
	v_cvt_f32_ubyte3_e32 v247, v211
	v_cvt_f32_ubyte0_e32 v248, v164
	v_cvt_f32_ubyte1_e32 v249, v164
	v_cvt_f32_ubyte2_e32 v250, v164
	v_cvt_f32_ubyte3_e32 v251, v164
	v_cvt_f32_ubyte0_e32 v252, v165
	v_cvt_f32_ubyte1_e32 v253, v165
	v_cvt_f32_ubyte2_e32 v254, v165
	v_cvt_f32_ubyte3_e32 v255, v165
	v_rcp_iflag_f32_e32 v248, v248
	v_rcp_iflag_f32_e32 v249, v249
	v_rcp_iflag_f32_e32 v250, v250
	v_rcp_iflag_f32_e32 v251, v251
	v_rcp_iflag_f32_e32 v252, v252
	v_rcp_iflag_f32_e32 v253, v253
	v_rcp_iflag_f32_e32 v254, v254
	v_rcp_iflag_f32_e32 v255, v255
	v_pk_mul_f32 v[240:241], v[248:249], v[240:241]
	v_pk_mul_f32 v[242:243], v[250:251], v[242:243]
	v_pk_mul_f32 v[244:245], v[252:253], v[244:245]
	v_pk_mul_f32 v[246:247], v[254:255], v[246:247]
	v_pk_mul_f32 v[12:13], v[12:13], v[240:241]
	v_pk_mul_f32 v[14:15], v[14:15], v[242:243]
	v_pk_mul_f32 v[8:9], v[8:9], v[244:245]
	v_pk_mul_f32 v[10:11], v[10:11], v[246:247]
	s_mov_b64 s[6:7], -1
	s_branch .Lmg1_done

; #define G_STAGE(bufoff, gbase, o0, h64) do { \
;         __builtin_amdgcn_global_load_lds((const unsigned*)((const char*)(gbase) + (o0)), (LAS unsigned*)(lds + (bufoff) + ldsw), 16, 0, 0); \
;         __builtin_amdgcn_global_load_lds((const unsigned*)((const char*)(gbase) + (h64) + (o0)), (LAS unsigned*)(lds + (bufoff) + ldsw + 8192), 16, 0, 0); } while (0)
; #define G_LDA(dst, b, h) do { _Pragma("unroll") for (int m = 0; m < 4; ++m) _Pragma("unroll") for (int k = 0; k < 2; ++k) dst[m][k] = *(const LAS bf16x8*)(lds + G_SA(b, h) + aoff + m * 2048 + k * 1024); } while (0)
; #define G_LDB(dst, b, h) do { _Pragma("unroll") for (int n = 0; n < 2; ++n) _Pragma("unroll") for (int k = 0; k < 2; ++k) dst[n][k] = *(const LAS bf16x8*)(lds + G_SB(b, h) + boff + n * 2048 + k * 1024); } while (0)
; #define G_WAIT_L(n) asm volatile("s_waitcnt lgkmcnt(" #n ")" ::: "memory")
; #define G_BAR __builtin_amdgcn_s_barrier()
; #define G_SCHED __builtin_amdgcn_sched_barrier(0)
;     ...
;         for (int t = 0; t < nt; t += 2) {
;             const bool last = (t == nt - 2);
;             const char* a1 = cA + (size_t)(t + 1) * ckA;
;             const char* a2 = last ? nA : cA + (size_t)(t + 2) * ckA; const char* b2 = last ? nB : cB + (size_t)(t + 2) * kB;
;             const char* a3 = a2 + ckA; const char* b3 = b2 + kB;
;             G_LDB(B0, 0, 0); G_SCHED; G_LDA(At, 0, 0); G_STAGE(G_SA(1, 1), a1 + chA, cA0, qA);
;             G_WAIT_L(8); G_BAR; G_WAIT_L(0); G_MMA(0, 0, At, B0); G_BAR; G_SCHED;
;             G_LDB(B1, 0, 1); G_STAGE(G_SB(0, 0), b2, cB0, qB);
;             G_BAR; G_WAIT_L(0); G_MMA(0, 1, At, B1); G_BAR;
;             G_LDA(At, 0, 1); G_STAGE(G_SA(0, 0), a2, cA0, qA);
;             G_BAR; G_WAIT_L(0); G_MMA(1, 0, At, B0); G_BAR; G_SCHED;
;     ...
;         if (!(cs.kind == K_MG_B && cur.aux < 2))
; #pragma unroll
;         for (int a = 0; a < 2; ++a)
; #pragma unroll
;             for (int b = 0; b < 2; ++b)
; #pragma unroll
;                 for (int m = 0; m < 4; ++m)
; #pragma unroll
;                     for (int n = 0; n < 2; ++n) acc[a][b][m][n] = (f32x4){0.f, 0.f, 0.f, 0.f};
.LBB0_1036:
	s_add_u32 s2, s2, 0x40080
	s_addc_u32 s3, s3, 0
	s_add_u32 s6, s6, 0x100
	s_waitcnt lgkmcnt(0)
	v_mov_b64_e32 v[8:9], 0
	s_addc_u32 s7, s7, 0
	s_mov_b32 s15, -2
	v_mov_b64_e32 v[10:11], 0
	v_mov_b64_e32 v[12:13], 0
	v_mov_b64_e32 v[14:15], 0
	v_mov_b64_e32 v[24:25], 0
	v_mov_b64_e32 v[26:27], 0
	v_mov_b64_e32 v[28:29], 0
	v_mov_b64_e32 v[30:31], 0
	v_mov_b64_e32 v[40:41], 0
	v_mov_b64_e32 v[42:43], 0
	v_mov_b64_e32 v[44:45], 0
	v_mov_b64_e32 v[46:47], 0
	v_mov_b64_e32 v[56:57], 0
	v_mov_b64_e32 v[58:59], 0
	v_mov_b64_e32 v[60:61], 0
	v_mov_b64_e32 v[62:63], 0
	v_mov_b64_e32 v[16:17], 0
	v_mov_b64_e32 v[18:19], 0
	v_mov_b64_e32 v[20:21], 0
	v_mov_b64_e32 v[22:23], 0
	v_mov_b64_e32 v[32:33], 0
	v_mov_b64_e32 v[34:35], 0
	v_mov_b64_e32 v[36:37], 0
	v_mov_b64_e32 v[38:39], 0
	v_mov_b64_e32 v[48:49], 0
	v_mov_b64_e32 v[50:51], 0
	v_mov_b64_e32 v[52:53], 0
	v_mov_b64_e32 v[54:55], 0
	v_mov_b64_e32 v[64:65], 0
	v_mov_b64_e32 v[66:67], 0
	v_mov_b64_e32 v[68:69], 0
	v_mov_b64_e32 v[70:71], 0
	v_mov_b64_e32 v[72:73], 0
	v_mov_b64_e32 v[74:75], 0
	v_mov_b64_e32 v[76:77], 0
	v_mov_b64_e32 v[78:79], 0
	v_mov_b64_e32 v[88:89], 0
	v_mov_b64_e32 v[90:91], 0
	v_mov_b64_e32 v[92:93], 0
	v_mov_b64_e32 v[94:95], 0
	v_mov_b64_e32 v[104:105], 0
	v_mov_b64_e32 v[106:107], 0
	v_mov_b64_e32 v[108:109], 0
	v_mov_b64_e32 v[110:111], 0
	v_mov_b64_e32 v[120:121], 0
	v_mov_b64_e32 v[122:123], 0
	v_mov_b64_e32 v[124:125], 0
	v_mov_b64_e32 v[126:127], 0
	v_mov_b64_e32 v[80:81], 0
	v_mov_b64_e32 v[82:83], 0
	v_mov_b64_e32 v[84:85], 0
	v_mov_b64_e32 v[86:87], 0
	v_mov_b64_e32 v[96:97], 0
	v_mov_b64_e32 v[98:99], 0
	v_mov_b64_e32 v[100:101], 0
	v_mov_b64_e32 v[102:103], 0
	v_mov_b64_e32 v[112:113], 0
	v_mov_b64_e32 v[114:115], 0
	v_mov_b64_e32 v[116:117], 0
	v_mov_b64_e32 v[118:119], 0
	v_mov_b64_e32 v[128:129], 0
	v_mov_b64_e32 v[130:131], 0
	v_mov_b64_e32 v[132:133], 0
	v_mov_b64_e32 v[134:135], 0
	s_mov_b64 s[42:43], 0x40000
	s_mov_b64 s[50:51], 0x60000
	s_mov_b64 s[52:53], 0x20080
	s_mov_b64 s[54:55], 0x40080
	s_mov_b64 s[58:59], 0x60080
	s_cmp_eq_u32 s101, 2
	s_cselect_b32 s101, 0, s101
	v_add_u32_e32 v255, 0x10000, v181
	ds_read_b128 v[136:139], v255 offset:0
	ds_read_b128 v[140:143], v255 offset:1024
	ds_read_b128 v[144:147], v255 offset:2048
	ds_read_b128 v[148:151], v255 offset:3072
.LBB0_1037:
	s_add_u32 s4, s2, 0xfffc0080
	s_addc_u32 s5, s3, -1
	s_add_i32 s33, 0, 0x10000
	s_cmp_eq_u32 s15, 12
	s_cselect_b32 s5, s17, s5
	s_cselect_b32 s4, s16, s4
	s_cselect_b32 s21, s19, s7
	s_cselect_b32 s20, s18, s6
	s_add_i32 m0, s24, 0xc000
	ds_read_b128 v[152:155], v182
	ds_read_b128 v[156:159], v182 offset:1024
	ds_read_b128 v[160:163], v182 offset:2048
	ds_read_b128 v[172:175], v182 offset:3072
	ds_read_b128 v[176:179], v182 offset:4096
	ds_read_b128 v[196:199], v182 offset:5120
	ds_read_b128 v[200:203], v182 offset:6144
	ds_read_b128 v[204:207], v182 offset:7168
	global_load_lds_dwordx4 v166, s[2:3]
	s_add_i32 m0, s24, 0xe000
	s_nop 0
	s_add_u32 vcc_lo, s2, s0
	s_addc_u32 vcc_hi, s3, s1
	global_load_lds_dwordx4 v166, vcc
	s_waitcnt lgkmcnt(8)
	s_cmp_eq_u32 s101, 1
	s_cbranch_scc1 .Ldb_WOUT_sk
	s_barrier
.Ldb_WOUT_sk:
	s_mov_b32 s101, 0
	s_waitcnt lgkmcnt(0)
	v_mfma_f32_16x16x32_bf16 v[132:135], v[136:139], v[152:155], v[132:135]
	v_mfma_f32_16x16x32_bf16 v[128:131], v[144:147], v[152:155], v[128:131]
	v_mfma_f32_16x16x32_bf16 v[116:119], v[136:139], v[160:163], v[116:119]
	v_mfma_f32_16x16x32_bf16 v[112:115], v[144:147], v[160:163], v[112:115]
	v_mfma_f32_16x16x32_bf16 v[100:103], v[136:139], v[176:179], v[100:103]
	v_mfma_f32_16x16x32_bf16 v[96:99], v[144:147], v[176:179], v[96:99]
	v_mfma_f32_16x16x32_bf16 v[84:87], v[136:139], v[200:203], v[84:87]
	v_mfma_f32_16x16x32_bf16 v[80:83], v[144:147], v[200:203], v[80:83]
	v_mfma_f32_16x16x32_bf16 v[132:135], v[140:143], v[156:159], v[132:135]
	v_mfma_f32_16x16x32_bf16 v[128:131], v[148:151], v[156:159], v[128:131]
	v_mfma_f32_16x16x32_bf16 v[116:119], v[140:143], v[172:175], v[116:119]
	v_mfma_f32_16x16x32_bf16 v[112:115], v[148:151], v[172:175], v[112:115]
	v_mfma_f32_16x16x32_bf16 v[100:103], v[140:143], v[196:199], v[100:103]
	v_mfma_f32_16x16x32_bf16 v[96:99], v[148:151], v[196:199], v[96:99]
	v_mfma_f32_16x16x32_bf16 v[84:87], v[140:143], v[204:207], v[84:87]
	v_mfma_f32_16x16x32_bf16 v[80:83], v[148:151], v[204:207], v[80:83]
	s_barrier
	s_add_i32 s41, 0, 0x14000
	s_add_i32 s100, s33, s23
	s_mov_b32 m0, s100
	ds_read_b128 v[208:211], v255 offset:16384
	ds_read_b128 v[212:215], v255 offset:17408
	ds_read_b128 v[216:219], v255 offset:18432
	ds_read_b128 v[220:223], v255 offset:19456
	global_load_lds_dwordx4 v164, s[20:21]
	s_add_i32 m0, s100, 0x2000
	s_nop 0
	s_add_u32 vcc_lo, s20, s0
	s_addc_u32 vcc_hi, s21, s1
	global_load_lds_dwordx4 v164, vcc
	s_barrier
	s_waitcnt lgkmcnt(0)
	v_mfma_f32_16x16x32_bf16 v[124:127], v[208:211], v[152:155], v[124:127]
	v_mfma_f32_16x16x32_bf16 v[120:123], v[216:219], v[152:155], v[120:123]
	v_mfma_f32_16x16x32_bf16 v[108:111], v[208:211], v[160:163], v[108:111]
	v_mfma_f32_16x16x32_bf16 v[104:107], v[216:219], v[160:163], v[104:107]
	v_mfma_f32_16x16x32_bf16 v[92:95], v[208:211], v[176:179], v[92:95]
	v_mfma_f32_16x16x32_bf16 v[88:91], v[216:219], v[176:179], v[88:91]
	v_mfma_f32_16x16x32_bf16 v[76:79], v[208:211], v[200:203], v[76:79]
	v_mfma_f32_16x16x32_bf16 v[72:75], v[216:219], v[200:203], v[72:75]
	v_mfma_f32_16x16x32_bf16 v[124:127], v[212:215], v[156:159], v[124:127]
	v_mfma_f32_16x16x32_bf16 v[120:123], v[220:223], v[156:159], v[120:123]
	v_mfma_f32_16x16x32_bf16 v[108:111], v[212:215], v[172:175], v[108:111]
	v_mfma_f32_16x16x32_bf16 v[104:107], v[220:223], v[172:175], v[104:107]
	v_mfma_f32_16x16x32_bf16 v[92:95], v[212:215], v[196:199], v[92:95]
	v_mfma_f32_16x16x32_bf16 v[88:91], v[220:223], v[196:199], v[88:91]
	v_mfma_f32_16x16x32_bf16 v[76:79], v[212:215], v[204:207], v[76:79]
	v_mfma_f32_16x16x32_bf16 v[72:75], v[220:223], v[204:207], v[72:75]
	s_barrier
; #define G_STAGE(bufoff, gbase, o0, h64) do { \
;         __builtin_amdgcn_global_load_lds((const unsigned*)((const char*)(gbase) + (o0)), (LAS unsigned*)(lds + (bufoff) + ldsw), 16, 0, 0); \
;         __builtin_amdgcn_global_load_lds((const unsigned*)((const char*)(gbase) + (h64) + (o0)), (LAS unsigned*)(lds + (bufoff) + ldsw + 8192), 16, 0, 0); } while (0)
; #define G_LDA(dst, b, h) do { _Pragma("unroll") for (int m = 0; m < 4; ++m) _Pragma("unroll") for (int k = 0; k < 2; ++k) dst[m][k] = *(const LAS bf16x8*)(lds + G_SA(b, h) + aoff + m * 2048 + k * 1024); } while (0)
; #define G_LDB(dst, b, h) do { _Pragma("unroll") for (int n = 0; n < 2; ++n) _Pragma("unroll") for (int k = 0; k < 2; ++k) dst[n][k] = *(const LAS bf16x8*)(lds + G_SB(b, h) + boff + n * 2048 + k * 1024); } while (0)
; #define G_WAIT_V(n) asm volatile("s_waitcnt vmcnt(" #n ")" ::: "memory")
; #define G_WAIT_L(n) asm volatile("s_waitcnt lgkmcnt(" #n ")" ::: "memory")
; #define G_BAR __builtin_amdgcn_s_barrier()
; #define G_SCHED __builtin_amdgcn_sched_barrier(0)
;     ...
;             G_BAR; G_WAIT_L(0); G_MMA(1, 0, At, B0); G_BAR; G_SCHED;
;             G_STAGE(G_SB(0, 1), b2 + chB, cB0, qB);
;             G_WAIT_V(6); G_BAR; G_MMA(1, 1, At, B1); G_BAR;
;             G_LDB(B0, 1, 0); G_SCHED; G_LDA(At, 1, 0); G_STAGE(G_SA(0, 1), a2 + chA, cA0, qA);
;             G_WAIT_L(8); G_BAR; G_WAIT_L(0); G_MMA(0, 0, At, B0); G_BAR; G_SCHED;
;             G_LDB(B1, 1, 1); G_STAGE(G_SB(1, 0), b3, cB0, qB);
	s_mov_b32 m0, s24
	v_lshl_add_u64 v[224:225], s[4:5], 0, v[2:3]
	ds_read_b128 v[152:155], v182 offset:16384
	ds_read_b128 v[156:159], v182 offset:17408
	ds_read_b128 v[160:163], v182 offset:18432
	ds_read_b128 v[172:175], v182 offset:19456
	ds_read_b128 v[176:179], v182 offset:20480
	ds_read_b128 v[196:199], v182 offset:21504
	ds_read_b128 v[200:203], v182 offset:22528
	ds_read_b128 v[204:207], v182 offset:23552
	global_load_lds_dwordx4 v2, s[4:5]
	s_mov_b32 m0, s25
	s_nop 0
	s_add_u32 vcc_lo, s4, s0
	s_addc_u32 vcc_hi, s5, s1
	global_load_lds_dwordx4 v2, vcc
	s_barrier
	s_waitcnt lgkmcnt(0)
	v_mfma_f32_16x16x32_bf16 v[68:71], v[136:139], v[152:155], v[68:71]
	v_mfma_f32_16x16x32_bf16 v[64:67], v[144:147], v[152:155], v[64:67]
	v_mfma_f32_16x16x32_bf16 v[52:55], v[136:139], v[160:163], v[52:55]
	v_mfma_f32_16x16x32_bf16 v[48:51], v[144:147], v[160:163], v[48:51]
	v_mfma_f32_16x16x32_bf16 v[36:39], v[136:139], v[176:179], v[36:39]
	v_mfma_f32_16x16x32_bf16 v[32:35], v[144:147], v[176:179], v[32:35]
	v_mfma_f32_16x16x32_bf16 v[20:23], v[136:139], v[200:203], v[20:23]
	v_mfma_f32_16x16x32_bf16 v[16:19], v[144:147], v[200:203], v[16:19]
	v_mfma_f32_16x16x32_bf16 v[68:71], v[140:143], v[156:159], v[68:71]
	v_mfma_f32_16x16x32_bf16 v[64:67], v[148:151], v[156:159], v[64:67]
	v_mfma_f32_16x16x32_bf16 v[52:55], v[140:143], v[172:175], v[52:55]
	v_mfma_f32_16x16x32_bf16 v[48:51], v[148:151], v[172:175], v[48:51]
	v_mfma_f32_16x16x32_bf16 v[36:39], v[140:143], v[196:199], v[36:39]
	v_mfma_f32_16x16x32_bf16 v[32:35], v[148:151], v[196:199], v[32:35]
	v_mfma_f32_16x16x32_bf16 v[20:23], v[140:143], v[204:207], v[20:23]
	v_mfma_f32_16x16x32_bf16 v[16:19], v[148:151], v[204:207], v[16:19]
	s_barrier
	s_add_i32 s100, s41, s23
	s_mov_b32 m0, s100
	s_nop 0
	s_add_u32 vcc_lo, s20, s42
	s_addc_u32 vcc_hi, s21, s43
	global_load_lds_dwordx4 v164, vcc
	s_add_i32 m0, s100, 0x2000
	s_nop 0
	s_add_u32 vcc_lo, s20, s50
	s_addc_u32 vcc_hi, s21, s51
	global_load_lds_dwordx4 v164, vcc
	s_waitcnt vmcnt(6)
	s_barrier
	v_mfma_f32_16x16x32_bf16 v[60:63], v[208:211], v[152:155], v[60:63]
	v_mfma_f32_16x16x32_bf16 v[56:59], v[216:219], v[152:155], v[56:59]
	v_mfma_f32_16x16x32_bf16 v[44:47], v[208:211], v[160:163], v[44:47]
	v_mfma_f32_16x16x32_bf16 v[40:43], v[216:219], v[160:163], v[40:43]
	ds_read_b128 v[136:139], v255 offset:32768
	ds_read_b128 v[140:143], v255 offset:33792
	ds_read_b128 v[144:147], v255 offset:34816
	ds_read_b128 v[148:151], v255 offset:35840
	v_mfma_f32_16x16x32_bf16 v[28:31], v[208:211], v[176:179], v[28:31]
	v_mfma_f32_16x16x32_bf16 v[24:27], v[216:219], v[176:179], v[24:27]
	v_mfma_f32_16x16x32_bf16 v[12:15], v[208:211], v[200:203], v[12:15]
	v_mfma_f32_16x16x32_bf16 v[8:11], v[216:219], v[200:203], v[8:11]
	v_mfma_f32_16x16x32_bf16 v[60:63], v[212:215], v[156:159], v[60:63]
	v_mfma_f32_16x16x32_bf16 v[56:59], v[220:223], v[156:159], v[56:59]
	v_mfma_f32_16x16x32_bf16 v[44:47], v[212:215], v[172:175], v[44:47]
	v_mfma_f32_16x16x32_bf16 v[40:43], v[220:223], v[172:175], v[40:43]
	v_mfma_f32_16x16x32_bf16 v[28:31], v[212:215], v[196:199], v[28:31]
	v_mfma_f32_16x16x32_bf16 v[24:27], v[220:223], v[196:199], v[24:27]
	v_mfma_f32_16x16x32_bf16 v[12:15], v[212:215], v[204:207], v[12:15]
	v_mfma_f32_16x16x32_bf16 v[8:11], v[220:223], v[204:207], v[8:11]
	s_barrier
	s_add_i32 s100, 0, 0x18000
	s_mov_b32 m0, s26
	ds_read_b128 v[152:155], v182 offset:32768
	ds_read_b128 v[156:159], v182 offset:33792
	ds_read_b128 v[160:163], v182 offset:34816
	ds_read_b128 v[172:175], v182 offset:35840
	ds_read_b128 v[176:179], v182 offset:36864
	ds_read_b128 v[196:199], v182 offset:37888
	ds_read_b128 v[200:203], v182 offset:38912
	ds_read_b128 v[204:207], v182 offset:39936
	s_add_u32 vcc_lo, s4, s42
	s_addc_u32 vcc_hi, s5, s43
	global_load_lds_dwordx4 v2, vcc
	s_mov_b32 m0, s27
	s_nop 0
	s_add_u32 vcc_lo, s4, s50
	s_addc_u32 vcc_hi, s5, s51
	global_load_lds_dwordx4 v2, vcc
	s_waitcnt lgkmcnt(8)
	s_barrier
	s_waitcnt lgkmcnt(0)
	v_mfma_f32_16x16x32_bf16 v[132:135], v[136:139], v[152:155], v[132:135]
	v_mfma_f32_16x16x32_bf16 v[128:131], v[144:147], v[152:155], v[128:131]
	v_mfma_f32_16x16x32_bf16 v[116:119], v[136:139], v[160:163], v[116:119]
	v_mfma_f32_16x16x32_bf16 v[112:115], v[144:147], v[160:163], v[112:115]
	v_mfma_f32_16x16x32_bf16 v[100:103], v[136:139], v[176:179], v[100:103]
	v_mfma_f32_16x16x32_bf16 v[96:99], v[144:147], v[176:179], v[96:99]
	v_mfma_f32_16x16x32_bf16 v[84:87], v[136:139], v[200:203], v[84:87]
	v_mfma_f32_16x16x32_bf16 v[80:83], v[144:147], v[200:203], v[80:83]
	v_mfma_f32_16x16x32_bf16 v[132:135], v[140:143], v[156:159], v[132:135]
	v_mfma_f32_16x16x32_bf16 v[128:131], v[148:151], v[156:159], v[128:131]
	v_mfma_f32_16x16x32_bf16 v[116:119], v[140:143], v[172:175], v[116:119]
	v_mfma_f32_16x16x32_bf16 v[112:115], v[148:151], v[172:175], v[112:115]
	v_mfma_f32_16x16x32_bf16 v[100:103], v[140:143], v[196:199], v[100:103]
	v_mfma_f32_16x16x32_bf16 v[96:99], v[148:151], v[196:199], v[96:99]
	v_mfma_f32_16x16x32_bf16 v[84:87], v[140:143], v[204:207], v[84:87]
	v_mfma_f32_16x16x32_bf16 v[80:83], v[148:151], v[204:207], v[80:83]
	s_barrier
; #define G_STAGE(bufoff, gbase, o0, h64) do { \
;         __builtin_amdgcn_global_load_lds((const unsigned*)((const char*)(gbase) + (o0)), (LAS unsigned*)(lds + (bufoff) + ldsw), 16, 0, 0); \
;         __builtin_amdgcn_global_load_lds((const unsigned*)((const char*)(gbase) + (h64) + (o0)), (LAS unsigned*)(lds + (bufoff) + ldsw + 8192), 16, 0, 0); } while (0)
; #define G_LDA(dst, b, h) do { _Pragma("unroll") for (int m = 0; m < 4; ++m) _Pragma("unroll") for (int k = 0; k < 2; ++k) dst[m][k] = *(const LAS bf16x8*)(lds + G_SA(b, h) + aoff + m * 2048 + k * 1024); } while (0)
; #define G_LDB(dst, b, h) do { _Pragma("unroll") for (int n = 0; n < 2; ++n) _Pragma("unroll") for (int k = 0; k < 2; ++k) dst[n][k] = *(const LAS bf16x8*)(lds + G_SB(b, h) + boff + n * 2048 + k * 1024); } while (0)
; #define G_WAIT_V(n) asm volatile("s_waitcnt vmcnt(" #n ")" ::: "memory")
; #define G_WAIT_L(n) asm volatile("s_waitcnt lgkmcnt(" #n ")" ::: "memory")
; #define G_BAR __builtin_amdgcn_s_barrier()
; #define G_SCHED __builtin_amdgcn_sched_barrier(0)
;     ...
;             G_WAIT_L(8); G_BAR; G_WAIT_L(0); G_MMA(0, 0, At, B0); G_BAR; G_SCHED;
;             G_LDB(B1, 1, 1); G_STAGE(G_SB(1, 0), b3, cB0, qB);
;             G_BAR; G_WAIT_L(0); G_MMA(0, 1, At, B1); G_BAR;
;             G_LDA(At, 1, 1); G_STAGE(G_SA(1, 0), a3, cA0, qA);
;             G_BAR; G_WAIT_L(0); G_MMA(1, 0, At, B0); G_BAR; G_SCHED;
;             G_STAGE(G_SB(1, 1), b3 + chB, cB0, qB);
;             G_WAIT_V(6); G_BAR; G_MMA(1, 1, At, B1); G_BAR;
;         }
	s_add_i32 s5, 0, 0x1c000
	s_add_i32 s4, s100, s23
	s_mov_b32 m0, s4
	ds_read_b128 v[208:211], v255 offset:49152
	ds_read_b128 v[212:215], v255 offset:50176
	ds_read_b128 v[216:219], v255 offset:51200
	ds_read_b128 v[220:223], v255 offset:52224
	s_add_u32 vcc_lo, s20, s46
	s_addc_u32 vcc_hi, s21, s47
	global_load_lds_dwordx4 v164, vcc
	s_add_i32 m0, s4, 0x2000
	s_nop 0
	s_add_u32 vcc_lo, s20, s52
	s_addc_u32 vcc_hi, s21, s53
	global_load_lds_dwordx4 v164, vcc
	s_barrier
	s_waitcnt lgkmcnt(0)
	v_mfma_f32_16x16x32_bf16 v[124:127], v[208:211], v[152:155], v[124:127]
	v_mfma_f32_16x16x32_bf16 v[120:123], v[216:219], v[152:155], v[120:123]
	v_mfma_f32_16x16x32_bf16 v[108:111], v[208:211], v[160:163], v[108:111]
	v_mfma_f32_16x16x32_bf16 v[104:107], v[216:219], v[160:163], v[104:107]
	v_mfma_f32_16x16x32_bf16 v[92:95], v[208:211], v[176:179], v[92:95]
	v_mfma_f32_16x16x32_bf16 v[88:91], v[216:219], v[176:179], v[88:91]
	v_mfma_f32_16x16x32_bf16 v[76:79], v[208:211], v[200:203], v[76:79]
	v_mfma_f32_16x16x32_bf16 v[72:75], v[216:219], v[200:203], v[72:75]
	v_mfma_f32_16x16x32_bf16 v[124:127], v[212:215], v[156:159], v[124:127]
	v_mfma_f32_16x16x32_bf16 v[120:123], v[220:223], v[156:159], v[120:123]
	v_mfma_f32_16x16x32_bf16 v[108:111], v[212:215], v[172:175], v[108:111]
	v_mfma_f32_16x16x32_bf16 v[104:107], v[220:223], v[172:175], v[104:107]
	v_mfma_f32_16x16x32_bf16 v[92:95], v[212:215], v[196:199], v[92:95]
	v_mfma_f32_16x16x32_bf16 v[88:91], v[220:223], v[196:199], v[88:91]
	v_mfma_f32_16x16x32_bf16 v[76:79], v[212:215], v[204:207], v[76:79]
	v_mfma_f32_16x16x32_bf16 v[72:75], v[220:223], v[204:207], v[72:75]
	s_barrier
	s_mov_b32 m0, s29
	v_lshl_add_u64 v[226:227], v[224:225], 0, s[46:47]
	ds_read_b128 v[152:155], v182 offset:49152
	ds_read_b128 v[156:159], v182 offset:50176
	ds_read_b128 v[160:163], v182 offset:51200
	ds_read_b128 v[172:175], v182 offset:52224
	ds_read_b128 v[176:179], v182 offset:53248
	ds_read_b128 v[196:199], v182 offset:54272
	ds_read_b128 v[200:203], v182 offset:55296
	ds_read_b128 v[204:207], v182 offset:56320
	global_load_lds_dwordx4 v[226:227], off
	v_lshl_add_u64 v[224:225], v[224:225], 0, s[52:53]
	s_mov_b32 m0, s30
	s_nop 0
	global_load_lds_dwordx4 v[224:225], off
	s_barrier
	s_waitcnt lgkmcnt(0)
	v_mfma_f32_16x16x32_bf16 v[68:71], v[136:139], v[152:155], v[68:71]
	v_mfma_f32_16x16x32_bf16 v[64:67], v[144:147], v[152:155], v[64:67]
	v_mfma_f32_16x16x32_bf16 v[52:55], v[136:139], v[160:163], v[52:55]
	v_mfma_f32_16x16x32_bf16 v[48:51], v[144:147], v[160:163], v[48:51]
	v_mfma_f32_16x16x32_bf16 v[36:39], v[136:139], v[176:179], v[36:39]
	v_mfma_f32_16x16x32_bf16 v[32:35], v[144:147], v[176:179], v[32:35]
	v_mfma_f32_16x16x32_bf16 v[20:23], v[136:139], v[200:203], v[20:23]
	v_mfma_f32_16x16x32_bf16 v[16:19], v[144:147], v[200:203], v[16:19]
	v_mfma_f32_16x16x32_bf16 v[68:71], v[140:143], v[156:159], v[68:71]
	v_mfma_f32_16x16x32_bf16 v[64:67], v[148:151], v[156:159], v[64:67]
	v_mfma_f32_16x16x32_bf16 v[52:55], v[140:143], v[172:175], v[52:55]
	v_mfma_f32_16x16x32_bf16 v[48:51], v[148:151], v[172:175], v[48:51]
	v_mfma_f32_16x16x32_bf16 v[36:39], v[140:143], v[196:199], v[36:39]
	v_mfma_f32_16x16x32_bf16 v[32:35], v[148:151], v[196:199], v[32:35]
	v_mfma_f32_16x16x32_bf16 v[20:23], v[140:143], v[204:207], v[20:23]
	v_mfma_f32_16x16x32_bf16 v[16:19], v[148:151], v[204:207], v[16:19]
	s_barrier
	s_add_i32 s4, s5, s23
	s_mov_b32 m0, s4
	s_nop 0
	s_add_u32 vcc_lo, s20, s54
	s_addc_u32 vcc_hi, s21, s55
	global_load_lds_dwordx4 v164, vcc
	s_add_i32 m0, s4, 0x2000
	s_nop 0
	s_add_u32 vcc_lo, s20, s58
	s_addc_u32 vcc_hi, s21, s59
	global_load_lds_dwordx4 v164, vcc
	s_add_i32 s15, s15, 2
	s_add_u32 s2, s2, 0x100
	s_addc_u32 s3, s3, 0
	s_add_u32 s6, s6, 0x100
	s_addc_u32 s7, s7, 0
	s_cmp_gt_u32 s15, 13
	s_waitcnt vmcnt(6)
	s_barrier
	v_mfma_f32_16x16x32_bf16 v[60:63], v[208:211], v[152:155], v[60:63]
	v_mfma_f32_16x16x32_bf16 v[56:59], v[216:219], v[152:155], v[56:59]
	v_mfma_f32_16x16x32_bf16 v[44:47], v[208:211], v[160:163], v[44:47]
	v_mfma_f32_16x16x32_bf16 v[40:43], v[216:219], v[160:163], v[40:43]
	ds_read_b128 v[136:139], v255 offset:0
	ds_read_b128 v[140:143], v255 offset:1024
	ds_read_b128 v[144:147], v255 offset:2048
	ds_read_b128 v[148:151], v255 offset:3072
	v_mfma_f32_16x16x32_bf16 v[28:31], v[208:211], v[176:179], v[28:31]
	v_mfma_f32_16x16x32_bf16 v[24:27], v[216:219], v[176:179], v[24:27]
	v_mfma_f32_16x16x32_bf16 v[12:15], v[208:211], v[200:203], v[12:15]
	v_mfma_f32_16x16x32_bf16 v[8:11], v[216:219], v[200:203], v[8:11]
	v_mfma_f32_16x16x32_bf16 v[60:63], v[212:215], v[156:159], v[60:63]
	v_mfma_f32_16x16x32_bf16 v[56:59], v[220:223], v[156:159], v[56:59]
	v_mfma_f32_16x16x32_bf16 v[44:47], v[212:215], v[172:175], v[44:47]
	v_mfma_f32_16x16x32_bf16 v[40:43], v[220:223], v[172:175], v[40:43]
	v_mfma_f32_16x16x32_bf16 v[28:31], v[212:215], v[196:199], v[28:31]
	v_mfma_f32_16x16x32_bf16 v[24:27], v[220:223], v[196:199], v[24:27]
	v_mfma_f32_16x16x32_bf16 v[12:15], v[212:215], v[204:207], v[12:15]
	v_mfma_f32_16x16x32_bf16 v[8:11], v[220:223], v[204:207], v[8:11]
	s_cbranch_scc0 .Ldb_WOUT_cont
	v_readfirstlane_b32 s101, v186
	s_cmpk_gt_u32 s101, 0xff
	s_cbranch_scc1 .Ldb_WOUT_young
	s_barrier
	s_mov_b32 s101, 1
	s_branch .Ldb_WOUT_exit

; __device__ __forceinline__ u32x4 pack8(const f32x4 a, const f32x4 b) { u32x4 w; w.x = cvt_pk_bf16(a[0], a[1]); w.y = cvt_pk_bf16(a[2], a[3]); w.z = cvt_pk_bf16(b[0], b[1]); w.w = cvt_pk_bf16(b[2], b[3]); return w; }
; __device__ __forceinline__ void unpack8(const u32x4 w, f32x4& a, f32x4& b) { a[0] = bf_lo(w.x); a[1] = bf_hi(w.x); a[2] = bf_lo(w.y); a[3] = bf_hi(w.y); b[0] = bf_lo(w.z); b[1] = bf_hi(w.z); b[2] = bf_lo(w.w); b[3] = bf_hi(w.w); }
; #define MEMFENCE asm volatile("" ::: "memory")
; #define XLOAD(gi, bufi) do { _Pragma("unroll") for (int ml = 0; ml < 2; ++ml) { const int m_ = ((gi) & 1) * 2 + ml; int row_ = rbase + ((gi) >> 1) * 128 + m_ * 16; asm volatile("" : "+v"(row_)); \
;                 _Pragma("unroll") for (int bj = 0; bj < 2; ++bj) xv[bufi][ml][bj] = *(const u32x4*)(xsrc + (size_t)row_ * 1024 + u.pn * 256 + bj * 128 + cl); } } while (0)
;     template <int KIND> __device__ __forceinline__ void run(f32x4 (&acc)[2][2][4][2], const Unit& u, int tid_in) const {
;     ...
;         if constexpr (KIND == K_XADD) {
;             const bf16_t* xsrc = xb0; bf16_t* xbo = (u.aux ? mg : xb0); float* sso = (u.aux ? ssq2 : ssq1);
;             u32x4 xv[2][2][2];
;     ...
;             XLOAD(0, 0);
; #pragma unroll
;             for (int gi = 0; gi < 4; ++gi) { const int ai = gi >> 1, mh = gi & 1, bufi = gi & 1;
;                 if (gi < 3) XLOAD(gi + 1, (gi + 1) & 1);
; #pragma unroll
;                 for (int ml = 0; ml < 2; ++ml) { const int m = mh * 2 + ml; int row = rbase + ai * 128 + m * 16; asm volatile("" : "+v"(row)); float ss = 0.f;
; #pragma unroll
;                     for (int bj = 0; bj < 2; ++bj) { const size_t off = (size_t)row * 1024 + u.pn * 256 + bj * 128 + cl; f32x4 x0, x1; unpack8(xv[bufi][ml][bj], x0, x1);
;                         const f32x4 o0 = x0 + acc[ai][bj][m][0], o1 = x1 + acc[ai][bj][m][1];
;                         *(u32x4*)(xbo + off) = pack8(o0, o1);
;                         ss += (o0[0] * o0[0] + o0[1] * o0[1]) + (o0[2] * o0[2] + o0[3] * o0[3]) + (o1[0] * o1[0] + o1[1] * o1[1]) + (o1[2] * o1[2] + o1[3] * o1[3]); }
;                     ss += __shfl_xor(ss, 16); ss += __shfl_xor(ss, 32);
;                     if (fq == 0) sso[((size_t)u.pn * T_TOK + row) * 4 + wc] = ss; }
;                 MEMFENCE; }
.Ldb_WOUT_exit:
	s_waitcnt lgkmcnt(0)
	v_mov_b32_e32 v0, v180
	s_lshl_b32 s3, s9, 8
	v_readfirstlane_b32 s2, v0
	s_bfe_u32 s15, s2, 0x20006
	s_ashr_i32 s2, s2, 2
	s_andn2_b32 s2, s2, 63
	s_add_i32 s2, s2, s3
	v_and_or_b32 v183, v0, 15, s2
	v_mov_b32_e32 v136, v183
	v_bfe_u32 v138, v0, 4, 2
	s_lshl_b32 s2, s8, 8
	v_ashrrev_i32_e32 v137, 31, v136
	v_lshlrev_b32_e32 v0, 3, v138
	v_lshlrev_b64 v[136:137], 11, v[136:137]
	s_ashr_i32 s3, s2, 31
	v_lshl_or_b32 v0, s15, 5, v0
	v_lshl_add_u64 v[136:137], s[10:11], 0, v[136:137]
	s_lshl_b64 s[20:21], s[2:3], 1
	v_lshl_add_u64 v[136:137], v[136:137], 0, s[20:21]
	v_lshlrev_b32_e32 v0, 1, v0
	v_lshl_add_u64 v[136:137], v[136:137], 0, v[0:1]
	global_load_dwordx4 v[196:199], v[136:137], off
	global_load_dwordx4 v[160:163], v[136:137], off offset:256
	v_or_b32_e32 v176, 16, v183
	v_mov_b32_e32 v136, v176
	v_or_b32_e32 v174, 32, v183
	v_ashrrev_i32_e32 v137, 31, v136
	v_lshlrev_b64 v[136:137], 11, v[136:137]
	v_lshl_add_u64 v[136:137], s[10:11], 0, v[136:137]
	v_lshl_add_u64 v[136:137], v[136:137], 0, s[20:21]
	v_lshl_add_u64 v[136:137], v[136:137], 0, v[0:1]
	global_load_dwordx4 v[156:159], v[136:137], off
	global_load_dwordx4 v[152:155], v[136:137], off offset:256
	v_mov_b32_e32 v136, v174
	v_or_b32_e32 v172, 48, v183
	v_ashrrev_i32_e32 v137, 31, v136
	v_lshlrev_b64 v[136:137], 11, v[136:137]
	v_lshl_add_u64 v[136:137], s[10:11], 0, v[136:137]
	v_lshl_add_u64 v[136:137], v[136:137], 0, s[20:21]
	v_lshl_add_u64 v[136:137], v[136:137], 0, v[0:1]
	global_load_dwordx4 v[148:151], v[136:137], off
	global_load_dwordx4 v[140:143], v[136:137], off offset:256
	v_mov_b32_e32 v136, v172
	v_cmp_eq_u32_e32 vcc, 0, v138
	v_ashrrev_i32_e32 v137, 31, v136
	v_lshlrev_b64 v[136:137], 11, v[136:137]
	v_lshl_add_u64 v[136:137], s[10:11], 0, v[136:137]
	v_lshl_add_u64 v[136:137], v[136:137], 0, s[20:21]
	v_lshl_add_u64 v[136:137], v[136:137], 0, v[0:1]
	global_load_dwordx4 v[144:147], v[136:137], off
	s_nop 0
	global_load_dwordx4 v[136:139], v[136:137], off offset:256
	v_mov_b32_e32 v178, v183
	s_waitcnt vmcnt(0)
	v_lshlrev_b32_e32 v200, 16, v196
	v_ashrrev_i32_e32 v179, 31, v178
	v_lshlrev_b64 v[184:185], 11, v[178:179]
	v_lshl_add_u64 v[184:185], s[10:11], 0, v[184:185]
	v_and_b32_e32 v201, 0xffff0000, v196
	v_lshlrev_b32_e32 v196, 16, v197
	v_and_b32_e32 v197, 0xffff0000, v197
	v_lshlrev_b32_e32 v202, 16, v198
	v_and_b32_e32 v203, 0xffff0000, v198
	v_lshlrev_b32_e32 v198, 16, v199
	v_and_b32_e32 v199, 0xffff0000, v199
	v_lshl_add_u64 v[184:185], v[184:185], 0, s[20:21]
	v_pk_add_f32 v[134:135], v[134:135], v[196:197]
	v_pk_add_f32 v[132:133], v[132:133], v[200:201]
	v_pk_add_f32 v[196:197], v[130:131], v[198:199]
	v_pk_add_f32 v[198:199], v[128:129], v[202:203]
	v_cvt_pk_bf16_f32 v128, v132, v133
	v_cvt_pk_bf16_f32 v129, v134, v135
	v_lshl_add_u64 v[184:185], v[184:185], 0, v[0:1]
	v_cvt_pk_bf16_f32 v130, v198, v199
	v_cvt_pk_bf16_f32 v131, v196, v197
	global_store_dwordx4 v[184:185], v[128:131], off
	s_nop 1
	v_mul_f32_e32 v128, v133, v133
	v_mul_f32_e32 v129, v135, v135
	v_fmac_f32_e32 v128, v132, v132
	v_fmac_f32_e32 v129, v134, v134
	v_add_f32_e32 v128, v128, v129
	v_mul_f32_e32 v129, v199, v199
	v_fmac_f32_e32 v129, v198, v198
	v_add_f32_e32 v128, v129, v128
	v_mul_f32_e32 v129, v197, v197
	v_fmac_f32_e32 v129, v196, v196
	v_add_f32_e32 v173, v129, v128
	v_lshlrev_b32_e32 v128, 16, v160
	v_and_b32_e32 v129, 0xffff0000, v160
	v_lshlrev_b32_e32 v130, 16, v161
	v_and_b32_e32 v131, 0xffff0000, v161
	v_lshlrev_b32_e32 v132, 16, v162
	v_and_b32_e32 v133, 0xffff0000, v162
	v_lshlrev_b32_e32 v134, 16, v163
	v_and_b32_e32 v135, 0xffff0000, v163
	v_pk_add_f32 v[126:127], v[126:127], v[130:131]
	v_pk_add_f32 v[124:125], v[124:125], v[128:129]
	v_pk_add_f32 v[130:131], v[120:121], v[132:133]
	v_cvt_pk_bf16_f32 v120, v124, v125
	v_cvt_pk_bf16_f32 v121, v126, v127
	v_pk_add_f32 v[128:129], v[122:123], v[134:135]
	v_cvt_pk_bf16_f32 v122, v130, v131
	s_nop 0
	v_cvt_pk_bf16_f32 v123, v128, v129
	global_store_dwordx4 v[184:185], v[120:123], off offset:256
	s_nop 1
	v_mul_f32_e32 v120, v125, v125
	v_mul_f32_e32 v121, v127, v127
	v_fmac_f32_e32 v120, v124, v124
	v_fmac_f32_e32 v121, v126, v126
	v_add_f32_e32 v120, v120, v121
	v_mul_f32_e32 v121, v131, v131
	v_fmac_f32_e32 v121, v130, v130
	v_add_f32_e32 v120, v121, v120
	v_mul_f32_e32 v121, v129, v129
	v_fmac_f32_e32 v121, v128, v128
	v_add_f32_e32 v120, v121, v120
	v_xor_b32_e32 v121, 16, v190
	v_cmp_lt_i32_e64 s[6:7], v121, v192
	v_add_f32_e32 v120, v173, v120
	s_nop 0
	v_cndmask_b32_e64 v121, v190, v121, s[6:7]
	v_lshlrev_b32_e32 v124, 2, v121
	ds_bpermute_b32 v121, v124, v120
	s_waitcnt lgkmcnt(0)
	v_add_f32_e32 v120, v120, v121
	v_xor_b32_e32 v121, 32, v190
	v_cmp_lt_i32_e64 s[6:7], v121, v192
	s_nop 1
	v_cndmask_b32_e64 v121, v190, v121, s[6:7]
	v_lshlrev_b32_e32 v125, 2, v121
	ds_bpermute_b32 v121, v125, v120
	s_and_saveexec_b64 s[6:7], vcc
	s_cbranch_execz .LBB0_1040
	s_ashr_i32 s9, s8, 31
	s_lshl_b64 s[4:5], s[8:9], 19
	s_add_u32 s4, s38, s4
	s_addc_u32 s5, s39, s5
	s_waitcnt lgkmcnt(0)
	v_add_f32_e32 v122, v120, v121
	v_lshl_add_u64 v[120:121], v[178:179], 4, s[4:5]
	s_lshl_b32 s74, s15, 2
	v_lshl_add_u64 v[120:121], v[120:121], 0, s[74:75]
	global_store_dword v[120:121], v122, off

; #define G_STAGE(bufoff, gbase, o0, h64) do { \
;         __builtin_amdgcn_global_load_lds((const unsigned*)((const char*)(gbase) + (o0)), (LAS unsigned*)(lds + (bufoff) + ldsw), 16, 0, 0); \
;         __builtin_amdgcn_global_load_lds((const unsigned*)((const char*)(gbase) + (h64) + (o0)), (LAS unsigned*)(lds + (bufoff) + ldsw + 8192), 16, 0, 0); } while (0)
; #define G_LDA(dst, b, h) do { _Pragma("unroll") for (int m = 0; m < 4; ++m) _Pragma("unroll") for (int k = 0; k < 2; ++k) dst[m][k] = *(const LAS bf16x8*)(lds + G_SA(b, h) + aoff + m * 2048 + k * 1024); } while (0)
; #define G_LDB(dst, b, h) do { _Pragma("unroll") for (int n = 0; n < 2; ++n) _Pragma("unroll") for (int k = 0; k < 2; ++k) dst[n][k] = *(const LAS bf16x8*)(lds + G_SB(b, h) + boff + n * 2048 + k * 1024); } while (0)
; #define G_WAIT_L(n) asm volatile("s_waitcnt lgkmcnt(" #n ")" ::: "memory")
; #define G_BAR __builtin_amdgcn_s_barrier()
; #define G_SCHED __builtin_amdgcn_sched_barrier(0)
;     ...
;         for (int t = 0; t < nt; t += 2) {
;             const bool last = (t == nt - 2);
;             const char* a1 = cA + (size_t)(t + 1) * ckA;
;             const char* a2 = last ? nA : cA + (size_t)(t + 2) * ckA; const char* b2 = last ? nB : cB + (size_t)(t + 2) * kB;
;             const char* a3 = a2 + ckA; const char* b3 = b2 + kB;
;             G_LDB(B0, 0, 0); G_SCHED; G_LDA(At, 0, 0); G_STAGE(G_SA(1, 1), a1 + chA, cA0, qA);
;             G_WAIT_L(8); G_BAR; G_WAIT_L(0); G_MMA(0, 0, At, B0); G_BAR; G_SCHED;
;             G_LDB(B1, 0, 1); G_STAGE(G_SB(0, 0), b2, cB0, qB);
;             G_BAR; G_WAIT_L(0); G_MMA(0, 1, At, B1); G_BAR;
;             G_LDA(At, 0, 1); G_STAGE(G_SA(0, 0), a2, cA0, qA);
;             G_BAR; G_WAIT_L(0); G_MMA(1, 0, At, B0); G_BAR; G_SCHED;
;     ...
;         if (!(cs.kind == K_MG_B && cur.aux < 2))
; #pragma unroll
;         for (int a = 0; a < 2; ++a)
; #pragma unroll
;             for (int b = 0; b < 2; ++b)
; #pragma unroll
;                 for (int m = 0; m < 4; ++m)
; #pragma unroll
;                     for (int n = 0; n < 2; ++n) acc[a][b][m][n] = (f32x4){0.f, 0.f, 0.f, 0.f};
.LBB0_1119:
	s_add_u32 s2, s16, 0x40080
	s_addc_u32 s3, s17, 0
	s_add_u32 s16, s18, 0x100
	v_mov_b64_e32 v[8:9], 0
	s_addc_u32 s17, s19, 0
	s_mov_b32 s18, -2
	v_mov_b64_e32 v[10:11], 0
	v_mov_b64_e32 v[16:17], 0
	v_mov_b64_e32 v[18:19], 0
	v_mov_b64_e32 v[24:25], 0
	v_mov_b64_e32 v[26:27], 0
	v_mov_b64_e32 v[32:33], 0
	v_mov_b64_e32 v[34:35], 0
	v_mov_b64_e32 v[40:41], 0
	v_mov_b64_e32 v[42:43], 0
	v_mov_b64_e32 v[48:49], 0
	v_mov_b64_e32 v[50:51], 0
	v_mov_b64_e32 v[56:57], 0
	v_mov_b64_e32 v[58:59], 0
	v_mov_b64_e32 v[64:65], 0
	v_mov_b64_e32 v[66:67], 0
	v_mov_b64_e32 v[12:13], 0
	v_mov_b64_e32 v[14:15], 0
	v_mov_b64_e32 v[20:21], 0
	v_mov_b64_e32 v[22:23], 0
	v_mov_b64_e32 v[28:29], 0
	v_mov_b64_e32 v[30:31], 0
	v_mov_b64_e32 v[36:37], 0
	v_mov_b64_e32 v[38:39], 0
	v_mov_b64_e32 v[44:45], 0
	v_mov_b64_e32 v[46:47], 0
	v_mov_b64_e32 v[52:53], 0
	v_mov_b64_e32 v[54:55], 0
	v_mov_b64_e32 v[60:61], 0
	v_mov_b64_e32 v[62:63], 0
	v_mov_b64_e32 v[68:69], 0
	v_mov_b64_e32 v[70:71], 0
	v_mov_b64_e32 v[72:73], 0
	v_mov_b64_e32 v[74:75], 0
	v_mov_b64_e32 v[80:81], 0
	v_mov_b64_e32 v[82:83], 0
	v_mov_b64_e32 v[88:89], 0
	v_mov_b64_e32 v[90:91], 0
	v_mov_b64_e32 v[96:97], 0
	v_mov_b64_e32 v[98:99], 0
	v_mov_b64_e32 v[104:105], 0
	v_mov_b64_e32 v[106:107], 0
	v_mov_b64_e32 v[112:113], 0
	v_mov_b64_e32 v[114:115], 0
	v_mov_b64_e32 v[120:121], 0
	v_mov_b64_e32 v[122:123], 0
	v_mov_b64_e32 v[128:129], 0
	v_mov_b64_e32 v[130:131], 0
	v_mov_b64_e32 v[76:77], 0
	v_mov_b64_e32 v[78:79], 0
	v_mov_b64_e32 v[84:85], 0
	v_mov_b64_e32 v[86:87], 0
	v_mov_b64_e32 v[92:93], 0
	v_mov_b64_e32 v[94:95], 0
	v_mov_b64_e32 v[100:101], 0
	v_mov_b64_e32 v[102:103], 0
	v_mov_b64_e32 v[108:109], 0
	v_mov_b64_e32 v[110:111], 0
	v_mov_b64_e32 v[116:117], 0
	v_mov_b64_e32 v[118:119], 0
	v_mov_b64_e32 v[124:125], 0
	v_mov_b64_e32 v[126:127], 0
	v_mov_b64_e32 v[132:133], 0
	v_mov_b64_e32 v[134:135], 0
	s_mov_b64 s[42:43], 0x40000
	s_mov_b64 s[50:51], 0x60000
	s_mov_b64 s[52:53], 0x20080
	s_mov_b64 s[54:55], 0x40080
	s_mov_b64 s[58:59], 0x60080
	s_cmp_eq_u32 s101, 2
	s_cselect_b32 s101, 0, s101
	v_add_u32_e32 v235, 0x10000, v149
	ds_read_b128 v[140:143], v235 offset:0
	ds_read_b128 v[144:147], v235 offset:1024
	ds_read_b128 v[152:155], v235 offset:2048
	ds_read_b128 v[156:159], v235 offset:3072
.LBB0_1120:
	s_add_u32 s4, s2, 0xfffc0080
	s_addc_u32 s5, s3, -1
	s_add_i32 s19, 0, 0x10000
	s_cmp_eq_u32 s18, 12
	s_cselect_b32 s5, s13, s5
	s_cselect_b32 s4, s12, s4
	s_cselect_b32 s41, s15, s17
	s_cselect_b32 s40, s14, s16
	s_add_i32 m0, s26, 0xc000
	ds_read_b128 v[160:163], v150
	ds_read_b128 v[164:167], v150 offset:1024
	ds_read_b128 v[172:175], v150 offset:2048
	ds_read_b128 v[176:179], v150 offset:3072
	ds_read_b128 v[180:183], v150 offset:4096
	ds_read_b128 v[196:199], v150 offset:5120
	ds_read_b128 v[200:203], v150 offset:6144
	ds_read_b128 v[204:207], v150 offset:7168
	global_load_lds_dwordx4 v138, s[2:3]
	s_add_i32 m0, s26, 0xe000
	s_nop 0
	s_add_u32 vcc_lo, s2, s0
	s_addc_u32 vcc_hi, s3, s1
	global_load_lds_dwordx4 v138, vcc
	s_waitcnt lgkmcnt(8)
	s_cmp_eq_u32 s101, 1
	s_cbranch_scc1 .Ldb_FFI_sk
	s_barrier
.Ldb_FFI_sk:
	s_mov_b32 s101, 0
	s_waitcnt lgkmcnt(0)
	v_mfma_f32_16x16x32_bf16 v[132:135], v[140:143], v[160:163], v[132:135]
	v_mfma_f32_16x16x32_bf16 v[124:127], v[152:155], v[160:163], v[124:127]
	v_mfma_f32_16x16x32_bf16 v[116:119], v[140:143], v[172:175], v[116:119]
	v_mfma_f32_16x16x32_bf16 v[108:111], v[152:155], v[172:175], v[108:111]
	v_mfma_f32_16x16x32_bf16 v[100:103], v[140:143], v[180:183], v[100:103]
	v_mfma_f32_16x16x32_bf16 v[92:95], v[152:155], v[180:183], v[92:95]
	v_mfma_f32_16x16x32_bf16 v[84:87], v[140:143], v[200:203], v[84:87]
	v_mfma_f32_16x16x32_bf16 v[76:79], v[152:155], v[200:203], v[76:79]
	v_mfma_f32_16x16x32_bf16 v[132:135], v[144:147], v[164:167], v[132:135]
	v_mfma_f32_16x16x32_bf16 v[124:127], v[156:159], v[164:167], v[124:127]
	v_mfma_f32_16x16x32_bf16 v[116:119], v[144:147], v[176:179], v[116:119]
	v_mfma_f32_16x16x32_bf16 v[108:111], v[156:159], v[176:179], v[108:111]
	v_mfma_f32_16x16x32_bf16 v[100:103], v[144:147], v[196:199], v[100:103]
	v_mfma_f32_16x16x32_bf16 v[92:95], v[156:159], v[196:199], v[92:95]
	v_mfma_f32_16x16x32_bf16 v[84:87], v[144:147], v[204:207], v[84:87]
	v_mfma_f32_16x16x32_bf16 v[76:79], v[156:159], v[204:207], v[76:79]
	s_barrier
	s_add_i32 s39, 0, 0x14000
	s_add_i32 s19, s19, s21
	s_mov_b32 m0, s19
	ds_read_b128 v[208:211], v235 offset:16384
	ds_read_b128 v[212:215], v235 offset:17408
	ds_read_b128 v[216:219], v235 offset:18432
	ds_read_b128 v[220:223], v235 offset:19456
	global_load_lds_dwordx4 v2, s[40:41]
	s_add_i32 m0, s19, 0x2000
	s_nop 0
	s_add_u32 vcc_lo, s40, s0
	s_addc_u32 vcc_hi, s41, s1
	global_load_lds_dwordx4 v2, vcc
	s_barrier
	s_waitcnt lgkmcnt(0)
	v_mfma_f32_16x16x32_bf16 v[128:131], v[208:211], v[160:163], v[128:131]
	v_mfma_f32_16x16x32_bf16 v[120:123], v[216:219], v[160:163], v[120:123]
	v_mfma_f32_16x16x32_bf16 v[112:115], v[208:211], v[172:175], v[112:115]
	v_mfma_f32_16x16x32_bf16 v[104:107], v[216:219], v[172:175], v[104:107]
	v_mfma_f32_16x16x32_bf16 v[96:99], v[208:211], v[180:183], v[96:99]
	v_mfma_f32_16x16x32_bf16 v[88:91], v[216:219], v[180:183], v[88:91]
	v_mfma_f32_16x16x32_bf16 v[80:83], v[208:211], v[200:203], v[80:83]
	v_mfma_f32_16x16x32_bf16 v[72:75], v[216:219], v[200:203], v[72:75]
	v_mfma_f32_16x16x32_bf16 v[128:131], v[212:215], v[164:167], v[128:131]
	v_mfma_f32_16x16x32_bf16 v[120:123], v[220:223], v[164:167], v[120:123]
	v_mfma_f32_16x16x32_bf16 v[112:115], v[212:215], v[176:179], v[112:115]
	v_mfma_f32_16x16x32_bf16 v[104:107], v[220:223], v[176:179], v[104:107]
	v_mfma_f32_16x16x32_bf16 v[96:99], v[212:215], v[196:199], v[96:99]
	v_mfma_f32_16x16x32_bf16 v[88:91], v[220:223], v[196:199], v[88:91]
	v_mfma_f32_16x16x32_bf16 v[80:83], v[212:215], v[204:207], v[80:83]
	v_mfma_f32_16x16x32_bf16 v[72:75], v[220:223], v[204:207], v[72:75]
	s_barrier
; #define G_STAGE(bufoff, gbase, o0, h64) do { \
;         __builtin_amdgcn_global_load_lds((const unsigned*)((const char*)(gbase) + (o0)), (LAS unsigned*)(lds + (bufoff) + ldsw), 16, 0, 0); \
;         __builtin_amdgcn_global_load_lds((const unsigned*)((const char*)(gbase) + (h64) + (o0)), (LAS unsigned*)(lds + (bufoff) + ldsw + 8192), 16, 0, 0); } while (0)
; #define G_LDA(dst, b, h) do { _Pragma("unroll") for (int m = 0; m < 4; ++m) _Pragma("unroll") for (int k = 0; k < 2; ++k) dst[m][k] = *(const LAS bf16x8*)(lds + G_SA(b, h) + aoff + m * 2048 + k * 1024); } while (0)
; #define G_LDB(dst, b, h) do { _Pragma("unroll") for (int n = 0; n < 2; ++n) _Pragma("unroll") for (int k = 0; k < 2; ++k) dst[n][k] = *(const LAS bf16x8*)(lds + G_SB(b, h) + boff + n * 2048 + k * 1024); } while (0)
; #define G_WAIT_V(n) asm volatile("s_waitcnt vmcnt(" #n ")" ::: "memory")
; #define G_WAIT_L(n) asm volatile("s_waitcnt lgkmcnt(" #n ")" ::: "memory")
; #define G_BAR __builtin_amdgcn_s_barrier()
; #define G_SCHED __builtin_amdgcn_sched_barrier(0)
;     ...
;             G_BAR; G_WAIT_L(0); G_MMA(1, 0, At, B0); G_BAR; G_SCHED;
;             G_STAGE(G_SB(0, 1), b2 + chB, cB0, qB);
;             G_WAIT_V(6); G_BAR; G_MMA(1, 1, At, B1); G_BAR;
;             G_LDB(B0, 1, 0); G_SCHED; G_LDA(At, 1, 0); G_STAGE(G_SA(0, 1), a2 + chA, cA0, qA);
;             G_WAIT_L(8); G_BAR; G_WAIT_L(0); G_MMA(0, 0, At, B0); G_BAR; G_SCHED;
;             G_LDB(B1, 1, 1); G_STAGE(G_SB(1, 0), b3, cB0, qB);
	s_mov_b32 m0, s26
	v_lshl_add_u64 v[224:225], s[4:5], 0, v[136:137]
	ds_read_b128 v[160:163], v150 offset:16384
	ds_read_b128 v[164:167], v150 offset:17408
	ds_read_b128 v[172:175], v150 offset:18432
	ds_read_b128 v[176:179], v150 offset:19456
	ds_read_b128 v[180:183], v150 offset:20480
	ds_read_b128 v[196:199], v150 offset:21504
	ds_read_b128 v[200:203], v150 offset:22528
	ds_read_b128 v[204:207], v150 offset:23552
	global_load_lds_dwordx4 v136, s[4:5]
	s_mov_b32 m0, s27
	s_nop 0
	s_add_u32 vcc_lo, s4, s0
	s_addc_u32 vcc_hi, s5, s1
	global_load_lds_dwordx4 v136, vcc
	s_barrier
	s_waitcnt lgkmcnt(0)
	v_mfma_f32_16x16x32_bf16 v[68:71], v[140:143], v[160:163], v[68:71]
	v_mfma_f32_16x16x32_bf16 v[60:63], v[152:155], v[160:163], v[60:63]
	v_mfma_f32_16x16x32_bf16 v[52:55], v[140:143], v[172:175], v[52:55]
	v_mfma_f32_16x16x32_bf16 v[44:47], v[152:155], v[172:175], v[44:47]
	v_mfma_f32_16x16x32_bf16 v[36:39], v[140:143], v[180:183], v[36:39]
	v_mfma_f32_16x16x32_bf16 v[28:31], v[152:155], v[180:183], v[28:31]
	v_mfma_f32_16x16x32_bf16 v[20:23], v[140:143], v[200:203], v[20:23]
	v_mfma_f32_16x16x32_bf16 v[12:15], v[152:155], v[200:203], v[12:15]
	v_mfma_f32_16x16x32_bf16 v[68:71], v[144:147], v[164:167], v[68:71]
	v_mfma_f32_16x16x32_bf16 v[60:63], v[156:159], v[164:167], v[60:63]
	v_mfma_f32_16x16x32_bf16 v[52:55], v[144:147], v[176:179], v[52:55]
	v_mfma_f32_16x16x32_bf16 v[44:47], v[156:159], v[176:179], v[44:47]
	v_mfma_f32_16x16x32_bf16 v[36:39], v[144:147], v[196:199], v[36:39]
	v_mfma_f32_16x16x32_bf16 v[28:31], v[156:159], v[196:199], v[28:31]
	v_mfma_f32_16x16x32_bf16 v[20:23], v[144:147], v[204:207], v[20:23]
	v_mfma_f32_16x16x32_bf16 v[12:15], v[156:159], v[204:207], v[12:15]
	s_barrier
	s_add_i32 s100, s39, s21
	s_mov_b32 m0, s100
	s_nop 0
	s_add_u32 vcc_lo, s40, s42
	s_addc_u32 vcc_hi, s41, s43
	global_load_lds_dwordx4 v2, vcc
	s_add_i32 m0, s100, 0x2000
	s_nop 0
	s_add_u32 vcc_lo, s40, s50
	s_addc_u32 vcc_hi, s41, s51
	global_load_lds_dwordx4 v2, vcc
	s_waitcnt vmcnt(6)
	s_barrier
	v_mfma_f32_16x16x32_bf16 v[64:67], v[208:211], v[160:163], v[64:67]
	v_mfma_f32_16x16x32_bf16 v[56:59], v[216:219], v[160:163], v[56:59]
	v_mfma_f32_16x16x32_bf16 v[48:51], v[208:211], v[172:175], v[48:51]
	v_mfma_f32_16x16x32_bf16 v[40:43], v[216:219], v[172:175], v[40:43]
	ds_read_b128 v[140:143], v235 offset:32768
	ds_read_b128 v[144:147], v235 offset:33792
	ds_read_b128 v[152:155], v235 offset:34816
	ds_read_b128 v[156:159], v235 offset:35840
	v_mfma_f32_16x16x32_bf16 v[32:35], v[208:211], v[180:183], v[32:35]
	v_mfma_f32_16x16x32_bf16 v[24:27], v[216:219], v[180:183], v[24:27]
	v_mfma_f32_16x16x32_bf16 v[16:19], v[208:211], v[200:203], v[16:19]
	v_mfma_f32_16x16x32_bf16 v[8:11], v[216:219], v[200:203], v[8:11]
	v_mfma_f32_16x16x32_bf16 v[64:67], v[212:215], v[164:167], v[64:67]
	v_mfma_f32_16x16x32_bf16 v[56:59], v[220:223], v[164:167], v[56:59]
	v_mfma_f32_16x16x32_bf16 v[48:51], v[212:215], v[176:179], v[48:51]
	v_mfma_f32_16x16x32_bf16 v[40:43], v[220:223], v[176:179], v[40:43]
	v_mfma_f32_16x16x32_bf16 v[32:35], v[212:215], v[196:199], v[32:35]
	v_mfma_f32_16x16x32_bf16 v[24:27], v[220:223], v[196:199], v[24:27]
	v_mfma_f32_16x16x32_bf16 v[16:19], v[212:215], v[204:207], v[16:19]
	v_mfma_f32_16x16x32_bf16 v[8:11], v[220:223], v[204:207], v[8:11]
	s_barrier
	s_add_i32 s100, 0, 0x18000
	s_mov_b32 m0, s29
	ds_read_b128 v[160:163], v150 offset:32768
	ds_read_b128 v[164:167], v150 offset:33792
	ds_read_b128 v[172:175], v150 offset:34816
	ds_read_b128 v[176:179], v150 offset:35840
	ds_read_b128 v[180:183], v150 offset:36864
	ds_read_b128 v[196:199], v150 offset:37888
	ds_read_b128 v[200:203], v150 offset:38912
	ds_read_b128 v[204:207], v150 offset:39936
	s_add_u32 vcc_lo, s4, s42
	s_addc_u32 vcc_hi, s5, s43
	global_load_lds_dwordx4 v136, vcc
	s_mov_b32 m0, s30
	s_nop 0
	s_add_u32 vcc_lo, s4, s50
	s_addc_u32 vcc_hi, s5, s51
	global_load_lds_dwordx4 v136, vcc
	s_waitcnt lgkmcnt(8)
	s_barrier
	s_waitcnt lgkmcnt(0)
	v_mfma_f32_16x16x32_bf16 v[132:135], v[140:143], v[160:163], v[132:135]
	v_mfma_f32_16x16x32_bf16 v[124:127], v[152:155], v[160:163], v[124:127]
	v_mfma_f32_16x16x32_bf16 v[116:119], v[140:143], v[172:175], v[116:119]
	v_mfma_f32_16x16x32_bf16 v[108:111], v[152:155], v[172:175], v[108:111]
	v_mfma_f32_16x16x32_bf16 v[100:103], v[140:143], v[180:183], v[100:103]
	v_mfma_f32_16x16x32_bf16 v[92:95], v[152:155], v[180:183], v[92:95]
	v_mfma_f32_16x16x32_bf16 v[84:87], v[140:143], v[200:203], v[84:87]
	v_mfma_f32_16x16x32_bf16 v[76:79], v[152:155], v[200:203], v[76:79]
	v_mfma_f32_16x16x32_bf16 v[132:135], v[144:147], v[164:167], v[132:135]
	v_mfma_f32_16x16x32_bf16 v[124:127], v[156:159], v[164:167], v[124:127]
	v_mfma_f32_16x16x32_bf16 v[116:119], v[144:147], v[176:179], v[116:119]
	v_mfma_f32_16x16x32_bf16 v[108:111], v[156:159], v[176:179], v[108:111]
	v_mfma_f32_16x16x32_bf16 v[100:103], v[144:147], v[196:199], v[100:103]
	v_mfma_f32_16x16x32_bf16 v[92:95], v[156:159], v[196:199], v[92:95]
	v_mfma_f32_16x16x32_bf16 v[84:87], v[144:147], v[204:207], v[84:87]
	v_mfma_f32_16x16x32_bf16 v[76:79], v[156:159], v[204:207], v[76:79]
	s_barrier
; #define G_STAGE(bufoff, gbase, o0, h64) do { \
;         __builtin_amdgcn_global_load_lds((const unsigned*)((const char*)(gbase) + (o0)), (LAS unsigned*)(lds + (bufoff) + ldsw), 16, 0, 0); \
;         __builtin_amdgcn_global_load_lds((const unsigned*)((const char*)(gbase) + (h64) + (o0)), (LAS unsigned*)(lds + (bufoff) + ldsw + 8192), 16, 0, 0); } while (0)
; #define G_LDA(dst, b, h) do { _Pragma("unroll") for (int m = 0; m < 4; ++m) _Pragma("unroll") for (int k = 0; k < 2; ++k) dst[m][k] = *(const LAS bf16x8*)(lds + G_SA(b, h) + aoff + m * 2048 + k * 1024); } while (0)
; #define G_LDB(dst, b, h) do { _Pragma("unroll") for (int n = 0; n < 2; ++n) _Pragma("unroll") for (int k = 0; k < 2; ++k) dst[n][k] = *(const LAS bf16x8*)(lds + G_SB(b, h) + boff + n * 2048 + k * 1024); } while (0)
; #define G_WAIT_V(n) asm volatile("s_waitcnt vmcnt(" #n ")" ::: "memory")
; #define G_WAIT_L(n) asm volatile("s_waitcnt lgkmcnt(" #n ")" ::: "memory")
; #define G_BAR __builtin_amdgcn_s_barrier()
; #define G_SCHED __builtin_amdgcn_sched_barrier(0)
;     ...
;             G_WAIT_L(8); G_BAR; G_WAIT_L(0); G_MMA(0, 0, At, B0); G_BAR; G_SCHED;
;             G_LDB(B1, 1, 1); G_STAGE(G_SB(1, 0), b3, cB0, qB);
;             G_BAR; G_WAIT_L(0); G_MMA(0, 1, At, B1); G_BAR;
;             G_LDA(At, 1, 1); G_STAGE(G_SA(1, 0), a3, cA0, qA);
;             G_BAR; G_WAIT_L(0); G_MMA(1, 0, At, B0); G_BAR; G_SCHED;
;             G_STAGE(G_SB(1, 1), b3 + chB, cB0, qB);
;             G_WAIT_V(6); G_BAR; G_MMA(1, 1, At, B1); G_BAR;
;         }
	s_add_i32 s5, 0, 0x1c000
	s_add_i32 s4, s100, s21
	s_mov_b32 m0, s4
	ds_read_b128 v[208:211], v235 offset:49152
	ds_read_b128 v[212:215], v235 offset:50176
	ds_read_b128 v[216:219], v235 offset:51200
	ds_read_b128 v[220:223], v235 offset:52224
	s_add_u32 vcc_lo, s40, s46
	s_addc_u32 vcc_hi, s41, s47
	global_load_lds_dwordx4 v2, vcc
	s_add_i32 m0, s4, 0x2000
	s_nop 0
	s_add_u32 vcc_lo, s40, s52
	s_addc_u32 vcc_hi, s41, s53
	global_load_lds_dwordx4 v2, vcc
	s_barrier
	s_waitcnt lgkmcnt(0)
	v_mfma_f32_16x16x32_bf16 v[128:131], v[208:211], v[160:163], v[128:131]
	v_mfma_f32_16x16x32_bf16 v[120:123], v[216:219], v[160:163], v[120:123]
	v_mfma_f32_16x16x32_bf16 v[112:115], v[208:211], v[172:175], v[112:115]
	v_mfma_f32_16x16x32_bf16 v[104:107], v[216:219], v[172:175], v[104:107]
	v_mfma_f32_16x16x32_bf16 v[96:99], v[208:211], v[180:183], v[96:99]
	v_mfma_f32_16x16x32_bf16 v[88:91], v[216:219], v[180:183], v[88:91]
	v_mfma_f32_16x16x32_bf16 v[80:83], v[208:211], v[200:203], v[80:83]
	v_mfma_f32_16x16x32_bf16 v[72:75], v[216:219], v[200:203], v[72:75]
	v_mfma_f32_16x16x32_bf16 v[128:131], v[212:215], v[164:167], v[128:131]
	v_mfma_f32_16x16x32_bf16 v[120:123], v[220:223], v[164:167], v[120:123]
	v_mfma_f32_16x16x32_bf16 v[112:115], v[212:215], v[176:179], v[112:115]
	v_mfma_f32_16x16x32_bf16 v[104:107], v[220:223], v[176:179], v[104:107]
	v_mfma_f32_16x16x32_bf16 v[96:99], v[212:215], v[196:199], v[96:99]
	v_mfma_f32_16x16x32_bf16 v[88:91], v[220:223], v[196:199], v[88:91]
	v_mfma_f32_16x16x32_bf16 v[80:83], v[212:215], v[204:207], v[80:83]
	v_mfma_f32_16x16x32_bf16 v[72:75], v[220:223], v[204:207], v[72:75]
	s_barrier
	s_mov_b32 m0, s31
	v_lshl_add_u64 v[226:227], v[224:225], 0, s[46:47]
	ds_read_b128 v[160:163], v150 offset:49152
	ds_read_b128 v[164:167], v150 offset:50176
	ds_read_b128 v[172:175], v150 offset:51200
	ds_read_b128 v[176:179], v150 offset:52224
	ds_read_b128 v[180:183], v150 offset:53248
	ds_read_b128 v[196:199], v150 offset:54272
	ds_read_b128 v[200:203], v150 offset:55296
	ds_read_b128 v[204:207], v150 offset:56320
	global_load_lds_dwordx4 v[226:227], off
	v_lshl_add_u64 v[224:225], v[224:225], 0, s[52:53]
	s_mov_b32 m0, s34
	s_nop 0
	global_load_lds_dwordx4 v[224:225], off
	s_barrier
	s_waitcnt lgkmcnt(0)
	v_mfma_f32_16x16x32_bf16 v[68:71], v[140:143], v[160:163], v[68:71]
	v_mfma_f32_16x16x32_bf16 v[60:63], v[152:155], v[160:163], v[60:63]
	v_mfma_f32_16x16x32_bf16 v[52:55], v[140:143], v[172:175], v[52:55]
	v_mfma_f32_16x16x32_bf16 v[44:47], v[152:155], v[172:175], v[44:47]
	v_mfma_f32_16x16x32_bf16 v[36:39], v[140:143], v[180:183], v[36:39]
	v_mfma_f32_16x16x32_bf16 v[28:31], v[152:155], v[180:183], v[28:31]
	v_mfma_f32_16x16x32_bf16 v[20:23], v[140:143], v[200:203], v[20:23]
	v_mfma_f32_16x16x32_bf16 v[12:15], v[152:155], v[200:203], v[12:15]
	v_mfma_f32_16x16x32_bf16 v[68:71], v[144:147], v[164:167], v[68:71]
	v_mfma_f32_16x16x32_bf16 v[60:63], v[156:159], v[164:167], v[60:63]
	v_mfma_f32_16x16x32_bf16 v[52:55], v[144:147], v[176:179], v[52:55]
	v_mfma_f32_16x16x32_bf16 v[44:47], v[156:159], v[176:179], v[44:47]
	v_mfma_f32_16x16x32_bf16 v[36:39], v[144:147], v[196:199], v[36:39]
	v_mfma_f32_16x16x32_bf16 v[28:31], v[156:159], v[196:199], v[28:31]
	v_mfma_f32_16x16x32_bf16 v[20:23], v[144:147], v[204:207], v[20:23]
	v_mfma_f32_16x16x32_bf16 v[12:15], v[156:159], v[204:207], v[12:15]
	s_barrier
	s_add_i32 s4, s5, s21
	s_mov_b32 m0, s4
	s_nop 0
	s_add_u32 vcc_lo, s40, s54
	s_addc_u32 vcc_hi, s41, s55
	global_load_lds_dwordx4 v2, vcc
	s_add_i32 m0, s4, 0x2000
	s_nop 0
	s_add_u32 vcc_lo, s40, s58
	s_addc_u32 vcc_hi, s41, s59
	global_load_lds_dwordx4 v2, vcc
	s_add_i32 s18, s18, 2
	s_add_u32 s2, s2, 0x100
	s_addc_u32 s3, s3, 0
	s_add_u32 s16, s16, 0x100
	s_addc_u32 s17, s17, 0
	s_cmp_gt_u32 s18, 13
	s_waitcnt vmcnt(6)
	s_barrier
	v_mfma_f32_16x16x32_bf16 v[64:67], v[208:211], v[160:163], v[64:67]
	v_mfma_f32_16x16x32_bf16 v[56:59], v[216:219], v[160:163], v[56:59]
	v_mfma_f32_16x16x32_bf16 v[48:51], v[208:211], v[172:175], v[48:51]
	v_mfma_f32_16x16x32_bf16 v[40:43], v[216:219], v[172:175], v[40:43]
	ds_read_b128 v[140:143], v235 offset:0
	ds_read_b128 v[144:147], v235 offset:1024
	ds_read_b128 v[152:155], v235 offset:2048
	ds_read_b128 v[156:159], v235 offset:3072
	v_mfma_f32_16x16x32_bf16 v[32:35], v[208:211], v[180:183], v[32:35]
	v_mfma_f32_16x16x32_bf16 v[24:27], v[216:219], v[180:183], v[24:27]
	v_mfma_f32_16x16x32_bf16 v[16:19], v[208:211], v[200:203], v[16:19]
	v_mfma_f32_16x16x32_bf16 v[8:11], v[216:219], v[200:203], v[8:11]
	v_mfma_f32_16x16x32_bf16 v[64:67], v[212:215], v[164:167], v[64:67]
	v_mfma_f32_16x16x32_bf16 v[56:59], v[220:223], v[164:167], v[56:59]
	v_mfma_f32_16x16x32_bf16 v[48:51], v[212:215], v[176:179], v[48:51]
	v_mfma_f32_16x16x32_bf16 v[40:43], v[220:223], v[176:179], v[40:43]
	v_mfma_f32_16x16x32_bf16 v[32:35], v[212:215], v[196:199], v[32:35]
	v_mfma_f32_16x16x32_bf16 v[24:27], v[220:223], v[196:199], v[24:27]
	v_mfma_f32_16x16x32_bf16 v[16:19], v[212:215], v[204:207], v[16:19]
	v_mfma_f32_16x16x32_bf16 v[8:11], v[220:223], v[204:207], v[8:11]
	s_cbranch_scc0 .Ldb_FFI_cont
	v_readfirstlane_b32 s101, v186
	s_cmpk_gt_u32 s101, 0xff
	s_cbranch_scc1 .Ldb_FFI_young
	s_barrier
	s_mov_b32 s101, 1
	s_branch .Ldb_FFI_exit

; __device__ __forceinline__ float sigmoidf_(float v) { return __builtin_amdgcn_rcpf(1.0f + __expf(-v)); }
; __device__ __forceinline__ u32x4 pack8(const f32x4 a, const f32x4 b) { u32x4 w; w.x = cvt_pk_bf16(a[0], a[1]); w.y = cvt_pk_bf16(a[2], a[3]); w.z = cvt_pk_bf16(b[0], b[1]); w.w = cvt_pk_bf16(b[2], b[3]); return w; }
; #define MEMFENCE asm volatile("" ::: "memory")
;     template <int KIND> __device__ __forceinline__ void run(f32x4 (&acc)[2][2][4][2], const Unit& u, int tid_in) const {
;     ...
;         if constexpr (KIND == K_FFI) { bf16_t* act = zb; float rs[8]; get_rs(u, wr, fr, rs);
; #pragma unroll
;             for (int ai = 0; ai < 2; ++ai)
; #pragma unroll
;                 for (int m = 0; m < 4; ++m) { int row = rbase + ai * 128 + m * 16; asm volatile("" : "+v"(row)); const float r = rs[ai * 4 + m]; f32x4 o[2];
; #pragma unroll
;                     for (int n = 0; n < 2; ++n) { const f32x4 g = acc[ai][0][m][n] * r, v = acc[ai][1][m][n] * r;
; #pragma unroll
;                         for (int j = 0; j < 4; ++j) o[n][j] = g[j] * sigmoidf_(g[j]) * v[j]; }
;                     *(u32x4*)(act + (size_t)row * ZW + u.pn * 128 + cl) = pack8(o[0], o[1]); MEMFENCE; }
.Ldb_FFI_exit:
	s_waitcnt lgkmcnt(0)
	v_readfirstlane_b32 s2, v148
	s_lshr_b32 s4, s2, 1
	s_and_b32 s4, s4, 0x60
	v_lshrrev_b32_e32 v0, 1, v148
	v_and_or_b32 v0, v0, 24, s4
	v_and_b32_e32 v140, 15, v148
	s_lshl_b32 s4, s38, 10
	s_and_b32 s3, s2, 0xffffff00
	s_add_i32 s4, s4, s3
	v_lshl_add_u32 v141, v140, 2, s4
	v_add_u32_e32 v141, 0x20010, v141
	ds_read_b32 v240, v141
	ds_read_b32 v242, v141 offset:64
	ds_read_b32 v244, v141 offset:128
	ds_read_b32 v246, v141 offset:192
	ds_read_b32 v248, v141 offset:512
	ds_read_b32 v250, v141 offset:576
	ds_read_b32 v252, v141 offset:640
	ds_read_b32 v254, v141 offset:704
	s_ashr_i32 s3, s2, 2
	s_andn2_b32 s3, s3, 63
	v_or_b32_e32 v140, s3, v140
	v_lshl_add_u32 v140, s37, 8, v140
	v_mul_lo_u32 v140, v140, s76
	s_lshl_b32 s3, s33, 8
	v_lshlrev_b32_e32 v0, 1, v0
	v_add3_u32 v140, v140, v0, s3
	s_mov_b64 s[4:5], s[6:7]
	s_mov_b32 s2, 0xbfb8aa3b
	s_mov_b32 s100, 1.0
	s_waitcnt lgkmcnt(0)
	v_pk_mul_f32 v[132:133], v[132:133], v[240:241] op_sel_hi:[1,0]
	v_pk_mul_f32 v[128:129], v[128:129], v[240:241] op_sel_hi:[1,0]
	v_pk_mul_f32 v[216:217], v[132:133], s[2:3] op_sel_hi:[1,0]
	v_pk_mul_f32 v[134:135], v[134:135], v[240:241] op_sel_hi:[1,0]
	v_pk_mul_f32 v[130:131], v[130:131], v[240:241] op_sel_hi:[1,0]
	v_pk_mul_f32 v[218:219], v[134:135], s[2:3] op_sel_hi:[1,0]
	v_pk_mul_f32 v[124:125], v[124:125], v[240:241] op_sel_hi:[1,0]
	v_pk_mul_f32 v[120:121], v[120:121], v[240:241] op_sel_hi:[1,0]
	v_pk_mul_f32 v[220:221], v[124:125], s[2:3] op_sel_hi:[1,0]
	v_pk_mul_f32 v[126:127], v[126:127], v[240:241] op_sel_hi:[1,0]
	v_pk_mul_f32 v[122:123], v[122:123], v[240:241] op_sel_hi:[1,0]
	v_pk_mul_f32 v[222:223], v[126:127], s[2:3] op_sel_hi:[1,0]
	v_exp_f32_e32 v216, v216
	v_exp_f32_e32 v217, v217
	v_exp_f32_e32 v218, v218
	v_exp_f32_e32 v219, v219
	v_exp_f32_e32 v220, v220
	v_exp_f32_e32 v221, v221
	v_exp_f32_e32 v222, v222
	v_exp_f32_e32 v223, v223
	v_pk_add_f32 v[216:217], v[216:217], s[100:101] op_sel_hi:[1,0]
	v_pk_add_f32 v[218:219], v[218:219], s[100:101] op_sel_hi:[1,0]
	v_pk_add_f32 v[220:221], v[220:221], s[100:101] op_sel_hi:[1,0]
	v_pk_add_f32 v[222:223], v[222:223], s[100:101] op_sel_hi:[1,0]
	v_rcp_f32_e32 v216, v216
	v_rcp_f32_e32 v217, v217
	v_rcp_f32_e32 v218, v218
	v_rcp_f32_e32 v219, v219
	v_rcp_f32_e32 v220, v220
	v_rcp_f32_e32 v221, v221
	v_rcp_f32_e32 v222, v222
	v_rcp_f32_e32 v223, v223
	v_pk_mul_f32 v[132:133], v[132:133], v[216:217]
	v_pk_mul_f32 v[134:135], v[134:135], v[218:219]
	v_pk_mul_f32 v[124:125], v[124:125], v[220:221]
	v_pk_mul_f32 v[126:127], v[126:127], v[222:223]
	v_pk_mul_f32 v[132:133], v[132:133], v[128:129]
	v_pk_mul_f32 v[134:135], v[134:135], v[130:131]
	v_pk_mul_f32 v[124:125], v[124:125], v[120:121]
	v_pk_mul_f32 v[126:127], v[126:127], v[122:123]
	v_cvt_pk_bf16_f32 v236, v132, v133
	v_cvt_pk_bf16_f32 v237, v134, v135
	v_cvt_pk_bf16_f32 v238, v124, v125
	v_cvt_pk_bf16_f32 v239, v126, v127
	global_store_dwordx4 v140, v[236:239], s[4:5]
	s_add_u32 s4, s4, 0x16000
	s_addc_u32 s5, s5, 0
	v_pk_mul_f32 v[116:117], v[116:117], v[242:243] op_sel_hi:[1,0]
	v_pk_mul_f32 v[112:113], v[112:113], v[242:243] op_sel_hi:[1,0]
	v_pk_mul_f32 v[216:217], v[116:117], s[2:3] op_sel_hi:[1,0]
	v_pk_mul_f32 v[118:119], v[118:119], v[242:243] op_sel_hi:[1,0]
	v_pk_mul_f32 v[114:115], v[114:115], v[242:243] op_sel_hi:[1,0]
	v_pk_mul_f32 v[218:219], v[118:119], s[2:3] op_sel_hi:[1,0]
	v_pk_mul_f32 v[108:109], v[108:109], v[242:243] op_sel_hi:[1,0]
	v_pk_mul_f32 v[104:105], v[104:105], v[242:243] op_sel_hi:[1,0]
	v_pk_mul_f32 v[220:221], v[108:109], s[2:3] op_sel_hi:[1,0]
	v_pk_mul_f32 v[110:111], v[110:111], v[242:243] op_sel_hi:[1,0]
	v_pk_mul_f32 v[106:107], v[106:107], v[242:243] op_sel_hi:[1,0]
	v_pk_mul_f32 v[222:223], v[110:111], s[2:3] op_sel_hi:[1,0]
	v_exp_f32_e32 v216, v216
	v_exp_f32_e32 v217, v217
	v_exp_f32_e32 v218, v218
	v_exp_f32_e32 v219, v219
	v_exp_f32_e32 v220, v220
	v_exp_f32_e32 v221, v221
	v_exp_f32_e32 v222, v222
	v_exp_f32_e32 v223, v223
	v_pk_add_f32 v[216:217], v[216:217], s[100:101] op_sel_hi:[1,0]
	v_pk_add_f32 v[218:219], v[218:219], s[100:101] op_sel_hi:[1,0]
	v_pk_add_f32 v[220:221], v[220:221], s[100:101] op_sel_hi:[1,0]
	v_pk_add_f32 v[222:223], v[222:223], s[100:101] op_sel_hi:[1,0]
	v_rcp_f32_e32 v216, v216
	v_rcp_f32_e32 v217, v217
	v_rcp_f32_e32 v218, v218
	v_rcp_f32_e32 v219, v219
	v_rcp_f32_e32 v220, v220
	v_rcp_f32_e32 v221, v221
	v_rcp_f32_e32 v222, v222
	v_rcp_f32_e32 v223, v223
	v_pk_mul_f32 v[116:117], v[116:117], v[216:217]
	v_pk_mul_f32 v[118:119], v[118:119], v[218:219]
	v_pk_mul_f32 v[108:109], v[108:109], v[220:221]
	v_pk_mul_f32 v[110:111], v[110:111], v[222:223]
	v_pk_mul_f32 v[116:117], v[116:117], v[112:113]
	v_pk_mul_f32 v[118:119], v[118:119], v[114:115]
	v_pk_mul_f32 v[108:109], v[108:109], v[104:105]
	v_pk_mul_f32 v[110:111], v[110:111], v[106:107]
	v_cvt_pk_bf16_f32 v236, v116, v117
	v_cvt_pk_bf16_f32 v237, v118, v119
	v_cvt_pk_bf16_f32 v238, v108, v109
	v_cvt_pk_bf16_f32 v239, v110, v111
	global_store_dwordx4 v140, v[236:239], s[4:5]
	s_add_u32 s4, s4, 0x16000
	s_addc_u32 s5, s5, 0
	v_pk_mul_f32 v[100:101], v[100:101], v[244:245] op_sel_hi:[1,0]
	v_pk_mul_f32 v[96:97], v[96:97], v[244:245] op_sel_hi:[1,0]
	v_pk_mul_f32 v[216:217], v[100:101], s[2:3] op_sel_hi:[1,0]
	v_pk_mul_f32 v[102:103], v[102:103], v[244:245] op_sel_hi:[1,0]
	v_pk_mul_f32 v[98:99], v[98:99], v[244:245] op_sel_hi:[1,0]
	v_pk_mul_f32 v[218:219], v[102:103], s[2:3] op_sel_hi:[1,0]
	v_pk_mul_f32 v[92:93], v[92:93], v[244:245] op_sel_hi:[1,0]
	v_pk_mul_f32 v[88:89], v[88:89], v[244:245] op_sel_hi:[1,0]
	v_pk_mul_f32 v[220:221], v[92:93], s[2:3] op_sel_hi:[1,0]
; __device__ __forceinline__ float sigmoidf_(float v) { return __builtin_amdgcn_rcpf(1.0f + __expf(-v)); }
; __device__ __forceinline__ u32x4 pack8(const f32x4 a, const f32x4 b) { u32x4 w; w.x = cvt_pk_bf16(a[0], a[1]); w.y = cvt_pk_bf16(a[2], a[3]); w.z = cvt_pk_bf16(b[0], b[1]); w.w = cvt_pk_bf16(b[2], b[3]); return w; }
; #define MEMFENCE asm volatile("" ::: "memory")
;     template <int KIND> __device__ __forceinline__ void run(f32x4 (&acc)[2][2][4][2], const Unit& u, int tid_in) const {
;     ...
;                 for (int m = 0; m < 4; ++m) { int row = rbase + ai * 128 + m * 16; asm volatile("" : "+v"(row)); const float r = rs[ai * 4 + m]; f32x4 o[2];
; #pragma unroll
;                     for (int n = 0; n < 2; ++n) { const f32x4 g = acc[ai][0][m][n] * r, v = acc[ai][1][m][n] * r;
; #pragma unroll
;                         for (int j = 0; j < 4; ++j) o[n][j] = g[j] * sigmoidf_(g[j]) * v[j]; }
;                     *(u32x4*)(act + (size_t)row * ZW + u.pn * 128 + cl) = pack8(o[0], o[1]); MEMFENCE; }
	v_pk_mul_f32 v[94:95], v[94:95], v[244:245] op_sel_hi:[1,0]
	v_pk_mul_f32 v[90:91], v[90:91], v[244:245] op_sel_hi:[1,0]
	v_pk_mul_f32 v[222:223], v[94:95], s[2:3] op_sel_hi:[1,0]
	v_exp_f32_e32 v216, v216
	v_exp_f32_e32 v217, v217
	v_exp_f32_e32 v218, v218
	v_exp_f32_e32 v219, v219
	v_exp_f32_e32 v220, v220
	v_exp_f32_e32 v221, v221
	v_exp_f32_e32 v222, v222
	v_exp_f32_e32 v223, v223
	v_pk_add_f32 v[216:217], v[216:217], s[100:101] op_sel_hi:[1,0]
	v_pk_add_f32 v[218:219], v[218:219], s[100:101] op_sel_hi:[1,0]
	v_pk_add_f32 v[220:221], v[220:221], s[100:101] op_sel_hi:[1,0]
	v_pk_add_f32 v[222:223], v[222:223], s[100:101] op_sel_hi:[1,0]
	v_rcp_f32_e32 v216, v216
	v_rcp_f32_e32 v217, v217
	v_rcp_f32_e32 v218, v218
	v_rcp_f32_e32 v219, v219
	v_rcp_f32_e32 v220, v220
	v_rcp_f32_e32 v221, v221
	v_rcp_f32_e32 v222, v222
	v_rcp_f32_e32 v223, v223
	v_pk_mul_f32 v[100:101], v[100:101], v[216:217]
	v_pk_mul_f32 v[102:103], v[102:103], v[218:219]
	v_pk_mul_f32 v[92:93], v[92:93], v[220:221]
	v_pk_mul_f32 v[94:95], v[94:95], v[222:223]
	v_pk_mul_f32 v[100:101], v[100:101], v[96:97]
	v_pk_mul_f32 v[102:103], v[102:103], v[98:99]
	v_pk_mul_f32 v[92:93], v[92:93], v[88:89]
	v_pk_mul_f32 v[94:95], v[94:95], v[90:91]
	v_cvt_pk_bf16_f32 v236, v100, v101
	v_cvt_pk_bf16_f32 v237, v102, v103
	v_cvt_pk_bf16_f32 v238, v92, v93
	v_cvt_pk_bf16_f32 v239, v94, v95
	global_store_dwordx4 v140, v[236:239], s[4:5]
	s_add_u32 s4, s4, 0x16000
	s_addc_u32 s5, s5, 0
	v_pk_mul_f32 v[84:85], v[84:85], v[246:247] op_sel_hi:[1,0]
	v_pk_mul_f32 v[80:81], v[80:81], v[246:247] op_sel_hi:[1,0]
	v_pk_mul_f32 v[216:217], v[84:85], s[2:3] op_sel_hi:[1,0]
	v_pk_mul_f32 v[86:87], v[86:87], v[246:247] op_sel_hi:[1,0]
	v_pk_mul_f32 v[82:83], v[82:83], v[246:247] op_sel_hi:[1,0]
	v_pk_mul_f32 v[218:219], v[86:87], s[2:3] op_sel_hi:[1,0]
	v_pk_mul_f32 v[76:77], v[76:77], v[246:247] op_sel_hi:[1,0]
	v_pk_mul_f32 v[72:73], v[72:73], v[246:247] op_sel_hi:[1,0]
	v_pk_mul_f32 v[220:221], v[76:77], s[2:3] op_sel_hi:[1,0]
	v_pk_mul_f32 v[78:79], v[78:79], v[246:247] op_sel_hi:[1,0]
	v_pk_mul_f32 v[74:75], v[74:75], v[246:247] op_sel_hi:[1,0]
	v_pk_mul_f32 v[222:223], v[78:79], s[2:3] op_sel_hi:[1,0]
	v_exp_f32_e32 v216, v216
	v_exp_f32_e32 v217, v217
	v_exp_f32_e32 v218, v218
	v_exp_f32_e32 v219, v219
	v_exp_f32_e32 v220, v220
	v_exp_f32_e32 v221, v221
	v_exp_f32_e32 v222, v222
	v_exp_f32_e32 v223, v223
	v_pk_add_f32 v[216:217], v[216:217], s[100:101] op_sel_hi:[1,0]
	v_pk_add_f32 v[218:219], v[218:219], s[100:101] op_sel_hi:[1,0]
	v_pk_add_f32 v[220:221], v[220:221], s[100:101] op_sel_hi:[1,0]
	v_pk_add_f32 v[222:223], v[222:223], s[100:101] op_sel_hi:[1,0]
	v_rcp_f32_e32 v216, v216
	v_rcp_f32_e32 v217, v217
	v_rcp_f32_e32 v218, v218
	v_rcp_f32_e32 v219, v219
	v_rcp_f32_e32 v220, v220
	v_rcp_f32_e32 v221, v221
	v_rcp_f32_e32 v222, v222
	v_rcp_f32_e32 v223, v223
	v_pk_mul_f32 v[84:85], v[84:85], v[216:217]
	v_pk_mul_f32 v[86:87], v[86:87], v[218:219]
	v_pk_mul_f32 v[76:77], v[76:77], v[220:221]
	v_pk_mul_f32 v[78:79], v[78:79], v[222:223]
	v_pk_mul_f32 v[84:85], v[84:85], v[80:81]
	v_pk_mul_f32 v[86:87], v[86:87], v[82:83]
	v_pk_mul_f32 v[76:77], v[76:77], v[72:73]
	v_pk_mul_f32 v[78:79], v[78:79], v[74:75]
	v_cvt_pk_bf16_f32 v236, v84, v85
	v_cvt_pk_bf16_f32 v237, v86, v87
	v_cvt_pk_bf16_f32 v238, v76, v77
	v_cvt_pk_bf16_f32 v239, v78, v79
	global_store_dwordx4 v140, v[236:239], s[4:5]
	s_add_u32 s4, s4, 0x6e000
	s_addc_u32 s5, s5, 0
	v_pk_mul_f32 v[68:69], v[68:69], v[248:249] op_sel_hi:[1,0]
	v_pk_mul_f32 v[64:65], v[64:65], v[248:249] op_sel_hi:[1,0]
	v_pk_mul_f32 v[216:217], v[68:69], s[2:3] op_sel_hi:[1,0]
	v_pk_mul_f32 v[70:71], v[70:71], v[248:249] op_sel_hi:[1,0]
	v_pk_mul_f32 v[66:67], v[66:67], v[248:249] op_sel_hi:[1,0]
	v_pk_mul_f32 v[218:219], v[70:71], s[2:3] op_sel_hi:[1,0]
	v_pk_mul_f32 v[60:61], v[60:61], v[248:249] op_sel_hi:[1,0]
	v_pk_mul_f32 v[56:57], v[56:57], v[248:249] op_sel_hi:[1,0]
	v_pk_mul_f32 v[220:221], v[60:61], s[2:3] op_sel_hi:[1,0]
	v_pk_mul_f32 v[62:63], v[62:63], v[248:249] op_sel_hi:[1,0]
	v_pk_mul_f32 v[58:59], v[58:59], v[248:249] op_sel_hi:[1,0]
	v_pk_mul_f32 v[222:223], v[62:63], s[2:3] op_sel_hi:[1,0]
	v_exp_f32_e32 v216, v216
	v_exp_f32_e32 v217, v217
	v_exp_f32_e32 v218, v218
	v_exp_f32_e32 v219, v219
	v_exp_f32_e32 v220, v220
	v_exp_f32_e32 v221, v221
	v_exp_f32_e32 v222, v222
	v_exp_f32_e32 v223, v223
	v_pk_add_f32 v[216:217], v[216:217], s[100:101] op_sel_hi:[1,0]
	v_pk_add_f32 v[218:219], v[218:219], s[100:101] op_sel_hi:[1,0]
	v_pk_add_f32 v[220:221], v[220:221], s[100:101] op_sel_hi:[1,0]
	v_pk_add_f32 v[222:223], v[222:223], s[100:101] op_sel_hi:[1,0]
	v_rcp_f32_e32 v216, v216
	v_rcp_f32_e32 v217, v217
	v_rcp_f32_e32 v218, v218
	v_rcp_f32_e32 v219, v219
	v_rcp_f32_e32 v220, v220
	v_rcp_f32_e32 v221, v221
	v_rcp_f32_e32 v222, v222
	v_rcp_f32_e32 v223, v223
	v_pk_mul_f32 v[68:69], v[68:69], v[216:217]
	v_pk_mul_f32 v[70:71], v[70:71], v[218:219]
	v_pk_mul_f32 v[60:61], v[60:61], v[220:221]
	v_pk_mul_f32 v[62:63], v[62:63], v[222:223]
	v_pk_mul_f32 v[68:69], v[68:69], v[64:65]
	v_pk_mul_f32 v[70:71], v[70:71], v[66:67]
	v_pk_mul_f32 v[60:61], v[60:61], v[56:57]
	v_pk_mul_f32 v[62:63], v[62:63], v[58:59]
	v_cvt_pk_bf16_f32 v236, v68, v69
	v_cvt_pk_bf16_f32 v237, v70, v71
	v_cvt_pk_bf16_f32 v238, v60, v61
	v_cvt_pk_bf16_f32 v239, v62, v63
	global_store_dwordx4 v140, v[236:239], s[4:5]
	s_add_u32 s4, s4, 0x16000
	s_addc_u32 s5, s5, 0
	v_pk_mul_f32 v[52:53], v[52:53], v[250:251] op_sel_hi:[1,0]
	v_pk_mul_f32 v[48:49], v[48:49], v[250:251] op_sel_hi:[1,0]
	v_pk_mul_f32 v[216:217], v[52:53], s[2:3] op_sel_hi:[1,0]
; __device__ __forceinline__ float sigmoidf_(float v) { return __builtin_amdgcn_rcpf(1.0f + __expf(-v)); }
; __device__ __forceinline__ u32x4 pack8(const f32x4 a, const f32x4 b) { u32x4 w; w.x = cvt_pk_bf16(a[0], a[1]); w.y = cvt_pk_bf16(a[2], a[3]); w.z = cvt_pk_bf16(b[0], b[1]); w.w = cvt_pk_bf16(b[2], b[3]); return w; }
; #define MEMFENCE asm volatile("" ::: "memory")
;     template <int KIND> __device__ __forceinline__ void run(f32x4 (&acc)[2][2][4][2], const Unit& u, int tid_in) const {
;     ...
;                 for (int m = 0; m < 4; ++m) { int row = rbase + ai * 128 + m * 16; asm volatile("" : "+v"(row)); const float r = rs[ai * 4 + m]; f32x4 o[2];
; #pragma unroll
;                     for (int n = 0; n < 2; ++n) { const f32x4 g = acc[ai][0][m][n] * r, v = acc[ai][1][m][n] * r;
; #pragma unroll
;                         for (int j = 0; j < 4; ++j) o[n][j] = g[j] * sigmoidf_(g[j]) * v[j]; }
;                     *(u32x4*)(act + (size_t)row * ZW + u.pn * 128 + cl) = pack8(o[0], o[1]); MEMFENCE; }
	v_pk_mul_f32 v[54:55], v[54:55], v[250:251] op_sel_hi:[1,0]
	v_pk_mul_f32 v[50:51], v[50:51], v[250:251] op_sel_hi:[1,0]
	v_pk_mul_f32 v[218:219], v[54:55], s[2:3] op_sel_hi:[1,0]
	v_pk_mul_f32 v[44:45], v[44:45], v[250:251] op_sel_hi:[1,0]
	v_pk_mul_f32 v[40:41], v[40:41], v[250:251] op_sel_hi:[1,0]
	v_pk_mul_f32 v[220:221], v[44:45], s[2:3] op_sel_hi:[1,0]
	v_pk_mul_f32 v[46:47], v[46:47], v[250:251] op_sel_hi:[1,0]
	v_pk_mul_f32 v[42:43], v[42:43], v[250:251] op_sel_hi:[1,0]
	v_pk_mul_f32 v[222:223], v[46:47], s[2:3] op_sel_hi:[1,0]
	v_exp_f32_e32 v216, v216
	v_exp_f32_e32 v217, v217
	v_exp_f32_e32 v218, v218
	v_exp_f32_e32 v219, v219
	v_exp_f32_e32 v220, v220
	v_exp_f32_e32 v221, v221
	v_exp_f32_e32 v222, v222
	v_exp_f32_e32 v223, v223
	v_pk_add_f32 v[216:217], v[216:217], s[100:101] op_sel_hi:[1,0]
	v_pk_add_f32 v[218:219], v[218:219], s[100:101] op_sel_hi:[1,0]
	v_pk_add_f32 v[220:221], v[220:221], s[100:101] op_sel_hi:[1,0]
	v_pk_add_f32 v[222:223], v[222:223], s[100:101] op_sel_hi:[1,0]
	v_rcp_f32_e32 v216, v216
	v_rcp_f32_e32 v217, v217
	v_rcp_f32_e32 v218, v218
	v_rcp_f32_e32 v219, v219
	v_rcp_f32_e32 v220, v220
	v_rcp_f32_e32 v221, v221
	v_rcp_f32_e32 v222, v222
	v_rcp_f32_e32 v223, v223
	v_pk_mul_f32 v[52:53], v[52:53], v[216:217]
	v_pk_mul_f32 v[54:55], v[54:55], v[218:219]
	v_pk_mul_f32 v[44:45], v[44:45], v[220:221]
	v_pk_mul_f32 v[46:47], v[46:47], v[222:223]
	v_pk_mul_f32 v[52:53], v[52:53], v[48:49]
	v_pk_mul_f32 v[54:55], v[54:55], v[50:51]
	v_pk_mul_f32 v[44:45], v[44:45], v[40:41]
	v_pk_mul_f32 v[46:47], v[46:47], v[42:43]
	v_cvt_pk_bf16_f32 v236, v52, v53
	v_cvt_pk_bf16_f32 v237, v54, v55
	v_cvt_pk_bf16_f32 v238, v44, v45
	v_cvt_pk_bf16_f32 v239, v46, v47
	global_store_dwordx4 v140, v[236:239], s[4:5]
	s_add_u32 s4, s4, 0x16000
	s_addc_u32 s5, s5, 0
	v_pk_mul_f32 v[36:37], v[36:37], v[252:253] op_sel_hi:[1,0]
	v_pk_mul_f32 v[32:33], v[32:33], v[252:253] op_sel_hi:[1,0]
	v_pk_mul_f32 v[216:217], v[36:37], s[2:3] op_sel_hi:[1,0]
	v_pk_mul_f32 v[38:39], v[38:39], v[252:253] op_sel_hi:[1,0]
	v_pk_mul_f32 v[34:35], v[34:35], v[252:253] op_sel_hi:[1,0]
	v_pk_mul_f32 v[218:219], v[38:39], s[2:3] op_sel_hi:[1,0]
	v_pk_mul_f32 v[28:29], v[28:29], v[252:253] op_sel_hi:[1,0]
	v_pk_mul_f32 v[24:25], v[24:25], v[252:253] op_sel_hi:[1,0]
	v_pk_mul_f32 v[220:221], v[28:29], s[2:3] op_sel_hi:[1,0]
	v_pk_mul_f32 v[30:31], v[30:31], v[252:253] op_sel_hi:[1,0]
	v_pk_mul_f32 v[26:27], v[26:27], v[252:253] op_sel_hi:[1,0]
	v_pk_mul_f32 v[222:223], v[30:31], s[2:3] op_sel_hi:[1,0]
	v_exp_f32_e32 v216, v216
	v_exp_f32_e32 v217, v217
	v_exp_f32_e32 v218, v218
	v_exp_f32_e32 v219, v219
	v_exp_f32_e32 v220, v220
	v_exp_f32_e32 v221, v221
	v_exp_f32_e32 v222, v222
	v_exp_f32_e32 v223, v223
	v_pk_add_f32 v[216:217], v[216:217], s[100:101] op_sel_hi:[1,0]
	v_pk_add_f32 v[218:219], v[218:219], s[100:101] op_sel_hi:[1,0]
	v_pk_add_f32 v[220:221], v[220:221], s[100:101] op_sel_hi:[1,0]
	v_pk_add_f32 v[222:223], v[222:223], s[100:101] op_sel_hi:[1,0]
	v_rcp_f32_e32 v216, v216
	v_rcp_f32_e32 v217, v217
	v_rcp_f32_e32 v218, v218
	v_rcp_f32_e32 v219, v219
	v_rcp_f32_e32 v220, v220
	v_rcp_f32_e32 v221, v221
	v_rcp_f32_e32 v222, v222
	v_rcp_f32_e32 v223, v223
	v_pk_mul_f32 v[36:37], v[36:37], v[216:217]
	v_pk_mul_f32 v[38:39], v[38:39], v[218:219]
	v_pk_mul_f32 v[28:29], v[28:29], v[220:221]
	v_pk_mul_f32 v[30:31], v[30:31], v[222:223]
	v_pk_mul_f32 v[36:37], v[36:37], v[32:33]
	v_pk_mul_f32 v[38:39], v[38:39], v[34:35]
	v_pk_mul_f32 v[28:29], v[28:29], v[24:25]
	v_pk_mul_f32 v[30:31], v[30:31], v[26:27]
	v_cvt_pk_bf16_f32 v236, v36, v37
	v_cvt_pk_bf16_f32 v237, v38, v39
	v_cvt_pk_bf16_f32 v238, v28, v29
	v_cvt_pk_bf16_f32 v239, v30, v31
	global_store_dwordx4 v140, v[236:239], s[4:5]
	s_add_u32 s4, s4, 0x16000
	s_addc_u32 s5, s5, 0
	v_pk_mul_f32 v[20:21], v[20:21], v[254:255] op_sel_hi:[1,0]
	v_pk_mul_f32 v[16:17], v[16:17], v[254:255] op_sel_hi:[1,0]
	v_pk_mul_f32 v[216:217], v[20:21], s[2:3] op_sel_hi:[1,0]
	v_pk_mul_f32 v[22:23], v[22:23], v[254:255] op_sel_hi:[1,0]
	v_pk_mul_f32 v[18:19], v[18:19], v[254:255] op_sel_hi:[1,0]
	v_pk_mul_f32 v[218:219], v[22:23], s[2:3] op_sel_hi:[1,0]
	v_pk_mul_f32 v[12:13], v[12:13], v[254:255] op_sel_hi:[1,0]
	v_pk_mul_f32 v[8:9], v[8:9], v[254:255] op_sel_hi:[1,0]
	v_pk_mul_f32 v[220:221], v[12:13], s[2:3] op_sel_hi:[1,0]
	v_pk_mul_f32 v[14:15], v[14:15], v[254:255] op_sel_hi:[1,0]
	v_pk_mul_f32 v[10:11], v[10:11], v[254:255] op_sel_hi:[1,0]
	v_pk_mul_f32 v[222:223], v[14:15], s[2:3] op_sel_hi:[1,0]
	v_exp_f32_e32 v216, v216
	v_exp_f32_e32 v217, v217
	v_exp_f32_e32 v218, v218
	v_exp_f32_e32 v219, v219
	v_exp_f32_e32 v220, v220
	v_exp_f32_e32 v221, v221
	v_exp_f32_e32 v222, v222
	v_exp_f32_e32 v223, v223
	v_pk_add_f32 v[216:217], v[216:217], s[100:101] op_sel_hi:[1,0]
	v_pk_add_f32 v[218:219], v[218:219], s[100:101] op_sel_hi:[1,0]
	v_pk_add_f32 v[220:221], v[220:221], s[100:101] op_sel_hi:[1,0]
	v_pk_add_f32 v[222:223], v[222:223], s[100:101] op_sel_hi:[1,0]
	v_rcp_f32_e32 v216, v216
	v_rcp_f32_e32 v217, v217
	v_rcp_f32_e32 v218, v218
	v_rcp_f32_e32 v219, v219
	v_rcp_f32_e32 v220, v220
	v_rcp_f32_e32 v221, v221
	v_rcp_f32_e32 v222, v222
	v_rcp_f32_e32 v223, v223
	v_pk_mul_f32 v[20:21], v[20:21], v[216:217]
	v_pk_mul_f32 v[22:23], v[22:23], v[218:219]
	v_pk_mul_f32 v[12:13], v[12:13], v[220:221]
	v_pk_mul_f32 v[14:15], v[14:15], v[222:223]
	v_pk_mul_f32 v[20:21], v[20:21], v[16:17]
	v_pk_mul_f32 v[22:23], v[22:23], v[18:19]
	v_pk_mul_f32 v[12:13], v[12:13], v[8:9]
	v_pk_mul_f32 v[14:15], v[14:15], v[10:11]
	v_cvt_pk_bf16_f32 v236, v20, v21
	v_cvt_pk_bf16_f32 v237, v22, v23
	v_cvt_pk_bf16_f32 v238, v12, v13
	v_cvt_pk_bf16_f32 v239, v14, v15
	global_store_dwordx4 v140, v[236:239], s[4:5]
	s_mov_b32 s38, s11
	s_mov_b32 s37, s10
	s_mov_b64 s[18:19], s[14:15]
	s_mov_b64 s[16:17], s[12:13]
	s_mov_b32 s33, s36
	s_and_b64 vcc, exec, s[8:9]
	s_cbranch_vccz .LBB0_1115
	s_cmp_eq_u32 s101, 2
	s_cbranch_scc0 .Ldbj_FFI_pe
	s_barrier

; #define G_STAGE(bufoff, gbase, o0, h64) do { \
;         __builtin_amdgcn_global_load_lds((const unsigned*)((const char*)(gbase) + (o0)), (LAS unsigned*)(lds + (bufoff) + ldsw), 16, 0, 0); \
;         __builtin_amdgcn_global_load_lds((const unsigned*)((const char*)(gbase) + (h64) + (o0)), (LAS unsigned*)(lds + (bufoff) + ldsw + 8192), 16, 0, 0); } while (0)
; #define G_LDA(dst, b, h) do { _Pragma("unroll") for (int m = 0; m < 4; ++m) _Pragma("unroll") for (int k = 0; k < 2; ++k) dst[m][k] = *(const LAS bf16x8*)(lds + G_SA(b, h) + aoff + m * 2048 + k * 1024); } while (0)
; #define G_LDB(dst, b, h) do { _Pragma("unroll") for (int n = 0; n < 2; ++n) _Pragma("unroll") for (int k = 0; k < 2; ++k) dst[n][k] = *(const LAS bf16x8*)(lds + G_SB(b, h) + boff + n * 2048 + k * 1024); } while (0)
; #define G_WAIT_L(n) asm volatile("s_waitcnt lgkmcnt(" #n ")" ::: "memory")
; #define G_BAR __builtin_amdgcn_s_barrier()
; #define G_SCHED __builtin_amdgcn_sched_barrier(0)
;     ...
;         for (int t = 0; t < nt; t += 2) {
;             const bool last = (t == nt - 2);
;             const char* a1 = cA + (size_t)(t + 1) * ckA;
;             const char* a2 = last ? nA : cA + (size_t)(t + 2) * ckA; const char* b2 = last ? nB : cB + (size_t)(t + 2) * kB;
;             const char* a3 = a2 + ckA; const char* b3 = b2 + kB;
;             G_LDB(B0, 0, 0); G_SCHED; G_LDA(At, 0, 0); G_STAGE(G_SA(1, 1), a1 + chA, cA0, qA);
;             G_WAIT_L(8); G_BAR; G_WAIT_L(0); G_MMA(0, 0, At, B0); G_BAR; G_SCHED;
;             G_LDB(B1, 0, 1); G_STAGE(G_SB(0, 0), b2, cB0, qB);
;             G_BAR; G_WAIT_L(0); G_MMA(0, 1, At, B1); G_BAR;
;             G_LDA(At, 0, 1); G_STAGE(G_SA(0, 0), a2, cA0, qA);
;             G_BAR; G_WAIT_L(0); G_MMA(1, 0, At, B0); G_BAR; G_SCHED;
;     ...
;         if (!(cs.kind == K_MG_B && cur.aux < 2))
; #pragma unroll
;         for (int a = 0; a < 2; ++a)
; #pragma unroll
;             for (int b = 0; b < 2; ++b)
; #pragma unroll
;                 for (int m = 0; m < 4; ++m)
; #pragma unroll
;                     for (int n = 0; n < 2; ++n) acc[a][b][m][n] = (f32x4){0.f, 0.f, 0.f, 0.f};
.LBB0_1184:
	s_add_u32 s2, s2, 0xb0080
	s_addc_u32 s3, s3, 0
	s_add_u32 s6, s6, 0x100
	s_waitcnt lgkmcnt(0)
	v_mov_b64_e32 v[8:9], 0
	s_addc_u32 s7, s7, 0
	s_mov_b32 s21, -2
	v_mov_b64_e32 v[10:11], 0
	v_mov_b64_e32 v[12:13], 0
	v_mov_b64_e32 v[14:15], 0
	v_mov_b64_e32 v[24:25], 0
	v_mov_b64_e32 v[26:27], 0
	v_mov_b64_e32 v[28:29], 0
	v_mov_b64_e32 v[30:31], 0
	v_mov_b64_e32 v[40:41], 0
	v_mov_b64_e32 v[42:43], 0
	v_mov_b64_e32 v[44:45], 0
	v_mov_b64_e32 v[46:47], 0
	v_mov_b64_e32 v[56:57], 0
	v_mov_b64_e32 v[58:59], 0
	v_mov_b64_e32 v[60:61], 0
	v_mov_b64_e32 v[62:63], 0
	v_mov_b64_e32 v[16:17], 0
	v_mov_b64_e32 v[18:19], 0
	v_mov_b64_e32 v[20:21], 0
	v_mov_b64_e32 v[22:23], 0
	v_mov_b64_e32 v[32:33], 0
	v_mov_b64_e32 v[34:35], 0
	v_mov_b64_e32 v[36:37], 0
	v_mov_b64_e32 v[38:39], 0
	v_mov_b64_e32 v[48:49], 0
	v_mov_b64_e32 v[50:51], 0
	v_mov_b64_e32 v[52:53], 0
	v_mov_b64_e32 v[54:55], 0
	v_mov_b64_e32 v[64:65], 0
	v_mov_b64_e32 v[66:67], 0
	v_mov_b64_e32 v[68:69], 0
	v_mov_b64_e32 v[70:71], 0
	v_mov_b64_e32 v[72:73], 0
	v_mov_b64_e32 v[74:75], 0
	v_mov_b64_e32 v[76:77], 0
	v_mov_b64_e32 v[78:79], 0
	v_mov_b64_e32 v[88:89], 0
	v_mov_b64_e32 v[90:91], 0
	v_mov_b64_e32 v[92:93], 0
	v_mov_b64_e32 v[94:95], 0
	v_mov_b64_e32 v[104:105], 0
	v_mov_b64_e32 v[106:107], 0
	v_mov_b64_e32 v[108:109], 0
	v_mov_b64_e32 v[110:111], 0
	v_mov_b64_e32 v[120:121], 0
	v_mov_b64_e32 v[122:123], 0
	v_mov_b64_e32 v[124:125], 0
	v_mov_b64_e32 v[126:127], 0
	v_mov_b64_e32 v[80:81], 0
	v_mov_b64_e32 v[82:83], 0
	v_mov_b64_e32 v[84:85], 0
	v_mov_b64_e32 v[86:87], 0
	v_mov_b64_e32 v[96:97], 0
	v_mov_b64_e32 v[98:99], 0
	v_mov_b64_e32 v[100:101], 0
	v_mov_b64_e32 v[102:103], 0
	v_mov_b64_e32 v[112:113], 0
	v_mov_b64_e32 v[114:115], 0
	v_mov_b64_e32 v[116:117], 0
	v_mov_b64_e32 v[118:119], 0
	v_mov_b64_e32 v[128:129], 0
	v_mov_b64_e32 v[130:131], 0
	v_mov_b64_e32 v[132:133], 0
	v_mov_b64_e32 v[134:135], 0
	s_mov_b64 s[52:53], 0xb0080
	s_mov_b64 s[54:55], 0x108080
	s_cmp_eq_u32 s101, 2
	s_cselect_b32 s101, 0, s101
	v_add_u32_e32 v255, 0x10000, v185
	ds_read_b128 v[136:139], v255 offset:0
	ds_read_b128 v[140:143], v255 offset:1024
	ds_read_b128 v[144:147], v255 offset:2048
	ds_read_b128 v[148:151], v255 offset:3072
.LBB0_1185:
	s_add_u32 s4, s2, 0xfff50080
	s_addc_u32 s5, s3, -1
	s_add_i32 s33, 0, 0x10000
	s_cmp_eq_u32 s21, 40
	s_cselect_b32 s5, s17, s5
	s_cselect_b32 s4, s16, s4
	s_cselect_b32 s23, s19, s7
	s_cselect_b32 s22, s18, s6
	s_add_i32 m0, s26, 0xc000
	ds_read_b128 v[152:155], v195
	ds_read_b128 v[156:159], v195 offset:1024
	ds_read_b128 v[160:163], v195 offset:2048
	ds_read_b128 v[164:167], v195 offset:3072
	ds_read_b128 v[176:179], v195 offset:4096
	ds_read_b128 v[180:183], v195 offset:5120
	ds_read_b128 v[196:199], v195 offset:6144
	ds_read_b128 v[200:203], v195 offset:7168
	global_load_lds_dwordx4 v174, s[2:3]
	s_add_i32 m0, s26, 0xe000
	s_nop 0
	s_add_u32 vcc_lo, s2, s86
	s_addc_u32 vcc_hi, s3, s87
	global_load_lds_dwordx4 v174, vcc
	s_waitcnt lgkmcnt(8)
	s_cmp_eq_u32 s101, 1
	s_cbranch_scc1 .Ldb_FFO_sk
	s_barrier
.Ldb_FFO_sk:
	s_mov_b32 s101, 0
	s_waitcnt lgkmcnt(0)
	v_mfma_f32_16x16x32_bf16 v[132:135], v[136:139], v[152:155], v[132:135]
	v_mfma_f32_16x16x32_bf16 v[128:131], v[144:147], v[152:155], v[128:131]
	v_mfma_f32_16x16x32_bf16 v[116:119], v[136:139], v[160:163], v[116:119]
	v_mfma_f32_16x16x32_bf16 v[112:115], v[144:147], v[160:163], v[112:115]
	v_mfma_f32_16x16x32_bf16 v[100:103], v[136:139], v[176:179], v[100:103]
	v_mfma_f32_16x16x32_bf16 v[96:99], v[144:147], v[176:179], v[96:99]
	v_mfma_f32_16x16x32_bf16 v[84:87], v[136:139], v[196:199], v[84:87]
	v_mfma_f32_16x16x32_bf16 v[80:83], v[144:147], v[196:199], v[80:83]
	v_mfma_f32_16x16x32_bf16 v[132:135], v[140:143], v[156:159], v[132:135]
	v_mfma_f32_16x16x32_bf16 v[128:131], v[148:151], v[156:159], v[128:131]
	v_mfma_f32_16x16x32_bf16 v[116:119], v[140:143], v[164:167], v[116:119]
	v_mfma_f32_16x16x32_bf16 v[112:115], v[148:151], v[164:167], v[112:115]
	v_mfma_f32_16x16x32_bf16 v[100:103], v[140:143], v[180:183], v[100:103]
	v_mfma_f32_16x16x32_bf16 v[96:99], v[148:151], v[180:183], v[96:99]
	v_mfma_f32_16x16x32_bf16 v[84:87], v[140:143], v[200:203], v[84:87]
	v_mfma_f32_16x16x32_bf16 v[80:83], v[148:151], v[200:203], v[80:83]
	s_barrier
	s_add_i32 s44, 0, 0x14000
	s_add_i32 s100, s33, s25
	s_mov_b32 m0, s100
	ds_read_b128 v[204:207], v255 offset:16384
	ds_read_b128 v[208:211], v255 offset:17408
	ds_read_b128 v[212:215], v255 offset:18432
	ds_read_b128 v[216:219], v255 offset:19456
	global_load_lds_dwordx4 v172, s[22:23]
	s_add_i32 m0, s100, 0x2000
	s_nop 0
	s_add_u32 vcc_lo, s22, s86
	s_addc_u32 vcc_hi, s23, s87
	global_load_lds_dwordx4 v172, vcc
	s_barrier
	s_waitcnt lgkmcnt(0)
	v_mfma_f32_16x16x32_bf16 v[124:127], v[204:207], v[152:155], v[124:127]
	v_mfma_f32_16x16x32_bf16 v[120:123], v[212:215], v[152:155], v[120:123]
	v_mfma_f32_16x16x32_bf16 v[108:111], v[204:207], v[160:163], v[108:111]
	v_mfma_f32_16x16x32_bf16 v[104:107], v[212:215], v[160:163], v[104:107]
	v_mfma_f32_16x16x32_bf16 v[92:95], v[204:207], v[176:179], v[92:95]
	v_mfma_f32_16x16x32_bf16 v[88:91], v[212:215], v[176:179], v[88:91]
	v_mfma_f32_16x16x32_bf16 v[76:79], v[204:207], v[196:199], v[76:79]
	v_mfma_f32_16x16x32_bf16 v[72:75], v[212:215], v[196:199], v[72:75]
	v_mfma_f32_16x16x32_bf16 v[124:127], v[208:211], v[156:159], v[124:127]
	v_mfma_f32_16x16x32_bf16 v[120:123], v[216:219], v[156:159], v[120:123]
	v_mfma_f32_16x16x32_bf16 v[108:111], v[208:211], v[164:167], v[108:111]
	v_mfma_f32_16x16x32_bf16 v[104:107], v[216:219], v[164:167], v[104:107]
	v_mfma_f32_16x16x32_bf16 v[92:95], v[208:211], v[180:183], v[92:95]
	v_mfma_f32_16x16x32_bf16 v[88:91], v[216:219], v[180:183], v[88:91]
	v_mfma_f32_16x16x32_bf16 v[76:79], v[208:211], v[200:203], v[76:79]
	v_mfma_f32_16x16x32_bf16 v[72:75], v[216:219], v[200:203], v[72:75]
	s_barrier
; #define G_STAGE(bufoff, gbase, o0, h64) do { \
;         __builtin_amdgcn_global_load_lds((const unsigned*)((const char*)(gbase) + (o0)), (LAS unsigned*)(lds + (bufoff) + ldsw), 16, 0, 0); \
;         __builtin_amdgcn_global_load_lds((const unsigned*)((const char*)(gbase) + (h64) + (o0)), (LAS unsigned*)(lds + (bufoff) + ldsw + 8192), 16, 0, 0); } while (0)
; #define G_LDA(dst, b, h) do { _Pragma("unroll") for (int m = 0; m < 4; ++m) _Pragma("unroll") for (int k = 0; k < 2; ++k) dst[m][k] = *(const LAS bf16x8*)(lds + G_SA(b, h) + aoff + m * 2048 + k * 1024); } while (0)
; #define G_LDB(dst, b, h) do { _Pragma("unroll") for (int n = 0; n < 2; ++n) _Pragma("unroll") for (int k = 0; k < 2; ++k) dst[n][k] = *(const LAS bf16x8*)(lds + G_SB(b, h) + boff + n * 2048 + k * 1024); } while (0)
; #define G_WAIT_V(n) asm volatile("s_waitcnt vmcnt(" #n ")" ::: "memory")
; #define G_WAIT_L(n) asm volatile("s_waitcnt lgkmcnt(" #n ")" ::: "memory")
; #define G_BAR __builtin_amdgcn_s_barrier()
; #define G_SCHED __builtin_amdgcn_sched_barrier(0)
;     ...
;             G_BAR; G_WAIT_L(0); G_MMA(1, 0, At, B0); G_BAR; G_SCHED;
;             G_STAGE(G_SB(0, 1), b2 + chB, cB0, qB);
;             G_WAIT_V(6); G_BAR; G_MMA(1, 1, At, B1); G_BAR;
;             G_LDB(B0, 1, 0); G_SCHED; G_LDA(At, 1, 0); G_STAGE(G_SA(0, 1), a2 + chA, cA0, qA);
;             G_WAIT_L(8); G_BAR; G_WAIT_L(0); G_MMA(0, 0, At, B0); G_BAR; G_SCHED;
;             G_LDB(B1, 1, 1); G_STAGE(G_SB(1, 0), b3, cB0, qB);
	s_mov_b32 m0, s26
	v_lshl_add_u64 v[222:223], s[4:5], 0, v[2:3]
	ds_read_b128 v[152:155], v195 offset:16384
	ds_read_b128 v[156:159], v195 offset:17408
	ds_read_b128 v[160:163], v195 offset:18432
	ds_read_b128 v[164:167], v195 offset:19456
	ds_read_b128 v[176:179], v195 offset:20480
	ds_read_b128 v[180:183], v195 offset:21504
	ds_read_b128 v[196:199], v195 offset:22528
	ds_read_b128 v[200:203], v195 offset:23552
	global_load_lds_dwordx4 v2, s[4:5]
	s_mov_b32 m0, s27
	s_nop 0
	s_add_u32 vcc_lo, s4, s86
	s_addc_u32 vcc_hi, s5, s87
	global_load_lds_dwordx4 v2, vcc
	s_barrier
	s_waitcnt lgkmcnt(0)
	v_mfma_f32_16x16x32_bf16 v[68:71], v[136:139], v[152:155], v[68:71]
	v_mfma_f32_16x16x32_bf16 v[64:67], v[144:147], v[152:155], v[64:67]
	v_mfma_f32_16x16x32_bf16 v[52:55], v[136:139], v[160:163], v[52:55]
	v_mfma_f32_16x16x32_bf16 v[48:51], v[144:147], v[160:163], v[48:51]
	v_mfma_f32_16x16x32_bf16 v[36:39], v[136:139], v[176:179], v[36:39]
	v_mfma_f32_16x16x32_bf16 v[32:35], v[144:147], v[176:179], v[32:35]
	v_mfma_f32_16x16x32_bf16 v[20:23], v[136:139], v[196:199], v[20:23]
	v_mfma_f32_16x16x32_bf16 v[16:19], v[144:147], v[196:199], v[16:19]
	v_mfma_f32_16x16x32_bf16 v[68:71], v[140:143], v[156:159], v[68:71]
	v_mfma_f32_16x16x32_bf16 v[64:67], v[148:151], v[156:159], v[64:67]
	v_mfma_f32_16x16x32_bf16 v[52:55], v[140:143], v[164:167], v[52:55]
	v_mfma_f32_16x16x32_bf16 v[48:51], v[148:151], v[164:167], v[48:51]
	v_mfma_f32_16x16x32_bf16 v[36:39], v[140:143], v[180:183], v[36:39]
	v_mfma_f32_16x16x32_bf16 v[32:35], v[148:151], v[180:183], v[32:35]
	v_mfma_f32_16x16x32_bf16 v[20:23], v[140:143], v[200:203], v[20:23]
	v_mfma_f32_16x16x32_bf16 v[16:19], v[148:151], v[200:203], v[16:19]
	s_barrier
	s_add_i32 s100, s44, s25
	s_mov_b32 m0, s100
	s_nop 0
	s_add_u32 vcc_lo, s22, s88
	s_addc_u32 vcc_hi, s23, s89
	global_load_lds_dwordx4 v172, vcc
	s_add_i32 m0, s100, 0x2000
	s_nop 0
	s_add_u32 vcc_lo, s22, s64
	s_addc_u32 vcc_hi, s23, s65
	global_load_lds_dwordx4 v172, vcc
	s_waitcnt vmcnt(6)
	s_barrier
	v_mfma_f32_16x16x32_bf16 v[60:63], v[204:207], v[152:155], v[60:63]
	v_mfma_f32_16x16x32_bf16 v[56:59], v[212:215], v[152:155], v[56:59]
	v_mfma_f32_16x16x32_bf16 v[44:47], v[204:207], v[160:163], v[44:47]
	v_mfma_f32_16x16x32_bf16 v[40:43], v[212:215], v[160:163], v[40:43]
	ds_read_b128 v[136:139], v255 offset:32768
	ds_read_b128 v[140:143], v255 offset:33792
	ds_read_b128 v[144:147], v255 offset:34816
	ds_read_b128 v[148:151], v255 offset:35840
	v_mfma_f32_16x16x32_bf16 v[28:31], v[204:207], v[176:179], v[28:31]
	v_mfma_f32_16x16x32_bf16 v[24:27], v[212:215], v[176:179], v[24:27]
	v_mfma_f32_16x16x32_bf16 v[12:15], v[204:207], v[196:199], v[12:15]
	v_mfma_f32_16x16x32_bf16 v[8:11], v[212:215], v[196:199], v[8:11]
	v_mfma_f32_16x16x32_bf16 v[60:63], v[208:211], v[156:159], v[60:63]
	v_mfma_f32_16x16x32_bf16 v[56:59], v[216:219], v[156:159], v[56:59]
	v_mfma_f32_16x16x32_bf16 v[44:47], v[208:211], v[164:167], v[44:47]
	v_mfma_f32_16x16x32_bf16 v[40:43], v[216:219], v[164:167], v[40:43]
	v_mfma_f32_16x16x32_bf16 v[28:31], v[208:211], v[180:183], v[28:31]
	v_mfma_f32_16x16x32_bf16 v[24:27], v[216:219], v[180:183], v[24:27]
	v_mfma_f32_16x16x32_bf16 v[12:15], v[208:211], v[200:203], v[12:15]
	v_mfma_f32_16x16x32_bf16 v[8:11], v[216:219], v[200:203], v[8:11]
	s_barrier
	s_add_i32 s100, 0, 0x18000
	s_mov_b32 m0, s29
	ds_read_b128 v[152:155], v195 offset:32768
	ds_read_b128 v[156:159], v195 offset:33792
	ds_read_b128 v[160:163], v195 offset:34816
	ds_read_b128 v[164:167], v195 offset:35840
	ds_read_b128 v[176:179], v195 offset:36864
	ds_read_b128 v[180:183], v195 offset:37888
	ds_read_b128 v[196:199], v195 offset:38912
	ds_read_b128 v[200:203], v195 offset:39936
	s_add_u32 vcc_lo, s4, s88
	s_addc_u32 vcc_hi, s5, s89
	global_load_lds_dwordx4 v2, vcc
	s_mov_b32 m0, s30
	s_nop 0
	s_add_u32 vcc_lo, s4, s64
	s_addc_u32 vcc_hi, s5, s65
	global_load_lds_dwordx4 v2, vcc
	s_waitcnt lgkmcnt(8)
	s_barrier
	s_waitcnt lgkmcnt(0)
	v_mfma_f32_16x16x32_bf16 v[132:135], v[136:139], v[152:155], v[132:135]
	v_mfma_f32_16x16x32_bf16 v[128:131], v[144:147], v[152:155], v[128:131]
	v_mfma_f32_16x16x32_bf16 v[116:119], v[136:139], v[160:163], v[116:119]
	v_mfma_f32_16x16x32_bf16 v[112:115], v[144:147], v[160:163], v[112:115]
	v_mfma_f32_16x16x32_bf16 v[100:103], v[136:139], v[176:179], v[100:103]
	v_mfma_f32_16x16x32_bf16 v[96:99], v[144:147], v[176:179], v[96:99]
	v_mfma_f32_16x16x32_bf16 v[84:87], v[136:139], v[196:199], v[84:87]
	v_mfma_f32_16x16x32_bf16 v[80:83], v[144:147], v[196:199], v[80:83]
	v_mfma_f32_16x16x32_bf16 v[132:135], v[140:143], v[156:159], v[132:135]
	v_mfma_f32_16x16x32_bf16 v[128:131], v[148:151], v[156:159], v[128:131]
	v_mfma_f32_16x16x32_bf16 v[116:119], v[140:143], v[164:167], v[116:119]
	v_mfma_f32_16x16x32_bf16 v[112:115], v[148:151], v[164:167], v[112:115]
	v_mfma_f32_16x16x32_bf16 v[100:103], v[140:143], v[180:183], v[100:103]
	v_mfma_f32_16x16x32_bf16 v[96:99], v[148:151], v[180:183], v[96:99]
	v_mfma_f32_16x16x32_bf16 v[84:87], v[140:143], v[200:203], v[84:87]
	v_mfma_f32_16x16x32_bf16 v[80:83], v[148:151], v[200:203], v[80:83]
	s_barrier
; #define G_STAGE(bufoff, gbase, o0, h64) do { \
;         __builtin_amdgcn_global_load_lds((const unsigned*)((const char*)(gbase) + (o0)), (LAS unsigned*)(lds + (bufoff) + ldsw), 16, 0, 0); \
;         __builtin_amdgcn_global_load_lds((const unsigned*)((const char*)(gbase) + (h64) + (o0)), (LAS unsigned*)(lds + (bufoff) + ldsw + 8192), 16, 0, 0); } while (0)
; #define G_LDA(dst, b, h) do { _Pragma("unroll") for (int m = 0; m < 4; ++m) _Pragma("unroll") for (int k = 0; k < 2; ++k) dst[m][k] = *(const LAS bf16x8*)(lds + G_SA(b, h) + aoff + m * 2048 + k * 1024); } while (0)
; #define G_LDB(dst, b, h) do { _Pragma("unroll") for (int n = 0; n < 2; ++n) _Pragma("unroll") for (int k = 0; k < 2; ++k) dst[n][k] = *(const LAS bf16x8*)(lds + G_SB(b, h) + boff + n * 2048 + k * 1024); } while (0)
; #define G_WAIT_V(n) asm volatile("s_waitcnt vmcnt(" #n ")" ::: "memory")
; #define G_WAIT_L(n) asm volatile("s_waitcnt lgkmcnt(" #n ")" ::: "memory")
; #define G_BAR __builtin_amdgcn_s_barrier()
; #define G_SCHED __builtin_amdgcn_sched_barrier(0)
;     ...
;             G_WAIT_L(8); G_BAR; G_WAIT_L(0); G_MMA(0, 0, At, B0); G_BAR; G_SCHED;
;             G_LDB(B1, 1, 1); G_STAGE(G_SB(1, 0), b3, cB0, qB);
;             G_BAR; G_WAIT_L(0); G_MMA(0, 1, At, B1); G_BAR;
;             G_LDA(At, 1, 1); G_STAGE(G_SA(1, 0), a3, cA0, qA);
;             G_BAR; G_WAIT_L(0); G_MMA(1, 0, At, B0); G_BAR; G_SCHED;
;             G_STAGE(G_SB(1, 1), b3 + chB, cB0, qB);
;             G_WAIT_V(6); G_BAR; G_MMA(1, 1, At, B1); G_BAR;
;         }
	s_add_i32 s5, 0, 0x1c000
	s_add_i32 s4, s100, s25
	s_mov_b32 m0, s4
	ds_read_b128 v[204:207], v255 offset:49152
	ds_read_b128 v[208:211], v255 offset:50176
	ds_read_b128 v[212:215], v255 offset:51200
	ds_read_b128 v[216:219], v255 offset:52224
	s_add_u32 vcc_lo, s22, s46
	s_addc_u32 vcc_hi, s23, s47
	global_load_lds_dwordx4 v172, vcc
	s_add_i32 m0, s4, 0x2000
	s_nop 0
	s_add_u32 vcc_lo, s22, s66
	s_addc_u32 vcc_hi, s23, s67
	global_load_lds_dwordx4 v172, vcc
	s_barrier
	s_waitcnt lgkmcnt(0)
	v_mfma_f32_16x16x32_bf16 v[124:127], v[204:207], v[152:155], v[124:127]
	v_mfma_f32_16x16x32_bf16 v[120:123], v[212:215], v[152:155], v[120:123]
	v_mfma_f32_16x16x32_bf16 v[108:111], v[204:207], v[160:163], v[108:111]
	v_mfma_f32_16x16x32_bf16 v[104:107], v[212:215], v[160:163], v[104:107]
	v_mfma_f32_16x16x32_bf16 v[92:95], v[204:207], v[176:179], v[92:95]
	v_mfma_f32_16x16x32_bf16 v[88:91], v[212:215], v[176:179], v[88:91]
	v_mfma_f32_16x16x32_bf16 v[76:79], v[204:207], v[196:199], v[76:79]
	v_mfma_f32_16x16x32_bf16 v[72:75], v[212:215], v[196:199], v[72:75]
	v_mfma_f32_16x16x32_bf16 v[124:127], v[208:211], v[156:159], v[124:127]
	v_mfma_f32_16x16x32_bf16 v[120:123], v[216:219], v[156:159], v[120:123]
	v_mfma_f32_16x16x32_bf16 v[108:111], v[208:211], v[164:167], v[108:111]
	v_mfma_f32_16x16x32_bf16 v[104:107], v[216:219], v[164:167], v[104:107]
	v_mfma_f32_16x16x32_bf16 v[92:95], v[208:211], v[180:183], v[92:95]
	v_mfma_f32_16x16x32_bf16 v[88:91], v[216:219], v[180:183], v[88:91]
	v_mfma_f32_16x16x32_bf16 v[76:79], v[208:211], v[200:203], v[76:79]
	v_mfma_f32_16x16x32_bf16 v[72:75], v[216:219], v[200:203], v[72:75]
	s_barrier
	s_mov_b32 m0, s31
	v_lshl_add_u64 v[224:225], v[222:223], 0, s[46:47]
	ds_read_b128 v[152:155], v195 offset:49152
	ds_read_b128 v[156:159], v195 offset:50176
	ds_read_b128 v[160:163], v195 offset:51200
	ds_read_b128 v[164:167], v195 offset:52224
	ds_read_b128 v[176:179], v195 offset:53248
	ds_read_b128 v[180:183], v195 offset:54272
	ds_read_b128 v[196:199], v195 offset:55296
	ds_read_b128 v[200:203], v195 offset:56320
	global_load_lds_dwordx4 v[224:225], off
	v_lshl_add_u64 v[222:223], v[222:223], 0, s[66:67]
	s_mov_b32 m0, s34
	s_nop 0
	global_load_lds_dwordx4 v[222:223], off
	s_barrier
	s_waitcnt lgkmcnt(0)
	v_mfma_f32_16x16x32_bf16 v[68:71], v[136:139], v[152:155], v[68:71]
	v_mfma_f32_16x16x32_bf16 v[64:67], v[144:147], v[152:155], v[64:67]
	v_mfma_f32_16x16x32_bf16 v[52:55], v[136:139], v[160:163], v[52:55]
	v_mfma_f32_16x16x32_bf16 v[48:51], v[144:147], v[160:163], v[48:51]
	v_mfma_f32_16x16x32_bf16 v[36:39], v[136:139], v[176:179], v[36:39]
	v_mfma_f32_16x16x32_bf16 v[32:35], v[144:147], v[176:179], v[32:35]
	v_mfma_f32_16x16x32_bf16 v[20:23], v[136:139], v[196:199], v[20:23]
	v_mfma_f32_16x16x32_bf16 v[16:19], v[144:147], v[196:199], v[16:19]
	v_mfma_f32_16x16x32_bf16 v[68:71], v[140:143], v[156:159], v[68:71]
	v_mfma_f32_16x16x32_bf16 v[64:67], v[148:151], v[156:159], v[64:67]
	v_mfma_f32_16x16x32_bf16 v[52:55], v[140:143], v[164:167], v[52:55]
	v_mfma_f32_16x16x32_bf16 v[48:51], v[148:151], v[164:167], v[48:51]
	v_mfma_f32_16x16x32_bf16 v[36:39], v[140:143], v[180:183], v[36:39]
	v_mfma_f32_16x16x32_bf16 v[32:35], v[148:151], v[180:183], v[32:35]
	v_mfma_f32_16x16x32_bf16 v[20:23], v[140:143], v[200:203], v[20:23]
	v_mfma_f32_16x16x32_bf16 v[16:19], v[148:151], v[200:203], v[16:19]
	s_barrier
	s_add_i32 s4, s5, s25
	s_mov_b32 m0, s4
	s_nop 0
	s_add_u32 vcc_lo, s22, s52
	s_addc_u32 vcc_hi, s23, s53
	global_load_lds_dwordx4 v172, vcc
	s_add_i32 m0, s4, 0x2000
	s_nop 0
	s_add_u32 vcc_lo, s22, s54
	s_addc_u32 vcc_hi, s23, s55
	global_load_lds_dwordx4 v172, vcc
	s_add_i32 s21, s21, 2
	s_add_u32 s2, s2, 0x100
	s_addc_u32 s3, s3, 0
	s_add_u32 s6, s6, 0x100
	s_addc_u32 s7, s7, 0
	s_cmp_gt_u32 s21, 41
	s_waitcnt vmcnt(6)
	s_barrier
	v_mfma_f32_16x16x32_bf16 v[60:63], v[204:207], v[152:155], v[60:63]
	v_mfma_f32_16x16x32_bf16 v[56:59], v[212:215], v[152:155], v[56:59]
	v_mfma_f32_16x16x32_bf16 v[44:47], v[204:207], v[160:163], v[44:47]
	v_mfma_f32_16x16x32_bf16 v[40:43], v[212:215], v[160:163], v[40:43]
	ds_read_b128 v[136:139], v255 offset:0
	ds_read_b128 v[140:143], v255 offset:1024
	ds_read_b128 v[144:147], v255 offset:2048
	ds_read_b128 v[148:151], v255 offset:3072
	v_mfma_f32_16x16x32_bf16 v[28:31], v[204:207], v[176:179], v[28:31]
	v_mfma_f32_16x16x32_bf16 v[24:27], v[212:215], v[176:179], v[24:27]
	v_mfma_f32_16x16x32_bf16 v[12:15], v[204:207], v[196:199], v[12:15]
	v_mfma_f32_16x16x32_bf16 v[8:11], v[212:215], v[196:199], v[8:11]
	v_mfma_f32_16x16x32_bf16 v[60:63], v[208:211], v[156:159], v[60:63]
	v_mfma_f32_16x16x32_bf16 v[56:59], v[216:219], v[156:159], v[56:59]
	v_mfma_f32_16x16x32_bf16 v[44:47], v[208:211], v[164:167], v[44:47]
	v_mfma_f32_16x16x32_bf16 v[40:43], v[216:219], v[164:167], v[40:43]
	v_mfma_f32_16x16x32_bf16 v[28:31], v[208:211], v[180:183], v[28:31]
	v_mfma_f32_16x16x32_bf16 v[24:27], v[216:219], v[180:183], v[24:27]
	v_mfma_f32_16x16x32_bf16 v[12:15], v[208:211], v[200:203], v[12:15]
	v_mfma_f32_16x16x32_bf16 v[8:11], v[216:219], v[200:203], v[8:11]
	s_cbranch_scc0 .Ldb_FFO_cont
	v_readfirstlane_b32 s101, v186
	s_cmpk_gt_u32 s101, 0xff
	s_cbranch_scc1 .Ldb_FFO_young
	s_barrier
	s_mov_b32 s101, 1
	s_branch .Ldb_FFO_exit

; __device__ __forceinline__ u32x4 pack8(const f32x4 a, const f32x4 b) { u32x4 w; w.x = cvt_pk_bf16(a[0], a[1]); w.y = cvt_pk_bf16(a[2], a[3]); w.z = cvt_pk_bf16(b[0], b[1]); w.w = cvt_pk_bf16(b[2], b[3]); return w; }
; __device__ __forceinline__ void unpack8(const u32x4 w, f32x4& a, f32x4& b) { a[0] = bf_lo(w.x); a[1] = bf_hi(w.x); a[2] = bf_lo(w.y); a[3] = bf_hi(w.y); b[0] = bf_lo(w.z); b[1] = bf_hi(w.z); b[2] = bf_lo(w.w); b[3] = bf_hi(w.w); }
; #define MEMFENCE asm volatile("" ::: "memory")
; #define XLOAD(gi, bufi) do { _Pragma("unroll") for (int ml = 0; ml < 2; ++ml) { const int m_ = ((gi) & 1) * 2 + ml; int row_ = rbase + ((gi) >> 1) * 128 + m_ * 16; asm volatile("" : "+v"(row_)); \
;                 _Pragma("unroll") for (int bj = 0; bj < 2; ++bj) xv[bufi][ml][bj] = *(const u32x4*)(xsrc + (size_t)row_ * 1024 + u.pn * 256 + bj * 128 + cl); } } while (0)
;     template <int KIND> __device__ __forceinline__ void run(f32x4 (&acc)[2][2][4][2], const Unit& u, int tid_in) const {
;     ...
;         if constexpr (KIND == K_XADD) {
;             const bf16_t* xsrc = xb0; bf16_t* xbo = (u.aux ? mg : xb0); float* sso = (u.aux ? ssq2 : ssq1);
;             u32x4 xv[2][2][2];
;     ...
;             XLOAD(0, 0);
; #pragma unroll
;             for (int gi = 0; gi < 4; ++gi) { const int ai = gi >> 1, mh = gi & 1, bufi = gi & 1;
;                 if (gi < 3) XLOAD(gi + 1, (gi + 1) & 1);
; #pragma unroll
;                 for (int ml = 0; ml < 2; ++ml) { const int m = mh * 2 + ml; int row = rbase + ai * 128 + m * 16; asm volatile("" : "+v"(row)); float ss = 0.f;
; #pragma unroll
;                     for (int bj = 0; bj < 2; ++bj) { const size_t off = (size_t)row * 1024 + u.pn * 256 + bj * 128 + cl; f32x4 x0, x1; unpack8(xv[bufi][ml][bj], x0, x1);
;                         const f32x4 o0 = x0 + acc[ai][bj][m][0], o1 = x1 + acc[ai][bj][m][1];
;                         *(u32x4*)(xbo + off) = pack8(o0, o1);
;                         ss += (o0[0] * o0[0] + o0[1] * o0[1]) + (o0[2] * o0[2] + o0[3] * o0[3]) + (o1[0] * o1[0] + o1[1] * o1[1]) + (o1[2] * o1[2] + o1[3] * o1[3]); }
;                     ss += __shfl_xor(ss, 16); ss += __shfl_xor(ss, 32);
;                     if (fq == 0) sso[((size_t)u.pn * T_TOK + row) * 4 + wc] = ss; }
;                 MEMFENCE; }
.Ldb_FFO_exit:
	s_waitcnt lgkmcnt(0)
	v_mov_b32_e32 v0, v184
	s_lshl_b32 s3, s20, 8
	v_readfirstlane_b32 s2, v0
	s_bfe_u32 s33, s2, 0x20006
	s_ashr_i32 s2, s2, 2
	s_andn2_b32 s2, s2, 63
	s_add_i32 s2, s2, s3
	v_and_or_b32 v196, v0, 15, s2
	v_mov_b32_e32 v136, v196
	v_bfe_u32 v138, v0, 4, 2
	s_lshl_b32 s2, s10, 8
	v_lshlrev_b32_e32 v0, 3, v138
	v_ashrrev_i32_e32 v137, 31, v136
	s_ashr_i32 s3, s2, 31
	v_lshlrev_b64 v[136:137], 11, v[136:137]
	v_lshl_or_b32 v0, s33, 5, v0
	s_lshl_b64 s[22:23], s[2:3], 1
	v_lshl_add_u64 v[136:137], s[12:13], 0, v[136:137]
	v_lshl_add_u64 v[136:137], v[136:137], 0, s[22:23]
	v_lshlrev_b32_e32 v0, 1, v0
	v_lshl_add_u64 v[136:137], v[136:137], 0, v[0:1]
	global_load_dwordx4 v[164:167], v[136:137], off
	global_load_dwordx4 v[160:163], v[136:137], off offset:256
	v_or_b32_e32 v180, 16, v196
	v_mov_b32_e32 v136, v180
	v_or_b32_e32 v178, 32, v196
	v_ashrrev_i32_e32 v137, 31, v136
	v_lshlrev_b64 v[136:137], 11, v[136:137]
	v_lshl_add_u64 v[136:137], s[12:13], 0, v[136:137]
	v_lshl_add_u64 v[136:137], v[136:137], 0, s[22:23]
	v_lshl_add_u64 v[136:137], v[136:137], 0, v[0:1]
	global_load_dwordx4 v[156:159], v[136:137], off
	global_load_dwordx4 v[152:155], v[136:137], off offset:256
	v_mov_b32_e32 v136, v178
	v_or_b32_e32 v176, 48, v196
	v_ashrrev_i32_e32 v137, 31, v136
	v_lshlrev_b64 v[136:137], 11, v[136:137]
	v_lshl_add_u64 v[136:137], s[12:13], 0, v[136:137]
	v_lshl_add_u64 v[136:137], v[136:137], 0, s[22:23]
	v_lshl_add_u64 v[136:137], v[136:137], 0, v[0:1]
	global_load_dwordx4 v[148:151], v[136:137], off
	global_load_dwordx4 v[140:143], v[136:137], off offset:256
	v_mov_b32_e32 v136, v176
	v_cmp_eq_u32_e32 vcc, 0, v138
	v_ashrrev_i32_e32 v137, 31, v136
	v_lshlrev_b64 v[136:137], 11, v[136:137]
	v_lshl_add_u64 v[136:137], s[12:13], 0, v[136:137]
	v_lshl_add_u64 v[136:137], v[136:137], 0, s[22:23]
	v_lshl_add_u64 v[136:137], v[136:137], 0, v[0:1]
	global_load_dwordx4 v[144:147], v[136:137], off
	s_nop 0
	global_load_dwordx4 v[136:139], v[136:137], off offset:256
	v_mov_b32_e32 v182, v196
	s_cmp_eq_u32 s11, 0
	s_cselect_b32 s21, s13, s41
	v_ashrrev_i32_e32 v183, 31, v182
	s_cselect_b32 s20, s12, s40
	v_lshlrev_b64 v[198:199], 11, v[182:183]
	v_lshl_add_u64 v[198:199], s[20:21], 0, v[198:199]
	v_lshl_add_u64 v[198:199], v[198:199], 0, s[22:23]
	v_lshl_add_u64 v[198:199], v[198:199], 0, v[0:1]
	s_mov_b32 s4, 0xaa00000
	s_cselect_b32 s4, s4, 0xac00000
	s_add_u32 s51, s8, s4
	s_addc_u32 s52, s9, 0
	s_waitcnt vmcnt(0)
	v_lshlrev_b32_e32 v200, 16, v164
	v_and_b32_e32 v201, 0xffff0000, v164
	v_lshlrev_b32_e32 v164, 16, v165
	v_and_b32_e32 v165, 0xffff0000, v165
	v_lshlrev_b32_e32 v202, 16, v166
	v_and_b32_e32 v203, 0xffff0000, v166
	v_lshlrev_b32_e32 v166, 16, v167
	v_and_b32_e32 v167, 0xffff0000, v167
	v_pk_add_f32 v[134:135], v[134:135], v[164:165]
	v_pk_add_f32 v[132:133], v[132:133], v[200:201]
	v_pk_add_f32 v[164:165], v[130:131], v[166:167]
	v_pk_add_f32 v[166:167], v[128:129], v[202:203]
	v_cvt_pk_bf16_f32 v128, v132, v133
	v_cvt_pk_bf16_f32 v129, v134, v135
	s_nop 0
	v_cvt_pk_bf16_f32 v130, v166, v167
	v_cvt_pk_bf16_f32 v131, v164, v165
	global_store_dwordx4 v[198:199], v[128:131], off
	s_nop 1
	v_mul_f32_e32 v128, v133, v133
	v_mul_f32_e32 v129, v135, v135
	v_fmac_f32_e32 v128, v132, v132
	v_fmac_f32_e32 v129, v134, v134
	v_add_f32_e32 v128, v128, v129
	v_mul_f32_e32 v129, v167, v167
	v_fmac_f32_e32 v129, v166, v166
	v_add_f32_e32 v128, v129, v128
	v_mul_f32_e32 v129, v165, v165
	v_fmac_f32_e32 v129, v164, v164
	v_add_f32_e32 v164, v129, v128
	v_lshlrev_b32_e32 v128, 16, v160
	v_and_b32_e32 v129, 0xffff0000, v160
	v_lshlrev_b32_e32 v130, 16, v161
	v_and_b32_e32 v131, 0xffff0000, v161
	v_lshlrev_b32_e32 v132, 16, v162
	v_and_b32_e32 v133, 0xffff0000, v162
	v_lshlrev_b32_e32 v134, 16, v163
	v_and_b32_e32 v135, 0xffff0000, v163
	v_pk_add_f32 v[126:127], v[126:127], v[130:131]
	v_pk_add_f32 v[124:125], v[124:125], v[128:129]
	v_pk_add_f32 v[130:131], v[120:121], v[132:133]
	v_cvt_pk_bf16_f32 v120, v124, v125
	v_cvt_pk_bf16_f32 v121, v126, v127
	v_pk_add_f32 v[128:129], v[122:123], v[134:135]
	v_cvt_pk_bf16_f32 v122, v130, v131
	s_nop 0
	v_cvt_pk_bf16_f32 v123, v128, v129
	global_store_dwordx4 v[198:199], v[120:123], off offset:256
	s_nop 1
	v_mul_f32_e32 v120, v125, v125
	v_mul_f32_e32 v121, v127, v127
	v_fmac_f32_e32 v120, v124, v124
	v_fmac_f32_e32 v121, v126, v126
	v_add_f32_e32 v120, v120, v121
	v_mul_f32_e32 v121, v131, v131
	v_fmac_f32_e32 v121, v130, v130
	v_add_f32_e32 v120, v121, v120
	v_mul_f32_e32 v121, v129, v129
	v_fmac_f32_e32 v121, v128, v128
	v_add_f32_e32 v120, v121, v120
	v_xor_b32_e32 v121, 16, v190
	v_cmp_lt_i32_e64 s[6:7], v121, v192
	v_add_f32_e32 v120, v164, v120
	s_nop 0
	v_cndmask_b32_e64 v121, v190, v121, s[6:7]
	v_lshlrev_b32_e32 v124, 2, v121
	ds_bpermute_b32 v121, v124, v120
	s_waitcnt lgkmcnt(0)
	v_add_f32_e32 v120, v120, v121
	v_xor_b32_e32 v121, 32, v190
	v_cmp_lt_i32_e64 s[6:7], v121, v192
	s_nop 1
	v_cndmask_b32_e64 v121, v190, v121, s[6:7]
	v_lshlrev_b32_e32 v125, 2, v121
	ds_bpermute_b32 v121, v125, v120
	s_and_saveexec_b64 s[6:7], vcc
	s_cbranch_execz .LBB0_1188
	s_ashr_i32 s11, s10, 31
	s_lshl_b64 s[4:5], s[10:11], 19
	s_add_u32 s4, s51, s4
	s_addc_u32 s5, s52, s5
	s_waitcnt lgkmcnt(0)
	v_add_f32_e32 v122, v120, v121
	v_lshl_add_u64 v[120:121], v[182:183], 4, s[4:5]
	s_lshl_b32 s74, s33, 2
	v_lshl_add_u64 v[120:121], v[120:121], 0, s[74:75]
	global_store_dword v[120:121], v122, off

; #define G_STAGE(bufoff, gbase, o0, h64) do { \
;         __builtin_amdgcn_global_load_lds((const unsigned*)((const char*)(gbase) + (o0)), (LAS unsigned*)(lds + (bufoff) + ldsw), 16, 0, 0); \
;         __builtin_amdgcn_global_load_lds((const unsigned*)((const char*)(gbase) + (h64) + (o0)), (LAS unsigned*)(lds + (bufoff) + ldsw + 8192), 16, 0, 0); } while (0)
; #define G_LDA(dst, b, h) do { _Pragma("unroll") for (int m = 0; m < 4; ++m) _Pragma("unroll") for (int k = 0; k < 2; ++k) dst[m][k] = *(const LAS bf16x8*)(lds + G_SA(b, h) + aoff + m * 2048 + k * 1024); } while (0)
; #define G_LDB(dst, b, h) do { _Pragma("unroll") for (int n = 0; n < 2; ++n) _Pragma("unroll") for (int k = 0; k < 2; ++k) dst[n][k] = *(const LAS bf16x8*)(lds + G_SB(b, h) + boff + n * 2048 + k * 1024); } while (0)
; #define G_WAIT_L(n) asm volatile("s_waitcnt lgkmcnt(" #n ")" ::: "memory")
; #define G_BAR __builtin_amdgcn_s_barrier()
; #define G_SCHED __builtin_amdgcn_sched_barrier(0)
;     ...
;         for (int t = 0; t < nt; t += 2) {
;             const bool last = (t == nt - 2);
;             const char* a1 = cA + (size_t)(t + 1) * ckA;
;             const char* a2 = last ? nA : cA + (size_t)(t + 2) * ckA; const char* b2 = last ? nB : cB + (size_t)(t + 2) * kB;
;             const char* a3 = a2 + ckA; const char* b3 = b2 + kB;
;             G_LDB(B0, 0, 0); G_SCHED; G_LDA(At, 0, 0); G_STAGE(G_SA(1, 1), a1 + chA, cA0, qA);
;             G_WAIT_L(8); G_BAR; G_WAIT_L(0); G_MMA(0, 0, At, B0); G_BAR; G_SCHED;
;             G_LDB(B1, 0, 1); G_STAGE(G_SB(0, 0), b2, cB0, qB);
;             G_BAR; G_WAIT_L(0); G_MMA(0, 1, At, B1); G_BAR;
;     ...
;         for (int a = 0; a < 2; ++a)
; #pragma unroll
;             for (int b = 0; b < 2; ++b)
; #pragma unroll
;                 for (int m = 0; m < 4; ++m)
; #pragma unroll
;                     for (int n = 0; n < 2; ++n) acc[a][b][m][n] = (f32x4){0.f, 0.f, 0.f, 0.f};
.LBB0_1259:
	v_mov_b64_e32 v[8:9], 0
	s_mov_b64 s[18:19], 0
	s_mov_b64 s[14:15], -1
	s_mov_b64 s[16:17], 0
	v_mov_b64_e32 v[10:11], 0
	v_mov_b64_e32 v[12:13], 0
	v_mov_b64_e32 v[14:15], 0
	v_mov_b64_e32 v[16:17], 0
	v_mov_b64_e32 v[18:19], 0
	v_mov_b64_e32 v[24:25], 0
	v_mov_b64_e32 v[26:27], 0
	v_mov_b64_e32 v[32:33], 0
	v_mov_b64_e32 v[34:35], 0
	v_mov_b64_e32 v[40:41], 0
	v_mov_b64_e32 v[42:43], 0
	v_mov_b64_e32 v[48:49], 0
	v_mov_b64_e32 v[50:51], 0
	v_mov_b64_e32 v[56:57], 0
	v_mov_b64_e32 v[58:59], 0
	v_mov_b64_e32 v[20:21], 0
	v_mov_b64_e32 v[22:23], 0
	v_mov_b64_e32 v[28:29], 0
	v_mov_b64_e32 v[30:31], 0
	v_mov_b64_e32 v[36:37], 0
	v_mov_b64_e32 v[38:39], 0
	v_mov_b64_e32 v[44:45], 0
	v_mov_b64_e32 v[46:47], 0
	v_mov_b64_e32 v[52:53], 0
	v_mov_b64_e32 v[54:55], 0
	v_mov_b64_e32 v[60:61], 0
	v_mov_b64_e32 v[62:63], 0
	v_mov_b64_e32 v[64:65], 0
	v_mov_b64_e32 v[66:67], 0
	v_mov_b64_e32 v[68:69], 0
	v_mov_b64_e32 v[70:71], 0
	v_mov_b64_e32 v[72:73], 0
	v_mov_b64_e32 v[74:75], 0
	v_mov_b64_e32 v[76:77], 0
	v_mov_b64_e32 v[78:79], 0
	v_mov_b64_e32 v[80:81], 0
	v_mov_b64_e32 v[82:83], 0
	v_mov_b64_e32 v[88:89], 0
	v_mov_b64_e32 v[90:91], 0
	v_mov_b64_e32 v[96:97], 0
	v_mov_b64_e32 v[98:99], 0
	v_mov_b64_e32 v[104:105], 0
	v_mov_b64_e32 v[106:107], 0
	v_mov_b64_e32 v[112:113], 0
	v_mov_b64_e32 v[114:115], 0
	v_mov_b64_e32 v[120:121], 0
	v_mov_b64_e32 v[122:123], 0
	v_mov_b64_e32 v[84:85], 0
	v_mov_b64_e32 v[86:87], 0
	v_mov_b64_e32 v[92:93], 0
	v_mov_b64_e32 v[94:95], 0
	v_mov_b64_e32 v[100:101], 0
	v_mov_b64_e32 v[102:103], 0
	v_mov_b64_e32 v[108:109], 0
	v_mov_b64_e32 v[110:111], 0
	v_mov_b64_e32 v[116:117], 0
	v_mov_b64_e32 v[118:119], 0
	v_mov_b64_e32 v[124:125], 0
	v_mov_b64_e32 v[126:127], 0
	v_mov_b64_e32 v[128:129], 0
	v_mov_b64_e32 v[130:131], 0
	v_mov_b64_e32 v[132:133], 0
	v_mov_b64_e32 v[134:135], 0
	s_mov_b64 s[58:59], 0x10000
	s_cmp_eq_u32 s101, 2
	s_cselect_b32 s101, 0, s101
	v_add_u32_e32 v255, 0x10000, v137
	ds_read_b128 v[140:143], v255 offset:0
	ds_read_b128 v[144:147], v255 offset:1024
	ds_read_b128 v[148:151], v255 offset:2048
	ds_read_b128 v[152:155], v255 offset:3072
.LBB0_1260:
	s_add_u32 s22, s10, s18
	s_addc_u32 s23, s11, s19
	s_add_u32 s20, s22, 0x100
	s_addc_u32 s21, s23, 0
	s_and_b64 s[4:5], s[16:17], exec
	s_cselect_b32 s20, s6, s20
	s_cselect_b32 s21, s7, s21
	s_add_u32 s4, s12, s18
	s_addc_u32 s5, s13, s19
	s_add_u32 s18, s4, 0x100
	s_addc_u32 s19, s5, 0
	s_add_i32 s44, 0, 0x10000
	s_and_b64 s[4:5], s[16:17], exec
	s_cselect_b32 s16, s8, s18
	s_cselect_b32 s17, s9, s19
	s_add_i32 s5, 0, 0x14000
	s_add_i32 s43, 0, 0x18000
	s_add_i32 s18, 0, 0x1c000
	s_add_i32 s45, s44, s25
	s_add_i32 s51, s5, s25
	s_add_i32 s19, s43, s25
	s_add_i32 s53, s18, s25
	s_mov_b64 s[64:65], 0x8000
	s_mov_b64 s[62:63], 0x10080
	s_add_i32 m0, s31, 0xc000
	s_add_i32 s4, s31, 0xe000
	s_add_i32 s54, s45, 0x2000
	s_add_i32 s50, s51, 0x2000
	s_add_i32 s44, s19, 0x2000
	s_add_i32 s52, s53, 0x2000
	ds_read_b128 v[156:159], v138
	ds_read_b128 v[160:163], v138 offset:1024
	ds_read_b128 v[164:167], v138 offset:2048
	ds_read_b128 v[172:175], v138 offset:3072
	ds_read_b128 v[176:179], v138 offset:4096
	ds_read_b128 v[180:183], v138 offset:5120
	ds_read_b128 v[196:199], v138 offset:6144
	ds_read_b128 v[200:203], v138 offset:7168
	s_add_u32 vcc_lo, s22, s62
	s_addc_u32 vcc_hi, s23, s63
	global_load_lds_dwordx4 v2, vcc
	s_mov_b32 m0, s4
	s_nop 0
	s_add_u32 vcc_lo, s22, s68
	s_addc_u32 vcc_hi, s23, s69
	global_load_lds_dwordx4 v2, vcc
	s_waitcnt lgkmcnt(8)
	s_cmp_eq_u32 s101, 1
	s_cbranch_scc1 .Ldb_PLE0_sk
	s_barrier
.Ldb_PLE0_sk:
	s_mov_b32 s101, 0
	s_waitcnt lgkmcnt(0)
	v_mfma_f32_16x16x32_bf16 v[132:135], v[140:143], v[156:159], v[132:135]
	v_mfma_f32_16x16x32_bf16 v[128:131], v[148:151], v[156:159], v[128:131]
	v_mfma_f32_16x16x32_bf16 v[124:127], v[140:143], v[164:167], v[124:127]
	v_mfma_f32_16x16x32_bf16 v[116:119], v[148:151], v[164:167], v[116:119]
	v_mfma_f32_16x16x32_bf16 v[108:111], v[140:143], v[176:179], v[108:111]
	v_mfma_f32_16x16x32_bf16 v[100:103], v[148:151], v[176:179], v[100:103]
	v_mfma_f32_16x16x32_bf16 v[92:95], v[140:143], v[196:199], v[92:95]
	v_mfma_f32_16x16x32_bf16 v[84:87], v[148:151], v[196:199], v[84:87]
	v_mfma_f32_16x16x32_bf16 v[132:135], v[144:147], v[160:163], v[132:135]
	v_mfma_f32_16x16x32_bf16 v[128:131], v[152:155], v[160:163], v[128:131]
	v_mfma_f32_16x16x32_bf16 v[124:127], v[144:147], v[172:175], v[124:127]
	v_mfma_f32_16x16x32_bf16 v[116:119], v[152:155], v[172:175], v[116:119]
	v_mfma_f32_16x16x32_bf16 v[108:111], v[144:147], v[180:183], v[108:111]
	v_mfma_f32_16x16x32_bf16 v[100:103], v[152:155], v[180:183], v[100:103]
	v_mfma_f32_16x16x32_bf16 v[92:95], v[144:147], v[200:203], v[92:95]
	v_mfma_f32_16x16x32_bf16 v[84:87], v[152:155], v[200:203], v[84:87]
	s_barrier
	s_mov_b32 m0, s45
	v_lshl_add_u64 v[184:185], s[16:17], 0, v[0:1]
	ds_read_b128 v[204:207], v255 offset:16384
	ds_read_b128 v[208:211], v255 offset:17408
	ds_read_b128 v[212:215], v255 offset:18432
	ds_read_b128 v[216:219], v255 offset:19456
	global_load_lds_dwordx4 v0, s[16:17]
	s_mov_b32 m0, s54
	s_nop 0
	s_add_u32 vcc_lo, s16, s64
	s_addc_u32 vcc_hi, s17, s65
	global_load_lds_dwordx4 v0, vcc
	s_barrier
; #define G_STAGE(bufoff, gbase, o0, h64) do { \
;         __builtin_amdgcn_global_load_lds((const unsigned*)((const char*)(gbase) + (o0)), (LAS unsigned*)(lds + (bufoff) + ldsw), 16, 0, 0); \
;         __builtin_amdgcn_global_load_lds((const unsigned*)((const char*)(gbase) + (h64) + (o0)), (LAS unsigned*)(lds + (bufoff) + ldsw + 8192), 16, 0, 0); } while (0)
; #define G_LDA(dst, b, h) do { _Pragma("unroll") for (int m = 0; m < 4; ++m) _Pragma("unroll") for (int k = 0; k < 2; ++k) dst[m][k] = *(const LAS bf16x8*)(lds + G_SA(b, h) + aoff + m * 2048 + k * 1024); } while (0)
; #define G_LDB(dst, b, h) do { _Pragma("unroll") for (int n = 0; n < 2; ++n) _Pragma("unroll") for (int k = 0; k < 2; ++k) dst[n][k] = *(const LAS bf16x8*)(lds + G_SB(b, h) + boff + n * 2048 + k * 1024); } while (0)
; #define G_WAIT_V(n) asm volatile("s_waitcnt vmcnt(" #n ")" ::: "memory")
; #define G_WAIT_L(n) asm volatile("s_waitcnt lgkmcnt(" #n ")" ::: "memory")
; #define G_BAR __builtin_amdgcn_s_barrier()
; #define G_SCHED __builtin_amdgcn_sched_barrier(0)
;     ...
;             G_BAR; G_WAIT_L(0); G_MMA(0, 1, At, B1); G_BAR;
;             G_LDA(At, 0, 1); G_STAGE(G_SA(0, 0), a2, cA0, qA);
;             G_BAR; G_WAIT_L(0); G_MMA(1, 0, At, B0); G_BAR; G_SCHED;
;             G_STAGE(G_SB(0, 1), b2 + chB, cB0, qB);
;             G_WAIT_V(6); G_BAR; G_MMA(1, 1, At, B1); G_BAR;
;             G_LDB(B0, 1, 0); G_SCHED; G_LDA(At, 1, 0); G_STAGE(G_SA(0, 1), a2 + chA, cA0, qA);
;             G_WAIT_L(8); G_BAR; G_WAIT_L(0); G_MMA(0, 0, At, B0); G_BAR; G_SCHED;
	s_waitcnt lgkmcnt(0)
	v_mfma_f32_16x16x32_bf16 v[120:123], v[204:207], v[156:159], v[120:123]
	v_mfma_f32_16x16x32_bf16 v[112:115], v[212:215], v[156:159], v[112:115]
	v_mfma_f32_16x16x32_bf16 v[104:107], v[204:207], v[164:167], v[104:107]
	v_mfma_f32_16x16x32_bf16 v[96:99], v[212:215], v[164:167], v[96:99]
	v_mfma_f32_16x16x32_bf16 v[88:91], v[204:207], v[176:179], v[88:91]
	v_mfma_f32_16x16x32_bf16 v[80:83], v[212:215], v[176:179], v[80:83]
	v_mfma_f32_16x16x32_bf16 v[76:79], v[204:207], v[196:199], v[76:79]
	v_mfma_f32_16x16x32_bf16 v[72:75], v[212:215], v[196:199], v[72:75]
	v_mfma_f32_16x16x32_bf16 v[120:123], v[208:211], v[160:163], v[120:123]
	v_mfma_f32_16x16x32_bf16 v[112:115], v[216:219], v[160:163], v[112:115]
	v_mfma_f32_16x16x32_bf16 v[104:107], v[208:211], v[172:175], v[104:107]
	v_mfma_f32_16x16x32_bf16 v[96:99], v[216:219], v[172:175], v[96:99]
	v_mfma_f32_16x16x32_bf16 v[88:91], v[208:211], v[180:183], v[88:91]
	v_mfma_f32_16x16x32_bf16 v[80:83], v[216:219], v[180:183], v[80:83]
	v_mfma_f32_16x16x32_bf16 v[76:79], v[208:211], v[200:203], v[76:79]
	v_mfma_f32_16x16x32_bf16 v[72:75], v[216:219], v[200:203], v[72:75]
	s_barrier
	s_mov_b32 m0, s31
	v_lshl_add_u64 v[220:221], s[20:21], 0, v[2:3]
	s_mov_b64 s[4:5], 0x8000
	ds_read_b128 v[156:159], v138 offset:16384
	ds_read_b128 v[160:163], v138 offset:17408
	ds_read_b128 v[164:167], v138 offset:18432
	ds_read_b128 v[172:175], v138 offset:19456
	ds_read_b128 v[176:179], v138 offset:20480
	ds_read_b128 v[180:183], v138 offset:21504
	ds_read_b128 v[196:199], v138 offset:22528
	ds_read_b128 v[200:203], v138 offset:23552
	global_load_lds_dwordx4 v2, s[20:21]
	s_mov_b32 m0, s33
	s_mov_b64 s[16:17], 0x18000
	s_add_u32 vcc_lo, s20, s4
	s_addc_u32 vcc_hi, s21, s5
	global_load_lds_dwordx4 v2, vcc
	s_barrier
	s_waitcnt lgkmcnt(0)
	s_mov_b64 s[20:21], 0x8080
	s_waitcnt lgkmcnt(0)
	v_mfma_f32_16x16x32_bf16 v[68:71], v[140:143], v[156:159], v[68:71]
	v_mfma_f32_16x16x32_bf16 v[64:67], v[148:151], v[156:159], v[64:67]
	v_mfma_f32_16x16x32_bf16 v[60:63], v[140:143], v[164:167], v[60:63]
	v_mfma_f32_16x16x32_bf16 v[52:55], v[148:151], v[164:167], v[52:55]
	v_mfma_f32_16x16x32_bf16 v[44:47], v[140:143], v[176:179], v[44:47]
	v_mfma_f32_16x16x32_bf16 v[36:39], v[148:151], v[176:179], v[36:39]
	v_mfma_f32_16x16x32_bf16 v[28:31], v[140:143], v[196:199], v[28:31]
	v_mfma_f32_16x16x32_bf16 v[20:23], v[148:151], v[196:199], v[20:23]
	v_mfma_f32_16x16x32_bf16 v[68:71], v[144:147], v[160:163], v[68:71]
	v_mfma_f32_16x16x32_bf16 v[64:67], v[152:155], v[160:163], v[64:67]
	v_mfma_f32_16x16x32_bf16 v[60:63], v[144:147], v[172:175], v[60:63]
	v_mfma_f32_16x16x32_bf16 v[52:55], v[152:155], v[172:175], v[52:55]
	v_mfma_f32_16x16x32_bf16 v[44:47], v[144:147], v[180:183], v[44:47]
	v_mfma_f32_16x16x32_bf16 v[36:39], v[152:155], v[180:183], v[36:39]
	v_mfma_f32_16x16x32_bf16 v[28:31], v[144:147], v[200:203], v[28:31]
	v_mfma_f32_16x16x32_bf16 v[20:23], v[152:155], v[200:203], v[20:23]
	s_barrier
	s_mov_b32 m0, s51
	v_lshl_add_u64 v[140:141], v[184:185], 0, s[58:59]
	global_load_lds_dwordx4 v[140:141], off
	v_lshl_add_u64 v[140:141], v[184:185], 0, s[16:17]
	s_mov_b32 m0, s50
	s_nop 0
	global_load_lds_dwordx4 v[140:141], off
	s_waitcnt vmcnt(6)
	s_barrier
	v_mfma_f32_16x16x32_bf16 v[56:59], v[204:207], v[156:159], v[56:59]
	v_mfma_f32_16x16x32_bf16 v[48:51], v[212:215], v[156:159], v[48:51]
	v_mfma_f32_16x16x32_bf16 v[40:43], v[204:207], v[164:167], v[40:43]
	v_mfma_f32_16x16x32_bf16 v[32:35], v[212:215], v[164:167], v[32:35]
	ds_read_b128 v[140:143], v255 offset:32768
	ds_read_b128 v[144:147], v255 offset:33792
	ds_read_b128 v[148:151], v255 offset:34816
	ds_read_b128 v[152:155], v255 offset:35840
	v_mfma_f32_16x16x32_bf16 v[24:27], v[204:207], v[176:179], v[24:27]
	v_mfma_f32_16x16x32_bf16 v[16:19], v[212:215], v[176:179], v[16:19]
	v_mfma_f32_16x16x32_bf16 v[12:15], v[204:207], v[196:199], v[12:15]
	v_mfma_f32_16x16x32_bf16 v[8:11], v[212:215], v[196:199], v[8:11]
	v_mfma_f32_16x16x32_bf16 v[56:59], v[208:211], v[160:163], v[56:59]
	v_mfma_f32_16x16x32_bf16 v[48:51], v[216:219], v[160:163], v[48:51]
	v_mfma_f32_16x16x32_bf16 v[40:43], v[208:211], v[172:175], v[40:43]
	v_mfma_f32_16x16x32_bf16 v[32:35], v[216:219], v[172:175], v[32:35]
	v_mfma_f32_16x16x32_bf16 v[24:27], v[208:211], v[180:183], v[24:27]
	v_mfma_f32_16x16x32_bf16 v[16:19], v[216:219], v[180:183], v[16:19]
	v_mfma_f32_16x16x32_bf16 v[12:15], v[208:211], v[200:203], v[12:15]
	v_mfma_f32_16x16x32_bf16 v[8:11], v[216:219], v[200:203], v[8:11]
	s_barrier
	s_mov_b32 m0, s34
	v_lshl_add_u64 v[204:205], v[220:221], 0, s[58:59]
	ds_read_b128 v[156:159], v138 offset:32768
	ds_read_b128 v[160:163], v138 offset:33792
	ds_read_b128 v[164:167], v138 offset:34816
	ds_read_b128 v[172:175], v138 offset:35840
	ds_read_b128 v[176:179], v138 offset:36864
	ds_read_b128 v[180:183], v138 offset:37888
	ds_read_b128 v[196:199], v138 offset:38912
	ds_read_b128 v[200:203], v138 offset:39936
	global_load_lds_dwordx4 v[204:205], off
	v_lshl_add_u64 v[204:205], v[220:221], 0, s[16:17]
	s_mov_b32 m0, s35
	s_nop 0
	global_load_lds_dwordx4 v[204:205], off
	s_waitcnt lgkmcnt(8)
	s_barrier
; #define G_STAGE(bufoff, gbase, o0, h64) do { \
;         __builtin_amdgcn_global_load_lds((const unsigned*)((const char*)(gbase) + (o0)), (LAS unsigned*)(lds + (bufoff) + ldsw), 16, 0, 0); \
;         __builtin_amdgcn_global_load_lds((const unsigned*)((const char*)(gbase) + (h64) + (o0)), (LAS unsigned*)(lds + (bufoff) + ldsw + 8192), 16, 0, 0); } while (0)
; #define G_LDA(dst, b, h) do { _Pragma("unroll") for (int m = 0; m < 4; ++m) _Pragma("unroll") for (int k = 0; k < 2; ++k) dst[m][k] = *(const LAS bf16x8*)(lds + G_SA(b, h) + aoff + m * 2048 + k * 1024); } while (0)
; #define G_LDB(dst, b, h) do { _Pragma("unroll") for (int n = 0; n < 2; ++n) _Pragma("unroll") for (int k = 0; k < 2; ++k) dst[n][k] = *(const LAS bf16x8*)(lds + G_SB(b, h) + boff + n * 2048 + k * 1024); } while (0)
; #define G_WAIT_V(n) asm volatile("s_waitcnt vmcnt(" #n ")" ::: "memory")
; #define G_WAIT_L(n) asm volatile("s_waitcnt lgkmcnt(" #n ")" ::: "memory")
; #define G_BAR __builtin_amdgcn_s_barrier()
; #define G_SCHED __builtin_amdgcn_sched_barrier(0)
;     ...
;             G_WAIT_L(8); G_BAR; G_WAIT_L(0); G_MMA(0, 0, At, B0); G_BAR; G_SCHED;
;             G_LDB(B1, 1, 1); G_STAGE(G_SB(1, 0), b3, cB0, qB);
;             G_BAR; G_WAIT_L(0); G_MMA(0, 1, At, B1); G_BAR;
;             G_LDA(At, 1, 1); G_STAGE(G_SA(1, 0), a3, cA0, qA);
;             G_BAR; G_WAIT_L(0); G_MMA(1, 0, At, B0); G_BAR; G_SCHED;
;             G_STAGE(G_SB(1, 1), b3 + chB, cB0, qB);
;             G_WAIT_V(6); G_BAR; G_MMA(1, 1, At, B1); G_BAR;
;         }
;         E.template run<cs.kind>(acc, cur, tid);
;         if (!has_next) break;
	s_waitcnt lgkmcnt(0)
	v_mfma_f32_16x16x32_bf16 v[132:135], v[140:143], v[156:159], v[132:135]
	v_mfma_f32_16x16x32_bf16 v[128:131], v[148:151], v[156:159], v[128:131]
	v_mfma_f32_16x16x32_bf16 v[124:127], v[140:143], v[164:167], v[124:127]
	v_mfma_f32_16x16x32_bf16 v[116:119], v[148:151], v[164:167], v[116:119]
	v_mfma_f32_16x16x32_bf16 v[108:111], v[140:143], v[176:179], v[108:111]
	v_mfma_f32_16x16x32_bf16 v[100:103], v[148:151], v[176:179], v[100:103]
	v_mfma_f32_16x16x32_bf16 v[92:95], v[140:143], v[196:199], v[92:95]
	v_mfma_f32_16x16x32_bf16 v[84:87], v[148:151], v[196:199], v[84:87]
	v_mfma_f32_16x16x32_bf16 v[132:135], v[144:147], v[160:163], v[132:135]
	v_mfma_f32_16x16x32_bf16 v[128:131], v[152:155], v[160:163], v[128:131]
	v_mfma_f32_16x16x32_bf16 v[124:127], v[144:147], v[172:175], v[124:127]
	v_mfma_f32_16x16x32_bf16 v[116:119], v[152:155], v[172:175], v[116:119]
	v_mfma_f32_16x16x32_bf16 v[108:111], v[144:147], v[180:183], v[108:111]
	v_mfma_f32_16x16x32_bf16 v[100:103], v[152:155], v[180:183], v[100:103]
	v_mfma_f32_16x16x32_bf16 v[92:95], v[144:147], v[200:203], v[92:95]
	v_mfma_f32_16x16x32_bf16 v[84:87], v[152:155], v[200:203], v[84:87]
	s_barrier
	s_mov_b32 m0, s19
	v_lshl_add_u64 v[222:223], v[184:185], 0, s[46:47]
	ds_read_b128 v[204:207], v255 offset:49152
	ds_read_b128 v[208:211], v255 offset:50176
	ds_read_b128 v[212:215], v255 offset:51200
	ds_read_b128 v[216:219], v255 offset:52224
	global_load_lds_dwordx4 v[222:223], off
	v_lshl_add_u64 v[222:223], v[184:185], 0, s[20:21]
	s_mov_b32 m0, s44
	s_mov_b64 s[4:5], 0x10080
	global_load_lds_dwordx4 v[222:223], off
	s_barrier
	s_waitcnt lgkmcnt(0)
	v_mfma_f32_16x16x32_bf16 v[120:123], v[204:207], v[156:159], v[120:123]
	v_mfma_f32_16x16x32_bf16 v[112:115], v[212:215], v[156:159], v[112:115]
	v_mfma_f32_16x16x32_bf16 v[104:107], v[204:207], v[164:167], v[104:107]
	v_mfma_f32_16x16x32_bf16 v[96:99], v[212:215], v[164:167], v[96:99]
	v_mfma_f32_16x16x32_bf16 v[88:91], v[204:207], v[176:179], v[88:91]
	v_mfma_f32_16x16x32_bf16 v[80:83], v[212:215], v[176:179], v[80:83]
	v_mfma_f32_16x16x32_bf16 v[76:79], v[204:207], v[196:199], v[76:79]
	v_mfma_f32_16x16x32_bf16 v[72:75], v[212:215], v[196:199], v[72:75]
	v_mfma_f32_16x16x32_bf16 v[120:123], v[208:211], v[160:163], v[120:123]
	v_mfma_f32_16x16x32_bf16 v[112:115], v[216:219], v[160:163], v[112:115]
	v_mfma_f32_16x16x32_bf16 v[104:107], v[208:211], v[172:175], v[104:107]
	v_mfma_f32_16x16x32_bf16 v[96:99], v[216:219], v[172:175], v[96:99]
	v_mfma_f32_16x16x32_bf16 v[88:91], v[208:211], v[180:183], v[88:91]
	v_mfma_f32_16x16x32_bf16 v[80:83], v[216:219], v[180:183], v[80:83]
	v_mfma_f32_16x16x32_bf16 v[76:79], v[208:211], v[200:203], v[76:79]
	v_mfma_f32_16x16x32_bf16 v[72:75], v[216:219], v[200:203], v[72:75]
	s_barrier
	s_mov_b32 m0, s36
	v_lshl_add_u64 v[222:223], v[220:221], 0, s[46:47]
	ds_read_b128 v[156:159], v138 offset:49152
	ds_read_b128 v[160:163], v138 offset:50176
	ds_read_b128 v[164:167], v138 offset:51200
	ds_read_b128 v[172:175], v138 offset:52224
	ds_read_b128 v[176:179], v138 offset:53248
	ds_read_b128 v[180:183], v138 offset:54272
	ds_read_b128 v[196:199], v138 offset:55296
	ds_read_b128 v[200:203], v138 offset:56320
	global_load_lds_dwordx4 v[222:223], off
	v_lshl_add_u64 v[220:221], v[220:221], 0, s[20:21]
	s_mov_b32 m0, s37
	s_nop 0
	global_load_lds_dwordx4 v[220:221], off
	s_barrier
	s_waitcnt lgkmcnt(0)
	v_mfma_f32_16x16x32_bf16 v[68:71], v[140:143], v[156:159], v[68:71]
	v_mfma_f32_16x16x32_bf16 v[64:67], v[148:151], v[156:159], v[64:67]
	v_mfma_f32_16x16x32_bf16 v[60:63], v[140:143], v[164:167], v[60:63]
	v_mfma_f32_16x16x32_bf16 v[52:55], v[148:151], v[164:167], v[52:55]
	v_mfma_f32_16x16x32_bf16 v[44:47], v[140:143], v[176:179], v[44:47]
	v_mfma_f32_16x16x32_bf16 v[36:39], v[148:151], v[176:179], v[36:39]
	v_mfma_f32_16x16x32_bf16 v[28:31], v[140:143], v[196:199], v[28:31]
	v_mfma_f32_16x16x32_bf16 v[20:23], v[148:151], v[196:199], v[20:23]
	v_mfma_f32_16x16x32_bf16 v[68:71], v[144:147], v[160:163], v[68:71]
	v_mfma_f32_16x16x32_bf16 v[64:67], v[152:155], v[160:163], v[64:67]
	v_mfma_f32_16x16x32_bf16 v[60:63], v[144:147], v[172:175], v[60:63]
	v_mfma_f32_16x16x32_bf16 v[52:55], v[152:155], v[172:175], v[52:55]
	v_mfma_f32_16x16x32_bf16 v[44:47], v[144:147], v[180:183], v[44:47]
	v_mfma_f32_16x16x32_bf16 v[36:39], v[152:155], v[180:183], v[36:39]
	v_mfma_f32_16x16x32_bf16 v[28:31], v[144:147], v[200:203], v[28:31]
	v_mfma_f32_16x16x32_bf16 v[20:23], v[152:155], v[200:203], v[20:23]
	s_barrier
	s_mov_b32 m0, s53
	v_lshl_add_u64 v[140:141], v[184:185], 0, s[4:5]
	global_load_lds_dwordx4 v[140:141], off
	v_lshl_add_u64 v[140:141], v[184:185], 0, s[68:69]
	s_mov_b32 m0, s52
	s_nop 0
	global_load_lds_dwordx4 v[140:141], off
	s_waitcnt vmcnt(6)
	s_barrier
	v_mfma_f32_16x16x32_bf16 v[56:59], v[204:207], v[156:159], v[56:59]
	v_mfma_f32_16x16x32_bf16 v[48:51], v[212:215], v[156:159], v[48:51]
	v_mfma_f32_16x16x32_bf16 v[40:43], v[204:207], v[164:167], v[40:43]
	v_mfma_f32_16x16x32_bf16 v[32:35], v[212:215], v[164:167], v[32:35]
	ds_read_b128 v[140:143], v255 offset:0
	ds_read_b128 v[144:147], v255 offset:1024
	ds_read_b128 v[148:151], v255 offset:2048
	ds_read_b128 v[152:155], v255 offset:3072
	v_mfma_f32_16x16x32_bf16 v[24:27], v[204:207], v[176:179], v[24:27]
	v_mfma_f32_16x16x32_bf16 v[16:19], v[212:215], v[176:179], v[16:19]
	v_mfma_f32_16x16x32_bf16 v[12:15], v[204:207], v[196:199], v[12:15]
	v_mfma_f32_16x16x32_bf16 v[8:11], v[212:215], v[196:199], v[8:11]
	v_mfma_f32_16x16x32_bf16 v[56:59], v[208:211], v[160:163], v[56:59]
	v_mfma_f32_16x16x32_bf16 v[48:51], v[216:219], v[160:163], v[48:51]
	v_mfma_f32_16x16x32_bf16 v[40:43], v[208:211], v[172:175], v[40:43]
	v_mfma_f32_16x16x32_bf16 v[32:35], v[216:219], v[172:175], v[32:35]
	v_mfma_f32_16x16x32_bf16 v[24:27], v[208:211], v[180:183], v[24:27]
	v_mfma_f32_16x16x32_bf16 v[16:19], v[216:219], v[180:183], v[16:19]
	v_mfma_f32_16x16x32_bf16 v[12:15], v[208:211], v[200:203], v[12:15]
	v_mfma_f32_16x16x32_bf16 v[8:11], v[216:219], v[200:203], v[8:11]
	s_andn2_b64 vcc, exec, s[14:15]
	s_mov_b64 s[16:17], -1
	s_mov_b64 s[14:15], 0
	s_mov_b64 s[18:19], 0x100
	s_cbranch_vccz .Ldb_PLE0_cont
	v_readfirstlane_b32 s101, v186
	s_cmpk_gt_u32 s101, 0xff
	s_cbranch_scc1 .Ldb_PLE0_young
	s_barrier
	s_mov_b32 s101, 1
	s_branch .Ldb_PLE0_exit

; __device__ __forceinline__ u32x4 pack8(const f32x4 a, const f32x4 b) { u32x4 w; w.x = cvt_pk_bf16(a[0], a[1]); w.y = cvt_pk_bf16(a[2], a[3]); w.z = cvt_pk_bf16(b[0], b[1]); w.w = cvt_pk_bf16(b[2], b[3]); return w; }
; #define MEMFENCE asm volatile("" ::: "memory")
;     template <int KIND> __device__ __forceinline__ void run(f32x4 (&acc)[2][2][4][2], const Unit& u, int tid_in) const {
;     ...
;         if constexpr (KIND == K_PP) {
; #pragma unroll
;             for (int ai = 0; ai < 2; ++ai)
; #pragma unroll
;                 for (int m = 0; m < 4; ++m)
; #pragma unroll
;                     for (int bj = 0; bj < 2; ++bj) { scr[((ai * 4 + m) * 2 + bj) * 512 + tid] = pack8(acc[ai][bj][m][0], acc[ai][bj][m][1]); if (bj == 1) MEMFENCE; }
;         }
.Ldb_PLE0_exit:
	s_waitcnt lgkmcnt(0)
	s_lshl_b32 s4, s42, 17
	s_and_b32 s4, s4, 0x20000
	v_mov_b32_e32 v140, v136
	s_add_u32 s4, s38, s4
	s_addc_u32 s5, s39, 0
	v_ashrrev_i32_e32 v141, 31, v140
	v_cvt_pk_bf16_f32 v132, v132, v133
	v_cvt_pk_bf16_f32 v133, v134, v135
	v_cvt_pk_bf16_f32 v134, v128, v129
	v_lshl_add_u64 v[128:129], v[140:141], 4, s[4:5]
	s_movk_i32 s4, 0x2000
	v_cvt_pk_bf16_f32 v135, v130, v131
	global_store_dwordx4 v[128:129], v[132:135], off
	v_cvt_pk_bf16_f32 v120, v120, v121
	v_cvt_pk_bf16_f32 v121, v122, v123
	v_cvt_pk_bf16_f32 v122, v112, v113
	v_add_co_u32_e32 v112, vcc, s4, v128
	v_cvt_pk_bf16_f32 v123, v114, v115
	s_movk_i32 s4, 0x6000
	s_nop 0
	v_addc_co_u32_e32 v113, vcc, 0, v129, vcc
	global_store_dwordx4 v[112:113], v[120:123], off
	v_cvt_pk_bf16_f32 v112, v124, v125
	v_cvt_pk_bf16_f32 v113, v126, v127
	v_cvt_pk_bf16_f32 v114, v116, v117
	v_add_co_u32_e32 v116, vcc, s49, v128
	v_cvt_pk_bf16_f32 v115, v118, v119
	s_mov_b32 s42, s41
	s_nop 0
	v_addc_co_u32_e32 v117, vcc, 0, v129, vcc
	global_store_dwordx4 v[116:117], v[112:115], off
	v_cvt_pk_bf16_f32 v104, v104, v105
	v_cvt_pk_bf16_f32 v105, v106, v107
	v_cvt_pk_bf16_f32 v106, v96, v97
	v_add_co_u32_e32 v96, vcc, s4, v128
	v_cvt_pk_bf16_f32 v107, v98, v99
	s_mov_b32 s4, 0xa000
	s_nop 0
	v_addc_co_u32_e32 v97, vcc, 0, v129, vcc
	global_store_dwordx4 v[96:97], v[104:107], off
	v_cvt_pk_bf16_f32 v96, v108, v109
	v_cvt_pk_bf16_f32 v97, v110, v111
	v_cvt_pk_bf16_f32 v98, v100, v101
	v_add_co_u32_e32 v100, vcc, s77, v128
	v_cvt_pk_bf16_f32 v99, v102, v103
	s_mov_b64 s[12:13], s[8:9]
	s_nop 0
	v_addc_co_u32_e32 v101, vcc, 0, v129, vcc
	global_store_dwordx4 v[100:101], v[96:99], off
	v_cvt_pk_bf16_f32 v88, v88, v89
	v_cvt_pk_bf16_f32 v89, v90, v91
	v_cvt_pk_bf16_f32 v90, v80, v81
	v_add_co_u32_e32 v80, vcc, s4, v128
	v_cvt_pk_bf16_f32 v91, v82, v83
	s_mov_b32 s4, 0xc000
	s_nop 0
	v_addc_co_u32_e32 v81, vcc, 0, v129, vcc
	global_store_dwordx4 v[80:81], v[88:91], off
	v_cvt_pk_bf16_f32 v80, v92, v93
	v_cvt_pk_bf16_f32 v81, v94, v95
	v_cvt_pk_bf16_f32 v82, v84, v85
	v_add_co_u32_e32 v84, vcc, s4, v128
	s_mov_b32 s4, 0xe000
	s_nop 0
	v_addc_co_u32_e32 v85, vcc, 0, v129, vcc
	v_cvt_pk_bf16_f32 v83, v86, v87
	global_store_dwordx4 v[84:85], v[80:83], off
	v_cvt_pk_bf16_f32 v76, v76, v77
	v_cvt_pk_bf16_f32 v77, v78, v79
	v_cvt_pk_bf16_f32 v78, v72, v73
	v_add_co_u32_e32 v72, vcc, s4, v128
	v_cvt_pk_bf16_f32 v79, v74, v75
	s_mov_b32 s4, 0x12000
	s_nop 0
	v_addc_co_u32_e32 v73, vcc, 0, v129, vcc
	global_store_dwordx4 v[72:73], v[76:79], off
	v_cvt_pk_bf16_f32 v68, v68, v69
	v_cvt_pk_bf16_f32 v69, v70, v71
	v_cvt_pk_bf16_f32 v70, v64, v65
	v_add_co_u32_e32 v64, vcc, s91, v128
	v_cvt_pk_bf16_f32 v71, v66, v67
	s_mov_b64 s[10:11], s[6:7]
	s_nop 0
	v_addc_co_u32_e32 v65, vcc, 0, v129, vcc
	global_store_dwordx4 v[64:65], v[68:71], off
	v_cvt_pk_bf16_f32 v56, v56, v57
	v_cvt_pk_bf16_f32 v57, v58, v59
	v_cvt_pk_bf16_f32 v58, v48, v49
	v_add_co_u32_e32 v48, vcc, s4, v128
	v_cvt_pk_bf16_f32 v59, v50, v51
	s_mov_b32 s4, 0x14000
	s_nop 0
	v_addc_co_u32_e32 v49, vcc, 0, v129, vcc
	global_store_dwordx4 v[48:49], v[56:59], off
	v_cvt_pk_bf16_f32 v48, v60, v61
	v_cvt_pk_bf16_f32 v49, v62, v63
	v_cvt_pk_bf16_f32 v50, v52, v53
	v_add_co_u32_e32 v52, vcc, s4, v128
	s_mov_b32 s4, 0x16000
	s_nop 0
	v_addc_co_u32_e32 v53, vcc, 0, v129, vcc
	v_cvt_pk_bf16_f32 v51, v54, v55
	global_store_dwordx4 v[52:53], v[48:51], off
	v_cvt_pk_bf16_f32 v40, v40, v41
	v_cvt_pk_bf16_f32 v41, v42, v43
	v_cvt_pk_bf16_f32 v42, v32, v33
	v_add_co_u32_e32 v32, vcc, s4, v128
	v_cvt_pk_bf16_f32 v43, v34, v35
	s_mov_b32 s4, 0x18000
	s_nop 0
	v_addc_co_u32_e32 v33, vcc, 0, v129, vcc
	global_store_dwordx4 v[32:33], v[40:43], off
	v_cvt_pk_bf16_f32 v32, v44, v45
	v_cvt_pk_bf16_f32 v33, v46, v47
	v_cvt_pk_bf16_f32 v34, v36, v37
	v_add_co_u32_e32 v36, vcc, s4, v128
	s_mov_b32 s4, 0x1a000
	s_nop 0
	v_addc_co_u32_e32 v37, vcc, 0, v129, vcc
	v_cvt_pk_bf16_f32 v35, v38, v39
	global_store_dwordx4 v[36:37], v[32:35], off
	v_cvt_pk_bf16_f32 v24, v24, v25
	v_cvt_pk_bf16_f32 v25, v26, v27
	v_cvt_pk_bf16_f32 v26, v16, v17
	v_add_co_u32_e32 v16, vcc, s4, v128
	v_cvt_pk_bf16_f32 v27, v18, v19
	s_mov_b32 s4, 0x1c000
	s_nop 0
	v_addc_co_u32_e32 v17, vcc, 0, v129, vcc
	global_store_dwordx4 v[16:17], v[24:27], off
	v_cvt_pk_bf16_f32 v16, v28, v29
	v_cvt_pk_bf16_f32 v17, v30, v31
	v_cvt_pk_bf16_f32 v18, v20, v21
	v_add_co_u32_e32 v20, vcc, s4, v128
	v_cvt_pk_bf16_f32 v19, v22, v23
	s_nop 1
	v_addc_co_u32_e32 v21, vcc, 0, v129, vcc
	global_store_dwordx4 v[20:21], v[16:19], off
	v_cvt_pk_bf16_f32 v12, v12, v13
	v_cvt_pk_bf16_f32 v13, v14, v15
	v_cvt_pk_bf16_f32 v14, v8, v9
	v_add_co_u32_e32 v8, vcc, 0x1e000, v128
	v_cvt_pk_bf16_f32 v15, v10, v11
	s_nop 1
	v_addc_co_u32_e32 v9, vcc, 0, v129, vcc
	global_store_dwordx4 v[8:9], v[12:15], off
	s_and_b64 vcc, exec, s[2:3]
	s_cbranch_vccz .LBB0_1257
	s_cmp_eq_u32 s101, 2
	s_cbranch_scc0 .Ldbj_PLE0_pe
	s_barrier

; #define G_STAGE(bufoff, gbase, o0, h64) do { \
;         __builtin_amdgcn_global_load_lds((const unsigned*)((const char*)(gbase) + (o0)), (LAS unsigned*)(lds + (bufoff) + ldsw), 16, 0, 0); \
;         __builtin_amdgcn_global_load_lds((const unsigned*)((const char*)(gbase) + (h64) + (o0)), (LAS unsigned*)(lds + (bufoff) + ldsw + 8192), 16, 0, 0); } while (0)
; #define G_LDA(dst, b, h) do { _Pragma("unroll") for (int m = 0; m < 4; ++m) _Pragma("unroll") for (int k = 0; k < 2; ++k) dst[m][k] = *(const LAS bf16x8*)(lds + G_SA(b, h) + aoff + m * 2048 + k * 1024); } while (0)
; #define G_LDB(dst, b, h) do { _Pragma("unroll") for (int n = 0; n < 2; ++n) _Pragma("unroll") for (int k = 0; k < 2; ++k) dst[n][k] = *(const LAS bf16x8*)(lds + G_SB(b, h) + boff + n * 2048 + k * 1024); } while (0)
; #define G_WAIT_L(n) asm volatile("s_waitcnt lgkmcnt(" #n ")" ::: "memory")
; #define G_BAR __builtin_amdgcn_s_barrier()
; #define G_SCHED __builtin_amdgcn_sched_barrier(0)
;     ...
;         for (int t = 0; t < nt; t += 2) {
;             const bool last = (t == nt - 2);
;             const char* a1 = cA + (size_t)(t + 1) * ckA;
;             const char* a2 = last ? nA : cA + (size_t)(t + 2) * ckA; const char* b2 = last ? nB : cB + (size_t)(t + 2) * kB;
;             const char* a3 = a2 + ckA; const char* b3 = b2 + kB;
;             G_LDB(B0, 0, 0); G_SCHED; G_LDA(At, 0, 0); G_STAGE(G_SA(1, 1), a1 + chA, cA0, qA);
;             G_WAIT_L(8); G_BAR; G_WAIT_L(0); G_MMA(0, 0, At, B0); G_BAR; G_SCHED;
;             G_LDB(B1, 0, 1); G_STAGE(G_SB(0, 0), b2, cB0, qB);
;             G_BAR; G_WAIT_L(0); G_MMA(0, 1, At, B1); G_BAR;
;     ...
;         for (int a = 0; a < 2; ++a)
; #pragma unroll
;             for (int b = 0; b < 2; ++b)
; #pragma unroll
;                 for (int m = 0; m < 4; ++m)
; #pragma unroll
;                     for (int n = 0; n < 2; ++n) acc[a][b][m][n] = (f32x4){0.f, 0.f, 0.f, 0.f};
.LBB0_1282:
	s_add_u32 s2, s24, 0x40080
	s_addc_u32 s3, s25, 0
	s_add_u32 s22, s22, 0x100
	s_waitcnt lgkmcnt(0)
	v_mov_b64_e32 v[8:9], 0
	s_addc_u32 s23, s23, 0
	s_mov_b32 s24, -2
	v_mov_b64_e32 v[10:11], 0
	v_mov_b64_e32 v[12:13], 0
	v_mov_b64_e32 v[14:15], 0
	v_mov_b64_e32 v[24:25], 0
	v_mov_b64_e32 v[26:27], 0
	v_mov_b64_e32 v[28:29], 0
	v_mov_b64_e32 v[30:31], 0
	v_mov_b64_e32 v[40:41], 0
	v_mov_b64_e32 v[42:43], 0
	v_mov_b64_e32 v[44:45], 0
	v_mov_b64_e32 v[46:47], 0
	v_mov_b64_e32 v[56:57], 0
	v_mov_b64_e32 v[58:59], 0
	v_mov_b64_e32 v[60:61], 0
	v_mov_b64_e32 v[62:63], 0
	v_mov_b64_e32 v[16:17], 0
	v_mov_b64_e32 v[18:19], 0
	v_mov_b64_e32 v[20:21], 0
	v_mov_b64_e32 v[22:23], 0
	v_mov_b64_e32 v[32:33], 0
	v_mov_b64_e32 v[34:35], 0
	v_mov_b64_e32 v[36:37], 0
	v_mov_b64_e32 v[38:39], 0
	v_mov_b64_e32 v[48:49], 0
	v_mov_b64_e32 v[50:51], 0
	v_mov_b64_e32 v[52:53], 0
	v_mov_b64_e32 v[54:55], 0
	v_mov_b64_e32 v[64:65], 0
	v_mov_b64_e32 v[66:67], 0
	v_mov_b64_e32 v[68:69], 0
	v_mov_b64_e32 v[70:71], 0
	v_mov_b64_e32 v[72:73], 0
	v_mov_b64_e32 v[74:75], 0
	v_mov_b64_e32 v[76:77], 0
	v_mov_b64_e32 v[78:79], 0
	v_mov_b64_e32 v[88:89], 0
	v_mov_b64_e32 v[90:91], 0
	v_mov_b64_e32 v[92:93], 0
	v_mov_b64_e32 v[94:95], 0
	v_mov_b64_e32 v[104:105], 0
	v_mov_b64_e32 v[106:107], 0
	v_mov_b64_e32 v[108:109], 0
	v_mov_b64_e32 v[110:111], 0
	v_mov_b64_e32 v[120:121], 0
	v_mov_b64_e32 v[122:123], 0
	v_mov_b64_e32 v[124:125], 0
	v_mov_b64_e32 v[126:127], 0
	v_mov_b64_e32 v[80:81], 0
	v_mov_b64_e32 v[82:83], 0
	v_mov_b64_e32 v[84:85], 0
	v_mov_b64_e32 v[86:87], 0
	v_mov_b64_e32 v[96:97], 0
	v_mov_b64_e32 v[98:99], 0
	v_mov_b64_e32 v[100:101], 0
	v_mov_b64_e32 v[102:103], 0
	v_mov_b64_e32 v[112:113], 0
	v_mov_b64_e32 v[114:115], 0
	v_mov_b64_e32 v[116:117], 0
	v_mov_b64_e32 v[118:119], 0
	v_mov_b64_e32 v[128:129], 0
	v_mov_b64_e32 v[130:131], 0
	v_mov_b64_e32 v[132:133], 0
	v_mov_b64_e32 v[134:135], 0
	s_mov_b64 s[54:55], 0x40000
	s_mov_b64 s[58:59], 0x60000
	s_mov_b64 s[62:63], 0x20080
	s_mov_b64 s[64:65], 0x40080
	s_mov_b64 s[66:67], 0x60080
	s_cmp_eq_u32 s101, 2
	s_cselect_b32 s101, 0, s101
	v_add_u32_e32 v255, 0x10000, v181
	ds_read_b128 v[136:139], v255 offset:0
	ds_read_b128 v[140:143], v255 offset:1024
	ds_read_b128 v[144:147], v255 offset:2048
	ds_read_b128 v[148:151], v255 offset:3072
.LBB0_1283:
	s_add_u32 s4, s2, 0xfffc0080
	s_addc_u32 s5, s3, -1
	s_add_i32 s25, 0, 0x10000
	s_cmp_eq_u32 s24, 12
	s_cselect_b32 s5, s19, s5
	s_cselect_b32 s4, s18, s4
	s_cselect_b32 s41, s21, s23
	s_cselect_b32 s40, s20, s22
	s_add_i32 m0, s29, 0xc000
	ds_read_b128 v[152:155], v182
	ds_read_b128 v[160:163], v182 offset:1024
	ds_read_b128 v[164:167], v182 offset:2048
	ds_read_b128 v[172:175], v182 offset:3072
	ds_read_b128 v[176:179], v182 offset:4096
	ds_read_b128 v[196:199], v182 offset:5120
	ds_read_b128 v[200:203], v182 offset:6144
	ds_read_b128 v[204:207], v182 offset:7168
	global_load_lds_dwordx4 v158, s[2:3]
	s_add_i32 m0, s29, 0xe000
	s_nop 0
	s_add_u32 vcc_lo, s2, s0
	s_addc_u32 vcc_hi, s3, s1
	global_load_lds_dwordx4 v158, vcc
	s_waitcnt lgkmcnt(8)
	s_cmp_eq_u32 s101, 1
	s_cbranch_scc1 .Ldb_PLE1_sk
	s_barrier
.Ldb_PLE1_sk:
	s_mov_b32 s101, 0
	s_waitcnt lgkmcnt(0)
	v_mfma_f32_16x16x32_bf16 v[132:135], v[136:139], v[152:155], v[132:135]
	v_mfma_f32_16x16x32_bf16 v[128:131], v[144:147], v[152:155], v[128:131]
	v_mfma_f32_16x16x32_bf16 v[116:119], v[136:139], v[164:167], v[116:119]
	v_mfma_f32_16x16x32_bf16 v[112:115], v[144:147], v[164:167], v[112:115]
	v_mfma_f32_16x16x32_bf16 v[100:103], v[136:139], v[176:179], v[100:103]
	v_mfma_f32_16x16x32_bf16 v[96:99], v[144:147], v[176:179], v[96:99]
	v_mfma_f32_16x16x32_bf16 v[84:87], v[136:139], v[200:203], v[84:87]
	v_mfma_f32_16x16x32_bf16 v[80:83], v[144:147], v[200:203], v[80:83]
	v_mfma_f32_16x16x32_bf16 v[132:135], v[140:143], v[160:163], v[132:135]
	v_mfma_f32_16x16x32_bf16 v[128:131], v[148:151], v[160:163], v[128:131]
	v_mfma_f32_16x16x32_bf16 v[116:119], v[140:143], v[172:175], v[116:119]
	v_mfma_f32_16x16x32_bf16 v[112:115], v[148:151], v[172:175], v[112:115]
	v_mfma_f32_16x16x32_bf16 v[100:103], v[140:143], v[196:199], v[100:103]
	v_mfma_f32_16x16x32_bf16 v[96:99], v[148:151], v[196:199], v[96:99]
	v_mfma_f32_16x16x32_bf16 v[84:87], v[140:143], v[204:207], v[84:87]
	v_mfma_f32_16x16x32_bf16 v[80:83], v[148:151], v[204:207], v[80:83]
	s_barrier
	s_add_i32 s44, 0, 0x14000
	s_add_i32 s25, s25, s27
	s_mov_b32 m0, s25
	ds_read_b128 v[208:211], v255 offset:16384
	ds_read_b128 v[212:215], v255 offset:17408
	ds_read_b128 v[216:219], v255 offset:18432
	ds_read_b128 v[220:223], v255 offset:19456
	global_load_lds_dwordx4 v156, s[40:41]
	s_add_i32 m0, s25, 0x2000
	s_nop 0
	s_add_u32 vcc_lo, s40, s0
	s_addc_u32 vcc_hi, s41, s1
	global_load_lds_dwordx4 v156, vcc
	s_barrier
	s_waitcnt lgkmcnt(0)
	v_mfma_f32_16x16x32_bf16 v[124:127], v[208:211], v[152:155], v[124:127]
	v_mfma_f32_16x16x32_bf16 v[120:123], v[216:219], v[152:155], v[120:123]
	v_mfma_f32_16x16x32_bf16 v[108:111], v[208:211], v[164:167], v[108:111]
	v_mfma_f32_16x16x32_bf16 v[104:107], v[216:219], v[164:167], v[104:107]
	v_mfma_f32_16x16x32_bf16 v[92:95], v[208:211], v[176:179], v[92:95]
	v_mfma_f32_16x16x32_bf16 v[88:91], v[216:219], v[176:179], v[88:91]
	v_mfma_f32_16x16x32_bf16 v[76:79], v[208:211], v[200:203], v[76:79]
	v_mfma_f32_16x16x32_bf16 v[72:75], v[216:219], v[200:203], v[72:75]
	v_mfma_f32_16x16x32_bf16 v[124:127], v[212:215], v[160:163], v[124:127]
	v_mfma_f32_16x16x32_bf16 v[120:123], v[220:223], v[160:163], v[120:123]
	v_mfma_f32_16x16x32_bf16 v[108:111], v[212:215], v[172:175], v[108:111]
	v_mfma_f32_16x16x32_bf16 v[104:107], v[220:223], v[172:175], v[104:107]
	v_mfma_f32_16x16x32_bf16 v[92:95], v[212:215], v[196:199], v[92:95]
	v_mfma_f32_16x16x32_bf16 v[88:91], v[220:223], v[196:199], v[88:91]
	v_mfma_f32_16x16x32_bf16 v[76:79], v[212:215], v[204:207], v[76:79]
	v_mfma_f32_16x16x32_bf16 v[72:75], v[220:223], v[204:207], v[72:75]
	s_barrier
; #define G_STAGE(bufoff, gbase, o0, h64) do { \
;         __builtin_amdgcn_global_load_lds((const unsigned*)((const char*)(gbase) + (o0)), (LAS unsigned*)(lds + (bufoff) + ldsw), 16, 0, 0); \
;         __builtin_amdgcn_global_load_lds((const unsigned*)((const char*)(gbase) + (h64) + (o0)), (LAS unsigned*)(lds + (bufoff) + ldsw + 8192), 16, 0, 0); } while (0)
; #define G_LDA(dst, b, h) do { _Pragma("unroll") for (int m = 0; m < 4; ++m) _Pragma("unroll") for (int k = 0; k < 2; ++k) dst[m][k] = *(const LAS bf16x8*)(lds + G_SA(b, h) + aoff + m * 2048 + k * 1024); } while (0)
; #define G_LDB(dst, b, h) do { _Pragma("unroll") for (int n = 0; n < 2; ++n) _Pragma("unroll") for (int k = 0; k < 2; ++k) dst[n][k] = *(const LAS bf16x8*)(lds + G_SB(b, h) + boff + n * 2048 + k * 1024); } while (0)
; #define G_WAIT_V(n) asm volatile("s_waitcnt vmcnt(" #n ")" ::: "memory")
; #define G_WAIT_L(n) asm volatile("s_waitcnt lgkmcnt(" #n ")" ::: "memory")
; #define G_BAR __builtin_amdgcn_s_barrier()
; #define G_SCHED __builtin_amdgcn_sched_barrier(0)
;     ...
;             G_BAR; G_WAIT_L(0); G_MMA(0, 1, At, B1); G_BAR;
;             G_LDA(At, 0, 1); G_STAGE(G_SA(0, 0), a2, cA0, qA);
;             G_BAR; G_WAIT_L(0); G_MMA(1, 0, At, B0); G_BAR; G_SCHED;
;             G_STAGE(G_SB(0, 1), b2 + chB, cB0, qB);
;             G_WAIT_V(6); G_BAR; G_MMA(1, 1, At, B1); G_BAR;
;             G_LDB(B0, 1, 0); G_SCHED; G_LDA(At, 1, 0); G_STAGE(G_SA(0, 1), a2 + chA, cA0, qA);
;             G_WAIT_L(8); G_BAR; G_WAIT_L(0); G_MMA(0, 0, At, B0); G_BAR; G_SCHED;
;             G_LDB(B1, 1, 1); G_STAGE(G_SB(1, 0), b3, cB0, qB);
;             G_BAR; G_WAIT_L(0); G_MMA(0, 1, At, B1); G_BAR;
	s_mov_b32 m0, s29
	v_lshl_add_u64 v[224:225], s[4:5], 0, v[2:3]
	ds_read_b128 v[152:155], v182 offset:16384
	ds_read_b128 v[160:163], v182 offset:17408
	ds_read_b128 v[164:167], v182 offset:18432
	ds_read_b128 v[172:175], v182 offset:19456
	ds_read_b128 v[176:179], v182 offset:20480
	ds_read_b128 v[196:199], v182 offset:21504
	ds_read_b128 v[200:203], v182 offset:22528
	ds_read_b128 v[204:207], v182 offset:23552
	global_load_lds_dwordx4 v2, s[4:5]
	s_mov_b32 m0, s30
	s_nop 0
	s_add_u32 vcc_lo, s4, s0
	s_addc_u32 vcc_hi, s5, s1
	global_load_lds_dwordx4 v2, vcc
	s_barrier
	s_waitcnt lgkmcnt(0)
	v_mfma_f32_16x16x32_bf16 v[68:71], v[136:139], v[152:155], v[68:71]
	v_mfma_f32_16x16x32_bf16 v[64:67], v[144:147], v[152:155], v[64:67]
	v_mfma_f32_16x16x32_bf16 v[52:55], v[136:139], v[164:167], v[52:55]
	v_mfma_f32_16x16x32_bf16 v[48:51], v[144:147], v[164:167], v[48:51]
	v_mfma_f32_16x16x32_bf16 v[36:39], v[136:139], v[176:179], v[36:39]
	v_mfma_f32_16x16x32_bf16 v[32:35], v[144:147], v[176:179], v[32:35]
	v_mfma_f32_16x16x32_bf16 v[20:23], v[136:139], v[200:203], v[20:23]
	v_mfma_f32_16x16x32_bf16 v[16:19], v[144:147], v[200:203], v[16:19]
	v_mfma_f32_16x16x32_bf16 v[68:71], v[140:143], v[160:163], v[68:71]
	v_mfma_f32_16x16x32_bf16 v[64:67], v[148:151], v[160:163], v[64:67]
	v_mfma_f32_16x16x32_bf16 v[52:55], v[140:143], v[172:175], v[52:55]
	v_mfma_f32_16x16x32_bf16 v[48:51], v[148:151], v[172:175], v[48:51]
	v_mfma_f32_16x16x32_bf16 v[36:39], v[140:143], v[196:199], v[36:39]
	v_mfma_f32_16x16x32_bf16 v[32:35], v[148:151], v[196:199], v[32:35]
	v_mfma_f32_16x16x32_bf16 v[20:23], v[140:143], v[204:207], v[20:23]
	v_mfma_f32_16x16x32_bf16 v[16:19], v[148:151], v[204:207], v[16:19]
	s_barrier
	s_add_i32 s100, s44, s27
	s_mov_b32 m0, s100
	s_nop 0
	s_add_u32 vcc_lo, s40, s54
	s_addc_u32 vcc_hi, s41, s55
	global_load_lds_dwordx4 v156, vcc
	s_add_i32 m0, s100, 0x2000
	s_nop 0
	s_add_u32 vcc_lo, s40, s58
	s_addc_u32 vcc_hi, s41, s59
	global_load_lds_dwordx4 v156, vcc
	s_waitcnt vmcnt(6)
	s_barrier
	v_mfma_f32_16x16x32_bf16 v[60:63], v[208:211], v[152:155], v[60:63]
	v_mfma_f32_16x16x32_bf16 v[56:59], v[216:219], v[152:155], v[56:59]
	v_mfma_f32_16x16x32_bf16 v[44:47], v[208:211], v[164:167], v[44:47]
	v_mfma_f32_16x16x32_bf16 v[40:43], v[216:219], v[164:167], v[40:43]
	ds_read_b128 v[136:139], v255 offset:32768
	ds_read_b128 v[140:143], v255 offset:33792
	ds_read_b128 v[144:147], v255 offset:34816
	ds_read_b128 v[148:151], v255 offset:35840
	v_mfma_f32_16x16x32_bf16 v[28:31], v[208:211], v[176:179], v[28:31]
	v_mfma_f32_16x16x32_bf16 v[24:27], v[216:219], v[176:179], v[24:27]
	v_mfma_f32_16x16x32_bf16 v[12:15], v[208:211], v[200:203], v[12:15]
	v_mfma_f32_16x16x32_bf16 v[8:11], v[216:219], v[200:203], v[8:11]
	v_mfma_f32_16x16x32_bf16 v[60:63], v[212:215], v[160:163], v[60:63]
	v_mfma_f32_16x16x32_bf16 v[56:59], v[220:223], v[160:163], v[56:59]
	v_mfma_f32_16x16x32_bf16 v[44:47], v[212:215], v[172:175], v[44:47]
	v_mfma_f32_16x16x32_bf16 v[40:43], v[220:223], v[172:175], v[40:43]
	v_mfma_f32_16x16x32_bf16 v[28:31], v[212:215], v[196:199], v[28:31]
	v_mfma_f32_16x16x32_bf16 v[24:27], v[220:223], v[196:199], v[24:27]
	v_mfma_f32_16x16x32_bf16 v[12:15], v[212:215], v[204:207], v[12:15]
	v_mfma_f32_16x16x32_bf16 v[8:11], v[220:223], v[204:207], v[8:11]
	s_barrier
	s_add_i32 s100, 0, 0x18000
	s_mov_b32 m0, s31
	ds_read_b128 v[152:155], v182 offset:32768
	ds_read_b128 v[160:163], v182 offset:33792
	ds_read_b128 v[164:167], v182 offset:34816
	ds_read_b128 v[172:175], v182 offset:35840
	ds_read_b128 v[176:179], v182 offset:36864
	ds_read_b128 v[196:199], v182 offset:37888
	ds_read_b128 v[200:203], v182 offset:38912
	ds_read_b128 v[204:207], v182 offset:39936
	s_add_u32 vcc_lo, s4, s54
	s_addc_u32 vcc_hi, s5, s55
	global_load_lds_dwordx4 v2, vcc
	s_mov_b32 m0, s34
	s_nop 0
	s_add_u32 vcc_lo, s4, s58
	s_addc_u32 vcc_hi, s5, s59
	global_load_lds_dwordx4 v2, vcc
	s_waitcnt lgkmcnt(8)
	s_barrier
	s_waitcnt lgkmcnt(0)
	v_mfma_f32_16x16x32_bf16 v[132:135], v[136:139], v[152:155], v[132:135]
	v_mfma_f32_16x16x32_bf16 v[128:131], v[144:147], v[152:155], v[128:131]
	v_mfma_f32_16x16x32_bf16 v[116:119], v[136:139], v[164:167], v[116:119]
	v_mfma_f32_16x16x32_bf16 v[112:115], v[144:147], v[164:167], v[112:115]
	v_mfma_f32_16x16x32_bf16 v[100:103], v[136:139], v[176:179], v[100:103]
	v_mfma_f32_16x16x32_bf16 v[96:99], v[144:147], v[176:179], v[96:99]
	v_mfma_f32_16x16x32_bf16 v[84:87], v[136:139], v[200:203], v[84:87]
	v_mfma_f32_16x16x32_bf16 v[80:83], v[144:147], v[200:203], v[80:83]
	v_mfma_f32_16x16x32_bf16 v[132:135], v[140:143], v[160:163], v[132:135]
	v_mfma_f32_16x16x32_bf16 v[128:131], v[148:151], v[160:163], v[128:131]
	v_mfma_f32_16x16x32_bf16 v[116:119], v[140:143], v[172:175], v[116:119]
	v_mfma_f32_16x16x32_bf16 v[112:115], v[148:151], v[172:175], v[112:115]
	v_mfma_f32_16x16x32_bf16 v[100:103], v[140:143], v[196:199], v[100:103]
	v_mfma_f32_16x16x32_bf16 v[96:99], v[148:151], v[196:199], v[96:99]
	v_mfma_f32_16x16x32_bf16 v[84:87], v[140:143], v[204:207], v[84:87]
	v_mfma_f32_16x16x32_bf16 v[80:83], v[148:151], v[204:207], v[80:83]
	s_barrier
; #define G_STAGE(bufoff, gbase, o0, h64) do { \
;         __builtin_amdgcn_global_load_lds((const unsigned*)((const char*)(gbase) + (o0)), (LAS unsigned*)(lds + (bufoff) + ldsw), 16, 0, 0); \
;         __builtin_amdgcn_global_load_lds((const unsigned*)((const char*)(gbase) + (h64) + (o0)), (LAS unsigned*)(lds + (bufoff) + ldsw + 8192), 16, 0, 0); } while (0)
; #define G_LDA(dst, b, h) do { _Pragma("unroll") for (int m = 0; m < 4; ++m) _Pragma("unroll") for (int k = 0; k < 2; ++k) dst[m][k] = *(const LAS bf16x8*)(lds + G_SA(b, h) + aoff + m * 2048 + k * 1024); } while (0)
; #define G_WAIT_V(n) asm volatile("s_waitcnt vmcnt(" #n ")" ::: "memory")
; #define G_WAIT_L(n) asm volatile("s_waitcnt lgkmcnt(" #n ")" ::: "memory")
; #define G_BAR __builtin_amdgcn_s_barrier()
; #define G_SCHED __builtin_amdgcn_sched_barrier(0)
;     ...
;             G_BAR; G_WAIT_L(0); G_MMA(0, 1, At, B1); G_BAR;
;             G_LDA(At, 1, 1); G_STAGE(G_SA(1, 0), a3, cA0, qA);
;             G_BAR; G_WAIT_L(0); G_MMA(1, 0, At, B0); G_BAR; G_SCHED;
;             G_STAGE(G_SB(1, 1), b3 + chB, cB0, qB);
;             G_WAIT_V(6); G_BAR; G_MMA(1, 1, At, B1); G_BAR;
;         }
;         E.template run<cs.kind>(acc, cur, tid);
;         if (!has_next) break;
	s_add_i32 s5, 0, 0x1c000
	s_add_i32 s4, s100, s27
	s_mov_b32 m0, s4
	ds_read_b128 v[208:211], v255 offset:49152
	ds_read_b128 v[212:215], v255 offset:50176
	ds_read_b128 v[216:219], v255 offset:51200
	ds_read_b128 v[220:223], v255 offset:52224
	s_add_u32 vcc_lo, s40, s46
	s_addc_u32 vcc_hi, s41, s47
	global_load_lds_dwordx4 v156, vcc
	s_add_i32 m0, s4, 0x2000
	s_nop 0
	s_add_u32 vcc_lo, s40, s62
	s_addc_u32 vcc_hi, s41, s63
	global_load_lds_dwordx4 v156, vcc
	s_barrier
	s_waitcnt lgkmcnt(0)
	v_mfma_f32_16x16x32_bf16 v[124:127], v[208:211], v[152:155], v[124:127]
	v_mfma_f32_16x16x32_bf16 v[120:123], v[216:219], v[152:155], v[120:123]
	v_mfma_f32_16x16x32_bf16 v[108:111], v[208:211], v[164:167], v[108:111]
	v_mfma_f32_16x16x32_bf16 v[104:107], v[216:219], v[164:167], v[104:107]
	v_mfma_f32_16x16x32_bf16 v[92:95], v[208:211], v[176:179], v[92:95]
	v_mfma_f32_16x16x32_bf16 v[88:91], v[216:219], v[176:179], v[88:91]
	v_mfma_f32_16x16x32_bf16 v[76:79], v[208:211], v[200:203], v[76:79]
	v_mfma_f32_16x16x32_bf16 v[72:75], v[216:219], v[200:203], v[72:75]
	v_mfma_f32_16x16x32_bf16 v[124:127], v[212:215], v[160:163], v[124:127]
	v_mfma_f32_16x16x32_bf16 v[120:123], v[220:223], v[160:163], v[120:123]
	v_mfma_f32_16x16x32_bf16 v[108:111], v[212:215], v[172:175], v[108:111]
	v_mfma_f32_16x16x32_bf16 v[104:107], v[220:223], v[172:175], v[104:107]
	v_mfma_f32_16x16x32_bf16 v[92:95], v[212:215], v[196:199], v[92:95]
	v_mfma_f32_16x16x32_bf16 v[88:91], v[220:223], v[196:199], v[88:91]
	v_mfma_f32_16x16x32_bf16 v[76:79], v[212:215], v[204:207], v[76:79]
	v_mfma_f32_16x16x32_bf16 v[72:75], v[220:223], v[204:207], v[72:75]
	s_barrier
	s_mov_b32 m0, s35
	v_lshl_add_u64 v[226:227], v[224:225], 0, s[46:47]
	ds_read_b128 v[152:155], v182 offset:49152
	ds_read_b128 v[160:163], v182 offset:50176
	ds_read_b128 v[164:167], v182 offset:51200
	ds_read_b128 v[172:175], v182 offset:52224
	ds_read_b128 v[176:179], v182 offset:53248
	ds_read_b128 v[196:199], v182 offset:54272
	ds_read_b128 v[200:203], v182 offset:55296
	ds_read_b128 v[204:207], v182 offset:56320
	global_load_lds_dwordx4 v[226:227], off
	v_lshl_add_u64 v[224:225], v[224:225], 0, s[62:63]
	s_mov_b32 m0, s36
	s_nop 0
	global_load_lds_dwordx4 v[224:225], off
	s_barrier
	s_waitcnt lgkmcnt(0)
	v_mfma_f32_16x16x32_bf16 v[68:71], v[136:139], v[152:155], v[68:71]
	v_mfma_f32_16x16x32_bf16 v[64:67], v[144:147], v[152:155], v[64:67]
	v_mfma_f32_16x16x32_bf16 v[52:55], v[136:139], v[164:167], v[52:55]
	v_mfma_f32_16x16x32_bf16 v[48:51], v[144:147], v[164:167], v[48:51]
	v_mfma_f32_16x16x32_bf16 v[36:39], v[136:139], v[176:179], v[36:39]
	v_mfma_f32_16x16x32_bf16 v[32:35], v[144:147], v[176:179], v[32:35]
	v_mfma_f32_16x16x32_bf16 v[20:23], v[136:139], v[200:203], v[20:23]
	v_mfma_f32_16x16x32_bf16 v[16:19], v[144:147], v[200:203], v[16:19]
	v_mfma_f32_16x16x32_bf16 v[68:71], v[140:143], v[160:163], v[68:71]
	v_mfma_f32_16x16x32_bf16 v[64:67], v[148:151], v[160:163], v[64:67]
	v_mfma_f32_16x16x32_bf16 v[52:55], v[140:143], v[172:175], v[52:55]
	v_mfma_f32_16x16x32_bf16 v[48:51], v[148:151], v[172:175], v[48:51]
	v_mfma_f32_16x16x32_bf16 v[36:39], v[140:143], v[196:199], v[36:39]
	v_mfma_f32_16x16x32_bf16 v[32:35], v[148:151], v[196:199], v[32:35]
	v_mfma_f32_16x16x32_bf16 v[20:23], v[140:143], v[204:207], v[20:23]
	v_mfma_f32_16x16x32_bf16 v[16:19], v[148:151], v[204:207], v[16:19]
	s_barrier
	s_add_i32 s4, s5, s27
	s_mov_b32 m0, s4
	s_nop 0
	s_add_u32 vcc_lo, s40, s64
	s_addc_u32 vcc_hi, s41, s65
	global_load_lds_dwordx4 v156, vcc
	s_add_i32 m0, s4, 0x2000
	s_nop 0
	s_add_u32 vcc_lo, s40, s66
	s_addc_u32 vcc_hi, s41, s67
	global_load_lds_dwordx4 v156, vcc
	s_add_i32 s24, s24, 2
	s_add_u32 s2, s2, 0x100
	s_addc_u32 s3, s3, 0
	s_add_u32 s22, s22, 0x100
	s_addc_u32 s23, s23, 0
	s_cmp_gt_u32 s24, 13
	s_waitcnt vmcnt(6)
	s_barrier
	v_mfma_f32_16x16x32_bf16 v[60:63], v[208:211], v[152:155], v[60:63]
	v_mfma_f32_16x16x32_bf16 v[56:59], v[216:219], v[152:155], v[56:59]
	v_mfma_f32_16x16x32_bf16 v[44:47], v[208:211], v[164:167], v[44:47]
	v_mfma_f32_16x16x32_bf16 v[40:43], v[216:219], v[164:167], v[40:43]
	ds_read_b128 v[136:139], v255 offset:0
	ds_read_b128 v[140:143], v255 offset:1024
	ds_read_b128 v[144:147], v255 offset:2048
	ds_read_b128 v[148:151], v255 offset:3072
	v_mfma_f32_16x16x32_bf16 v[28:31], v[208:211], v[176:179], v[28:31]
	v_mfma_f32_16x16x32_bf16 v[24:27], v[216:219], v[176:179], v[24:27]
	v_mfma_f32_16x16x32_bf16 v[12:15], v[208:211], v[200:203], v[12:15]
	v_mfma_f32_16x16x32_bf16 v[8:11], v[216:219], v[200:203], v[8:11]
	v_mfma_f32_16x16x32_bf16 v[60:63], v[212:215], v[160:163], v[60:63]
	v_mfma_f32_16x16x32_bf16 v[56:59], v[220:223], v[160:163], v[56:59]
	v_mfma_f32_16x16x32_bf16 v[44:47], v[212:215], v[172:175], v[44:47]
	v_mfma_f32_16x16x32_bf16 v[40:43], v[220:223], v[172:175], v[40:43]
	v_mfma_f32_16x16x32_bf16 v[28:31], v[212:215], v[196:199], v[28:31]
	v_mfma_f32_16x16x32_bf16 v[24:27], v[220:223], v[196:199], v[24:27]
	v_mfma_f32_16x16x32_bf16 v[12:15], v[212:215], v[204:207], v[12:15]
	v_mfma_f32_16x16x32_bf16 v[8:11], v[220:223], v[204:207], v[8:11]
	s_cbranch_scc0 .Ldb_PLE1_cont
	v_readfirstlane_b32 s101, v186
	s_cmpk_gt_u32 s101, 0xff
	s_cbranch_scc1 .Ldb_PLE1_young
	s_barrier
	s_mov_b32 s101, 1
	s_branch .Ldb_PLE1_exit

; __device__ __forceinline__ float sigmoidf_(float v) { return __builtin_amdgcn_rcpf(1.0f + __expf(-v)); }
; __device__ __forceinline__ void unpack8(const u32x4 w, f32x4& a, f32x4& b) { a[0] = bf_lo(w.x); a[1] = bf_hi(w.x); a[2] = bf_lo(w.y); a[3] = bf_hi(w.y); b[0] = bf_lo(w.z); b[1] = bf_hi(w.z); b[2] = bf_lo(w.w); b[3] = bf_hi(w.w); }
;     template <int KIND> __device__ __forceinline__ void run(f32x4 (&acc)[2][2][4][2], const Unit& u, int tid_in) const {
;     ...
;         if constexpr (KIND == K_PLE) {
;             const bf16_t* xsrc = mg; float rs[8]; get_rs(u, wr, fr, rs);
; #pragma unroll
;             for (int ai = 0; ai < 2; ++ai)
; #pragma unroll
;                 for (int mh = 0; mh < 2; ++mh) { u32x4 xv[2][2], pv[2][2];
; #pragma unroll
;                     for (int ml = 0; ml < 2; ++ml) { const int m = mh * 2 + ml; int row = rbase + ai * 128 + m * 16; asm volatile("" : "+v"(row));
; #pragma unroll
;                         for (int bj = 0; bj < 2; ++bj) { xv[ml][bj] = *(const u32x4*)(xsrc + (size_t)row * 1024 + u.pn * 256 + bj * 128 + cl); pv[ml][bj] = scr[((ai * 4 + m) * 2 + bj) * 512 + tid]; } }
; #pragma unroll
;                     for (int ml = 0; ml < 2; ++ml) { const int m = mh * 2 + ml; int row = rbase + ai * 128 + m * 16; asm volatile("" : "+v"(row)); float ss = 0.f; const float r = rs[ai * 4 + m];
; #pragma unroll
;                         for (int bj = 0; bj < 2; ++bj) { const size_t off = (size_t)row * 1024 + u.pn * 256 + bj * 128 + cl; f32x4 a = acc[ai][bj][m][0], b = acc[ai][bj][m][1], p0, p1, x0, x1;
;                             unpack8(pv[ml][bj], p0, p1); unpack8(xv[ml][bj], x0, x1);
; #pragma unroll
;                             for (int j = 0; j < 4; ++j) { a[j] = sigmoidf_(a[j] * r) * p0[j]; b[j] = sigmoidf_(b[j] * r) * p1[j]; }
.Ldb_PLE1_exit:
	s_waitcnt lgkmcnt(0)
	v_mov_b32_e32 v136, v180
	s_lshl_b32 s2, s33, 17
	v_readfirstlane_b32 s4, v136
	s_bfe_u32 s53, s4, 0x20006
	s_and_b32 s2, s2, 0x20000
	s_add_u32 s2, s43, s2
	s_addc_u32 s3, s50, 0
	s_lshl_b32 s5, s7, 8
	s_ashr_i32 s7, s4, 2
	s_andn2_b32 s7, s7, 63
	s_add_i32 s7, s7, s5
	s_lshl_b32 s5, s33, 10
	s_add_i32 s5, s5, 0
	s_and_b32 s4, s4, 0xffffff00
	v_and_b32_e32 v0, 15, v136
	s_add_i32 s5, s5, s4
	v_or_b32_e32 v183, s7, v0
	v_lshl_add_u32 v0, v0, 2, s5
	v_add_u32_e32 v0, 0x20010, v0
	v_mov_b32_e32 v138, v183
	v_bfe_u32 v140, v136, 4, 2
	ds_read2_b32 v[176:177], v0 offset1:16
	ds_read2_b32 v[172:173], v0 offset0:32 offset1:48
	ds_read2_b32 v[166:167], v0 offset0:128 offset1:144
	ds_read2_b32 v[160:161], v0 offset0:160 offset1:176
	s_lshl_b32 s22, s6, 8
	v_ashrrev_i32_e32 v139, 31, v138
	v_lshlrev_b32_e32 v137, 3, v140
	v_lshlrev_b64 v[138:139], 11, v[138:139]
	s_ashr_i32 s23, s22, 31
	v_lshl_or_b32 v162, s53, 5, v137
	v_lshl_add_u64 v[138:139], s[8:9], 0, v[138:139]
	s_lshl_b64 s[24:25], s[22:23], 1
	v_lshl_add_u64 v[138:139], v[138:139], 0, s[24:25]
	v_lshlrev_b32_e32 v0, 1, v162
	v_ashrrev_i32_e32 v137, 31, v136
	v_lshl_add_u64 v[138:139], v[138:139], 0, v[0:1]
	v_lshl_add_u64 v[164:165], v[136:137], 4, s[2:3]
	global_load_dwordx4 v[196:199], v[138:139], off
	global_load_dwordx4 v[200:203], v[164:165], off
	s_movk_i32 s2, 0x2000
	v_add_co_u32_e32 v136, vcc, s2, v164
	v_cmp_eq_u32_e64 s[40:41], 0, v140
	s_nop 0
	v_addc_co_u32_e32 v137, vcc, 0, v165, vcc
	global_load_dwordx4 v[204:207], v[138:139], off offset:256
	global_load_dwordx4 v[152:155], v[136:137], off
	v_add_co_u32_e32 v140, vcc, s49, v164
	v_or_b32_e32 v174, 16, v183
	s_nop 0
	v_addc_co_u32_e32 v141, vcc, 0, v165, vcc
	s_movk_i32 s2, 0x6000
	v_mov_b32_e32 v148, v174
	s_waitcnt lgkmcnt(0)
	v_mul_f32_e32 v132, v132, v176
	v_mul_f32_e32 v133, v133, v176
	v_add_co_u32_e32 v142, vcc, s2, v164
	v_mul_f32_e32 v132, 0xbfb8aa3b, v132
	v_mul_f32_e32 v133, 0xbfb8aa3b, v133
	v_ashrrev_i32_e32 v149, 31, v148
	v_addc_co_u32_e32 v143, vcc, 0, v165, vcc
	global_load_dwordx4 v[144:147], v[140:141], off
	global_load_dwordx4 v[136:139], v[142:143], off
	v_exp_f32_e32 v140, v132
	v_exp_f32_e32 v195, v133
	v_lshlrev_b64 v[132:133], 11, v[148:149]
	v_lshl_add_u64 v[132:133], s[8:9], 0, v[132:133]
	v_mul_f32_e32 v128, v128, v176
	v_lshl_add_u64 v[132:133], v[132:133], 0, s[24:25]
	v_mul_f32_e32 v128, 0xbfb8aa3b, v128
	v_lshl_add_u64 v[132:133], v[132:133], 0, v[0:1]
	v_exp_f32_e32 v175, v128
	v_add_f32_e32 v128, 1.0, v140
	global_load_dwordx4 v[148:151], v[132:133], off
	global_load_dwordx4 v[140:143], v[132:133], off offset:256
	v_mul_f32_e32 v129, v129, v176
	v_add_f32_e32 v175, 1.0, v175
	v_mul_f32_e32 v129, 0xbfb8aa3b, v129
	v_rcp_f32_e32 v212, v175
	v_add_f32_e32 v175, 1.0, v195
	v_exp_f32_e32 v195, v129
	v_mul_f32_e32 v134, v134, v176
	v_mul_f32_e32 v134, 0xbfb8aa3b, v134
	v_mul_f32_e32 v130, v130, v176
	v_rcp_f32_e32 v129, v175
	v_add_f32_e32 v175, 1.0, v195
	v_exp_f32_e32 v134, v134
	v_mul_f32_e32 v130, 0xbfb8aa3b, v130
	v_rcp_f32_e32 v213, v175
	v_exp_f32_e32 v175, v130
	v_mul_f32_e32 v130, v135, v176
	v_mul_f32_e32 v130, 0xbfb8aa3b, v130
	v_mul_f32_e32 v131, v131, v176
	v_add_f32_e32 v134, 1.0, v134
	v_exp_f32_e32 v135, v130
	v_mul_f32_e32 v131, 0xbfb8aa3b, v131
	v_rcp_f32_e32 v130, v134
	v_add_f32_e32 v134, 1.0, v175
	v_exp_f32_e32 v175, v131
	v_mov_b32_e32 v178, v183
	v_add_f32_e32 v135, 1.0, v135
	v_mov_b64_e32 v[184:185], s[10:11]
	v_rcp_f32_e32 v128, v128
	v_ashrrev_i32_e32 v179, 31, v178
	v_rcp_f32_e32 v131, v135
	v_add_f32_e32 v135, 1.0, v175
	v_mad_i64_i32 v[132:133], s[2:3], v178, s76, v[184:185]
	v_lshlrev_b64 v[184:185], 11, v[178:179]
	v_rcp_f32_e32 v134, v134
	v_rcp_f32_e32 v135, v135
	v_lshl_add_u64 v[184:185], s[12:13], 0, v[184:185]
	v_lshl_add_u64 v[184:185], v[184:185], 0, s[24:25]
	v_lshl_add_u64 v[184:185], v[184:185], 0, v[0:1]
	v_mov_b32_e32 v163, v1
	v_mul_f32_e32 v124, v124, v176
	s_waitcnt vmcnt(0)
; __device__ __forceinline__ float sigmoidf_(float v) { return __builtin_amdgcn_rcpf(1.0f + __expf(-v)); }
; __device__ __forceinline__ u32x4 pack8(const f32x4 a, const f32x4 b) { u32x4 w; w.x = cvt_pk_bf16(a[0], a[1]); w.y = cvt_pk_bf16(a[2], a[3]); w.z = cvt_pk_bf16(b[0], b[1]); w.w = cvt_pk_bf16(b[2], b[3]); return w; }
; __device__ __forceinline__ void unpack8(const u32x4 w, f32x4& a, f32x4& b) { a[0] = bf_lo(w.x); a[1] = bf_hi(w.x); a[2] = bf_lo(w.y); a[3] = bf_hi(w.y); b[0] = bf_lo(w.z); b[1] = bf_hi(w.z); b[2] = bf_lo(w.w); b[3] = bf_hi(w.w); }
; __device__ __forceinline__ unsigned pack4_fp8(float a, float b, float c, float d) { unsigned w = 0u; w = __builtin_amdgcn_cvt_pk_fp8_f32(a, b, w, false); w = __builtin_amdgcn_cvt_pk_fp8_f32(c, d, w, true); return w; }
; #define MEMFENCE asm volatile("" ::: "memory")
;     template <int KIND> __device__ __forceinline__ void run(f32x4 (&acc)[2][2][4][2], const Unit& u, int tid_in) const {
;     ...
;                     for (int ml = 0; ml < 2; ++ml) { const int m = mh * 2 + ml; int row = rbase + ai * 128 + m * 16; asm volatile("" : "+v"(row)); float ss = 0.f; const float r = rs[ai * 4 + m];
; #pragma unroll
;                         for (int bj = 0; bj < 2; ++bj) { const size_t off = (size_t)row * 1024 + u.pn * 256 + bj * 128 + cl; f32x4 a = acc[ai][bj][m][0], b = acc[ai][bj][m][1], p0, p1, x0, x1;
;                             unpack8(pv[ml][bj], p0, p1); unpack8(xv[ml][bj], x0, x1);
; #pragma unroll
;                             for (int j = 0; j < 4; ++j) { a[j] = sigmoidf_(a[j] * r) * p0[j]; b[j] = sigmoidf_(b[j] * r) * p1[j]; }
;                             const f32x4 o0 = x0 + a, o1 = x1 + b;
;                             *(u32x4*)(xb0 + off) = pack8(o0, o1);
;                             { u32x2 w8; w8.x = pack4_fp8(o0[0], o0[1], o0[2], o0[3]); w8.y = pack4_fp8(o1[0], o1[1], o1[2], o1[3]); *(u32x2*)((unsigned char*)zb + (size_t)row * (ZW * 2) + u.pn * 256 + bj * 128 + cl) = w8; }
;                             ss += (o0[0] * o0[0] + o0[1] * o0[1]) + (o0[2] * o0[2] + o0[3] * o0[3]) + (o1[0] * o1[0] + o1[1] * o1[1]) + (o1[2] * o1[2] + o1[3] * o1[3]); }
;                         ss += __shfl_xor(ss, 16); ss += __shfl_xor(ss, 32);
;                         if (fq == 0) ssq0[((size_t)u.pn * T_TOK + row) * 4 + wc] = ss; }
;                     MEMFENCE; }
	v_lshlrev_b32_e32 v208, 16, v196
	v_and_b32_e32 v209, 0xffff0000, v196
	v_lshlrev_b32_e32 v196, 16, v197
	v_and_b32_e32 v197, 0xffff0000, v197
	v_lshlrev_b32_e32 v214, 16, v200
	v_and_b32_e32 v215, 0xffff0000, v200
	v_lshlrev_b32_e32 v200, 16, v201
	v_and_b32_e32 v201, 0xffff0000, v201
	v_lshlrev_b32_e32 v210, 16, v198
	v_and_b32_e32 v211, 0xffff0000, v198
	v_lshlrev_b32_e32 v198, 16, v199
	v_and_b32_e32 v199, 0xffff0000, v199
	v_lshlrev_b32_e32 v216, 16, v202
	v_and_b32_e32 v217, 0xffff0000, v202
	v_lshlrev_b32_e32 v202, 16, v203
	v_and_b32_e32 v203, 0xffff0000, v203
	v_pk_fma_f32 v[196:197], v[130:131], v[200:201], v[196:197]
	v_pk_fma_f32 v[200:201], v[128:129], v[214:215], v[208:209]
	v_pk_fma_f32 v[134:135], v[134:135], v[202:203], v[198:199]
	v_cvt_pk_bf16_f32 v128, v200, v201
	v_cvt_pk_bf16_f32 v129, v196, v197
	v_pk_fma_f32 v[198:199], v[212:213], v[216:217], v[210:211]
	v_mul_f32_e32 v0, v201, v201
	v_cvt_pk_bf16_f32 v130, v198, v199
	v_cvt_pk_bf16_f32 v131, v134, v135
	global_store_dwordx4 v[184:185], v[128:131], off
	v_mul_f32_e32 v124, 0xbfb8aa3b, v124
	v_mul_f32_e32 v120, v120, v176
	v_lshl_add_u64 v[128:129], v[132:133], 0, s[22:23]
	v_lshl_add_u64 v[130:131], v[128:129], 0, v[162:163]
	v_mul_f32_e32 v128, v197, v197
	v_fmac_f32_e32 v0, v200, v200
	v_fmac_f32_e32 v128, v196, v196
	v_exp_f32_e32 v124, v124
	v_mul_f32_e32 v120, 0xbfb8aa3b, v120
	v_mul_f32_e32 v122, v122, v176
	v_mov_b32_e32 v203, v1
	v_add_f32_e32 v0, v0, v128
	v_mul_f32_e32 v128, v199, v199
	v_exp_f32_e32 v175, v120
	v_mul_f32_e32 v122, 0xbfb8aa3b, v122
	v_cvt_pk_fp8_f32 v203, v198, v199
	v_fmac_f32_e32 v128, v198, v198
	v_mul_f32_e32 v120, v125, v176
	v_lshlrev_b32_e32 v198, 16, v152
	v_and_b32_e32 v199, 0xffff0000, v152
	v_mul_f32_e32 v126, v126, v176
	v_exp_f32_e32 v152, v122
	v_mul_f32_e32 v122, v127, v176
	v_mul_f32_e32 v120, 0xbfb8aa3b, v120
	v_mul_f32_e32 v121, v121, v176
	v_mul_f32_e32 v126, 0xbfb8aa3b, v126
	v_mul_f32_e32 v122, 0xbfb8aa3b, v122
	v_add_f32_e32 v124, 1.0, v124
	v_exp_f32_e32 v125, v120
	v_mul_f32_e32 v121, 0xbfb8aa3b, v121
	v_exp_f32_e32 v126, v126
	v_exp_f32_e32 v127, v122
	v_rcp_f32_e32 v120, v124
	v_add_f32_e32 v124, 1.0, v175
	v_exp_f32_e32 v175, v121
	v_mul_f32_e32 v123, v123, v176
	v_mov_b32_e32 v202, v1
	v_mul_f32_e32 v123, 0xbfb8aa3b, v123
	v_cvt_pk_fp8_f32 v202, v200, v201
	v_add_f32_e32 v125, 1.0, v125
	v_lshlrev_b32_e32 v200, 16, v154
	v_and_b32_e32 v201, 0xffff0000, v154
	v_add_f32_e32 v126, 1.0, v126
	v_add_f32_e32 v127, 1.0, v127
	v_exp_f32_e32 v154, v123
	v_rcp_f32_e32 v121, v125
	v_add_f32_e32 v125, 1.0, v175
	v_rcp_f32_e32 v122, v126
	v_rcp_f32_e32 v123, v127
	v_add_f32_e32 v0, v128, v0
	v_mul_f32_e32 v128, v135, v135
	v_rcp_f32_e32 v124, v124
	v_rcp_f32_e32 v125, v125
	v_fmac_f32_e32 v128, v134, v134
	v_add_f32_e32 v0, v128, v0
	v_lshlrev_b32_e32 v128, 16, v204
	v_and_b32_e32 v129, 0xffff0000, v204
	v_lshlrev_b32_e32 v132, 16, v205
	v_and_b32_e32 v133, 0xffff0000, v205
	v_add_f32_e32 v126, 1.0, v152
	v_lshlrev_b32_e32 v152, 16, v153
	v_and_b32_e32 v153, 0xffff0000, v153
	v_add_f32_e32 v127, 1.0, v154
	v_cvt_pk_fp8_f32 v203, v134, v135 op_sel:[0,0,1]
	v_lshlrev_b32_e32 v134, 16, v206
	v_and_b32_e32 v135, 0xffff0000, v206
	v_rcp_f32_e32 v126, v126
	v_rcp_f32_e32 v127, v127
	v_pk_fma_f32 v[122:123], v[122:123], v[152:153], v[132:133]
	v_pk_fma_f32 v[120:121], v[120:121], v[198:199], v[128:129]
	v_pk_fma_f32 v[128:129], v[124:125], v[200:201], v[134:135]
	v_mul_f32_e32 v124, v121, v121
	v_mul_f32_e32 v125, v123, v123
	v_fmac_f32_e32 v124, v120, v120
	v_fmac_f32_e32 v125, v122, v122
	v_cvt_pk_fp8_f32 v202, v196, v197 op_sel:[0,0,1]
	v_lshlrev_b32_e32 v196, 16, v207
	v_and_b32_e32 v197, 0xffff0000, v207
	v_lshlrev_b32_e32 v154, 16, v155
	v_and_b32_e32 v155, 0xffff0000, v155
	v_add_f32_e32 v124, v124, v125
	v_mul_f32_e32 v125, v129, v129
	v_pk_fma_f32 v[132:133], v[126:127], v[154:155], v[196:197]
	v_fmac_f32_e32 v125, v128, v128
	v_add_f32_e32 v124, v125, v124
	v_mul_f32_e32 v125, v133, v133
	v_fmac_f32_e32 v125, v132, v132
	v_add_f32_e32 v124, v125, v124
	v_add_f32_e32 v0, v0, v124
	v_xor_b32_e32 v124, 16, v190
	v_cmp_lt_i32_e32 vcc, v124, v192
	v_mov_b32_e32 v134, v1
	global_store_dwordx2 v[130:131], v[202:203], off
	v_cndmask_b32_e32 v124, v190, v124, vcc
	v_lshlrev_b32_e32 v124, 2, v124
	ds_bpermute_b32 v125, v124, v0
	v_cvt_pk_fp8_f32 v134, v120, v121
	v_cvt_pk_bf16_f32 v126, v120, v121
	v_xor_b32_e32 v120, 32, v190
	v_mov_b32_e32 v135, v1
	v_cmp_lt_i32_e32 vcc, v120, v192
	v_cvt_pk_fp8_f32 v135, v128, v129
	s_waitcnt lgkmcnt(0)
	v_add_f32_e32 v0, v0, v125
	v_cndmask_b32_e32 v120, v190, v120, vcc
	v_lshlrev_b32_e32 v125, 2, v120
	ds_bpermute_b32 v120, v125, v0
	v_cvt_pk_fp8_f32 v134, v122, v123 op_sel:[0,0,1]
	v_cvt_pk_fp8_f32 v135, v132, v133 op_sel:[0,0,1]
	v_cvt_pk_bf16_f32 v127, v122, v123
	v_cvt_pk_bf16_f32 v128, v128, v129
	v_cvt_pk_bf16_f32 v129, v132, v133
	global_store_dwordx4 v[184:185], v[126:129], off offset:256
	global_store_dwordx2 v[130:131], v[134:135], off offset:128
	s_and_saveexec_b64 s[2:3], s[40:41]
	s_cbranch_execz .LBB0_1286
	s_ashr_i32 s7, s6, 31
	s_lshl_b64 s[4:5], s[6:7], 19
	s_add_u32 s4, s39, s4
	s_addc_u32 s5, s42, s5
	s_waitcnt lgkmcnt(0)
	v_add_f32_e32 v0, v0, v120
	v_lshl_add_u64 v[120:121], v[178:179], 4, s[4:5]
	s_lshl_b32 s74, s53, 2
	v_lshl_add_u64 v[120:121], v[120:121], 0, s[74:75]
	global_store_dword v[120:121], v0, off
